# scalar f32 ops from the packed split re-encoded as VOP2 (e32 / v_fmac) where operands allow: 1442 instructions 8 to 4 bytes
# baseline (speedup 1.0000x reference)
; DI void transpose_tile(const float* __restrict__ W, bf16_t* __restrict__ out, int K, int N, int k0, int n0, const float* __restrict__ scale, float* tile) {
;     ...
;   for (int i = 0; i < 16; ++i) {
;     const int kk = i * 4 + (tid >> 6), nn = tid & 63, n = n0 + nn;
;     tv[i] = (n < N) ? W[(size_t)(k0 + kk) * N + n] : 0.f;
;   }
; #pragma unroll
;   for (int i = 0; i < 16; ++i) {
;     const int kk = i * 4 + (tid >> 6), nn = tid & 63;
;     float v = tv[i];
;     if (scale) v *= scale[k0 + kk];
;     tile[kk * 65 + nn] = v;
.LBB0_41:
	s_andn2_b64 vcc, exec, s[6:7]
	s_cbranch_vccnz .LBB0_49
	s_add_i32 s6, s57, 0x100
	s_and_b32 s48, s6, 0x7fffffc0
	s_add_i32 s6, s55, 0x1000
	s_and_b32 s97, s6, 0x3c0
	v_or_b32_e32 v0, s97, v181
	v_or_b32_e32 v8, s48, v254
	v_lshl_or_b32 v38, v8, 10, v0
	v_add_u32_e32 v2, 0x1000, v38
	v_mov_b32_e32 v3, v39
	v_lshl_add_u64 v[0:1], v[38:39], 2, s[38:39]
	v_lshl_add_u64 v[2:3], v[2:3], 2, s[38:39]
	global_load_dword v15, v[0:1], off
	global_load_dword v17, v[2:3], off
	v_add_u32_e32 v2, 0x2000, v38
	v_mov_b32_e32 v3, v39
	v_lshl_add_u64 v[2:3], v[2:3], 2, s[38:39]
	global_load_dword v18, v[2:3], off
	v_add_u32_e32 v2, 0x3000, v38
	v_mov_b32_e32 v3, v39
	v_lshl_add_u64 v[2:3], v[2:3], 2, s[38:39]
	global_load_dword v19, v[2:3], off
	v_add_co_u32_e32 v2, vcc, s60, v0
	v_cmp_ne_u32_e64 s[6:7], 1, v177
	s_nop 0
	v_addc_co_u32_e32 v3, vcc, 0, v1, vcc
	global_load_dword v4, v[2:3], off
	v_add_u32_e32 v2, 0x5000, v38
	v_mov_b32_e32 v3, v39
	v_lshl_add_u64 v[2:3], v[2:3], 2, s[38:39]
	global_load_dword v5, v[2:3], off
	v_add_u32_e32 v2, 0x6000, v38
	v_mov_b32_e32 v3, v39
	v_lshl_add_u64 v[2:3], v[2:3], 2, s[38:39]
	global_load_dword v6, v[2:3], off
	v_add_u32_e32 v2, 0x7000, v38
	v_mov_b32_e32 v3, v39
	v_lshl_add_u64 v[2:3], v[2:3], 2, s[38:39]
	global_load_dword v7, v[2:3], off
	v_add_co_u32_e32 v2, vcc, s61, v0
	s_nop 1
	v_addc_co_u32_e32 v3, vcc, 0, v1, vcc
	v_add_co_u32_e32 v0, vcc, s3, v0
	global_load_dword v12, v[2:3], off
	s_nop 0
	v_addc_co_u32_e32 v1, vcc, 0, v1, vcc
	global_load_dword v0, v[0:1], off
	v_add_u32_e32 v2, 0x9000, v38
	v_mov_b32_e32 v3, v39
	v_lshl_add_u64 v[2:3], v[2:3], 2, s[38:39]
	global_load_dword v13, v[2:3], off
	v_add_u32_e32 v2, 0xa000, v38
	v_mov_b32_e32 v3, v39
	v_lshl_add_u64 v[2:3], v[2:3], 2, s[38:39]
	global_load_dword v14, v[2:3], off
	v_add_u32_e32 v2, 0xb000, v38
	v_mov_b32_e32 v3, v39
	v_lshl_add_u64 v[2:3], v[2:3], 2, s[38:39]
	global_load_dword v16, v[2:3], off
	v_add_u32_e32 v2, 0xd000, v38
	v_mov_b32_e32 v3, v39
	v_lshl_add_u64 v[2:3], v[2:3], 2, s[38:39]
	global_load_dword v1, v[2:3], off
	v_add_u32_e32 v2, 0xe000, v38
	v_mov_b32_e32 v3, v39
	v_add_u32_e32 v38, 0xf000, v38
	v_lshl_add_u64 v[2:3], v[2:3], 2, s[38:39]
	v_lshl_add_u64 v[10:11], v[38:39], 2, s[38:39]
	global_load_dword v2, v[2:3], off
	s_andn2_b64 vcc, exec, s[40:41]
	global_load_dword v3, v[10:11], off
	v_add_u32_e32 v38, s48, v254
	s_cbranch_vccnz .LBB0_99
	v_mov_b32_e32 v9, v39
	v_lshl_add_u64 v[8:9], v[8:9], 2, s[22:23]
	global_load_dword v8, v[8:9], off
	v_lshl_add_u64 v[10:11], v[38:39], 2, s[22:23]
	global_load_dword v20, v[10:11], off offset:32
	global_load_dword v9, v[10:11], off offset:16
	global_load_dword v21, v[10:11], off offset:48
	s_waitcnt vmcnt(3)
	v_mul_f32_e32 v8, v15, v8
	s_waitcnt vmcnt(2)
	v_mul_f32_e32 v20, v18, v20
	s_waitcnt vmcnt(1)
	v_mul_f32_e32 v9, v17, v9
	s_waitcnt vmcnt(0)
	v_mul_f32_e32 v21, v19, v21
	ds_write_b32 v175, v8
	ds_write_b32 v185, v9
	ds_write_b32 v185, v20 offset:1040
	ds_write_b32 v185, v21 offset:2080
	global_load_dword v8, v[10:11], off offset:64
	global_load_dword v9, v[10:11], off offset:80
	global_load_dword v20, v[10:11], off offset:96
	global_load_dword v21, v[10:11], off offset:112
	s_waitcnt vmcnt(2)
	v_mul_f32_e32 v8, v4, v8
	v_mul_f32_e32 v9, v5, v9
	s_waitcnt vmcnt(0)
	v_mul_f32_e32 v10, v6, v20
	v_mul_f32_e32 v11, v7, v21
	s_cbranch_execnz .LBB0_45

; DI void transpose_tile(const float* __restrict__ W, bf16_t* __restrict__ out, int K, int N, int k0, int n0, const float* __restrict__ scale, float* tile) {
;     ...
;   for (int i = 0; i < 16; ++i) {
;     const int kk = i * 4 + (tid >> 6), nn = tid & 63, n = n0 + nn;
;     tv[i] = (n < N) ? W[(size_t)(k0 + kk) * N + n] : 0.f;
;   }
; #pragma unroll
;   for (int i = 0; i < 16; ++i) {
;     const int kk = i * 4 + (tid >> 6), nn = tid & 63;
;     float v = tv[i];
;     if (scale) v *= scale[k0 + kk];
;     tile[kk * 65 + nn] = v;
.LBB0_45:
	s_and_b64 vcc, exec, s[6:7]
	ds_write_b32 v185, v8 offset:3120
	ds_write_b32 v185, v9 offset:4160
	ds_write_b32 v185, v10 offset:5200
	ds_write_b32 v185, v11 offset:6240
	s_cbranch_vccnz .LBB0_100
	s_waitcnt vmcnt(10)
	v_lshl_add_u64 v[4:5], v[38:39], 2, s[22:23]
	global_load_dword v10, v[4:5], off offset:128
	global_load_dword v11, v[4:5], off offset:144
	global_load_dword v15, v[4:5], off offset:160
	global_load_dword v17, v[4:5], off offset:176
	global_load_dword v6, v[4:5], off offset:192
	global_load_dword v7, v[4:5], off offset:208
	global_load_dword v8, v[4:5], off offset:224
	global_load_dword v9, v[4:5], off offset:240
	s_waitcnt vmcnt(7)
	v_mul_f32_e32 v10, v12, v10
	s_waitcnt vmcnt(6)
	v_mul_f32_e32 v11, v13, v11
	s_waitcnt vmcnt(5)
	v_mul_f32_e32 v15, v14, v15
	s_waitcnt vmcnt(4)
	v_mul_f32_e32 v17, v16, v17
	ds_write_b32 v185, v10 offset:7280
	ds_write_b32 v185, v11 offset:8320
	ds_write_b32 v185, v15 offset:9360
	ds_write_b32 v185, v17 offset:10400
	s_waitcnt vmcnt(2)
	v_mul_f32_e32 v4, v0, v6
	v_mul_f32_e32 v5, v1, v7
	s_waitcnt vmcnt(0)
	v_mul_f32_e32 v6, v2, v8
	v_mul_f32_e32 v7, v3, v9
	s_cbranch_execnz .LBB0_48

; DI void transpose_tile(const float* __restrict__ W, bf16_t* __restrict__ out, int K, int N, int k0, int n0, const float* __restrict__ scale, float* tile) {
;     ...
;   for (int i = 0; i < 16; ++i) {
;     const int kk = i * 4 + (tid >> 6), nn = tid & 63, n = n0 + nn;
;     tv[i] = (n < N) ? W[(size_t)(k0 + kk) * N + n] : 0.f;
;   }
; #pragma unroll
;   for (int i = 0; i < 16; ++i) {
;     const int kk = i * 4 + (tid >> 6), nn = tid & 63;
;     float v = tv[i];
;     if (scale) v *= scale[k0 + kk];
;     tile[kk * 65 + nn] = v;
.LBB0_50:
	s_andn2_b64 vcc, exec, s[6:7]
	s_cbranch_vccnz .LBB0_58
	s_and_b32 s6, s2, 0xff
	s_mulk_i32 s6, 0xab
	s_lshr_b32 s6, s6, 11
	s_lshl_b32 s48, s6, 6
	s_mul_i32 s6, s6, 12
	s_sub_i32 s6, s2, s6
	s_and_b32 s6, s6, 0xff
	s_lshl_b32 s97, s6, 6
	v_or_b32_e32 v0, s97, v181
	v_or_b32_e32 v8, s48, v254
	v_mad_u32_u24 v38, v8, s62, v0
	v_add_u32_e32 v4, 0x1800, v38
	v_mov_b32_e32 v5, v39
	v_add_u32_e32 v6, 0x2400, v38
	v_mov_b32_e32 v7, v39
	v_add_u32_e32 v12, 0x3c00, v38
	v_mov_b32_e32 v13, v39
	v_lshl_add_u64 v[0:1], v[38:39], 2, s[20:21]
	v_add_u32_e32 v2, 0xc00, v38
	v_mov_b32_e32 v3, v39
	v_lshl_add_u64 v[4:5], v[4:5], 2, s[20:21]
	v_lshl_add_u64 v[6:7], v[6:7], 2, s[20:21]
	v_add_u32_e32 v10, 0x3000, v38
	v_mov_b32_e32 v11, v39
	v_lshl_add_u64 v[12:13], v[12:13], 2, s[20:21]
	v_add_u32_e32 v14, 0x4800, v38
	v_mov_b32_e32 v15, v39
	v_add_u32_e32 v16, 0x5400, v38
	v_mov_b32_e32 v17, v39
	v_lshl_add_u64 v[2:3], v[2:3], 2, s[20:21]
	v_lshl_add_u64 v[10:11], v[10:11], 2, s[20:21]
	v_lshl_add_u64 v[14:15], v[14:15], 2, s[20:21]
	v_lshl_add_u64 v[20:21], v[16:17], 2, s[20:21]
	global_load_dword v16, v[0:1], off
	global_load_dword v17, v[2:3], off
	global_load_dword v18, v[4:5], off
	global_load_dword v19, v[6:7], off
	s_nop 0
	global_load_dword v6, v[10:11], off
	global_load_dword v7, v[12:13], off
	global_load_dword v4, v[14:15], off
	global_load_dword v5, v[20:21], off
	v_add_u32_e32 v12, 0x8400, v38
	v_mov_b32_e32 v13, v39
	v_lshl_add_u64 v[20:21], v[12:13], 2, s[20:21]
	v_add_u32_e32 v12, 0x9000, v38
	v_add_u32_e32 v0, 0x6000, v38
	v_mov_b32_e32 v1, v39
	v_add_u32_e32 v2, 0x6c00, v38
	v_mov_b32_e32 v3, v39
	v_lshl_add_u64 v[22:23], v[12:13], 2, s[20:21]
	v_add_u32_e32 v12, 0x9c00, v38
	v_lshl_add_u64 v[0:1], v[0:1], 2, s[20:21]
	v_lshl_add_u64 v[2:3], v[2:3], 2, s[20:21]
	v_add_u32_e32 v10, 0x7800, v38
	v_mov_b32_e32 v11, v39
	v_lshl_add_u64 v[24:25], v[12:13], 2, s[20:21]
	v_add_u32_e32 v12, 0xa800, v38
	v_add_u32_e32 v38, 0xb400, v38
	v_lshl_add_u64 v[10:11], v[10:11], 2, s[20:21]
	v_lshl_add_u64 v[26:27], v[12:13], 2, s[20:21]
	v_lshl_add_u64 v[28:29], v[38:39], 2, s[20:21]
	global_load_dword v12, v[0:1], off
	global_load_dword v13, v[2:3], off
	global_load_dword v14, v[10:11], off
	global_load_dword v15, v[20:21], off
	s_nop 0
	global_load_dword v2, v[22:23], off
	global_load_dword v3, v[24:25], off
	global_load_dword v0, v[26:27], off
	global_load_dword v1, v[28:29], off
	v_cmp_ne_u32_e64 s[6:7], 1, v179
	s_andn2_b64 vcc, exec, s[36:37]
	v_add_lshl_u32 v20, s48, v254, 2
	s_cbranch_vccnz .LBB0_97
	v_lshlrev_b32_e32 v8, 2, v8
	global_load_dword v8, v8, s[18:19]
	s_nop 0
	global_load_dword v9, v20, s[18:19] offset:16
	global_load_dword v10, v20, s[18:19] offset:32
	global_load_dword v11, v20, s[18:19] offset:48
	s_waitcnt vmcnt(3)
	v_mul_f32_e32 v8, v16, v8
	s_waitcnt vmcnt(2)
	v_mul_f32_e32 v9, v17, v9
	s_waitcnt vmcnt(1)
	v_mul_f32_e32 v10, v18, v10
	s_waitcnt vmcnt(0)
	v_mul_f32_e32 v11, v19, v11
	ds_write_b32 v175, v8
	ds_write_b32 v185, v9
	ds_write_b32 v185, v10 offset:1040
	ds_write_b32 v185, v11 offset:2080
	global_load_dword v8, v20, s[18:19] offset:64
	global_load_dword v9, v20, s[18:19] offset:80
	global_load_dword v10, v20, s[18:19] offset:96
	global_load_dword v11, v20, s[18:19] offset:112
	s_waitcnt vmcnt(2)
	v_mul_f32_e32 v8, v6, v8
	v_mul_f32_e32 v9, v7, v9
	s_waitcnt vmcnt(0)
	v_mul_f32_e32 v10, v4, v10
	v_mul_f32_e32 v11, v5, v11
	s_cbranch_execnz .LBB0_54

; DI void transpose_tile(const float* __restrict__ W, bf16_t* __restrict__ out, int K, int N, int k0, int n0, const float* __restrict__ scale, float* tile) {
;     ...
; #pragma unroll
;   for (int i = 0; i < 16; ++i) {
;     const int kk = i * 4 + (tid >> 6), nn = tid & 63;
;     float v = tv[i];
;     if (scale) v *= scale[k0 + kk];
;     tile[kk * 65 + nn] = v;
.LBB0_54:
	s_and_b64 vcc, exec, s[6:7]
	ds_write_b32 v185, v8 offset:3120
	ds_write_b32 v185, v9 offset:4160
	ds_write_b32 v185, v10 offset:5200
	ds_write_b32 v185, v11 offset:6240
	s_cbranch_vccnz .LBB0_98
	global_load_dword v8, v20, s[18:19] offset:128
	global_load_dword v9, v20, s[18:19] offset:144
	global_load_dword v10, v20, s[18:19] offset:160
	global_load_dword v11, v20, s[18:19] offset:176
	global_load_dword v4, v20, s[18:19] offset:192
	global_load_dword v5, v20, s[18:19] offset:208
	global_load_dword v6, v20, s[18:19] offset:224
	global_load_dword v7, v20, s[18:19] offset:240
	s_waitcnt vmcnt(7)
	v_mul_f32_e32 v8, v12, v8
	s_waitcnt vmcnt(6)
	v_mul_f32_e32 v9, v13, v9
	s_waitcnt vmcnt(5)
	v_mul_f32_e32 v10, v14, v10
	s_waitcnt vmcnt(4)
	v_mul_f32_e32 v11, v15, v11
	ds_write_b32 v185, v8 offset:7280
	ds_write_b32 v185, v9 offset:8320
	ds_write_b32 v185, v10 offset:9360
	ds_write_b32 v185, v11 offset:10400
	s_waitcnt vmcnt(2)
	v_mul_f32_e32 v4, v2, v4
	v_mul_f32_e32 v5, v3, v5
	s_waitcnt vmcnt(0)
	v_mul_f32_e32 v6, v0, v6
	v_mul_f32_e32 v7, v1, v7
	s_cbranch_execnz .LBB0_57

; DI void ada_item(const Params& p, float* red, int item) {
;     ...
;   for (int kq = 0; kq < 2; ++kq) {
;     float wv[32];
; #pragma unroll
;     for (int j = 0; j < 32; ++j) wv[j] = p.w_ada[(size_t)(ks * 64 + kq * 32 + j) * 3072 + n];
; #pragma unroll
;     for (int j = 0; j < 32; ++j) {
;       const int k = ks * 64 + kq * 32 + j;
;       const float c0 = p.c[k], c1 = p.c[1024 + k];
;       a0 += (c0 / (1.f + __expf(-c0))) * wv[j];
.LBB0_94:
	s_andn2_b64 vcc, exec, s[6:7]
	s_cbranch_vccnz .LBB0_23
	v_ashrrev_i32_e32 v147, 31, v146
	v_lshl_add_u64 v[160:161], v[146:147], 2, s[12:13]
	v_lshl_add_u64 v[162:163], v[50:51], 2, v[160:161]
	v_add_co_u32_e32 v0, vcc, 0x3000, v162
	v_lshl_add_u64 v[2:3], v[52:53], 2, v[160:161]
	s_nop 0
	v_addc_co_u32_e32 v1, vcc, 0, v163, vcc
	v_add_co_u32_e32 v4, vcc, 0x9000, v162
	s_movk_i32 s6, 0x6000
	s_nop 0
	v_addc_co_u32_e32 v5, vcc, 0, v163, vcc
	v_add_co_u32_e32 v6, vcc, s6, v2
	s_mov_b32 s6, 0xf000
	s_nop 0
	v_addc_co_u32_e32 v7, vcc, 0, v3, vcc
	v_add_co_u32_e32 v8, vcc, s6, v162
	s_mov_b32 s6, 0x12000
	s_nop 0
	v_addc_co_u32_e32 v9, vcc, 0, v163, vcc
	v_add_co_u32_e32 v10, vcc, 0xc000, v2
	v_lshl_add_u64 v[36:37], v[54:55], 2, v[160:161]
	s_nop 0
	v_addc_co_u32_e32 v11, vcc, 0, v3, vcc
	v_add_co_u32_e32 v12, vcc, s52, v162
	v_lshl_add_u64 v[40:41], v[56:57], 2, v[160:161]
	s_nop 0
	v_addc_co_u32_e32 v13, vcc, 0, v163, vcc
	global_load_dword v212, v[162:163], off
	global_load_dword v34, v[0:1], off
	global_load_dword v30, v[2:3], off
	global_load_dword v28, v[4:5], off
	global_load_dword v26, v[6:7], off
	global_load_dword v24, v[8:9], off
	global_load_dword v22, v[10:11], off
	global_load_dword v20, v[12:13], off
	s_nop 0
	global_load_dwordx4 v[8:11], v[132:133], off offset:16
	global_load_dwordx4 v[12:15], v[132:133], off
	global_load_dwordx4 v[16:19], v[134:135], off
	v_add_co_u32_e32 v32, vcc, s6, v2
	global_load_dwordx4 v[4:7], v[134:135], off offset:32
	s_nop 0
	v_addc_co_u32_e32 v33, vcc, 0, v3, vcc
	global_load_dwordx4 v[0:3], v[132:133], off offset:32
	v_add_co_u32_e32 v186, vcc, s53, v162
	v_lshl_add_u64 v[44:45], v[58:59], 2, v[160:161]
	s_nop 0
	v_addc_co_u32_e32 v187, vcc, 0, v163, vcc
	v_add_co_u32_e32 v190, vcc, s79, v162
	v_lshl_add_u64 v[188:189], v[60:61], 2, v[160:161]
	s_nop 0
	v_addc_co_u32_e32 v191, vcc, 0, v163, vcc
	v_lshl_add_u64 v[192:193], v[62:63], 2, v[160:161]
	global_load_dword v32, v[32:33], off
	s_nop 0
	global_load_dword v208, v[36:37], off
	global_load_dword v210, v[40:41], off
	global_load_dword v206, v[44:45], off
	global_load_dword v204, v[186:187], off
	global_load_dword v202, v[188:189], off
	global_load_dword v200, v[190:191], off
	global_load_dword v198, v[192:193], off
	v_add_co_u32_e32 v36, vcc, s3, v162
	v_lshl_add_u64 v[40:41], v[64:65], 2, v[160:161]
	s_nop 0
	v_addc_co_u32_e32 v37, vcc, 0, v163, vcc
	v_add_co_u32_e32 v44, vcc, s80, v162
	v_lshl_add_u64 v[186:187], v[66:67], 2, v[160:161]
	s_nop 0
	v_addc_co_u32_e32 v45, vcc, 0, v163, vcc
	v_add_co_u32_e32 v218, vcc, s81, v162
	v_lshl_add_u64 v[188:189], v[68:69], 2, v[160:161]
	s_nop 0
	v_addc_co_u32_e32 v219, vcc, 0, v163, vcc
	v_lshl_add_u64 v[214:215], v[70:71], 2, v[160:161]
	v_lshl_add_u64 v[216:217], v[72:73], 2, v[160:161]
	global_load_dword v196, v[36:37], off
	global_load_dword v194, v[40:41], off
	global_load_dword v192, v[44:45], off
	global_load_dword v190, v[186:187], off
	s_nop 0
	global_load_dword v186, v[188:189], off
	s_nop 0
	global_load_dword v188, v[214:215], off
	global_load_dword v184, v[216:217], off
	global_load_dword v182, v[218:219], off
	v_add_co_u32_e32 v40, vcc, s82, v162
	v_lshl_add_u64 v[36:37], v[74:75], 2, v[160:161]
	s_nop 0
	v_addc_co_u32_e32 v41, vcc, 0, v163, vcc
	v_add_co_u32_e32 v214, vcc, s83, v162
	v_lshl_add_u64 v[44:45], v[76:77], 2, v[160:161]
	s_nop 0
	v_addc_co_u32_e32 v215, vcc, 0, v163, vcc
	v_add_co_u32_e32 v218, vcc, s84, v162
	v_lshl_add_u64 v[216:217], v[78:79], 2, v[160:161]
	s_nop 0
	v_addc_co_u32_e32 v219, vcc, 0, v163, vcc
	v_lshl_add_u64 v[220:221], v[80:81], 2, v[160:161]
	v_lshl_add_u64 v[222:223], v[82:83], 2, v[160:161]
	global_load_dword v180, v[36:37], off
	global_load_dword v178, v[40:41], off
	global_load_dword v174, v[44:45], off
	global_load_dword v172, v[214:215], off
	global_load_dword v170, v[216:217], off
	global_load_dword v168, v[218:219], off
	global_load_dword v166, v[220:221], off
	global_load_dword v164, v[222:223], off
	global_load_dwordx3 v[36:38], v[132:133], off offset:48
	global_load_dwordx3 v[40:42], v[132:133], off offset:244
	s_nop 0
	global_load_dwordx4 v[216:219], v[134:135], off offset:16
	global_load_dwordx3 v[44:46], v[134:135], off offset:48
	v_lshl_add_u64 v[224:225], v[122:123], 2, v[160:161]
	s_waitcnt vmcnt(31)
	v_mul_f32_e32 v21, 0xbfb8aa3b, v12
	v_exp_f32_e32 v214, v21
	s_waitcnt vmcnt(30)
	v_mul_f32_e32 v21, 0xbfb8aa3b, v16
	v_exp_f32_e32 v215, v21
	s_waitcnt vmcnt(28)
; DI void ada_item(const Params& p, float* red, int item) {
;     ...
;     for (int j = 0; j < 32; ++j) {
;       const int k = ks * 64 + kq * 32 + j;
;       const float c0 = p.c[k], c1 = p.c[1024 + k];
;       a0 += (c0 / (1.f + __expf(-c0))) * wv[j];
;       a1 += (c1 / (1.f + __expf(-c1))) * wv[j];
;     }
	v_mul_f32_e32 v21, 0xbfb8aa3b, v0
	v_add_f32_e32 v214, 1.0, v214
	v_add_f32_e32 v215, 1.0, v215
	v_exp_f32_e32 v220, v21
	v_div_scale_f32 v23, s[6:7], v215, v215, v16
	v_rcp_f32_e32 v25, v23
	v_mul_f32_e32 v21, 0xbfb8aa3b, v4
	v_exp_f32_e32 v221, v21
	v_fma_f32 v21, -v23, v25, 1.0
	v_fmac_f32_e32 v25, v21, v25
	v_div_scale_f32 v21, vcc, v16, v215, v16
	v_mul_f32_e32 v27, v21, v25
	v_fma_f32 v29, -v23, v27, v21
	v_fmac_f32_e32 v27, v29, v25
	v_fma_f32 v21, -v23, v27, v21
	v_div_scale_f32 v23, s[6:7], v214, v214, v12
	v_rcp_f32_e32 v29, v23
	v_div_fmas_f32 v21, v21, v25, v27
	v_mul_f32_e32 v25, 0xbfb8aa3b, v13
	v_exp_f32_e32 v222, v25
	v_mul_f32_e32 v25, 0xbfb8aa3b, v17
	v_div_fixup_f32 v215, v21, v215, v16
	v_fma_f32 v16, -v23, v29, 1.0
	v_exp_f32_e32 v223, v25
	v_fmac_f32_e32 v29, v16, v29
	v_div_scale_f32 v16, vcc, v12, v214, v12
	v_mul_f32_e32 v21, v16, v29
	v_fma_f32 v25, -v23, v21, v16
	v_fmac_f32_e32 v21, v25, v29
	v_add_f32_e32 v222, 1.0, v222
	v_add_f32_e32 v223, 1.0, v223
	v_fma_f32 v16, -v23, v21, v16
	v_div_scale_f32 v23, s[6:7], v223, v223, v17
	v_rcp_f32_e32 v25, v23
	v_div_fmas_f32 v16, v16, v29, v21
	v_div_fixup_f32 v214, v16, v214, v12
	v_fma_f32 v213, v212, v215, 0
	v_fma_f32 v212, v212, v214, 0
	v_fma_f32 v12, -v23, v25, 1.0
	v_fmac_f32_e32 v25, v12, v25
	v_div_scale_f32 v12, vcc, v17, v223, v17
	v_mul_f32_e32 v16, v12, v25
	v_fma_f32 v21, -v23, v16, v12
	v_fmac_f32_e32 v16, v21, v25
	v_div_scale_f32 v21, s[6:7], v222, v222, v13
	v_fma_f32 v12, -v23, v16, v12
	v_rcp_f32_e32 v23, v21
	v_div_fmas_f32 v12, v12, v25, v16
	v_mul_f32_e32 v25, 0xbfb8aa3b, v14
	v_exp_f32_e32 v214, v25
	v_mul_f32_e32 v25, 0xbfb8aa3b, v18
	v_div_fixup_f32 v17, v12, v223, v17
	v_fma_f32 v12, -v21, v23, 1.0
	v_exp_f32_e32 v215, v25
	v_fmac_f32_e32 v23, v12, v23
	v_div_scale_f32 v12, vcc, v13, v222, v13
	v_mul_f32_e32 v16, v12, v23
	v_fma_f32 v25, -v21, v16, v12
	v_fmac_f32_e32 v16, v25, v23
	v_add_f32_e32 v214, 1.0, v214
	v_add_f32_e32 v215, 1.0, v215
	v_fma_f32 v12, -v21, v16, v12
	v_div_scale_f32 v21, s[6:7], v215, v215, v18
	v_rcp_f32_e32 v25, v21
	v_div_fmas_f32 v12, v12, v23, v16
	v_div_fixup_f32 v16, v12, v222, v13
	v_fma_f32 v12, v34, v16, v212
	v_fma_f32 v13, v34, v17, v213
	v_fma_f32 v16, -v21, v25, 1.0
	v_fmac_f32_e32 v25, v16, v25
	v_div_scale_f32 v16, vcc, v18, v215, v18
	v_mul_f32_e32 v17, v16, v25
	v_fma_f32 v23, -v21, v17, v16
	v_fmac_f32_e32 v17, v23, v25
	v_fma_f32 v16, -v21, v17, v16
	v_div_scale_f32 v21, s[6:7], v214, v214, v14
	v_rcp_f32_e32 v23, v21
	v_div_fmas_f32 v16, v16, v25, v17
	v_mul_f32_e32 v25, 0xbfb8aa3b, v15
	v_exp_f32_e32 v34, v25
	v_mul_f32_e32 v25, 0xbfb8aa3b, v19
	v_div_fixup_f32 v17, v16, v215, v18
	v_fma_f32 v16, -v21, v23, 1.0
	v_exp_f32_e32 v35, v25
	v_fmac_f32_e32 v23, v16, v23
	v_div_scale_f32 v16, vcc, v14, v214, v14
	v_mul_f32_e32 v18, v16, v23
	v_fma_f32 v25, -v21, v18, v16
	v_fmac_f32_e32 v18, v25, v23
	v_add_f32_e32 v34, 1.0, v34
	v_add_f32_e32 v35, 1.0, v35
	v_fma_f32 v16, -v21, v18, v16
	v_div_scale_f32 v21, s[6:7], v35, v35, v19
	v_rcp_f32_e32 v25, v21
	v_div_fmas_f32 v16, v16, v23, v18
	v_div_fixup_f32 v16, v16, v214, v14
	v_fmac_f32_e32 v12, v30, v16
	v_fmac_f32_e32 v13, v30, v17
	v_fma_f32 v14, -v21, v25, 1.0
	v_fmac_f32_e32 v25, v14, v25
	v_div_scale_f32 v14, vcc, v19, v35, v19
	v_mul_f32_e32 v16, v14, v25
	v_fma_f32 v17, -v21, v16, v14
	v_fmac_f32_e32 v16, v17, v25
	v_fma_f32 v14, -v21, v16, v14
	v_div_scale_f32 v21, s[6:7], v34, v34, v15
	v_rcp_f32_e32 v23, v21
	v_div_fmas_f32 v14, v14, v25, v16
	v_div_fixup_f32 v17, v14, v35, v19
	v_mul_f32_e32 v18, 0xbfb8aa3b, v8
	s_waitcnt vmcnt(1)
	v_mul_f32_e32 v19, 0xbfb8aa3b, v216
	v_fma_f32 v14, -v21, v23, 1.0
	v_exp_f32_e32 v18, v18
	v_exp_f32_e32 v19, v19
	v_fmac_f32_e32 v23, v14, v23
	v_div_scale_f32 v14, vcc, v15, v34, v15
	v_mul_f32_e32 v16, v14, v23
	v_fma_f32 v25, -v21, v16, v14
	v_fmac_f32_e32 v16, v25, v23
	v_add_f32_e32 v18, 1.0, v18
	v_add_f32_e32 v19, 1.0, v19
	v_fma_f32 v14, -v21, v16, v14
	v_div_scale_f32 v21, s[6:7], v19, v19, v216
	v_rcp_f32_e32 v25, v21
	v_div_fmas_f32 v14, v14, v23, v16
	v_div_fixup_f32 v16, v14, v34, v15
	v_fmac_f32_e32 v12, v28, v16
	v_fmac_f32_e32 v13, v28, v17
	v_fma_f32 v14, -v21, v25, 1.0
	v_fmac_f32_e32 v25, v14, v25
	v_div_scale_f32 v14, vcc, v216, v19, v216
	v_mul_f32_e32 v15, v14, v25
	v_fma_f32 v16, -v21, v15, v14
	v_fmac_f32_e32 v15, v16, v25
	v_fma_f32 v14, -v21, v15, v14
	v_div_scale_f32 v21, s[6:7], v18, v18, v8
	v_rcp_f32_e32 v23, v21
	v_div_fmas_f32 v14, v14, v25, v15
	v_mul_f32_e32 v16, 0xbfb8aa3b, v9
	v_mul_f32_e32 v17, 0xbfb8aa3b, v217
	v_div_fixup_f32 v15, v14, v19, v216
	v_fma_f32 v14, -v21, v23, 1.0
	v_exp_f32_e32 v16, v16
	v_exp_f32_e32 v17, v17
	v_fmac_f32_e32 v23, v14, v23
	v_div_scale_f32 v14, vcc, v8, v18, v8
	v_mul_f32_e32 v19, v14, v23
	v_fma_f32 v25, -v21, v19, v14
	v_fmac_f32_e32 v19, v25, v23
	v_add_f32_e32 v16, 1.0, v16
	v_add_f32_e32 v17, 1.0, v17
	v_fma_f32 v14, -v21, v19, v14
	v_div_scale_f32 v21, s[6:7], v17, v17, v217
	v_rcp_f32_e32 v25, v21
	v_div_fmas_f32 v14, v14, v23, v19
	v_div_fixup_f32 v14, v14, v18, v8
	v_fmac_f32_e32 v12, v26, v14
	v_fmac_f32_e32 v13, v26, v15
	v_fma_f32 v8, -v21, v25, 1.0
	v_fmac_f32_e32 v25, v8, v25
	v_div_scale_f32 v8, vcc, v217, v17, v217
	v_mul_f32_e32 v14, v8, v25
	v_fma_f32 v15, -v21, v14, v8
	v_fmac_f32_e32 v14, v15, v25
	v_fma_f32 v8, -v21, v14, v8
	v_div_scale_f32 v21, s[6:7], v16, v16, v9
	v_rcp_f32_e32 v23, v21
	v_div_fmas_f32 v8, v8, v25, v14
	v_div_fixup_f32 v15, v8, v17, v217
	v_mul_f32_e32 v17, 0xbfb8aa3b, v10
	v_exp_f32_e32 v18, v17
	v_mul_f32_e32 v17, 0xbfb8aa3b, v218
	v_exp_f32_e32 v19, v17
	v_fma_f32 v8, -v21, v23, 1.0
; DI void ada_item(const Params& p, float* red, int item) {
;     ...
;     for (int j = 0; j < 32; ++j) {
;       const int k = ks * 64 + kq * 32 + j;
;       const float c0 = p.c[k], c1 = p.c[1024 + k];
;       a0 += (c0 / (1.f + __expf(-c0))) * wv[j];
;       a1 += (c1 / (1.f + __expf(-c1))) * wv[j];
;     }
	v_fmac_f32_e32 v23, v8, v23
	v_div_scale_f32 v8, vcc, v9, v16, v9
	v_mul_f32_e32 v14, v8, v23
	v_fma_f32 v17, -v21, v14, v8
	v_add_f32_e32 v18, 1.0, v18
	v_add_f32_e32 v19, 1.0, v19
	v_fmac_f32_e32 v14, v17, v23
	v_div_scale_f32 v17, s[6:7], v19, v19, v218
	v_fma_f32 v8, -v21, v14, v8
	v_rcp_f32_e32 v21, v17
	v_div_fmas_f32 v8, v8, v23, v14
	v_div_fixup_f32 v14, v8, v16, v9
	v_fma_f32 v8, v24, v14, v12
	v_fma_f32 v9, v24, v15, v13
	v_fma_f32 v12, -v17, v21, 1.0
	v_fmac_f32_e32 v21, v12, v21
	v_div_scale_f32 v12, vcc, v218, v19, v218
	v_mul_f32_e32 v13, v12, v21
	v_fma_f32 v14, -v17, v13, v12
	v_fmac_f32_e32 v13, v14, v21
	v_div_scale_f32 v16, s[6:7], v18, v18, v10
	v_fma_f32 v12, -v17, v13, v12
	v_rcp_f32_e32 v17, v16
	v_div_fmas_f32 v12, v12, v21, v13
	v_mul_f32_e32 v14, 0xbfb8aa3b, v11
	v_mul_f32_e32 v15, 0xbfb8aa3b, v219
	v_div_fixup_f32 v13, v12, v19, v218
	v_fma_f32 v12, -v16, v17, 1.0
	v_exp_f32_e32 v14, v14
	v_exp_f32_e32 v15, v15
	v_fmac_f32_e32 v17, v12, v17
	v_div_scale_f32 v12, vcc, v10, v18, v10
	v_mul_f32_e32 v19, v12, v17
	v_fma_f32 v21, -v16, v19, v12
	v_fmac_f32_e32 v19, v21, v17
	v_add_f32_e32 v14, 1.0, v14
	v_add_f32_e32 v15, 1.0, v15
	v_fma_f32 v12, -v16, v19, v12
	v_div_scale_f32 v16, s[6:7], v15, v15, v219
	v_rcp_f32_e32 v21, v16
	v_div_fmas_f32 v12, v12, v17, v19
	v_div_fixup_f32 v12, v12, v18, v10
	v_fmac_f32_e32 v8, v22, v12
	v_fmac_f32_e32 v9, v22, v13
	v_fma_f32 v10, -v16, v21, 1.0
	v_fmac_f32_e32 v21, v10, v21
	v_div_scale_f32 v10, vcc, v219, v15, v219
	v_mul_f32_e32 v12, v10, v21
	v_fma_f32 v13, -v16, v12, v10
	v_fmac_f32_e32 v12, v13, v21
	v_fma_f32 v10, -v16, v12, v10
	v_div_scale_f32 v16, s[6:7], v14, v14, v11
	v_rcp_f32_e32 v18, v16
	global_load_dwordx4 v[24:27], v[132:133], off offset:76
	global_load_dwordx4 v[28:31], v[136:137], off offset:16
	v_div_fmas_f32 v10, v10, v21, v12
	v_div_fixup_f32 v13, v10, v15, v219
	v_fma_f32 v10, -v16, v18, 1.0
	v_fmac_f32_e32 v18, v10, v18
	v_div_scale_f32 v10, vcc, v11, v14, v11
	v_mul_f32_e32 v12, v10, v18
	v_fma_f32 v15, -v16, v12, v10
	v_fmac_f32_e32 v12, v15, v18
	v_fma_f32 v10, -v16, v12, v10
	v_add_f32_e32 v16, 1.0, v220
	v_add_f32_e32 v17, 1.0, v221
	v_div_fmas_f32 v10, v10, v18, v12
	v_div_scale_f32 v15, s[6:7], v17, v17, v4
	v_rcp_f32_e32 v19, v15
	v_div_fixup_f32 v12, v10, v14, v11
	v_fmac_f32_e32 v8, v20, v12
	v_fmac_f32_e32 v9, v20, v13
	v_div_scale_f32 v14, s[6:7], v16, v16, v0
	v_fma_f32 v10, -v15, v19, 1.0
	v_fmac_f32_e32 v19, v10, v19
	v_div_scale_f32 v10, vcc, v4, v17, v4
	v_mul_f32_e32 v11, v10, v19
	v_fma_f32 v12, -v15, v11, v10
	v_fmac_f32_e32 v11, v12, v19
	v_fma_f32 v10, -v15, v11, v10
	v_rcp_f32_e32 v15, v14
	v_div_fmas_f32 v10, v10, v19, v11
	v_mul_f32_e32 v12, 0xbfb8aa3b, v1
	v_mul_f32_e32 v13, 0xbfb8aa3b, v5
	v_div_fixup_f32 v11, v10, v17, v4
	v_fma_f32 v4, -v14, v15, 1.0
	v_exp_f32_e32 v12, v12
	v_exp_f32_e32 v13, v13
	v_fmac_f32_e32 v15, v4, v15
	v_div_scale_f32 v4, vcc, v0, v16, v0
	v_mul_f32_e32 v10, v4, v15
	v_fma_f32 v17, -v14, v10, v4
	v_fmac_f32_e32 v10, v17, v15
	v_add_f32_e32 v12, 1.0, v12
	v_add_f32_e32 v13, 1.0, v13
	v_fma_f32 v4, -v14, v10, v4
	v_div_scale_f32 v14, s[6:7], v13, v13, v5
	v_rcp_f32_e32 v17, v14
	v_div_fmas_f32 v4, v4, v15, v10
	v_div_fixup_f32 v10, v4, v16, v0
	v_fma_f32 v216, v32, v10, v8
	v_fma_f32 v217, v32, v11, v9
	v_fma_f32 v0, -v14, v17, 1.0
	v_fmac_f32_e32 v17, v0, v17
	v_div_scale_f32 v0, vcc, v5, v13, v5
	v_mul_f32_e32 v4, v0, v17
	v_div_scale_f32 v10, s[6:7], v12, v12, v1
	v_fma_f32 v8, -v14, v4, v0
	v_rcp_f32_e32 v11, v10
	v_fmac_f32_e32 v4, v8, v17
	v_fma_f32 v0, -v14, v4, v0
	v_div_fmas_f32 v0, v0, v17, v4
	v_mul_f32_e32 v8, 0xbfb8aa3b, v2
	v_mul_f32_e32 v9, 0xbfb8aa3b, v6
	v_div_fixup_f32 v5, v0, v13, v5
	v_fma_f32 v0, -v10, v11, 1.0
	v_exp_f32_e32 v8, v8
	v_exp_f32_e32 v9, v9
	v_fmac_f32_e32 v11, v0, v11
	v_div_scale_f32 v0, vcc, v1, v12, v1
	v_mul_f32_e32 v4, v0, v11
	v_fma_f32 v13, -v10, v4, v0
	v_fmac_f32_e32 v4, v13, v11
	v_add_f32_e32 v8, 1.0, v8
	v_add_f32_e32 v9, 1.0, v9
	v_fma_f32 v0, -v10, v4, v0
	v_div_scale_f32 v10, s[6:7], v9, v9, v6
	v_rcp_f32_e32 v13, v10
	v_div_fmas_f32 v0, v0, v11, v4
	v_div_fixup_f32 v4, v0, v12, v1
	v_fma_f32 v4, v208, v4, v216
	v_fma_f32 v5, v208, v5, v217
	v_fma_f32 v0, -v10, v13, 1.0
	v_fmac_f32_e32 v13, v0, v13
	v_div_scale_f32 v0, vcc, v6, v9, v6
	v_mul_f32_e32 v1, v0, v13
	v_fma_f32 v11, -v10, v1, v0
	v_fmac_f32_e32 v1, v11, v13
	v_fma_f32 v0, -v10, v1, v0
	v_div_scale_f32 v10, s[6:7], v8, v8, v2
	v_rcp_f32_e32 v11, v10
	v_div_fmas_f32 v0, v0, v13, v1
	v_div_fixup_f32 v1, v0, v9, v6
	v_lshl_add_u64 v[222:223], v[114:115], 2, v[160:161]
	v_fma_f32 v0, -v10, v11, 1.0
	v_fmac_f32_e32 v11, v0, v11
	v_div_scale_f32 v0, vcc, v2, v8, v2
	v_mul_f32_e32 v6, v0, v11
	v_fma_f32 v9, -v10, v6, v0
	v_fmac_f32_e32 v6, v9, v11
	v_fma_f32 v0, -v10, v6, v0
	v_div_fmas_f32 v0, v0, v11, v6
	v_div_fixup_f32 v0, v0, v8, v2
	global_load_dwordx4 v[32:35], v[132:133], off offset:60
	global_load_dwordx4 v[8:11], v[132:133], off offset:108
	global_load_dwordx4 v[16:19], v[132:133], off offset:92
	global_load_dwordx4 v[12:15], v[136:137], off offset:48
	global_load_dwordx4 v[212:215], v[136:137], off
	global_load_dwordx4 v[20:23], v[136:137], off offset:32
	v_mul_f32_e32 v2, 0xbfb8aa3b, v3
	v_exp_f32_e32 v218, v2
	v_mul_f32_e32 v2, 0xbfb8aa3b, v7
	v_exp_f32_e32 v219, v2
	s_waitcnt vmcnt(7)
	v_mul_f32_e32 v2, 0xbfb8aa3b, v24
	v_exp_f32_e32 v220, v2
	s_waitcnt vmcnt(6)
; DI void ada_item(const Params& p, float* red, int item) {
;     ...
;     for (int j = 0; j < 32; ++j) {
;       const int k = ks * 64 + kq * 32 + j;
;       const float c0 = p.c[k], c1 = p.c[1024 + k];
;       a0 += (c0 / (1.f + __expf(-c0))) * wv[j];
;       a1 += (c1 / (1.f + __expf(-c1))) * wv[j];
;     }
	v_mul_f32_e32 v2, 0xbfb8aa3b, v28
	v_add_f32_e32 v218, 1.0, v218
	v_add_f32_e32 v219, 1.0, v219
	v_exp_f32_e32 v221, v2
	v_div_scale_f32 v6, s[6:7], v219, v219, v7
	v_rcp_f32_e32 v145, v6
	v_fma_f32 v0, v210, v0, v4
	v_fma_f32 v1, v210, v1, v5
	v_div_scale_f32 v187, s[6:7], v218, v218, v3
	v_fma_f32 v2, -v6, v145, 1.0
	v_fmac_f32_e32 v145, v2, v145
	v_div_scale_f32 v2, vcc, v7, v219, v7
	v_mul_f32_e32 v4, v2, v145
	v_fma_f32 v5, -v6, v4, v2
	v_fmac_f32_e32 v4, v5, v145
	v_fma_f32 v2, -v6, v4, v2
	v_rcp_f32_e32 v189, v187
	v_div_fmas_f32 v2, v2, v145, v4
	v_div_fixup_f32 v5, v2, v219, v7
	v_mul_f32_e32 v6, 0xbfb8aa3b, v36
	v_mul_f32_e32 v7, 0xbfb8aa3b, v44
	v_exp_f32_e32 v6, v6
	v_exp_f32_e32 v7, v7
	v_fma_f32 v2, -v187, v189, 1.0
	v_fmac_f32_e32 v189, v2, v189
	v_div_scale_f32 v2, vcc, v3, v218, v3
	v_mul_f32_e32 v4, v2, v189
	v_fma_f32 v145, -v187, v4, v2
	v_add_f32_e32 v6, 1.0, v6
	v_add_f32_e32 v7, 1.0, v7
	v_fmac_f32_e32 v4, v145, v189
	v_div_scale_f32 v145, s[6:7], v7, v7, v44
	v_fma_f32 v2, -v187, v4, v2
	v_rcp_f32_e32 v187, v145
	v_div_fmas_f32 v2, v2, v189, v4
	v_div_fixup_f32 v4, v2, v218, v3
	v_fmac_f32_e32 v0, v206, v4
	v_fmac_f32_e32 v1, v206, v5
	v_fma_f32 v2, -v145, v187, 1.0
	v_fmac_f32_e32 v187, v2, v187
	v_div_scale_f32 v2, vcc, v44, v7, v44
	v_mul_f32_e32 v3, v2, v187
	v_fma_f32 v4, -v145, v3, v2
	v_fmac_f32_e32 v3, v4, v187
	v_fma_f32 v2, -v145, v3, v2
	v_div_scale_f32 v145, s[6:7], v6, v6, v36
	v_rcp_f32_e32 v189, v145
	v_mul_f32_e32 v4, 0xbfb8aa3b, v37
	v_mul_f32_e32 v5, 0xbfb8aa3b, v45
	v_div_fmas_f32 v2, v2, v187, v3
	v_exp_f32_e32 v4, v4
	v_exp_f32_e32 v5, v5
	v_div_fixup_f32 v3, v2, v7, v44
	v_fma_f32 v2, -v145, v189, 1.0
	v_fmac_f32_e32 v189, v2, v189
	v_div_scale_f32 v2, vcc, v36, v6, v36
	v_mul_f32_e32 v7, v2, v189
	v_fma_f32 v44, -v145, v7, v2
	v_add_f32_e32 v4, 1.0, v4
	v_add_f32_e32 v5, 1.0, v5
	v_fmac_f32_e32 v7, v44, v189
	v_div_scale_f32 v44, s[6:7], v5, v5, v45
	v_fma_f32 v2, -v145, v7, v2
	v_rcp_f32_e32 v145, v44
	v_div_fmas_f32 v2, v2, v189, v7
	v_div_fixup_f32 v2, v2, v6, v36
	v_fmac_f32_e32 v0, v204, v2
	v_fmac_f32_e32 v1, v204, v3
	v_fma_f32 v2, -v44, v145, 1.0
	v_fmac_f32_e32 v145, v2, v145
	v_div_scale_f32 v2, vcc, v45, v5, v45
	v_mul_f32_e32 v3, v2, v145
	v_fma_f32 v6, -v44, v3, v2
	v_fmac_f32_e32 v3, v6, v145
	v_div_scale_f32 v36, s[6:7], v4, v4, v37
	v_fma_f32 v2, -v44, v3, v2
	v_rcp_f32_e32 v44, v36
	v_div_fmas_f32 v2, v2, v145, v3
	v_mul_f32_e32 v6, 0xbfb8aa3b, v38
	v_mul_f32_e32 v7, 0xbfb8aa3b, v46
	v_div_fixup_f32 v3, v2, v5, v45
	v_fma_f32 v2, -v36, v44, 1.0
	v_exp_f32_e32 v6, v6
	v_exp_f32_e32 v7, v7
	v_fmac_f32_e32 v44, v2, v44
	v_div_scale_f32 v2, vcc, v37, v4, v37
	v_mul_f32_e32 v5, v2, v44
	v_fma_f32 v45, -v36, v5, v2
	v_fmac_f32_e32 v5, v45, v44
	v_add_f32_e32 v6, 1.0, v6
	v_add_f32_e32 v7, 1.0, v7
	v_fma_f32 v2, -v36, v5, v2
	v_div_scale_f32 v36, s[6:7], v7, v7, v46
	v_rcp_f32_e32 v45, v36
	v_div_fmas_f32 v2, v2, v44, v5
	v_div_fixup_f32 v2, v2, v4, v37
	v_fmac_f32_e32 v0, v202, v2
	v_fmac_f32_e32 v1, v202, v3
	v_fma_f32 v2, -v36, v45, 1.0
	v_fmac_f32_e32 v45, v2, v45
	v_div_scale_f32 v2, vcc, v46, v7, v46
	v_mul_f32_e32 v3, v2, v45
	v_fma_f32 v4, -v36, v3, v2
	v_fmac_f32_e32 v3, v4, v45
	v_fma_f32 v2, -v36, v3, v2
	v_div_scale_f32 v36, s[6:7], v6, v6, v38
	v_rcp_f32_e32 v37, v36
	v_div_fmas_f32 v2, v2, v45, v3
	s_waitcnt vmcnt(5)
	v_mul_f32_e32 v4, 0xbfb8aa3b, v32
	s_waitcnt vmcnt(1)
	v_mul_f32_e32 v5, 0xbfb8aa3b, v212
	v_div_fixup_f32 v3, v2, v7, v46
	v_fma_f32 v2, -v36, v37, 1.0
	v_exp_f32_e32 v4, v4
	v_exp_f32_e32 v5, v5
	v_fmac_f32_e32 v37, v2, v37
	v_div_scale_f32 v2, vcc, v38, v6, v38
	v_mul_f32_e32 v7, v2, v37
	v_fma_f32 v44, -v36, v7, v2
	v_fmac_f32_e32 v7, v44, v37
	v_add_f32_e32 v4, 1.0, v4
	v_add_f32_e32 v5, 1.0, v5
	v_fma_f32 v2, -v36, v7, v2
	v_div_scale_f32 v36, s[6:7], v5, v5, v212
	v_rcp_f32_e32 v44, v36
	v_div_fmas_f32 v2, v2, v37, v7
	v_div_fixup_f32 v2, v2, v6, v38
	v_fmac_f32_e32 v0, v200, v2
	v_fmac_f32_e32 v1, v200, v3
	v_fma_f32 v2, -v36, v44, 1.0
	v_fmac_f32_e32 v44, v2, v44
	v_div_scale_f32 v2, vcc, v212, v5, v212
	v_mul_f32_e32 v3, v2, v44
	v_fma_f32 v6, -v36, v3, v2
	v_fmac_f32_e32 v3, v6, v44
	v_fma_f32 v2, -v36, v3, v2
	v_div_scale_f32 v36, s[6:7], v4, v4, v32
	v_rcp_f32_e32 v37, v36
	v_div_fmas_f32 v2, v2, v44, v3
	v_mul_f32_e32 v6, 0xbfb8aa3b, v33
	v_mul_f32_e32 v7, 0xbfb8aa3b, v213
	v_div_fixup_f32 v3, v2, v5, v212
	v_fma_f32 v2, -v36, v37, 1.0
	v_exp_f32_e32 v6, v6
	v_exp_f32_e32 v7, v7
	v_fmac_f32_e32 v37, v2, v37
	v_div_scale_f32 v2, vcc, v32, v4, v32
	v_mul_f32_e32 v5, v2, v37
	v_fma_f32 v38, -v36, v5, v2
	v_fmac_f32_e32 v5, v38, v37
	v_add_f32_e32 v6, 1.0, v6
	v_add_f32_e32 v7, 1.0, v7
	v_fma_f32 v2, -v36, v5, v2
	v_div_scale_f32 v36, s[6:7], v7, v7, v213
	v_rcp_f32_e32 v38, v36
	v_div_fmas_f32 v2, v2, v37, v5
	v_div_fixup_f32 v2, v2, v4, v32
	v_fmac_f32_e32 v0, v198, v2
	v_fmac_f32_e32 v1, v198, v3
	v_fma_f32 v2, -v36, v38, 1.0
	v_fmac_f32_e32 v38, v2, v38
	v_div_scale_f32 v2, vcc, v213, v7, v213
	v_mul_f32_e32 v3, v2, v38
	v_fma_f32 v4, -v36, v3, v2
	v_fmac_f32_e32 v3, v4, v38
	v_div_scale_f32 v32, s[6:7], v6, v6, v33
	v_fma_f32 v2, -v36, v3, v2
	v_rcp_f32_e32 v36, v32
	v_div_fmas_f32 v2, v2, v38, v3
	v_mul_f32_e32 v4, 0xbfb8aa3b, v34
	v_mul_f32_e32 v5, 0xbfb8aa3b, v214
	v_div_fixup_f32 v3, v2, v7, v213
	v_fma_f32 v2, -v32, v36, 1.0
	v_exp_f32_e32 v4, v4
	v_exp_f32_e32 v5, v5
	v_fmac_f32_e32 v36, v2, v36
	v_div_scale_f32 v2, vcc, v33, v6, v33
	v_mul_f32_e32 v7, v2, v36
	v_fma_f32 v37, -v32, v7, v2
	v_fmac_f32_e32 v7, v37, v36
	v_add_f32_e32 v4, 1.0, v4
	v_add_f32_e32 v5, 1.0, v5
	v_fma_f32 v2, -v32, v7, v2
	v_div_scale_f32 v32, s[6:7], v5, v5, v214
; DI void ada_item(const Params& p, float* red, int item) {
;     ...
;     for (int j = 0; j < 32; ++j) {
;       const int k = ks * 64 + kq * 32 + j;
;       const float c0 = p.c[k], c1 = p.c[1024 + k];
;       a0 += (c0 / (1.f + __expf(-c0))) * wv[j];
;       a1 += (c1 / (1.f + __expf(-c1))) * wv[j];
;     }
	v_rcp_f32_e32 v37, v32
	v_div_fmas_f32 v2, v2, v36, v7
	v_div_fixup_f32 v2, v2, v6, v33
	v_fmac_f32_e32 v0, v196, v2
	v_fmac_f32_e32 v1, v196, v3
	v_fma_f32 v2, -v32, v37, 1.0
	v_fmac_f32_e32 v37, v2, v37
	v_div_scale_f32 v2, vcc, v214, v5, v214
	v_mul_f32_e32 v3, v2, v37
	v_fma_f32 v6, -v32, v3, v2
	v_fmac_f32_e32 v3, v6, v37
	v_fma_f32 v2, -v32, v3, v2
	v_div_scale_f32 v32, s[6:7], v4, v4, v34
	v_rcp_f32_e32 v33, v32
	v_div_fmas_f32 v2, v2, v37, v3
	v_mul_f32_e32 v6, 0xbfb8aa3b, v35
	v_mul_f32_e32 v7, 0xbfb8aa3b, v215
	v_div_fixup_f32 v3, v2, v5, v214
	v_fma_f32 v2, -v32, v33, 1.0
	v_exp_f32_e32 v6, v6
	v_exp_f32_e32 v7, v7
	v_fmac_f32_e32 v33, v2, v33
	v_div_scale_f32 v2, vcc, v34, v4, v34
	v_mul_f32_e32 v5, v2, v33
	v_fma_f32 v36, -v32, v5, v2
	v_fmac_f32_e32 v5, v36, v33
	v_add_f32_e32 v6, 1.0, v6
	v_add_f32_e32 v7, 1.0, v7
	v_fma_f32 v2, -v32, v5, v2
	v_div_scale_f32 v32, s[6:7], v7, v7, v215
	v_rcp_f32_e32 v36, v32
	v_div_fmas_f32 v2, v2, v33, v5
	v_div_fixup_f32 v2, v2, v4, v34
	v_fmac_f32_e32 v0, v194, v2
	v_fmac_f32_e32 v1, v194, v3
	v_fma_f32 v2, -v32, v36, 1.0
	v_fmac_f32_e32 v36, v2, v36
	v_div_scale_f32 v2, vcc, v215, v7, v215
	v_mul_f32_e32 v3, v2, v36
	v_fma_f32 v4, -v32, v3, v2
	v_fmac_f32_e32 v3, v4, v36
	v_div_scale_f32 v4, s[6:7], v6, v6, v35
	v_fma_f32 v2, -v32, v3, v2
	v_rcp_f32_e32 v32, v4
	v_div_fmas_f32 v2, v2, v36, v3
	v_div_fixup_f32 v3, v2, v7, v215
	v_lshl_add_u64 v[44:45], v[88:89], 2, v[160:161]
	v_fma_f32 v2, -v4, v32, 1.0
	v_fmac_f32_e32 v32, v2, v32
	v_div_scale_f32 v2, vcc, v35, v6, v35
	v_mul_f32_e32 v7, v2, v32
	v_fma_f32 v5, -v4, v7, v2
	v_fmac_f32_e32 v7, v5, v32
	v_fma_f32 v2, -v4, v7, v2
	v_add_f32_e32 v4, 1.0, v220
	v_add_f32_e32 v5, 1.0, v221
	v_div_fmas_f32 v2, v2, v32, v7
	v_div_scale_f32 v33, s[6:7], v5, v5, v28
	v_rcp_f32_e32 v34, v33
	v_div_fixup_f32 v2, v2, v6, v35
	v_fmac_f32_e32 v0, v192, v2
	v_fmac_f32_e32 v1, v192, v3
	v_div_scale_f32 v32, s[6:7], v4, v4, v24
	v_fma_f32 v2, -v33, v34, 1.0
	v_fmac_f32_e32 v34, v2, v34
	v_div_scale_f32 v2, vcc, v28, v5, v28
	v_mul_f32_e32 v3, v2, v34
	v_fma_f32 v6, -v33, v3, v2
	v_fmac_f32_e32 v3, v6, v34
	v_fma_f32 v2, -v33, v3, v2
	v_rcp_f32_e32 v33, v32
	v_mul_f32_e32 v6, 0xbfb8aa3b, v25
	v_mul_f32_e32 v7, 0xbfb8aa3b, v29
	v_div_fmas_f32 v2, v2, v34, v3
	v_exp_f32_e32 v6, v6
	v_exp_f32_e32 v7, v7
	v_div_fixup_f32 v3, v2, v5, v28
	v_fma_f32 v2, -v32, v33, 1.0
	v_fmac_f32_e32 v33, v2, v33
	v_div_scale_f32 v2, vcc, v24, v4, v24
	v_mul_f32_e32 v5, v2, v33
	v_fma_f32 v28, -v32, v5, v2
	v_add_f32_e32 v6, 1.0, v6
	v_add_f32_e32 v7, 1.0, v7
	v_fmac_f32_e32 v5, v28, v33
	v_div_scale_f32 v28, s[6:7], v7, v7, v29
	v_fma_f32 v2, -v32, v5, v2
	v_rcp_f32_e32 v32, v28
	v_div_fmas_f32 v2, v2, v33, v5
	v_div_fixup_f32 v2, v2, v4, v24
	v_fma_f32 v4, v190, v2, v0
	v_fma_f32 v5, v190, v3, v1
	v_fma_f32 v0, -v28, v32, 1.0
	v_fmac_f32_e32 v32, v0, v32
	v_div_scale_f32 v0, vcc, v29, v7, v29
	v_mul_f32_e32 v1, v0, v32
	v_fma_f32 v2, -v28, v1, v0
	v_fmac_f32_e32 v1, v2, v32
	v_div_scale_f32 v2, s[6:7], v6, v6, v25
	v_rcp_f32_e32 v3, v2
	v_fma_f32 v0, -v28, v1, v0
	v_div_fmas_f32 v0, v0, v32, v1
	v_div_fixup_f32 v7, v0, v7, v29
	v_fma_f32 v0, -v2, v3, 1.0
	v_fmac_f32_e32 v3, v0, v3
	v_mul_f32_e32 v0, 0xbfb8aa3b, v26
	v_mul_f32_e32 v1, 0xbfb8aa3b, v30
	v_exp_f32_e32 v0, v0
	v_exp_f32_e32 v1, v1
	v_div_scale_f32 v24, vcc, v25, v6, v25
	v_mul_f32_e32 v28, v24, v3
	v_fma_f32 v29, -v2, v28, v24
	v_fmac_f32_e32 v28, v29, v3
	v_add_f32_e32 v0, 1.0, v0
	v_add_f32_e32 v1, 1.0, v1
	v_fma_f32 v2, -v2, v28, v24
	v_div_scale_f32 v24, s[6:7], v1, v1, v30
	v_rcp_f32_e32 v29, v24
	v_div_fmas_f32 v2, v2, v3, v28
	v_div_fixup_f32 v6, v2, v6, v25
	v_fmac_f32_e32 v4, v186, v6
	v_fmac_f32_e32 v5, v186, v7
	v_fma_f32 v2, -v24, v29, 1.0
	v_fmac_f32_e32 v29, v2, v29
	v_div_scale_f32 v2, vcc, v30, v1, v30
	v_mul_f32_e32 v3, v2, v29
	v_fma_f32 v25, -v24, v3, v2
	v_fmac_f32_e32 v3, v25, v29
	v_fma_f32 v2, -v24, v3, v2
	v_div_scale_f32 v24, s[6:7], v0, v0, v26
	v_rcp_f32_e32 v28, v24
	v_div_fmas_f32 v2, v2, v29, v3
	v_div_fixup_f32 v25, v2, v1, v30
	v_lshl_add_u64 v[192:193], v[92:93], 2, v[160:161]
	v_fma_f32 v1, -v24, v28, 1.0
	v_fmac_f32_e32 v28, v1, v28
	v_div_scale_f32 v1, vcc, v26, v0, v26
	v_mul_f32_e32 v2, v1, v28
	v_fma_f32 v3, -v24, v2, v1
	v_fmac_f32_e32 v2, v3, v28
	v_fma_f32 v1, -v24, v2, v1
	v_div_fmas_f32 v1, v1, v28, v2
	v_div_fixup_f32 v24, v1, v0, v26
	v_mul_f32_e32 v1, 0xbfb8aa3b, v27
	v_exp_f32_e32 v28, v1
	v_mul_f32_e32 v1, 0xbfb8aa3b, v31
	v_exp_f32_e32 v29, v1
	v_mul_f32_e32 v26, 0xbfb8aa3b, v15
	v_fmac_f32_e32 v4, v188, v24
	v_fmac_f32_e32 v5, v188, v25
	v_exp_f32_e32 v33, v26
	v_add_f32_e32 v28, 1.0, v28
	v_add_f32_e32 v29, 1.0, v29
	s_waitcnt vmcnt(0)
; DI void ada_item(const Params& p, float* red, int item) {
;     ...
;     for (int j = 0; j < 32; ++j) {
;       const int k = ks * 64 + kq * 32 + j;
;       const float c0 = p.c[k], c1 = p.c[1024 + k];
;       a0 += (c0 / (1.f + __expf(-c0))) * wv[j];
;       a1 += (c1 / (1.f + __expf(-c1))) * wv[j];
;     }
	v_mul_f32_e32 v25, 0xbfb8aa3b, v20
	v_div_scale_f32 v30, s[6:7], v29, v29, v31
	v_rcp_f32_e32 v34, v30
	v_div_scale_f32 v26, s[6:7], v28, v28, v27
	v_exp_f32_e32 v25, v25
	v_fma_f32 v6, -v30, v34, 1.0
	v_fmac_f32_e32 v34, v6, v34
	v_div_scale_f32 v6, vcc, v31, v29, v31
	v_mul_f32_e32 v7, v6, v34
	v_fma_f32 v24, -v30, v7, v6
	v_fmac_f32_e32 v7, v24, v34
	v_fma_f32 v6, -v30, v7, v6
	v_rcp_f32_e32 v30, v26
	v_div_fmas_f32 v6, v6, v34, v7
	v_mul_f32_e32 v24, 0xbfb8aa3b, v16
	v_div_fixup_f32 v7, v6, v29, v31
	v_fma_f32 v6, -v26, v30, 1.0
	v_exp_f32_e32 v24, v24
	v_fmac_f32_e32 v30, v6, v30
	v_div_scale_f32 v6, vcc, v27, v28, v27
	v_mul_f32_e32 v29, v6, v30
	v_fma_f32 v31, -v26, v29, v6
	v_fmac_f32_e32 v29, v31, v30
	v_add_f32_e32 v24, 1.0, v24
	v_add_f32_e32 v25, 1.0, v25
	v_fma_f32 v6, -v26, v29, v6
	v_div_scale_f32 v26, s[6:7], v25, v25, v20
	v_rcp_f32_e32 v31, v26
	v_div_fmas_f32 v6, v6, v30, v29
	v_div_fixup_f32 v6, v6, v28, v27
	v_fmac_f32_e32 v4, v184, v6
	v_fmac_f32_e32 v5, v184, v7
	v_fma_f32 v6, -v26, v31, 1.0
	v_fmac_f32_e32 v31, v6, v31
	v_div_scale_f32 v6, vcc, v20, v25, v20
	v_mul_f32_e32 v7, v6, v31
	v_fma_f32 v27, -v26, v7, v6
	v_fmac_f32_e32 v7, v27, v31
	v_fma_f32 v6, -v26, v7, v6
	v_div_scale_f32 v28, s[6:7], v24, v24, v16
	v_rcp_f32_e32 v29, v28
	v_div_fmas_f32 v6, v6, v31, v7
	v_div_fixup_f32 v7, v6, v25, v20
	v_mul_f32_e32 v25, 0xbfb8aa3b, v17
	v_exp_f32_e32 v26, v25
	v_mul_f32_e32 v25, 0xbfb8aa3b, v21
	v_exp_f32_e32 v27, v25
	v_fma_f32 v6, -v28, v29, 1.0
	v_fmac_f32_e32 v29, v6, v29
	v_div_scale_f32 v6, vcc, v16, v24, v16
	v_mul_f32_e32 v20, v6, v29
	v_fma_f32 v25, -v28, v20, v6
	v_add_f32_e32 v26, 1.0, v26
	v_add_f32_e32 v27, 1.0, v27
	v_fmac_f32_e32 v20, v25, v29
	v_div_scale_f32 v25, s[6:7], v27, v27, v21
	v_fma_f32 v6, -v28, v20, v6
	v_rcp_f32_e32 v28, v25
	v_div_fmas_f32 v6, v6, v29, v20
	v_div_fixup_f32 v6, v6, v24, v16
	v_fmac_f32_e32 v4, v182, v6
	v_fmac_f32_e32 v5, v182, v7
	v_fma_f32 v6, -v25, v28, 1.0
	v_fmac_f32_e32 v28, v6, v28
	v_div_scale_f32 v6, vcc, v21, v27, v21
	v_mul_f32_e32 v7, v6, v28
	v_fma_f32 v16, -v25, v7, v6
	v_fmac_f32_e32 v7, v16, v28
	v_div_scale_f32 v16, s[6:7], v26, v26, v17
	v_rcp_f32_e32 v24, v16
	v_fma_f32 v6, -v25, v7, v6
	v_div_fmas_f32 v6, v6, v28, v7
	v_div_fixup_f32 v7, v6, v27, v21
	v_mul_f32_e32 v20, 0xbfb8aa3b, v18
	v_mul_f32_e32 v21, 0xbfb8aa3b, v22
	v_fma_f32 v6, -v16, v24, 1.0
	v_exp_f32_e32 v20, v20
	v_exp_f32_e32 v21, v21
	v_fmac_f32_e32 v24, v6, v24
	v_div_scale_f32 v6, vcc, v17, v26, v17
	v_mul_f32_e32 v25, v6, v24
	v_fma_f32 v27, -v16, v25, v6
	v_fmac_f32_e32 v25, v27, v24
	v_add_f32_e32 v20, 1.0, v20
	v_add_f32_e32 v21, 1.0, v21
	v_fma_f32 v6, -v16, v25, v6
	v_div_scale_f32 v16, s[6:7], v21, v21, v22
	v_rcp_f32_e32 v27, v16
	v_div_fmas_f32 v6, v6, v24, v25
	v_div_fixup_f32 v6, v6, v26, v17
	v_fmac_f32_e32 v4, v180, v6
	v_fmac_f32_e32 v5, v180, v7
	v_fma_f32 v6, -v16, v27, 1.0
	v_fmac_f32_e32 v27, v6, v27
	v_div_scale_f32 v6, vcc, v22, v21, v22
	v_mul_f32_e32 v7, v6, v27
	v_div_scale_f32 v24, s[6:7], v20, v20, v18
	v_fma_f32 v17, -v16, v7, v6
	v_rcp_f32_e32 v25, v24
	v_fmac_f32_e32 v7, v17, v27
	v_fma_f32 v6, -v16, v7, v6
	v_mul_f32_e32 v16, 0xbfb8aa3b, v19
	v_mul_f32_e32 v17, 0xbfb8aa3b, v23
	v_div_fmas_f32 v6, v6, v27, v7
	v_exp_f32_e32 v16, v16
	v_exp_f32_e32 v17, v17
	v_div_fixup_f32 v7, v6, v21, v22
	v_fma_f32 v6, -v24, v25, 1.0
	v_fmac_f32_e32 v25, v6, v25
	v_div_scale_f32 v6, vcc, v18, v20, v18
	v_mul_f32_e32 v21, v6, v25
	v_fma_f32 v22, -v24, v21, v6
	v_add_f32_e32 v16, 1.0, v16
	v_add_f32_e32 v17, 1.0, v17
	v_fmac_f32_e32 v21, v22, v25
	v_div_scale_f32 v22, s[6:7], v17, v17, v23
	v_fma_f32 v6, -v24, v21, v6
	v_rcp_f32_e32 v24, v22
	v_div_fmas_f32 v6, v6, v25, v21
	v_div_fixup_f32 v6, v6, v20, v18
	v_fmac_f32_e32 v4, v178, v6
	v_fmac_f32_e32 v5, v178, v7
	v_fma_f32 v6, -v22, v24, 1.0
	v_fmac_f32_e32 v24, v6, v24
	v_div_scale_f32 v6, vcc, v23, v17, v23
	v_mul_f32_e32 v7, v6, v24
	v_fma_f32 v18, -v22, v7, v6
	v_fmac_f32_e32 v7, v18, v24
	v_div_scale_f32 v18, s[6:7], v16, v16, v19
	v_fma_f32 v6, -v22, v7, v6
	v_rcp_f32_e32 v22, v18
	v_div_fmas_f32 v6, v6, v24, v7
	v_mul_f32_e32 v20, 0xbfb8aa3b, v8
	v_mul_f32_e32 v21, 0xbfb8aa3b, v12
	v_div_fixup_f32 v7, v6, v17, v23
	v_fma_f32 v6, -v18, v22, 1.0
	v_exp_f32_e32 v20, v20
	v_exp_f32_e32 v21, v21
	v_fmac_f32_e32 v22, v6, v22
	v_div_scale_f32 v6, vcc, v19, v16, v19
	v_mul_f32_e32 v17, v6, v22
	v_fma_f32 v23, -v18, v17, v6
	v_fmac_f32_e32 v17, v23, v22
	v_add_f32_e32 v20, 1.0, v20
	v_add_f32_e32 v21, 1.0, v21
	v_fma_f32 v6, -v18, v17, v6
	v_div_scale_f32 v18, s[6:7], v21, v21, v12
	v_rcp_f32_e32 v23, v18
	v_div_fmas_f32 v6, v6, v22, v17
	v_div_fixup_f32 v6, v6, v16, v19
	v_fmac_f32_e32 v4, v174, v6
	v_fmac_f32_e32 v5, v174, v7
	v_fma_f32 v6, -v18, v23, 1.0
	v_fmac_f32_e32 v23, v6, v23
	v_div_scale_f32 v6, vcc, v12, v21, v12
	v_mul_f32_e32 v7, v6, v23
	v_fma_f32 v16, -v18, v7, v6
	v_fmac_f32_e32 v7, v16, v23
	v_fma_f32 v6, -v18, v7, v6
	v_div_scale_f32 v18, s[6:7], v20, v20, v8
	v_rcp_f32_e32 v19, v18
	v_mul_f32_e32 v16, 0xbfb8aa3b, v9
	v_mul_f32_e32 v17, 0xbfb8aa3b, v13
	v_exp_f32_e32 v16, v16
	v_exp_f32_e32 v17, v17
	v_div_fmas_f32 v6, v6, v23, v7
	v_div_fixup_f32 v7, v6, v21, v12
	v_fma_f32 v6, -v18, v19, 1.0
	v_fmac_f32_e32 v19, v6, v19
	v_div_scale_f32 v6, vcc, v8, v20, v8
	v_mul_f32_e32 v12, v6, v19
	v_add_f32_e32 v24, 1.0, v16
	v_add_f32_e32 v25, 1.0, v17
	v_fma_f32 v21, -v18, v12, v6
	v_div_scale_f32 v16, s[6:7], v25, v25, v13
	v_fmac_f32_e32 v12, v21, v19
	v_rcp_f32_e32 v26, v16
	v_fma_f32 v6, -v18, v12, v6
	v_div_fmas_f32 v6, v6, v19, v12
	v_div_fixup_f32 v6, v6, v20, v8
	v_fmac_f32_e32 v4, v172, v6
; DI void ada_item(const Params& p, float* red, int item) {
;     ...
;     for (int j = 0; j < 32; ++j) wv[j] = p.w_ada[(size_t)(ks * 64 + kq * 32 + j) * 3072 + n];
; #pragma unroll
;     for (int j = 0; j < 32; ++j) {
;       const int k = ks * 64 + kq * 32 + j;
;       const float c0 = p.c[k], c1 = p.c[1024 + k];
;       a0 += (c0 / (1.f + __expf(-c0))) * wv[j];
;       a1 += (c1 / (1.f + __expf(-c1))) * wv[j];
;     }
	v_fmac_f32_e32 v5, v172, v7
	v_fma_f32 v6, -v16, v26, 1.0
	v_fmac_f32_e32 v26, v6, v26
	v_div_scale_f32 v6, vcc, v13, v25, v13
	v_mul_f32_e32 v7, v6, v26
	v_fma_f32 v8, -v16, v7, v6
	v_mul_f32_e32 v0, 0xbfb8aa3b, v11
	v_fmac_f32_e32 v7, v8, v26
	v_exp_f32_e32 v32, v0
	global_load_dwordx4 v[0:3], v[138:139], off
	v_fma_f32 v6, -v16, v7, v6
	global_load_dwordx4 v[16:19], v[132:133], off offset:140
	global_load_dwordx4 v[20:23], v[132:133], off offset:124
	v_div_scale_f32 v8, s[6:7], v24, v24, v9
	v_rcp_f32_e32 v27, v8
	v_div_fmas_f32 v6, v6, v26, v7
	v_div_fixup_f32 v7, v6, v25, v13
	v_mul_f32_e32 v12, 0xbfb8aa3b, v10
	v_mul_f32_e32 v13, 0xbfb8aa3b, v14
	v_fma_f32 v6, -v8, v27, 1.0
	v_exp_f32_e32 v12, v12
	v_exp_f32_e32 v13, v13
	v_fmac_f32_e32 v27, v6, v27
	v_div_scale_f32 v6, vcc, v9, v24, v9
	v_mul_f32_e32 v25, v6, v27
	v_fma_f32 v26, -v8, v25, v6
	v_fmac_f32_e32 v25, v26, v27
	v_add_f32_e32 v12, 1.0, v12
	v_add_f32_e32 v13, 1.0, v13
	v_fma_f32 v6, -v8, v25, v6
	v_div_scale_f32 v8, s[6:7], v13, v13, v14
	v_rcp_f32_e32 v26, v8
	v_div_fmas_f32 v6, v6, v27, v25
	v_div_fixup_f32 v6, v6, v24, v9
	v_fmac_f32_e32 v4, v170, v6
	v_fmac_f32_e32 v5, v170, v7
	v_fma_f32 v6, -v8, v26, 1.0
	v_fmac_f32_e32 v26, v6, v26
	v_div_scale_f32 v6, vcc, v14, v13, v14
	v_mul_f32_e32 v7, v6, v26
	v_fma_f32 v9, -v8, v7, v6
	v_fmac_f32_e32 v7, v9, v26
	v_fma_f32 v6, -v8, v7, v6
	v_div_scale_f32 v8, s[6:7], v12, v12, v10
	v_rcp_f32_e32 v24, v8
	v_div_fmas_f32 v6, v6, v26, v7
	v_div_fixup_f32 v7, v6, v13, v14
	v_lshl_add_u64 v[188:189], v[90:91], 2, v[160:161]
	v_fma_f32 v6, -v8, v24, 1.0
	v_fmac_f32_e32 v24, v6, v24
	v_div_scale_f32 v6, vcc, v10, v12, v10
	v_mul_f32_e32 v13, v6, v24
	v_fma_f32 v9, -v8, v13, v6
	v_fmac_f32_e32 v13, v9, v24
	v_fma_f32 v6, -v8, v13, v6
	v_add_f32_e32 v8, 1.0, v32
	v_add_f32_e32 v9, 1.0, v33
	v_div_fmas_f32 v6, v6, v24, v13
	v_div_scale_f32 v14, s[6:7], v9, v9, v15
	v_rcp_f32_e32 v25, v14
	v_div_fixup_f32 v6, v6, v12, v10
	v_fmac_f32_e32 v4, v168, v6
	v_fmac_f32_e32 v5, v168, v7
	v_lshl_add_u64 v[218:219], v[102:103], 2, v[160:161]
	v_fma_f32 v6, -v14, v25, 1.0
	v_fmac_f32_e32 v25, v6, v25
	v_div_scale_f32 v6, vcc, v15, v9, v15
	v_mul_f32_e32 v7, v6, v25
	v_fma_f32 v10, -v14, v7, v6
	v_fmac_f32_e32 v7, v10, v25
	v_div_scale_f32 v10, s[6:7], v8, v8, v11
	v_rcp_f32_e32 v12, v10
	v_fma_f32 v6, -v14, v7, v6
	v_div_fmas_f32 v6, v6, v25, v7
	v_div_fixup_f32 v7, v6, v9, v15
	v_fma_f32 v6, -v10, v12, 1.0
	v_fmac_f32_e32 v12, v6, v12
	v_div_scale_f32 v6, vcc, v11, v8, v11
	v_mul_f32_e32 v9, v6, v12
	v_fma_f32 v13, -v10, v9, v6
	v_fmac_f32_e32 v9, v13, v12
	v_fma_f32 v6, -v10, v9, v6
	v_div_fmas_f32 v6, v6, v12, v9
	v_div_fixup_f32 v6, v6, v8, v11
	s_waitcnt vmcnt(2)
	v_mul_f32_e32 v9, 0xbfb8aa3b, v0
	v_exp_f32_e32 v9, v9
	s_waitcnt vmcnt(0)
	v_mul_f32_e32 v8, 0xbfb8aa3b, v20
	v_exp_f32_e32 v8, v8
	v_fma_f32 v200, v166, v6, v4
	v_fma_f32 v201, v166, v7, v5
	global_load_dwordx3 v[24:26], v[132:133], off offset:172
	global_load_dwordx4 v[4:7], v[132:133], off offset:156
	v_add_f32_e32 v32, 1.0, v8
	v_add_f32_e32 v33, 1.0, v9
	s_nop 0
	v_div_scale_f32 v27, s[6:7], v33, v33, v0
	v_rcp_f32_e32 v31, v27
	global_load_dwordx3 v[28:30], v[138:139], off offset:48
	global_load_dwordx4 v[8:11], v[138:139], off offset:32
	global_load_dwordx4 v[12:15], v[138:139], off offset:16
	v_fma_f32 v34, -v27, v31, 1.0
	v_fmac_f32_e32 v31, v34, v31
	v_div_scale_f32 v34, vcc, v0, v33, v0
	v_mul_f32_e32 v35, v34, v31
	v_fma_f32 v36, -v27, v35, v34
	v_fmac_f32_e32 v35, v36, v31
	v_fma_f32 v27, -v27, v35, v34
	v_div_scale_f32 v34, s[6:7], v32, v32, v20
	v_rcp_f32_e32 v36, v34
	v_div_fmas_f32 v27, v27, v31, v35
	v_div_fixup_f32 v203, v27, v33, v0
	v_fma_f32 v0, -v34, v36, 1.0
	v_fmac_f32_e32 v36, v0, v36
	v_div_scale_f32 v0, vcc, v20, v32, v20
	v_mul_f32_e32 v27, v0, v36
	v_fma_f32 v31, -v34, v27, v0
	v_fmac_f32_e32 v27, v31, v36
	v_fma_f32 v0, -v34, v27, v0
	v_div_fmas_f32 v0, v0, v36, v27
	v_add_co_u32_e32 v36, vcc, s85, v162
	v_div_fixup_f32 v202, v0, v32, v20
	s_nop 0
	v_addc_co_u32_e32 v37, vcc, 0, v163, vcc
	v_add_co_u32_e32 v186, vcc, s86, v162
	v_lshl_add_u64 v[32:33], v[84:85], 2, v[160:161]
	s_nop 0
	v_addc_co_u32_e32 v187, vcc, 0, v163, vcc
	v_add_co_u32_e32 v190, vcc, s87, v162
	v_lshl_add_u64 v[34:35], v[86:87], 2, v[160:161]
	s_nop 0
	v_addc_co_u32_e32 v191, vcc, 0, v163, vcc
	global_load_dword v204, v[32:33], off
	global_load_dword v206, v[34:35], off
	global_load_dword v208, v[36:37], off
	global_load_dword v210, v[44:45], off
	global_load_dword v212, v[186:187], off
	global_load_dword v214, v[188:189], off
	global_load_dword v198, v[190:191], off
	global_load_dword v196, v[192:193], off
	v_add_co_u32_e32 v32, vcc, s88, v162
	v_lshl_add_u64 v[34:35], v[94:95], 2, v[160:161]
	s_nop 0
	v_addc_co_u32_e32 v33, vcc, 0, v163, vcc
	v_add_co_u32_e32 v216, vcc, s89, v162
	v_lshl_add_u64 v[186:187], v[100:101], 2, v[160:161]
	s_nop 0
	v_addc_co_u32_e32 v217, vcc, 0, v163, vcc
	v_add_co_u32_e32 v220, vcc, s90, v162
	v_lshl_add_u64 v[36:37], v[96:97], 2, v[160:161]
	s_nop 0
	v_addc_co_u32_e32 v221, vcc, 0, v163, vcc
	v_lshl_add_u64 v[44:45], v[98:99], 2, v[160:161]
	global_load_dword v0, v[32:33], off
	global_load_dword v194, v[34:35], off
	global_load_dword v190, v[36:37], off
	global_load_dword v192, v[44:45], off
	global_load_dword v188, v[186:187], off
	s_nop 0
	global_load_dword v186, v[216:217], off
	global_load_dword v184, v[218:219], off
	global_load_dword v182, v[220:221], off
	v_add_co_u32_e32 v34, vcc, s91, v162
	v_lshl_add_u64 v[32:33], v[104:105], 2, v[160:161]
	s_nop 0
	v_addc_co_u32_e32 v35, vcc, 0, v163, vcc
	v_add_co_u32_e32 v44, vcc, s92, v162
; DI void ada_item(const Params& p, float* red, int item) {
;     ...
;     for (int j = 0; j < 32; ++j) wv[j] = p.w_ada[(size_t)(ks * 64 + kq * 32 + j) * 3072 + n];
; #pragma unroll
;     for (int j = 0; j < 32; ++j) {
;       const int k = ks * 64 + kq * 32 + j;
;       const float c0 = p.c[k], c1 = p.c[1024 + k];
;       a0 += (c0 / (1.f + __expf(-c0))) * wv[j];
;       a1 += (c1 / (1.f + __expf(-c1))) * wv[j];
;     }
	v_lshl_add_u64 v[220:221], v[112:113], 2, v[160:161]
	v_mul_f32_e32 v27, 0xbfb8aa3b, v21
	v_lshl_add_u64 v[36:37], v[106:107], 2, v[160:161]
	v_addc_co_u32_e32 v45, vcc, 0, v163, vcc
	v_lshl_add_u64 v[216:217], v[108:109], 2, v[160:161]
	v_lshl_add_u64 v[218:219], v[110:111], 2, v[160:161]
	global_load_dword v180, v[32:33], off
	global_load_dword v178, v[34:35], off
	global_load_dword v174, v[36:37], off
	global_load_dword v20, v[44:45], off
	global_load_dword v172, v[216:217], off
	global_load_dword v168, v[218:219], off
	global_load_dword v170, v[220:221], off
	global_load_dword v166, v[222:223], off
	v_exp_f32_e32 v220, v27
	v_mul_f32_e32 v27, 0xbfb8aa3b, v1
	v_exp_f32_e32 v221, v27
	v_add_co_u32_e32 v32, vcc, s93, v162
	v_lshl_add_u64 v[34:35], v[116:117], 2, v[160:161]
	s_nop 0
	v_addc_co_u32_e32 v33, vcc, 0, v163, vcc
	v_add_f32_e32 v220, 1.0, v220
	v_add_f32_e32 v221, 1.0, v221
	v_add_co_u32_e32 v36, vcc, s94, v162
	v_div_scale_f32 v27, s[6:7], v221, v221, v1
	s_nop 0
	v_addc_co_u32_e32 v37, vcc, 0, v163, vcc
	v_rcp_f32_e32 v31, v27
	v_add_co_u32_e32 v216, vcc, s95, v162
	v_lshl_add_u64 v[44:45], v[118:119], 2, v[160:161]
	s_nop 0
	v_addc_co_u32_e32 v217, vcc, 0, v163, vcc
	v_add_co_u32_e32 v222, vcc, s96, v162
	v_lshl_add_u64 v[218:219], v[120:121], 2, v[160:161]
	s_nop 0
	v_addc_co_u32_e32 v223, vcc, 0, v163, vcc
	global_load_dword v162, v[32:33], off
	global_load_dword v160, v[34:35], off
	global_load_dword v46, v[36:37], off
	s_nop 0
	global_load_dword v44, v[44:45], off
	s_nop 0
	global_load_dword v38, v[216:217], off
	global_load_dword v36, v[218:219], off
	global_load_dword v34, v[222:223], off
	global_load_dword v32, v[224:225], off
	v_fma_f32 v33, -v27, v31, 1.0
	v_fmac_f32_e32 v31, v33, v31
	v_div_scale_f32 v33, vcc, v1, v221, v1
	v_mul_f32_e32 v35, v33, v31
	v_fma_f32 v37, -v27, v35, v33
	v_fmac_f32_e32 v35, v37, v31
	v_fma_f32 v27, -v27, v35, v33
	v_div_scale_f32 v33, s[6:7], v220, v220, v21
	v_rcp_f32_e32 v37, v33
	v_div_fmas_f32 v27, v27, v31, v35
	v_div_fixup_f32 v217, v27, v221, v1
	v_fmac_f32_e32 v200, v164, v202
	v_fmac_f32_e32 v201, v164, v203
	v_fma_f32 v1, -v33, v37, 1.0
	v_fmac_f32_e32 v37, v1, v37
	v_div_scale_f32 v1, vcc, v21, v220, v21
	v_mul_f32_e32 v27, v1, v37
	v_fma_f32 v31, -v33, v27, v1
	v_fmac_f32_e32 v27, v31, v37
	v_fma_f32 v1, -v33, v27, v1
	v_div_fmas_f32 v1, v1, v37, v27
	v_div_fixup_f32 v216, v1, v220, v21
	v_mul_f32_e32 v1, 0xbfb8aa3b, v22
	v_exp_f32_e32 v218, v1
	v_mul_f32_e32 v1, 0xbfb8aa3b, v2
	v_exp_f32_e32 v219, v1
	s_waitcnt vmcnt(35)
	v_mul_f32_e32 v1, 0xbfb8aa3b, v6
	v_exp_f32_e32 v220, v1
	s_waitcnt vmcnt(33)
	v_mul_f32_e32 v1, 0xbfb8aa3b, v10
	v_add_f32_e32 v218, 1.0, v218
	v_add_f32_e32 v219, 1.0, v219
	v_exp_f32_e32 v221, v1
	v_div_scale_f32 v21, s[6:7], v219, v219, v2
	v_rcp_f32_e32 v27, v21
	s_waitcnt vmcnt(31)
	v_fmac_f32_e32 v200, v204, v216
	v_fmac_f32_e32 v201, v204, v217
	v_fma_f32 v1, -v21, v27, 1.0
	v_fmac_f32_e32 v27, v1, v27
	v_div_scale_f32 v1, vcc, v2, v219, v2
	v_mul_f32_e32 v31, v1, v27
	v_fma_f32 v33, -v21, v31, v1
	v_fmac_f32_e32 v31, v33, v27
	v_fma_f32 v1, -v21, v31, v1
	v_div_scale_f32 v21, s[6:7], v218, v218, v22
	v_rcp_f32_e32 v33, v21
	v_div_fmas_f32 v1, v1, v27, v31
	v_mul_f32_e32 v27, 0xbfb8aa3b, v23
	v_exp_f32_e32 v204, v27
	v_mul_f32_e32 v27, 0xbfb8aa3b, v3
	v_div_fixup_f32 v203, v1, v219, v2
	v_fma_f32 v1, -v21, v33, 1.0
	v_exp_f32_e32 v205, v27
	v_fmac_f32_e32 v33, v1, v33
	v_div_scale_f32 v1, vcc, v22, v218, v22
	v_mul_f32_e32 v2, v1, v33
	v_fma_f32 v27, -v21, v2, v1
	v_fmac_f32_e32 v2, v27, v33
	v_add_f32_e32 v204, 1.0, v204
	v_add_f32_e32 v205, 1.0, v205
	v_fma_f32 v1, -v21, v2, v1
	v_div_scale_f32 v21, s[6:7], v205, v205, v3
	v_rcp_f32_e32 v27, v21
	v_div_fmas_f32 v1, v1, v33, v2
	v_div_fixup_f32 v202, v1, v218, v22
	s_waitcnt vmcnt(30)
	v_fmac_f32_e32 v200, v206, v202
	v_fmac_f32_e32 v201, v206, v203
	v_fma_f32 v1, -v21, v27, 1.0
	v_fmac_f32_e32 v27, v1, v27
	v_div_scale_f32 v1, vcc, v3, v205, v3
	v_mul_f32_e32 v2, v1, v27
	v_fma_f32 v22, -v21, v2, v1
	v_fmac_f32_e32 v2, v22, v27
	v_fma_f32 v1, -v21, v2, v1
	v_div_scale_f32 v21, s[6:7], v204, v204, v23
	v_rcp_f32_e32 v22, v21
	v_div_fmas_f32 v1, v1, v27, v2
	v_mul_f32_e32 v27, 0xbfb8aa3b, v16
	v_exp_f32_e32 v202, v27
	v_mul_f32_e32 v27, 0xbfb8aa3b, v12
	v_div_fixup_f32 v3, v1, v205, v3
	v_fma_f32 v1, -v21, v22, 1.0
	v_exp_f32_e32 v203, v27
	v_fmac_f32_e32 v22, v1, v22
	v_div_scale_f32 v1, vcc, v23, v204, v23
	v_mul_f32_e32 v2, v1, v22
	v_fma_f32 v27, -v21, v2, v1
	v_fmac_f32_e32 v2, v27, v22
	v_add_f32_e32 v202, 1.0, v202
	v_add_f32_e32 v203, 1.0, v203
	v_fma_f32 v1, -v21, v2, v1
	v_div_scale_f32 v21, s[6:7], v203, v203, v12
	v_rcp_f32_e32 v27, v21
	v_div_fmas_f32 v1, v1, v22, v2
	v_div_fixup_f32 v2, v1, v204, v23
	s_waitcnt vmcnt(29)
	v_fma_f32 v2, v208, v2, v200
	v_fma_f32 v3, v208, v3, v201
	v_fma_f32 v1, -v21, v27, 1.0
	v_fmac_f32_e32 v27, v1, v27
	v_div_scale_f32 v1, vcc, v12, v203, v12
	v_mul_f32_e32 v22, v1, v27
	v_fma_f32 v23, -v21, v22, v1
	v_fmac_f32_e32 v22, v23, v27
	v_fma_f32 v1, -v21, v22, v1
	v_div_scale_f32 v21, s[6:7], v202, v202, v16
	v_rcp_f32_e32 v31, v21
	v_div_fmas_f32 v1, v1, v27, v22
	v_mul_f32_e32 v22, 0xbfb8aa3b, v17
	v_exp_f32_e32 v200, v22
	v_mul_f32_e32 v22, 0xbfb8aa3b, v13
	v_div_fixup_f32 v23, v1, v203, v12
	v_fma_f32 v1, -v21, v31, 1.0
	v_exp_f32_e32 v201, v22
	v_fmac_f32_e32 v31, v1, v31
	v_div_scale_f32 v1, vcc, v16, v202, v16
	v_mul_f32_e32 v12, v1, v31
	v_fma_f32 v22, -v21, v12, v1
	v_fmac_f32_e32 v12, v22, v31
	v_add_f32_e32 v200, 1.0, v200
	v_add_f32_e32 v201, 1.0, v201
	v_fma_f32 v1, -v21, v12, v1
	v_div_scale_f32 v21, s[6:7], v201, v201, v13
	v_rcp_f32_e32 v27, v21
	v_div_fmas_f32 v1, v1, v31, v12
	v_div_fixup_f32 v22, v1, v202, v16
	s_waitcnt vmcnt(28)
; DI void ada_item(const Params& p, float* red, int item) {
;     ...
;     for (int j = 0; j < 32; ++j) {
;       const int k = ks * 64 + kq * 32 + j;
;       const float c0 = p.c[k], c1 = p.c[1024 + k];
;       a0 += (c0 / (1.f + __expf(-c0))) * wv[j];
;       a1 += (c1 / (1.f + __expf(-c1))) * wv[j];
;     }
	v_fmac_f32_e32 v2, v210, v22
	v_fmac_f32_e32 v3, v210, v23
	v_fma_f32 v1, -v21, v27, 1.0
	v_fmac_f32_e32 v27, v1, v27
	v_div_scale_f32 v1, vcc, v13, v201, v13
	v_mul_f32_e32 v12, v1, v27
	v_fma_f32 v16, -v21, v12, v1
	v_fmac_f32_e32 v12, v16, v27
	v_div_scale_f32 v16, s[6:7], v200, v200, v17
	v_fma_f32 v1, -v21, v12, v1
	v_rcp_f32_e32 v21, v16
	v_div_fmas_f32 v1, v1, v27, v12
	v_mul_f32_e32 v22, 0xbfb8aa3b, v18
	v_mul_f32_e32 v23, 0xbfb8aa3b, v14
	v_div_fixup_f32 v13, v1, v201, v13
	v_fma_f32 v1, -v16, v21, 1.0
	v_exp_f32_e32 v22, v22
	v_exp_f32_e32 v23, v23
	v_fmac_f32_e32 v21, v1, v21
	v_div_scale_f32 v1, vcc, v17, v200, v17
	v_mul_f32_e32 v12, v1, v21
	v_fma_f32 v27, -v16, v12, v1
	v_fmac_f32_e32 v12, v27, v21
	v_add_f32_e32 v22, 1.0, v22
	v_add_f32_e32 v23, 1.0, v23
	v_fma_f32 v1, -v16, v12, v1
	v_div_scale_f32 v16, s[6:7], v23, v23, v14
	v_rcp_f32_e32 v27, v16
	v_div_fmas_f32 v1, v1, v21, v12
	v_div_fixup_f32 v12, v1, v200, v17
	s_waitcnt vmcnt(27)
	v_fmac_f32_e32 v2, v212, v12
	v_fmac_f32_e32 v3, v212, v13
	v_fma_f32 v1, -v16, v27, 1.0
	v_fmac_f32_e32 v27, v1, v27
	v_div_scale_f32 v1, vcc, v14, v23, v14
	v_mul_f32_e32 v12, v1, v27
	v_fma_f32 v13, -v16, v12, v1
	v_fmac_f32_e32 v12, v13, v27
	v_fma_f32 v1, -v16, v12, v1
	v_div_scale_f32 v21, s[6:7], v22, v22, v18
	v_rcp_f32_e32 v31, v21
	v_div_fmas_f32 v1, v1, v27, v12
	v_div_fixup_f32 v13, v1, v23, v14
	v_mul_f32_e32 v14, 0xbfb8aa3b, v19
	v_exp_f32_e32 v16, v14
	v_mul_f32_e32 v14, 0xbfb8aa3b, v15
	v_exp_f32_e32 v17, v14
	v_fma_f32 v1, -v21, v31, 1.0
	v_fmac_f32_e32 v31, v1, v31
	v_div_scale_f32 v1, vcc, v18, v22, v18
	v_mul_f32_e32 v12, v1, v31
	v_fma_f32 v14, -v21, v12, v1
	v_add_f32_e32 v16, 1.0, v16
	v_add_f32_e32 v17, 1.0, v17
	v_fmac_f32_e32 v12, v14, v31
	v_div_scale_f32 v14, s[6:7], v17, v17, v15
	v_fma_f32 v1, -v21, v12, v1
	v_rcp_f32_e32 v21, v14
	v_div_fmas_f32 v1, v1, v31, v12
	v_div_fixup_f32 v12, v1, v22, v18
	s_waitcnt vmcnt(26)
	v_fmac_f32_e32 v2, v214, v12
	v_fmac_f32_e32 v3, v214, v13
	v_fma_f32 v1, -v14, v21, 1.0
	v_fmac_f32_e32 v21, v1, v21
	v_div_scale_f32 v1, vcc, v15, v17, v15
	v_mul_f32_e32 v12, v1, v21
	v_fma_f32 v13, -v14, v12, v1
	v_fmac_f32_e32 v12, v13, v21
	v_div_scale_f32 v18, s[6:7], v16, v16, v19
	v_fma_f32 v1, -v14, v12, v1
	v_rcp_f32_e32 v22, v18
	v_div_fmas_f32 v1, v1, v21, v12
	v_div_fixup_f32 v13, v1, v17, v15
	v_mul_f32_e32 v14, 0xbfb8aa3b, v4
	v_mul_f32_e32 v15, 0xbfb8aa3b, v8
	v_exp_f32_e32 v14, v14
	v_exp_f32_e32 v15, v15
	v_fma_f32 v1, -v18, v22, 1.0
	v_fmac_f32_e32 v22, v1, v22
	v_div_scale_f32 v1, vcc, v19, v16, v19
	v_mul_f32_e32 v12, v1, v22
	v_fma_f32 v17, -v18, v12, v1
	v_add_f32_e32 v14, 1.0, v14
	v_add_f32_e32 v15, 1.0, v15
	v_fmac_f32_e32 v12, v17, v22
	v_div_scale_f32 v17, s[6:7], v15, v15, v8
	v_fma_f32 v1, -v18, v12, v1
	v_rcp_f32_e32 v18, v17
	v_div_fmas_f32 v1, v1, v22, v12
	v_div_fixup_f32 v12, v1, v16, v19
	s_waitcnt vmcnt(25)
	v_fmac_f32_e32 v2, v198, v12
	v_fmac_f32_e32 v3, v198, v13
	v_fma_f32 v1, -v17, v18, 1.0
	v_fmac_f32_e32 v18, v1, v18
	v_div_scale_f32 v1, vcc, v8, v15, v8
	v_mul_f32_e32 v12, v1, v18
	v_fma_f32 v13, -v17, v12, v1
	v_fmac_f32_e32 v12, v13, v18
	v_fma_f32 v1, -v17, v12, v1
	v_div_scale_f32 v19, s[6:7], v14, v14, v4
	v_div_fmas_f32 v1, v1, v18, v12
	v_mul_f32_e32 v12, 0xbfb8aa3b, v5
	v_rcp_f32_e32 v21, v19
	v_exp_f32_e32 v16, v12
	v_mul_f32_e32 v12, 0xbfb8aa3b, v9
	v_exp_f32_e32 v17, v12
	v_div_fixup_f32 v13, v1, v15, v8
	v_fma_f32 v1, -v19, v21, 1.0
	v_fmac_f32_e32 v21, v1, v21
	v_div_scale_f32 v1, vcc, v4, v14, v4
	v_add_f32_e32 v16, 1.0, v16
	v_add_f32_e32 v17, 1.0, v17
	v_mul_f32_e32 v8, v1, v21
	v_div_scale_f32 v15, s[6:7], v17, v17, v9
	v_fma_f32 v12, -v19, v8, v1
	v_rcp_f32_e32 v18, v15
	v_fmac_f32_e32 v8, v12, v21
	v_fma_f32 v1, -v19, v8, v1
	v_div_fmas_f32 v1, v1, v21, v8
	v_div_fixup_f32 v12, v1, v14, v4
	v_fma_f32 v1, -v15, v18, 1.0
	v_fmac_f32_e32 v18, v1, v18
	v_div_scale_f32 v1, vcc, v9, v17, v9
	v_mul_f32_e32 v4, v1, v18
	v_fma_f32 v8, -v15, v4, v1
	v_fmac_f32_e32 v4, v8, v18
	v_div_scale_f32 v8, s[6:7], v16, v16, v5
	s_waitcnt vmcnt(24)
	v_fmac_f32_e32 v2, v196, v12
	v_fmac_f32_e32 v3, v196, v13
	v_rcp_f32_e32 v12, v8
	v_fma_f32 v1, -v15, v4, v1
	v_div_fmas_f32 v1, v1, v18, v4
	v_div_fixup_f32 v9, v1, v17, v9
	v_fma_f32 v1, -v8, v12, 1.0
	v_fmac_f32_e32 v12, v1, v12
	v_div_scale_f32 v1, vcc, v5, v16, v5
	v_mul_f32_e32 v4, v1, v12
	v_fma_f32 v13, -v8, v4, v1
	v_add_f32_e32 v22, 1.0, v220
	v_add_f32_e32 v23, 1.0, v221
	v_fmac_f32_e32 v4, v13, v12
	v_div_scale_f32 v13, s[6:7], v23, v23, v10
	v_rcp_f32_e32 v14, v13
	v_fma_f32 v1, -v8, v4, v1
	v_div_fmas_f32 v1, v1, v12, v4
	v_div_fixup_f32 v8, v1, v16, v5
	s_waitcnt vmcnt(23)
	v_fma_f32 v4, v0, v8, v2
	v_fma_f32 v5, v0, v9, v3
	v_fma_f32 v0, -v13, v14, 1.0
	v_fmac_f32_e32 v14, v0, v14
	v_div_scale_f32 v0, vcc, v10, v23, v10
	v_mul_f32_e32 v1, v0, v14
	v_div_scale_f32 v8, s[6:7], v22, v22, v6
	v_fma_f32 v2, -v13, v1, v0
	v_rcp_f32_e32 v21, v8
	v_fmac_f32_e32 v1, v2, v14
	v_fma_f32 v0, -v13, v1, v0
	v_div_fmas_f32 v0, v0, v14, v1
	v_div_fixup_f32 v9, v0, v23, v10
	v_fma_f32 v0, -v8, v21, 1.0
	v_fmac_f32_e32 v21, v0, v21
	v_mul_f32_e32 v0, 0xbfb8aa3b, v7
	v_exp_f32_e32 v196, v0
	v_mul_f32_e32 v0, 0xbfb8aa3b, v11
	v_exp_f32_e32 v197, v0
	global_load_dwordx4 v[12:15], v[132:133], off offset:200
	global_load_dwordx4 v[0:3], v[140:141], off offset:32
	global_load_dwordx4 v[16:19], v[140:141], off offset:16
	v_div_scale_f32 v10, vcc, v6, v22, v6
	v_mul_f32_e32 v23, v10, v21
	v_fma_f32 v27, -v8, v23, v10
	v_fmac_f32_e32 v23, v27, v21
	v_add_f32_e32 v198, 1.0, v196
	v_add_f32_e32 v199, 1.0, v197
	v_fma_f32 v8, -v8, v23, v10
	v_div_scale_f32 v10, s[6:7], v199, v199, v11
	v_rcp_f32_e32 v27, v10
	v_div_fmas_f32 v8, v8, v21, v23
	v_div_fixup_f32 v8, v8, v22, v6
	s_waitcnt vmcnt(25)
; DI void ada_item(const Params& p, float* red, int item) {
;     ...
;     for (int j = 0; j < 32; ++j) {
;       const int k = ks * 64 + kq * 32 + j;
;       const float c0 = p.c[k], c1 = p.c[1024 + k];
;       a0 += (c0 / (1.f + __expf(-c0))) * wv[j];
;       a1 += (c1 / (1.f + __expf(-c1))) * wv[j];
;     }
	v_fma_f32 v22, v194, v8, v4
	v_fma_f32 v23, v194, v9, v5
	v_fma_f32 v4, -v10, v27, 1.0
	v_fmac_f32_e32 v27, v4, v27
	v_div_scale_f32 v4, vcc, v11, v199, v11
	v_mul_f32_e32 v5, v4, v27
	v_fma_f32 v6, -v10, v5, v4
	v_fmac_f32_e32 v5, v6, v27
	v_div_scale_f32 v6, s[6:7], v198, v198, v7
	v_rcp_f32_e32 v8, v6
	v_fma_f32 v4, -v10, v5, v4
	v_div_fmas_f32 v4, v4, v27, v5
	v_div_fixup_f32 v203, v4, v199, v11
	v_fma_f32 v4, -v6, v8, 1.0
	v_fmac_f32_e32 v8, v4, v8
	v_div_scale_f32 v9, vcc, v7, v198, v7
	v_mul_f32_e32 v10, v9, v8
	v_fma_f32 v11, -v6, v10, v9
	v_fmac_f32_e32 v10, v11, v8
	v_fma_f32 v6, -v6, v10, v9
	v_div_fmas_f32 v6, v6, v8, v10
	global_load_dwordx4 v[194:197], v[140:141], off
	v_div_fixup_f32 v202, v6, v198, v7
	global_load_dwordx4 v[198:201], v[132:133], off offset:184
	v_mul_f32_e32 v4, 0xbfb8aa3b, v24
	v_mul_f32_e32 v5, 0xbfb8aa3b, v28
	v_exp_f32_e32 v4, v4
	v_exp_f32_e32 v5, v5
	s_waitcnt vmcnt(26)
	v_fmac_f32_e32 v22, v190, v202
	v_fmac_f32_e32 v23, v190, v203
	v_add_f32_e32 v4, 1.0, v4
	v_add_f32_e32 v5, 1.0, v5
	s_nop 0
	v_div_scale_f32 v9, s[6:7], v5, v5, v28
	v_rcp_f32_e32 v11, v9
	s_nop 0
	v_fma_f32 v6, -v9, v11, 1.0
	v_fmac_f32_e32 v11, v6, v11
	v_div_scale_f32 v6, vcc, v28, v5, v28
	v_mul_f32_e32 v7, v6, v11
	v_fma_f32 v8, -v9, v7, v6
	v_fmac_f32_e32 v7, v8, v11
	v_div_scale_f32 v8, s[6:7], v4, v4, v24
	v_fma_f32 v6, -v9, v7, v6
	v_rcp_f32_e32 v9, v8
	v_div_fmas_f32 v6, v6, v11, v7
	v_mul_f32_e32 v11, 0xbfb8aa3b, v25
	v_div_fixup_f32 v205, v6, v5, v28
	v_fma_f32 v5, -v8, v9, 1.0
	v_exp_f32_e32 v206, v11
	v_mul_f32_e32 v11, 0xbfb8aa3b, v29
	v_fmac_f32_e32 v9, v5, v9
	v_div_scale_f32 v5, vcc, v24, v4, v24
	v_exp_f32_e32 v207, v11
	v_mul_f32_e32 v6, v5, v9
	v_fma_f32 v7, -v8, v6, v5
	v_fmac_f32_e32 v6, v7, v9
	v_fma_f32 v5, -v8, v6, v5
	v_add_f32_e32 v206, 1.0, v206
	v_add_f32_e32 v207, 1.0, v207
	v_div_fmas_f32 v5, v5, v9, v6
	v_div_scale_f32 v21, s[6:7], v207, v207, v29
	v_div_fixup_f32 v204, v5, v4, v24
	v_rcp_f32_e32 v24, v21
	s_waitcnt vmcnt(4)
	v_mul_f32_e32 v11, 0xbfb8aa3b, v14
	v_exp_f32_e32 v208, v11
	s_waitcnt vmcnt(2)
	v_mul_f32_e32 v11, 0xbfb8aa3b, v18
	v_exp_f32_e32 v209, v11
	v_fma_f32 v11, -v21, v24, 1.0
	v_fmac_f32_e32 v24, v11, v24
	v_div_scale_f32 v11, vcc, v29, v207, v29
	v_mul_f32_e32 v27, v11, v24
	v_fma_f32 v28, -v21, v27, v11
	v_fmac_f32_e32 v27, v28, v24
	v_fma_f32 v11, -v21, v27, v11
	v_div_scale_f32 v21, s[6:7], v206, v206, v25
	v_rcp_f32_e32 v28, v21
	v_div_fmas_f32 v11, v11, v24, v27
	v_mul_f32_e32 v27, 0xbfb8aa3b, v26
	v_exp_f32_e32 v190, v27
	v_mul_f32_e32 v27, 0xbfb8aa3b, v30
	v_div_fixup_f32 v29, v11, v207, v29
	v_fma_f32 v11, -v21, v28, 1.0
	v_exp_f32_e32 v191, v27
	v_fmac_f32_e32 v28, v11, v28
	v_div_scale_f32 v11, vcc, v25, v206, v25
	v_mul_f32_e32 v24, v11, v28
	v_fma_f32 v27, -v21, v24, v11
	v_fmac_f32_e32 v24, v27, v28
	v_add_f32_e32 v190, 1.0, v190
	v_add_f32_e32 v191, 1.0, v191
	v_fma_f32 v11, -v21, v24, v11
	v_div_scale_f32 v21, s[6:7], v191, v191, v30
	v_rcp_f32_e32 v27, v21
	v_div_fmas_f32 v11, v11, v28, v24
	v_div_fixup_f32 v28, v11, v206, v25
	v_fmac_f32_e32 v22, v192, v204
	v_fmac_f32_e32 v23, v192, v205
	v_fma_f32 v11, -v21, v27, 1.0
	v_fmac_f32_e32 v27, v11, v27
	v_div_scale_f32 v11, vcc, v30, v191, v30
	v_mul_f32_e32 v24, v11, v27
	v_fma_f32 v25, -v21, v24, v11
	v_fmac_f32_e32 v24, v25, v27
	v_fma_f32 v11, -v21, v24, v11
	v_div_scale_f32 v21, s[6:7], v190, v190, v26
	v_rcp_f32_e32 v31, v21
	v_div_fmas_f32 v11, v11, v27, v24
	s_waitcnt vmcnt(0)
	v_mul_f32_e32 v27, 0xbfb8aa3b, v198
	v_fmac_f32_e32 v22, v188, v28
	v_fmac_f32_e32 v23, v188, v29
	v_exp_f32_e32 v28, v27
	v_mul_f32_e32 v27, 0xbfb8aa3b, v194
	v_div_fixup_f32 v25, v11, v191, v30
	v_fma_f32 v11, -v21, v31, 1.0
	v_exp_f32_e32 v29, v27
	v_fmac_f32_e32 v31, v11, v31
	v_div_scale_f32 v11, vcc, v26, v190, v26
	v_mul_f32_e32 v24, v11, v31
	v_fma_f32 v27, -v21, v24, v11
	v_fmac_f32_e32 v24, v27, v31
	v_add_f32_e32 v28, 1.0, v28
	v_add_f32_e32 v29, 1.0, v29
	v_fma_f32 v11, -v21, v24, v11
	v_div_scale_f32 v21, s[6:7], v29, v29, v194
	v_rcp_f32_e32 v27, v21
	v_div_fmas_f32 v11, v11, v31, v24
	v_div_fixup_f32 v24, v11, v190, v26
	v_fmac_f32_e32 v22, v186, v24
	v_fmac_f32_e32 v23, v186, v25
	v_fma_f32 v11, -v21, v27, 1.0
	v_fmac_f32_e32 v27, v11, v27
	v_div_scale_f32 v11, vcc, v194, v29, v194
	v_mul_f32_e32 v24, v11, v27
	v_fma_f32 v25, -v21, v24, v11
	v_fmac_f32_e32 v24, v25, v27
	v_fma_f32 v11, -v21, v24, v11
	v_div_scale_f32 v21, s[6:7], v28, v28, v198
	v_rcp_f32_e32 v30, v21
	v_div_fmas_f32 v11, v11, v27, v24
	v_mul_f32_e32 v26, 0xbfb8aa3b, v199
	v_mul_f32_e32 v27, 0xbfb8aa3b, v195
	v_div_fixup_f32 v25, v11, v29, v194
	v_fma_f32 v11, -v21, v30, 1.0
	v_exp_f32_e32 v26, v26
	v_exp_f32_e32 v27, v27
	v_fmac_f32_e32 v30, v11, v30
	v_div_scale_f32 v11, vcc, v198, v28, v198
	v_mul_f32_e32 v24, v11, v30
	v_fma_f32 v29, -v21, v24, v11
	v_fmac_f32_e32 v24, v29, v30
	v_add_f32_e32 v26, 1.0, v26
	v_add_f32_e32 v27, 1.0, v27
	v_fma_f32 v11, -v21, v24, v11
	v_div_scale_f32 v21, s[6:7], v27, v27, v195
	v_rcp_f32_e32 v29, v21
	v_div_fmas_f32 v11, v11, v30, v24
	v_div_fixup_f32 v24, v11, v28, v198
	v_fmac_f32_e32 v22, v184, v24
	v_fmac_f32_e32 v23, v184, v25
	v_fma_f32 v11, -v21, v29, 1.0
	v_fmac_f32_e32 v29, v11, v29
	v_div_scale_f32 v11, vcc, v195, v27, v195
	v_mul_f32_e32 v24, v11, v29
	v_fma_f32 v25, -v21, v24, v11
	v_fmac_f32_e32 v24, v25, v29
	v_fma_f32 v11, -v21, v24, v11
	v_div_scale_f32 v21, s[6:7], v26, v26, v199
	v_rcp_f32_e32 v30, v21
	v_div_fmas_f32 v11, v11, v29, v24
	v_div_fixup_f32 v25, v11, v27, v195
	v_mul_f32_e32 v27, 0xbfb8aa3b, v200
	v_exp_f32_e32 v28, v27
	v_mul_f32_e32 v27, 0xbfb8aa3b, v196
	v_fma_f32 v11, -v21, v30, 1.0
; DI void ada_item(const Params& p, float* red, int item) {
;     ...
;     for (int j = 0; j < 32; ++j) {
;       const int k = ks * 64 + kq * 32 + j;
;       const float c0 = p.c[k], c1 = p.c[1024 + k];
;       a0 += (c0 / (1.f + __expf(-c0))) * wv[j];
;       a1 += (c1 / (1.f + __expf(-c1))) * wv[j];
;     }
	v_exp_f32_e32 v29, v27
	v_fmac_f32_e32 v30, v11, v30
	v_div_scale_f32 v11, vcc, v199, v26, v199
	v_mul_f32_e32 v24, v11, v30
	v_fma_f32 v27, -v21, v24, v11
	v_fmac_f32_e32 v24, v27, v30
	v_add_f32_e32 v28, 1.0, v28
	v_add_f32_e32 v29, 1.0, v29
	v_fma_f32 v11, -v21, v24, v11
	v_div_scale_f32 v21, s[6:7], v29, v29, v196
	v_rcp_f32_e32 v27, v21
	v_div_fmas_f32 v11, v11, v30, v24
	v_div_fixup_f32 v24, v11, v26, v199
	v_fmac_f32_e32 v22, v182, v24
	v_fmac_f32_e32 v23, v182, v25
	v_fma_f32 v11, -v21, v27, 1.0
	v_fmac_f32_e32 v27, v11, v27
	v_div_scale_f32 v11, vcc, v196, v29, v196
	v_mul_f32_e32 v24, v11, v27
	v_fma_f32 v25, -v21, v24, v11
	v_fmac_f32_e32 v24, v25, v27
	v_fma_f32 v11, -v21, v24, v11
	v_div_scale_f32 v21, s[6:7], v28, v28, v200
	v_rcp_f32_e32 v30, v21
	v_div_fmas_f32 v11, v11, v27, v24
	v_mul_f32_e32 v26, 0xbfb8aa3b, v201
	v_mul_f32_e32 v27, 0xbfb8aa3b, v197
	v_div_fixup_f32 v25, v11, v29, v196
	v_fma_f32 v11, -v21, v30, 1.0
	v_exp_f32_e32 v26, v26
	v_exp_f32_e32 v27, v27
	v_fmac_f32_e32 v30, v11, v30
	v_div_scale_f32 v11, vcc, v200, v28, v200
	v_mul_f32_e32 v24, v11, v30
	v_fma_f32 v29, -v21, v24, v11
	v_fmac_f32_e32 v24, v29, v30
	v_add_f32_e32 v26, 1.0, v26
	v_add_f32_e32 v27, 1.0, v27
	v_fma_f32 v11, -v21, v24, v11
	v_div_scale_f32 v21, s[6:7], v27, v27, v197
	v_rcp_f32_e32 v29, v21
	v_div_fmas_f32 v11, v11, v30, v24
	v_div_fixup_f32 v24, v11, v28, v200
	v_fmac_f32_e32 v22, v180, v24
	v_fmac_f32_e32 v23, v180, v25
	v_fma_f32 v11, -v21, v29, 1.0
	v_fmac_f32_e32 v29, v11, v29
	v_div_scale_f32 v11, vcc, v197, v27, v197
	v_mul_f32_e32 v24, v11, v29
	v_fma_f32 v25, -v21, v24, v11
	v_fmac_f32_e32 v24, v25, v29
	v_fma_f32 v11, -v21, v24, v11
	v_div_scale_f32 v21, s[6:7], v26, v26, v201
	v_rcp_f32_e32 v30, v21
	v_div_fmas_f32 v11, v11, v29, v24
	v_div_fixup_f32 v25, v11, v27, v197
	v_mul_f32_e32 v27, 0xbfb8aa3b, v12
	v_exp_f32_e32 v28, v27
	v_mul_f32_e32 v27, 0xbfb8aa3b, v16
	v_fma_f32 v11, -v21, v30, 1.0
	v_exp_f32_e32 v29, v27
	v_fmac_f32_e32 v30, v11, v30
	v_div_scale_f32 v11, vcc, v201, v26, v201
	v_mul_f32_e32 v24, v11, v30
	v_fma_f32 v27, -v21, v24, v11
	v_fmac_f32_e32 v24, v27, v30
	v_add_f32_e32 v28, 1.0, v28
	v_add_f32_e32 v29, 1.0, v29
	v_fma_f32 v11, -v21, v24, v11
	v_div_scale_f32 v21, s[6:7], v29, v29, v16
	v_rcp_f32_e32 v27, v21
	v_div_fmas_f32 v11, v11, v30, v24
	v_div_fixup_f32 v24, v11, v26, v201
	v_fmac_f32_e32 v22, v178, v24
	v_fmac_f32_e32 v23, v178, v25
	v_fma_f32 v11, -v21, v27, 1.0
	v_fmac_f32_e32 v27, v11, v27
	v_div_scale_f32 v11, vcc, v16, v29, v16
	v_mul_f32_e32 v24, v11, v27
	v_fma_f32 v25, -v21, v24, v11
	v_fmac_f32_e32 v24, v25, v27
	v_fma_f32 v11, -v21, v24, v11
	v_div_scale_f32 v21, s[6:7], v28, v28, v12
	v_rcp_f32_e32 v30, v21
	global_load_dwordx4 v[4:7], v[132:133], off offset:216
	global_load_dwordx3 v[8:10], v[132:133], off offset:232
	v_div_fmas_f32 v11, v11, v27, v24
	v_mul_f32_e32 v24, 0xbfb8aa3b, v13
	v_exp_f32_e32 v26, v24
	v_mul_f32_e32 v24, 0xbfb8aa3b, v17
	v_div_fixup_f32 v25, v11, v29, v16
	v_fma_f32 v11, -v21, v30, 1.0
	v_exp_f32_e32 v27, v24
	v_fmac_f32_e32 v30, v11, v30
	v_div_scale_f32 v11, vcc, v12, v28, v12
	v_mul_f32_e32 v16, v11, v30
	v_fma_f32 v24, -v21, v16, v11
	v_fmac_f32_e32 v16, v24, v30
	v_add_f32_e32 v26, 1.0, v26
	v_add_f32_e32 v27, 1.0, v27
	v_fma_f32 v11, -v21, v16, v11
	v_div_scale_f32 v21, s[6:7], v27, v27, v17
	v_rcp_f32_e32 v29, v21
	v_div_fmas_f32 v11, v11, v30, v16
	v_div_fixup_f32 v24, v11, v28, v12
	v_fmac_f32_e32 v22, v174, v24
	v_fmac_f32_e32 v23, v174, v25
	v_fma_f32 v11, -v21, v29, 1.0
	v_fmac_f32_e32 v29, v11, v29
	v_div_scale_f32 v11, vcc, v17, v27, v17
	v_mul_f32_e32 v12, v11, v29
	v_fma_f32 v16, -v21, v12, v11
	v_fmac_f32_e32 v12, v16, v29
	v_div_scale_f32 v16, s[6:7], v26, v26, v13
	v_fma_f32 v11, -v21, v12, v11
	v_rcp_f32_e32 v21, v16
	v_div_fmas_f32 v11, v11, v29, v12
	v_div_fixup_f32 v17, v11, v27, v17
	v_fma_f32 v11, -v16, v21, 1.0
	v_fmac_f32_e32 v21, v11, v21
	v_div_scale_f32 v11, vcc, v13, v26, v13
	v_mul_f32_e32 v12, v11, v21
	v_fma_f32 v24, -v16, v12, v11
	v_fmac_f32_e32 v12, v24, v21
	v_add_f32_e32 v24, 1.0, v208
	v_add_f32_e32 v25, 1.0, v209
	v_fma_f32 v11, -v16, v12, v11
	v_div_scale_f32 v27, s[6:7], v25, v25, v18
	v_rcp_f32_e32 v28, v27
	v_div_fmas_f32 v11, v11, v21, v12
	v_div_fixup_f32 v16, v11, v26, v13
	v_fma_f32 v12, v20, v16, v22
	v_fma_f32 v13, v20, v17, v23
	v_fma_f32 v11, -v27, v28, 1.0
	v_fmac_f32_e32 v28, v11, v28
	v_div_scale_f32 v11, vcc, v18, v25, v18
	v_mul_f32_e32 v16, v11, v28
	v_fma_f32 v17, -v27, v16, v11
	v_fmac_f32_e32 v16, v17, v28
	v_fma_f32 v11, -v27, v16, v11
	v_div_fmas_f32 v11, v11, v28, v16
	v_div_fixup_f32 v25, v11, v25, v18
	global_load_dwordx3 v[20:22], v[140:141], off offset:48
	global_load_dwordx3 v[16:18], v[142:143], off
	v_div_scale_f32 v23, s[6:7], v24, v24, v14
	v_rcp_f32_e32 v29, v23
	v_mul_f32_e32 v26, 0xbfb8aa3b, v15
	v_mul_f32_e32 v27, 0xbfb8aa3b, v19
	v_exp_f32_e32 v26, v26
	v_fma_f32 v11, -v23, v29, 1.0
	v_exp_f32_e32 v27, v27
	v_fmac_f32_e32 v29, v11, v29
	v_div_scale_f32 v11, vcc, v14, v24, v14
	v_mul_f32_e32 v28, v11, v29
	v_fma_f32 v30, -v23, v28, v11
	v_fmac_f32_e32 v28, v30, v29
	v_add_f32_e32 v26, 1.0, v26
	v_add_f32_e32 v27, 1.0, v27
	v_fma_f32 v11, -v23, v28, v11
	v_div_scale_f32 v23, s[6:7], v27, v27, v19
	v_rcp_f32_e32 v30, v23
	v_div_fmas_f32 v11, v11, v29, v28
	v_div_fixup_f32 v24, v11, v24, v14
	v_fma_f32 v24, v172, v24, v12
	v_fma_f32 v25, v172, v25, v13
	v_fma_f32 v11, -v23, v30, 1.0
	v_fmac_f32_e32 v30, v11, v30
	v_div_scale_f32 v11, vcc, v19, v27, v19
	v_mul_f32_e32 v12, v11, v30
	v_fma_f32 v13, -v23, v12, v11
	v_fmac_f32_e32 v12, v13, v30
	v_div_scale_f32 v14, s[6:7], v26, v26, v15
	v_fma_f32 v11, -v23, v12, v11
	v_rcp_f32_e32 v23, v14
	v_div_fmas_f32 v11, v11, v30, v12
	s_waitcnt vmcnt(3)
; DI void ada_item(const Params& p, float* red, int item) {
;     ...
;     for (int j = 0; j < 32; ++j) {
;       const int k = ks * 64 + kq * 32 + j;
;       const float c0 = p.c[k], c1 = p.c[1024 + k];
;       a0 += (c0 / (1.f + __expf(-c0))) * wv[j];
;       a1 += (c1 / (1.f + __expf(-c1))) * wv[j];
;     }
	v_mul_f32_e32 v12, 0xbfb8aa3b, v4
	v_mul_f32_e32 v13, 0xbfb8aa3b, v0
	v_div_fixup_f32 v27, v11, v27, v19
	v_fma_f32 v11, -v14, v23, 1.0
	v_exp_f32_e32 v12, v12
	v_exp_f32_e32 v13, v13
	v_fmac_f32_e32 v23, v11, v23
	v_div_scale_f32 v11, vcc, v15, v26, v15
	v_mul_f32_e32 v19, v11, v23
	v_fma_f32 v28, -v14, v19, v11
	v_fmac_f32_e32 v19, v28, v23
	v_add_f32_e32 v12, 1.0, v12
	v_add_f32_e32 v13, 1.0, v13
	v_fma_f32 v11, -v14, v19, v11
	v_div_scale_f32 v14, s[6:7], v13, v13, v0
	v_rcp_f32_e32 v28, v14
	v_div_fmas_f32 v11, v11, v23, v19
	v_div_fixup_f32 v26, v11, v26, v15
	v_fmac_f32_e32 v24, v168, v26
	v_fmac_f32_e32 v25, v168, v27
	v_fma_f32 v11, -v14, v28, 1.0
	v_fmac_f32_e32 v28, v11, v28
	v_div_scale_f32 v11, vcc, v0, v13, v0
	v_mul_f32_e32 v15, v11, v28
	v_fma_f32 v19, -v14, v15, v11
	v_fmac_f32_e32 v15, v19, v28
	v_fma_f32 v11, -v14, v15, v11
	v_div_scale_f32 v14, s[6:7], v12, v12, v4
	v_rcp_f32_e32 v19, v14
	v_div_fmas_f32 v11, v11, v28, v15
	v_div_fixup_f32 v15, v11, v13, v0
	v_fma_f32 v0, -v14, v19, 1.0
	v_fmac_f32_e32 v19, v0, v19
	v_div_scale_f32 v0, vcc, v4, v12, v4
	v_mul_f32_e32 v11, v0, v19
	v_fma_f32 v13, -v14, v11, v0
	v_fmac_f32_e32 v11, v13, v19
	v_fma_f32 v0, -v14, v11, v0
	v_div_fmas_f32 v0, v0, v19, v11
	v_div_fixup_f32 v14, v0, v12, v4
	v_mul_f32_e32 v0, 0xbfb8aa3b, v5
	v_exp_f32_e32 v28, v0
	v_mul_f32_e32 v0, 0xbfb8aa3b, v1
	v_exp_f32_e32 v29, v0
	v_mul_f32_e32 v0, 0xbfb8aa3b, v42
	v_exp_f32_e32 v12, v0
	s_waitcnt vmcnt(0)
	v_mul_f32_e32 v0, 0xbfb8aa3b, v18
	v_add_f32_e32 v28, 1.0, v28
	v_add_f32_e32 v29, 1.0, v29
	v_exp_f32_e32 v13, v0
	v_div_scale_f32 v4, s[6:7], v29, v29, v1
	v_rcp_f32_e32 v11, v4
	v_fma_f32 v14, v170, v14, v24
	v_fma_f32 v15, v170, v15, v25
	v_fma_f32 v0, -v4, v11, 1.0
	v_fmac_f32_e32 v11, v0, v11
	v_div_scale_f32 v0, vcc, v1, v29, v1
	v_mul_f32_e32 v19, v0, v11
	v_fma_f32 v23, -v4, v19, v0
	v_fmac_f32_e32 v19, v23, v11
	v_fma_f32 v0, -v4, v19, v0
	v_div_scale_f32 v4, s[6:7], v28, v28, v5
	v_rcp_f32_e32 v23, v4
	v_div_fmas_f32 v0, v0, v11, v19
	v_mul_f32_e32 v19, 0xbfb8aa3b, v6
	v_exp_f32_e32 v24, v19
	v_mul_f32_e32 v19, 0xbfb8aa3b, v2
	v_div_fixup_f32 v1, v0, v29, v1
	v_fma_f32 v0, -v4, v23, 1.0
	v_exp_f32_e32 v25, v19
	v_fmac_f32_e32 v23, v0, v23
	v_div_scale_f32 v0, vcc, v5, v28, v5
	v_mul_f32_e32 v11, v0, v23
	v_fma_f32 v19, -v4, v11, v0
	v_fmac_f32_e32 v11, v19, v23
	v_add_f32_e32 v24, 1.0, v24
	v_add_f32_e32 v25, 1.0, v25
	v_fma_f32 v0, -v4, v11, v0
	v_div_scale_f32 v4, s[6:7], v25, v25, v2
	v_rcp_f32_e32 v19, v4
	v_div_fmas_f32 v0, v0, v23, v11
	v_div_fixup_f32 v0, v0, v28, v5
	v_fma_f32 v0, v166, v0, v14
	v_fma_f32 v1, v166, v1, v15
	v_fma_f32 v5, -v4, v19, 1.0
	v_fmac_f32_e32 v19, v5, v19
	v_div_scale_f32 v5, vcc, v2, v25, v2
	v_mul_f32_e32 v11, v5, v19
	v_fma_f32 v14, -v4, v11, v5
	v_fmac_f32_e32 v11, v14, v19
	v_div_scale_f32 v23, s[6:7], v24, v24, v6
	v_fma_f32 v4, -v4, v11, v5
	v_rcp_f32_e32 v26, v23
	v_div_fmas_f32 v4, v4, v19, v11
	v_mul_f32_e32 v11, 0xbfb8aa3b, v7
	v_exp_f32_e32 v14, v11
	v_mul_f32_e32 v11, 0xbfb8aa3b, v3
	v_exp_f32_e32 v15, v11
	v_div_fixup_f32 v5, v4, v25, v2
	v_fma_f32 v2, -v23, v26, 1.0
	v_fmac_f32_e32 v26, v2, v26
	v_div_scale_f32 v2, vcc, v6, v24, v6
	v_mul_f32_e32 v4, v2, v26
	v_fma_f32 v11, -v23, v4, v2
	v_add_f32_e32 v14, 1.0, v14
	v_add_f32_e32 v15, 1.0, v15
	v_fmac_f32_e32 v4, v11, v26
	v_div_scale_f32 v11, s[6:7], v15, v15, v3
	v_rcp_f32_e32 v19, v11
	v_fma_f32 v2, -v23, v4, v2
	v_div_fmas_f32 v2, v2, v26, v4
	v_div_fixup_f32 v4, v2, v24, v6
	v_fma_f32 v2, -v11, v19, 1.0
	v_fmac_f32_e32 v19, v2, v19
	v_div_scale_f32 v2, vcc, v3, v15, v3
	v_fmac_f32_e32 v0, v162, v4
	v_fmac_f32_e32 v1, v162, v5
	v_mul_f32_e32 v4, v2, v19
	v_fma_f32 v5, -v11, v4, v2
	v_fmac_f32_e32 v4, v5, v19
	v_div_scale_f32 v6, s[6:7], v14, v14, v7
	v_fma_f32 v2, -v11, v4, v2
	v_rcp_f32_e32 v11, v6
	v_div_fmas_f32 v2, v2, v19, v4
	v_mul_f32_e32 v4, 0xbfb8aa3b, v8
	v_mul_f32_e32 v5, 0xbfb8aa3b, v20
	v_div_fixup_f32 v3, v2, v15, v3
	v_fma_f32 v2, -v6, v11, 1.0
	v_exp_f32_e32 v4, v4
	v_exp_f32_e32 v5, v5
	v_fmac_f32_e32 v11, v2, v11
	v_div_scale_f32 v2, vcc, v7, v14, v7
	v_mul_f32_e32 v15, v2, v11
	v_fma_f32 v19, -v6, v15, v2
	v_fmac_f32_e32 v15, v19, v11
	v_add_f32_e32 v4, 1.0, v4
	v_add_f32_e32 v5, 1.0, v5
	v_fma_f32 v2, -v6, v15, v2
	v_div_scale_f32 v6, s[6:7], v5, v5, v20
	v_rcp_f32_e32 v19, v6
	v_div_fmas_f32 v2, v2, v11, v15
	v_div_fixup_f32 v2, v2, v14, v7
	v_fmac_f32_e32 v0, v160, v2
	v_fmac_f32_e32 v1, v160, v3
	v_fma_f32 v2, -v6, v19, 1.0
	v_fmac_f32_e32 v19, v2, v19
	v_div_scale_f32 v2, vcc, v20, v5, v20
	v_mul_f32_e32 v3, v2, v19
	v_div_scale_f32 v11, s[6:7], v4, v4, v8
	v_fma_f32 v7, -v6, v3, v2
	v_rcp_f32_e32 v14, v11
	v_fmac_f32_e32 v3, v7, v19
	v_fma_f32 v2, -v6, v3, v2
	v_div_fmas_f32 v2, v2, v19, v3
	v_mul_f32_e32 v6, 0xbfb8aa3b, v9
	v_mul_f32_e32 v7, 0xbfb8aa3b, v21
	v_div_fixup_f32 v3, v2, v5, v20
	v_fma_f32 v2, -v11, v14, 1.0
	v_exp_f32_e32 v6, v6
	v_exp_f32_e32 v7, v7
	v_fmac_f32_e32 v14, v2, v14
	v_div_scale_f32 v2, vcc, v8, v4, v8
	v_mul_f32_e32 v5, v2, v14
	v_fma_f32 v15, -v11, v5, v2
	v_fmac_f32_e32 v5, v15, v14
	v_add_f32_e32 v6, 1.0, v6
	v_add_f32_e32 v7, 1.0, v7
	v_fma_f32 v2, -v11, v5, v2
	v_div_scale_f32 v11, s[6:7], v7, v7, v21
	v_rcp_f32_e32 v15, v11
	v_div_fmas_f32 v2, v2, v14, v5
	v_div_fixup_f32 v2, v2, v4, v8
	v_fmac_f32_e32 v0, v46, v2
	v_fmac_f32_e32 v1, v46, v3
	v_fma_f32 v2, -v11, v15, 1.0
	v_fmac_f32_e32 v15, v2, v15
	v_div_scale_f32 v2, vcc, v21, v7, v21
; DI void ada_item(const Params& p, float* red, int item) {
;     ...
;   for (int kq = 0; kq < 2; ++kq) {
;     float wv[32];
; #pragma unroll
;     for (int j = 0; j < 32; ++j) wv[j] = p.w_ada[(size_t)(ks * 64 + kq * 32 + j) * 3072 + n];
; #pragma unroll
;     for (int j = 0; j < 32; ++j) {
;       const int k = ks * 64 + kq * 32 + j;
;       const float c0 = p.c[k], c1 = p.c[1024 + k];
;       a0 += (c0 / (1.f + __expf(-c0))) * wv[j];
;       a1 += (c1 / (1.f + __expf(-c1))) * wv[j];
;     }
;   }
;   red[(ks * 16 + col) * 2 + 0] = a0;
;   red[(ks * 16 + col) * 2 + 1] = a1;
;   __syncthreads();
;   if (tid < 32) {
;     const int cc = tid & 15, b = tid >> 4;
;     float s = 0.f;
;     for (int q = 0; q < 16; ++q) s += red[(q * 16 + cc) * 2 + b];
;     p.ada[b * 3072 + item * 16 + cc] = s + p.b_ada[item * 16 + cc];
	v_mul_f32_e32 v3, v2, v15
	v_fma_f32 v4, -v11, v3, v2
	v_fmac_f32_e32 v3, v4, v15
	v_div_scale_f32 v8, s[6:7], v6, v6, v9
	v_fma_f32 v2, -v11, v3, v2
	v_rcp_f32_e32 v11, v8
	v_div_fmas_f32 v2, v2, v15, v3
	v_mul_f32_e32 v4, 0xbfb8aa3b, v10
	v_mul_f32_e32 v5, 0xbfb8aa3b, v22
	v_div_fixup_f32 v3, v2, v7, v21
	v_fma_f32 v2, -v8, v11, 1.0
	v_exp_f32_e32 v4, v4
	v_exp_f32_e32 v5, v5
	v_fmac_f32_e32 v11, v2, v11
	v_div_scale_f32 v2, vcc, v9, v6, v9
	v_mul_f32_e32 v7, v2, v11
	v_fma_f32 v14, -v8, v7, v2
	v_fmac_f32_e32 v7, v14, v11
	v_add_f32_e32 v4, 1.0, v4
	v_add_f32_e32 v5, 1.0, v5
	v_fma_f32 v2, -v8, v7, v2
	v_div_scale_f32 v8, s[6:7], v5, v5, v22
	v_rcp_f32_e32 v14, v8
	v_div_fmas_f32 v2, v2, v11, v7
	v_div_fixup_f32 v2, v2, v6, v9
	v_fmac_f32_e32 v0, v44, v2
	v_fmac_f32_e32 v1, v44, v3
	v_fma_f32 v2, -v8, v14, 1.0
	v_fmac_f32_e32 v14, v2, v14
	v_div_scale_f32 v2, vcc, v22, v5, v22
	v_mul_f32_e32 v3, v2, v14
	v_fma_f32 v6, -v8, v3, v2
	v_fmac_f32_e32 v3, v6, v14
	v_fma_f32 v2, -v8, v3, v2
	v_div_scale_f32 v8, s[6:7], v4, v4, v10
	v_rcp_f32_e32 v9, v8
	v_div_fmas_f32 v2, v2, v14, v3
	v_mul_f32_e32 v6, 0xbfb8aa3b, v40
	v_mul_f32_e32 v7, 0xbfb8aa3b, v16
	v_div_fixup_f32 v3, v2, v5, v22
	v_fma_f32 v2, -v8, v9, 1.0
	v_exp_f32_e32 v6, v6
	v_exp_f32_e32 v7, v7
	v_fmac_f32_e32 v9, v2, v9
	v_div_scale_f32 v2, vcc, v10, v4, v10
	v_mul_f32_e32 v5, v2, v9
	v_fma_f32 v11, -v8, v5, v2
	v_fmac_f32_e32 v5, v11, v9
	v_add_f32_e32 v6, 1.0, v6
	v_add_f32_e32 v7, 1.0, v7
	v_fma_f32 v2, -v8, v5, v2
	v_div_scale_f32 v8, s[6:7], v7, v7, v16
	v_rcp_f32_e32 v11, v8
	v_div_fmas_f32 v2, v2, v9, v5
	v_div_fixup_f32 v2, v2, v4, v10
	v_fmac_f32_e32 v0, v38, v2
	v_fmac_f32_e32 v1, v38, v3
	v_fma_f32 v2, -v8, v11, 1.0
	v_fmac_f32_e32 v11, v2, v11
	v_div_scale_f32 v2, vcc, v16, v7, v16
	v_mul_f32_e32 v3, v2, v11
	v_fma_f32 v4, -v8, v3, v2
	v_fmac_f32_e32 v3, v4, v11
	v_fma_f32 v2, -v8, v3, v2
	v_div_scale_f32 v8, s[6:7], v6, v6, v40
	v_rcp_f32_e32 v9, v8
	v_div_fmas_f32 v2, v2, v11, v3
	v_mul_f32_e32 v4, 0xbfb8aa3b, v41
	v_mul_f32_e32 v5, 0xbfb8aa3b, v17
	v_div_fixup_f32 v3, v2, v7, v16
	v_fma_f32 v2, -v8, v9, 1.0
	v_exp_f32_e32 v4, v4
	v_exp_f32_e32 v5, v5
	v_fmac_f32_e32 v9, v2, v9
	v_div_scale_f32 v2, vcc, v40, v6, v40
	v_mul_f32_e32 v7, v2, v9
	v_fma_f32 v10, -v8, v7, v2
	v_fmac_f32_e32 v7, v10, v9
	v_add_f32_e32 v4, 1.0, v4
	v_add_f32_e32 v5, 1.0, v5
	v_fma_f32 v2, -v8, v7, v2
	v_div_scale_f32 v8, s[6:7], v5, v5, v17
	v_rcp_f32_e32 v10, v8
	v_div_fmas_f32 v2, v2, v9, v7
	v_div_fixup_f32 v2, v2, v6, v40
	v_fmac_f32_e32 v0, v36, v2
	v_fmac_f32_e32 v1, v36, v3
	v_fma_f32 v2, -v8, v10, 1.0
	v_fmac_f32_e32 v10, v2, v10
	v_div_scale_f32 v2, vcc, v17, v5, v17
	v_mul_f32_e32 v3, v2, v10
	v_fma_f32 v6, -v8, v3, v2
	v_fmac_f32_e32 v3, v6, v10
	v_div_scale_f32 v6, s[6:7], v4, v4, v41
	v_fma_f32 v2, -v8, v3, v2
	v_rcp_f32_e32 v8, v6
	v_div_fmas_f32 v2, v2, v10, v3
	v_div_fixup_f32 v3, v2, v5, v17
	v_fma_f32 v2, -v6, v8, 1.0
	v_fmac_f32_e32 v8, v2, v8
	v_div_scale_f32 v2, vcc, v41, v4, v41
	v_mul_f32_e32 v5, v2, v8
	v_fma_f32 v7, -v6, v5, v2
	v_fmac_f32_e32 v5, v7, v8
	v_fma_f32 v2, -v6, v5, v2
	v_add_f32_e32 v6, 1.0, v12
	v_add_f32_e32 v7, 1.0, v13
	v_div_fmas_f32 v2, v2, v8, v5
	v_div_scale_f32 v9, s[6:7], v7, v7, v18
	v_rcp_f32_e32 v10, v9
	v_div_fixup_f32 v2, v2, v4, v41
	v_fmac_f32_e32 v0, v34, v2
	v_fmac_f32_e32 v1, v34, v3
	v_fma_f32 v2, -v9, v10, 1.0
	v_fmac_f32_e32 v10, v2, v10
	v_div_scale_f32 v2, vcc, v18, v7, v18
	v_mul_f32_e32 v3, v2, v10
	v_fma_f32 v4, -v9, v3, v2
	v_fmac_f32_e32 v3, v4, v10
	v_div_scale_f32 v4, s[6:7], v6, v6, v42
	v_rcp_f32_e32 v5, v4
	v_fma_f32 v2, -v9, v3, v2
	v_div_fmas_f32 v2, v2, v10, v3
	v_div_fixup_f32 v3, v2, v7, v18
	v_fma_f32 v2, -v4, v5, 1.0
	v_fmac_f32_e32 v5, v2, v5
	v_div_scale_f32 v2, vcc, v42, v6, v42
	v_mul_f32_e32 v7, v2, v5
	v_fma_f32 v8, -v4, v7, v2
	v_fmac_f32_e32 v7, v8, v5
	v_fma_f32 v2, -v4, v7, v2
	v_div_fmas_f32 v2, v2, v5, v7
	v_div_fixup_f32 v2, v2, v6, v42
	v_fmac_f32_e32 v0, v32, v2
	v_fmac_f32_e32 v1, v32, v3
	ds_write_b64 v176, v[0:1]
	s_waitcnt lgkmcnt(0)
	s_barrier
	s_and_saveexec_b64 s[6:7], s[4:5]
	s_cbranch_execz .LBB0_22
	v_lshl_add_u64 v[0:1], v[146:147], 2, s[14:15]
	global_load_dword v18, v[0:1], off
	ds_read2_b32 v[0:1], v171 offset1:32
	ds_read2_b32 v[2:3], v171 offset0:64 offset1:96
	ds_read2_b32 v[4:5], v171 offset0:128 offset1:160
	ds_read2_b32 v[6:7], v171 offset0:192 offset1:224
	v_add_u32_e32 v9, 0x400, v171
	s_waitcnt lgkmcnt(3)
	v_add_f32_e32 v0, 0, v0
	v_add_f32_e32 v0, v0, v1
	s_waitcnt lgkmcnt(2)
	v_add_f32_e32 v0, v0, v2
	v_add_f32_e32 v0, v0, v3
	s_waitcnt lgkmcnt(1)
	v_add_f32_e32 v0, v0, v4
	v_add_f32_e32 v0, v0, v5
	ds_read2_b32 v[10:11], v9 offset1:32
	ds_read2_b32 v[12:13], v9 offset0:64 offset1:96
	ds_read2_b32 v[14:15], v9 offset0:128 offset1:160
	ds_read2_b32 v[16:17], v9 offset0:192 offset1:224
	s_waitcnt lgkmcnt(4)
	v_add_f32_e32 v0, v0, v6
	v_add_f32_e32 v0, v0, v7
	s_waitcnt lgkmcnt(3)
	v_add_f32_e32 v0, v0, v10
	v_add_f32_e32 v0, v0, v11
	s_waitcnt lgkmcnt(2)
	v_add_f32_e32 v0, v0, v12
	v_add_f32_e32 v0, v0, v13
	s_waitcnt lgkmcnt(1)
	v_add_f32_e32 v0, v0, v14
	v_add_f32_e32 v0, v0, v15
	v_add_u32_e32 v8, v173, v146
	s_waitcnt lgkmcnt(0)
	v_add_f32_e32 v0, v0, v16
	v_ashrrev_i32_e32 v9, 31, v8
	v_add_f32_e32 v0, v0, v17
	s_waitcnt vmcnt(0)
	v_add_f32_e32 v2, v0, v18
	v_lshl_add_u64 v[0:1], v[8:9], 2, s[34:35]
	global_store_dword v[0:1], v2, off sc1
	s_branch .LBB0_22

; DI void phase1(const Params& p, const Sched sc) {
;     ...
;     const int rowa = v * 2048 + l * 16 + wave * 4, b = rowa >> 13;
;     f32x4 v4[4][4];
; #pragma unroll
;     for (int q = 0; q < 4; ++q) {
;       const f32x4* xr = (const f32x4*)(p.x + (size_t)(rowa + q) * DM);
; #pragma unroll
;       for (int i = 0; i < 2; ++i) { v4[q][2 * i] = xr[2 * lane + 128 * i]; v4[q][2 * i + 1] = xr[2 * lane + 128 * i + 1]; }
;     }
;     const float* ad = p.ada + b * 3072;
;     f32x4 nw[4], sh[4];
; #pragma unroll
;     for (int j = 0; j < 4; ++j) {
;       const int k = (2 * lane + 128 * (j >> 1) + (j & 1)) * 4;
;       nw[j] = *(const f32x4*)(p.norm_w + k); sh[j] = *(const f32x4*)(ad + k);
;       const f32x4 sc4 = *(const f32x4*)(ad + 1024 + k);
; #pragma unroll
;       for (int e = 0; e < 4; ++e) nw[j][e] *= 1.f + sc4[e];
;     }
; #pragma unroll
;     for (int q = 0; q < 4; ++q) {
;       float ss = 0.f;
; #pragma unroll
;       for (int j = 0; j < 4; ++j) ss += v4[q][j][0] * v4[q][j][0] + v4[q][j][1] * v4[q][j][1] + v4[q][j][2] * v4[q][j][2] + v4[q][j][3] * v4[q][j][3];
; #pragma unroll
;       for (int o = 1; o < 64; o <<= 1) ss += __shfl_xor(ss, o);
.LBB0_161:
	v_ashrrev_i32_e32 v93, 31, v92
	v_lshlrev_b64 v[0:1], 12, v[92:93]
	v_add_u32_e32 v98, 1, v92
	v_lshl_add_u64 v[0:1], v[88:89], 0, v[0:1]
	v_ashrrev_i32_e32 v99, 31, v98
	global_load_dwordx4 v[76:79], v[0:1], off
	global_load_dwordx4 v[72:75], v[0:1], off offset:16
	global_load_dwordx4 v[68:71], v[0:1], off offset:2048
	global_load_dwordx4 v[64:67], v[0:1], off offset:2064
	v_lshlrev_b64 v[0:1], 12, v[98:99]
	v_lshl_add_u64 v[0:1], v[88:89], 0, v[0:1]
	global_load_dwordx4 v[36:39], v[0:1], off
	global_load_dwordx4 v[32:35], v[0:1], off offset:16
	global_load_dwordx4 v[20:23], v[0:1], off offset:2048
	global_load_dwordx4 v[16:19], v[0:1], off offset:2064
	v_ashrrev_i32_e32 v0, 13, v92
	v_add_u32_e32 v94, 2, v92
	v_mul_i32_i24_e32 v0, 0xc00, v0
	v_ashrrev_i32_e32 v95, 31, v94
	v_ashrrev_i32_e32 v1, 31, v0
	v_mov_b32_e32 v91, v81
	v_lshlrev_b64 v[2:3], 12, v[94:95]
	v_lshl_add_u64 v[0:1], v[0:1], 2, s[2:3]
	v_lshl_add_u64 v[40:41], v[88:89], 0, v[2:3]
	v_lshl_add_u64 v[42:43], v[0:1], 0, s[6:7]
	v_lshl_add_u64 v[2:3], v[0:1], 0, v[80:81]
	v_lshl_add_u64 v[44:45], v[0:1], 0, v[90:91]
	global_load_dwordx4 v[106:109], v[82:83], off offset:16
	global_load_dwordx4 v[100:103], v[82:83], off
	global_load_dwordx4 v[112:115], v[84:85], off offset:16
	global_load_dwordx4 v[132:135], v[84:85], off
	global_load_dwordx4 v[28:31], v[40:41], off
	global_load_dwordx4 v[24:27], v[40:41], off offset:16
	global_load_dwordx4 v[8:11], v[2:3], off offset:16
	global_load_dwordx4 v[12:15], v[2:3], off
	v_lshl_add_u64 v[46:47], v[42:43], 0, v[80:81]
	global_load_dwordx4 v[0:3], v[44:45], off offset:16
	global_load_dwordx4 v[4:7], v[44:45], off
	global_load_dwordx4 v[136:139], v[46:47], off offset:16
	global_load_dwordx4 v[140:143], v[46:47], off
	v_lshl_add_u64 v[42:43], v[42:43], 0, v[90:91]
	global_load_dwordx4 v[144:147], v[42:43], off offset:16
	global_load_dwordx4 v[148:151], v[42:43], off
	s_add_i32 s14, s14, s33
	s_cmpk_gt_i32 s14, 0x7f
	s_waitcnt vmcnt(21)
	v_mov_b32_e32 v44, v77
	s_waitcnt vmcnt(20)
	v_mov_b32_e32 v45, v73
	s_waitcnt vmcnt(19)
	v_mov_b32_e32 v52, v69
	s_waitcnt vmcnt(18)
	v_mov_b32_e32 v53, v65
	v_mov_b32_e32 v42, v76
	v_mov_b32_e32 v43, v72
	v_mov_b32_e32 v50, v68
	v_mov_b32_e32 v51, v64
	v_mul_f32_e32 v44, v44, v44
	v_mul_f32_e32 v45, v45, v45
	v_mul_f32_e32 v52, v52, v52
	v_mul_f32_e32 v53, v53, v53
	s_waitcnt vmcnt(17)
	v_mov_b32_e32 v60, v37
	s_waitcnt vmcnt(16)
	v_mov_b32_e32 v61, v33
	v_mov_b32_e32 v46, v78
	v_mov_b32_e32 v47, v74
	v_mov_b32_e32 v58, v36
	v_mov_b32_e32 v59, v32
	s_waitcnt vmcnt(15)
	v_mov_b32_e32 v110, v21
	s_waitcnt vmcnt(14)
	v_mov_b32_e32 v111, v17
	v_fma_f32 v42, v42, v42, v44
	v_fma_f32 v43, v43, v43, v45
	v_fma_f32 v44, v50, v50, v52
	v_fma_f32 v45, v51, v51, v53
	v_mul_f32_e32 v50, v60, v60
	v_mul_f32_e32 v51, v61, v61
	v_mov_b32_e32 v62, v38
	v_mov_b32_e32 v63, v34
	v_mov_b32_e32 v104, v20
	v_mov_b32_e32 v105, v16
	v_mul_f32_e32 v52, v110, v110
	v_mul_f32_e32 v53, v111, v111
	v_fmac_f32_e32 v42, v46, v46
	v_fmac_f32_e32 v43, v47, v47
	v_fma_f32 v46, v58, v58, v50
	v_fma_f32 v47, v59, v59, v51
	v_mov_b32_e32 v48, v79
	v_mov_b32_e32 v49, v75
	v_mov_b32_e32 v54, v70
	v_mov_b32_e32 v55, v66
	v_mov_b32_e32 v96, v39
	v_mov_b32_e32 v97, v35
	v_mov_b32_e32 v152, v22
	v_mov_b32_e32 v153, v18
	v_fma_f32 v50, v104, v104, v52
	v_fma_f32 v51, v105, v105, v53
	v_fmac_f32_e32 v46, v62, v62
	v_fmac_f32_e32 v47, v63, v63
	v_mov_b32_e32 v56, v71
	v_mov_b32_e32 v57, v67
	v_mov_b32_e32 v154, v23
	v_fmac_f32_e32 v44, v54, v54
	v_fmac_f32_e32 v45, v55, v55
	v_fmac_f32_e32 v42, v48, v48
	v_fmac_f32_e32 v43, v49, v49
	v_fma_f32 v48, v152, v152, v50
	v_fma_f32 v49, v153, v153, v51
	v_fmac_f32_e32 v46, v96, v96
	v_fmac_f32_e32 v47, v97, v97
	v_mov_b32_e32 v155, v19
	v_fmac_f32_e32 v44, v56, v56
	v_fmac_f32_e32 v45, v57, v57
	v_fmac_f32_e32 v48, v154, v154
	v_fmac_f32_e32 v49, v155, v155
	v_mov_b32_e32 v50, v46
	v_mov_b32_e32 v51, v42
	v_mov_b32_e32 v42, v47
	v_add_f32_e32 v42, v50, v42
	v_add_f32_e32 v43, v51, v43
	v_mov_b32_e32 v46, v48
	v_mov_b32_e32 v47, v44
	v_add_f32_e32 v42, v42, v46
	v_add_f32_e32 v43, v43, v47
	v_mov_b32_e32 v44, v49
	v_add_f32_e32 v42, v42, v44
	v_add_f32_e32 v43, v43, v45
	ds_bpermute_b32 v45, v125, v43
	ds_bpermute_b32 v44, v125, v42
	v_add_u32_e32 v96, 3, v92
	global_load_dwordx4 v[60:63], v[40:41], off offset:2048
	global_load_dwordx4 v[56:59], v[40:41], off offset:2064
	v_ashrrev_i32_e32 v97, 31, v96
	v_lshlrev_b64 v[154:155], 11, v[92:93]
	s_waitcnt lgkmcnt(0)
	v_add_f32_e32 v40, v42, v44
	v_add_f32_e32 v41, v43, v45
	ds_bpermute_b32 v43, v126, v41
	ds_bpermute_b32 v42, v126, v40
	v_lshlrev_b64 v[44:45], 12, v[96:97]
	v_lshl_add_u64 v[104:105], v[88:89], 0, v[44:45]
	global_load_dwordx4 v[52:55], v[104:105], off
	global_load_dwordx4 v[48:51], v[104:105], off offset:16
	v_add_u32_e32 v92, s11, v92
	s_waitcnt lgkmcnt(0)
	v_add_f32_e32 v110, v40, v42
	v_add_f32_e32 v111, v41, v43
	global_load_dwordx4 v[44:47], v[104:105], off offset:2048
	global_load_dwordx4 v[40:43], v[104:105], off offset:2064
	ds_bpermute_b32 v153, v127, v111
	ds_bpermute_b32 v152, v127, v110
	s_waitcnt vmcnt(8)
	v_add_f32_e32 v104, 1.0, v140
	v_add_f32_e32 v105, 1.0, v141
	s_waitcnt lgkmcnt(0)
	v_add_f32_e32 v110, v110, v152
	v_add_f32_e32 v111, v111, v153
	ds_bpermute_b32 v141, v128, v111
	ds_bpermute_b32 v140, v128, v110
	v_mul_f32_e32 v100, v100, v104
	v_mul_f32_e32 v101, v101, v105
	v_add_f32_e32 v104, 1.0, v142
	v_add_f32_e32 v105, 1.0, v143
	s_nop 0
	v_mul_f32_e32 v104, v102, v104
	v_mul_f32_e32 v105, v103, v105
	v_add_f32_e32 v102, 1.0, v136
	v_add_f32_e32 v103, 1.0, v137
	s_nop 0
	v_mul_f32_e32 v102, v106, v102
	v_mul_f32_e32 v103, v107, v103
	s_waitcnt lgkmcnt(0)
; DI unsigned pk_bf16(float lo, float hi) { f32x2 v = {lo, hi}; bf2_t b = __builtin_convertvector(v, bf2_t); return __builtin_bit_cast(unsigned, b); }
; DI void phase1(const Params& p, const Sched sc) {
;     ...
;     for (int j = 0; j < 4; ++j) {
;       const int k = (2 * lane + 128 * (j >> 1) + (j & 1)) * 4;
;       nw[j] = *(const f32x4*)(p.norm_w + k); sh[j] = *(const f32x4*)(ad + k);
;       const f32x4 sc4 = *(const f32x4*)(ad + 1024 + k);
; #pragma unroll
;       for (int e = 0; e < 4; ++e) nw[j][e] *= 1.f + sc4[e];
;     }
; #pragma unroll
;     for (int q = 0; q < 4; ++q) {
;       float ss = 0.f;
; #pragma unroll
;       for (int j = 0; j < 4; ++j) ss += v4[q][j][0] * v4[q][j][0] + v4[q][j][1] * v4[q][j][1] + v4[q][j][2] * v4[q][j][2] + v4[q][j][3] * v4[q][j][3];
; #pragma unroll
;       for (int o = 1; o < 64; o <<= 1) ss += __shfl_xor(ss, o);
;       const float rstd = rsqrtf(ss * (1.f / DM) + 1e-6f);
; #pragma unroll
;       for (int i = 0; i < 2; ++i) {
;         u32x4 w;
; #pragma unroll
;         for (int jj = 0; jj < 2; ++jj) {
;           const int j = 2 * i + jj;
;           float o[4];
; #pragma unroll
;           for (int e = 0; e < 4; ++e) o[e] = (v4[q][j][e] * rstd) * nw[j][e] + sh[j][e];
;           w[2 * jj] = pk_bf16(o[0], o[1]); w[2 * jj + 1] = pk_bf16(o[2], o[3]);
;         }
;         *(u32x4*)(p.H + (size_t)(rowa + q) * DM + (2 * lane + 128 * i) * 4) = w;
;       }
	v_add_f32_e32 v106, v110, v140
	v_add_f32_e32 v107, v111, v141
	ds_bpermute_b32 v137, v129, v107
	ds_bpermute_b32 v136, v129, v106
	v_add_f32_e32 v110, 1.0, v138
	v_add_f32_e32 v111, 1.0, v139
	v_lshl_add_u64 v[138:139], v[86:87], 0, v[154:155]
	v_mul_f32_e32 v110, v108, v110
	v_mul_f32_e32 v111, v109, v111
	s_waitcnt vmcnt(6)
	v_add_f32_e32 v108, 1.0, v148
	v_add_f32_e32 v109, 1.0, v149
	s_waitcnt lgkmcnt(0)
	v_add_f32_e32 v136, v106, v136
	v_add_f32_e32 v137, v107, v137
	ds_bpermute_b32 v141, v130, v137
	ds_bpermute_b32 v140, v130, v136
	v_mul_f32_e32 v106, v132, v108
	v_mul_f32_e32 v107, v133, v109
	v_add_f32_e32 v108, 1.0, v150
	v_add_f32_e32 v109, 1.0, v151
	v_add_f32_e32 v132, 1.0, v144
	v_add_f32_e32 v133, 1.0, v145
	v_mul_f32_e32 v108, v134, v108
	v_mul_f32_e32 v109, v135, v109
	s_waitcnt lgkmcnt(0)
	v_add_f32_e32 v134, v136, v140
	v_add_f32_e32 v135, v137, v141
	v_mov_b64_e32 v[136:137], s[10:11]
	v_fma_f32 v134, v134, s8, v136
	v_fma_f32 v135, v135, s8, v136
	v_mul_f32_e32 v112, v112, v132
	v_mul_f32_e32 v113, v113, v133
	v_mul_f32_e32 v91, 0x4b800000, v135
	v_cmp_gt_f32_e32 vcc, s12, v135
	v_add_f32_e32 v132, 1.0, v146
	v_add_f32_e32 v133, 1.0, v147
	s_nop 0
	v_cndmask_b32_e32 v91, v135, v91, vcc
	v_rsq_f32_e32 v91, v91
	v_mul_f32_e32 v114, v114, v132
	v_mul_f32_e32 v115, v115, v133
	v_mul_f32_e32 v93, 0x45800000, v91
	v_cndmask_b32_e32 v132, v91, v93, vcc
	v_mul_f32_e32 v68, v68, v132
	v_mul_f32_e32 v69, v69, v132
	v_mul_f32_e32 v70, v70, v132
	v_mul_f32_e32 v71, v71, v132
	v_fma_f32 v68, v106, v68, v4
	v_fma_f32 v69, v107, v69, v5
	v_fma_f32 v70, v108, v70, v6
	v_fma_f32 v71, v109, v71, v7
	v_mul_f32_e32 v76, v76, v132
	v_mul_f32_e32 v77, v77, v132
	v_mul_f32_e32 v78, v78, v132
	v_mul_f32_e32 v79, v79, v132
	v_mul_f32_e32 v72, v72, v132
	v_mul_f32_e32 v73, v73, v132
	v_cvt_pk_bf16_f32 v68, v68, v69
	v_cvt_pk_bf16_f32 v69, v70, v71
	v_mul_f32_e32 v70, 0x4b800000, v134
	v_cmp_gt_f32_e32 vcc, s12, v134
	v_fma_f32 v76, v100, v76, v12
	v_fma_f32 v77, v101, v77, v13
	v_fma_f32 v78, v104, v78, v14
	v_fma_f32 v79, v105, v79, v15
	v_fma_f32 v72, v102, v72, v8
	v_fma_f32 v73, v103, v73, v9
	v_mul_f32_e32 v64, v64, v132
	v_mul_f32_e32 v65, v65, v132
	v_mul_f32_e32 v66, v66, v132
	v_mul_f32_e32 v67, v67, v132
	v_cndmask_b32_e32 v70, v134, v70, vcc
	v_cvt_pk_bf16_f32 v76, v76, v77
	v_cvt_pk_bf16_f32 v77, v78, v79
	v_cvt_pk_bf16_f32 v78, v72, v73
	v_fma_f32 v64, v112, v64, v0
	v_fma_f32 v65, v113, v65, v1
	v_fma_f32 v66, v114, v66, v2
	v_fma_f32 v67, v115, v67, v3
	v_rsq_f32_e32 v72, v70
	v_cvt_pk_bf16_f32 v70, v64, v65
	v_cvt_pk_bf16_f32 v71, v66, v67
	global_store_dwordx4 v[138:139], v[68:71], off offset:1024
	v_mul_f32_e32 v64, 0x45800000, v72
	v_cndmask_b32_e32 v64, v72, v64, vcc
	v_mov_b32_e32 v70, v29
	v_mov_b32_e32 v71, v25
	v_mov_b32_e32 v68, v28
	v_mov_b32_e32 v69, v24
	v_mul_f32_e32 v70, v70, v70
	v_mul_f32_e32 v71, v71, v71
	s_waitcnt vmcnt(6)
	v_mov_b32_e32 v72, v61
	v_fma_f32 v68, v68, v68, v70
	v_fma_f32 v69, v69, v69, v71
	v_mov_b32_e32 v70, v30
	v_mov_b32_e32 v71, v26
	v_fmac_f32_e32 v68, v70, v70
	v_fmac_f32_e32 v69, v71, v71
	v_mov_b32_e32 v70, v31
	v_mov_b32_e32 v71, v27
	s_waitcnt vmcnt(5)
	v_mov_b32_e32 v73, v57
	v_mul_f32_e32 v74, v74, v132
	v_mul_f32_e32 v75, v75, v132
	v_fmac_f32_e32 v68, v70, v70
	v_fmac_f32_e32 v69, v71, v71
	v_mov_b32_e32 v70, v60
	v_mov_b32_e32 v71, v56
	v_mul_f32_e32 v72, v72, v72
	v_mul_f32_e32 v73, v73, v73
	v_fma_f32 v74, v110, v74, v10
	v_fma_f32 v75, v111, v75, v11
	v_fma_f32 v70, v70, v70, v72
	v_fma_f32 v71, v71, v71, v73
	v_mov_b32_e32 v72, v62
	v_mov_b32_e32 v73, v58
	v_cvt_pk_bf16_f32 v79, v74, v75
	v_fmac_f32_e32 v70, v72, v72
	v_fmac_f32_e32 v71, v73, v73
	v_mov_b32_e32 v72, v63
	v_mov_b32_e32 v73, v59
	s_waitcnt vmcnt(4)
	v_mov_b32_e32 v74, v53
	s_waitcnt vmcnt(3)
	v_mov_b32_e32 v75, v49
	v_fmac_f32_e32 v70, v72, v72
	v_fmac_f32_e32 v71, v73, v73
	v_mov_b32_e32 v72, v52
	v_mov_b32_e32 v73, v48
	v_mul_f32_e32 v74, v74, v74
	v_mul_f32_e32 v75, v75, v75
	global_store_dwordx4 v[138:139], v[76:79], off
	v_fma_f32 v72, v72, v72, v74
	v_fma_f32 v73, v73, v73, v75
	v_mov_b32_e32 v74, v54
	v_mov_b32_e32 v75, v50
	v_fmac_f32_e32 v72, v74, v74
	v_fmac_f32_e32 v73, v75, v75
	v_mov_b32_e32 v74, v55
	v_mov_b32_e32 v75, v51
	s_waitcnt vmcnt(3)
	v_mov_b32_e32 v76, v45
	s_waitcnt vmcnt(2)
	v_mov_b32_e32 v77, v41
	v_fmac_f32_e32 v72, v74, v74
	v_fmac_f32_e32 v73, v75, v75
	v_mov_b32_e32 v74, v44
	v_mov_b32_e32 v75, v40
	v_mul_f32_e32 v76, v76, v76
	v_mul_f32_e32 v77, v77, v77
	v_mul_f32_e32 v36, v36, v64
	v_mul_f32_e32 v37, v37, v64
	v_fma_f32 v74, v74, v74, v76
	v_fma_f32 v75, v75, v75, v77
	v_mov_b32_e32 v76, v46
	v_mov_b32_e32 v77, v42
	v_fmac_f32_e32 v74, v76, v76
	v_fmac_f32_e32 v75, v77, v77
	v_mov_b32_e32 v76, v47
	v_mov_b32_e32 v77, v43
	v_fmac_f32_e32 v74, v76, v76
	v_fmac_f32_e32 v75, v77, v77
	v_mov_b32_e32 v76, v72
	v_mov_b32_e32 v77, v68
	v_mov_b32_e32 v68, v73
	v_add_f32_e32 v68, v76, v68
	v_add_f32_e32 v69, v77, v69
	v_mov_b32_e32 v72, v74
	v_mov_b32_e32 v73, v70
	v_add_f32_e32 v68, v68, v72
	v_add_f32_e32 v69, v69, v73
	v_mov_b32_e32 v70, v75
	v_add_f32_e32 v68, v68, v70
	v_add_f32_e32 v69, v69, v71
	ds_bpermute_b32 v71, v125, v69
	ds_bpermute_b32 v70, v125, v68
	v_mul_f32_e32 v38, v38, v64
	v_mul_f32_e32 v39, v39, v64
	v_fma_f32 v36, v100, v36, v12
	v_fma_f32 v37, v101, v37, v13
	v_fma_f32 v38, v104, v38, v14
	v_fma_f32 v39, v105, v39, v15
	v_cvt_pk_bf16_f32 v36, v36, v37
	v_cvt_pk_bf16_f32 v37, v38, v39
	s_waitcnt lgkmcnt(0)
; DI unsigned pk_bf16(float lo, float hi) { f32x2 v = {lo, hi}; bf2_t b = __builtin_convertvector(v, bf2_t); return __builtin_bit_cast(unsigned, b); }
; DI void phase1(const Params& p, const Sched sc) {
;     ...
; #pragma unroll
;     for (int q = 0; q < 4; ++q) {
;       float ss = 0.f;
; #pragma unroll
;       for (int j = 0; j < 4; ++j) ss += v4[q][j][0] * v4[q][j][0] + v4[q][j][1] * v4[q][j][1] + v4[q][j][2] * v4[q][j][2] + v4[q][j][3] * v4[q][j][3];
; #pragma unroll
;       for (int o = 1; o < 64; o <<= 1) ss += __shfl_xor(ss, o);
;       const float rstd = rsqrtf(ss * (1.f / DM) + 1e-6f);
; #pragma unroll
;       for (int i = 0; i < 2; ++i) {
;         u32x4 w;
; #pragma unroll
;         for (int jj = 0; jj < 2; ++jj) {
;           const int j = 2 * i + jj;
;           float o[4];
; #pragma unroll
;           for (int e = 0; e < 4; ++e) o[e] = (v4[q][j][e] * rstd) * nw[j][e] + sh[j][e];
;           w[2 * jj] = pk_bf16(o[0], o[1]); w[2 * jj + 1] = pk_bf16(o[2], o[3]);
;         }
;         *(u32x4*)(p.H + (size_t)(rowa + q) * DM + (2 * lane + 128 * i) * 4) = w;
;       }
	v_add_f32_e32 v38, v68, v70
	v_add_f32_e32 v39, v69, v71
	ds_bpermute_b32 v69, v126, v39
	ds_bpermute_b32 v68, v126, v38
	v_mul_f32_e32 v32, v32, v64
	v_mul_f32_e32 v33, v33, v64
	v_mul_f32_e32 v34, v34, v64
	v_mul_f32_e32 v35, v35, v64
	v_lshlrev_b64 v[66:67], 11, v[98:99]
	v_fma_f32 v32, v102, v32, v8
	v_fma_f32 v33, v103, v33, v9
	s_waitcnt lgkmcnt(0)
	v_add_f32_e32 v68, v38, v68
	v_add_f32_e32 v69, v39, v69
	ds_bpermute_b32 v71, v127, v69
	ds_bpermute_b32 v70, v127, v68
	v_fma_f32 v34, v110, v34, v10
	v_fma_f32 v35, v111, v35, v11
	v_cvt_pk_bf16_f32 v38, v32, v33
	v_cvt_pk_bf16_f32 v39, v34, v35
	v_lshl_add_u64 v[32:33], v[86:87], 0, v[66:67]
	s_waitcnt lgkmcnt(0)
	v_add_f32_e32 v34, v68, v70
	v_add_f32_e32 v35, v69, v71
	global_store_dwordx4 v[32:33], v[36:39], off
	ds_bpermute_b32 v37, v128, v35
	ds_bpermute_b32 v36, v128, v34
	v_mul_f32_e32 v20, v20, v64
	v_mul_f32_e32 v21, v21, v64
	v_mul_f32_e32 v22, v22, v64
	v_mul_f32_e32 v23, v23, v64
	v_mul_f32_e32 v16, v16, v64
	v_mul_f32_e32 v17, v17, v64
	v_fma_f32 v20, v106, v20, v4
	v_fma_f32 v21, v107, v21, v5
	s_waitcnt lgkmcnt(0)
	v_add_f32_e32 v34, v34, v36
	v_add_f32_e32 v35, v35, v37
	ds_bpermute_b32 v37, v129, v35
	ds_bpermute_b32 v36, v129, v34
	v_fma_f32 v22, v108, v22, v6
	v_fma_f32 v23, v109, v23, v7
	v_fma_f32 v16, v112, v16, v0
	v_fma_f32 v17, v113, v17, v1
	v_cvt_pk_bf16_f32 v20, v20, v21
	v_cvt_pk_bf16_f32 v21, v22, v23
	s_waitcnt lgkmcnt(0)
	v_add_f32_e32 v34, v34, v36
	v_add_f32_e32 v35, v35, v37
	ds_bpermute_b32 v37, v130, v35
	ds_bpermute_b32 v36, v130, v34
	v_cvt_pk_bf16_f32 v22, v16, v17
	v_mul_f32_e32 v18, v18, v64
	v_mul_f32_e32 v19, v19, v64
	s_waitcnt lgkmcnt(0)
	v_add_f32_e32 v16, v34, v36
	v_add_f32_e32 v17, v35, v37
	s_nop 0
	v_fma_f32 v34, v16, s8, v136
	v_fma_f32 v35, v17, s8, v136
	v_fma_f32 v18, v114, v18, v2
	v_fma_f32 v19, v115, v19, v3
	v_mul_f32_e32 v16, 0x4b800000, v35
	v_cmp_gt_f32_e32 vcc, s12, v35
	v_cvt_pk_bf16_f32 v23, v18, v19
	global_store_dwordx4 v[32:33], v[20:23], off offset:1024
	v_cndmask_b32_e32 v16, v35, v16, vcc
	v_rsq_f32_e32 v18, v16
	v_lshlrev_b64 v[16:17], 11, v[94:95]
	v_lshl_add_u64 v[20:21], v[86:87], 0, v[16:17]
	v_mul_f32_e32 v16, 0x45800000, v18
	v_cndmask_b32_e32 v22, v18, v16, vcc
	v_mul_f32_e32 v16, v28, v22
	v_mul_f32_e32 v17, v29, v22
	v_mul_f32_e32 v18, v30, v22
	v_mul_f32_e32 v19, v31, v22
	v_fma_f32 v16, v100, v16, v12
	v_fma_f32 v17, v101, v17, v13
	v_fma_f32 v18, v104, v18, v14
	v_fma_f32 v19, v105, v19, v15
	v_cvt_pk_bf16_f32 v16, v16, v17
	v_cvt_pk_bf16_f32 v17, v18, v19
	v_mul_f32_e32 v18, v24, v22
	v_mul_f32_e32 v19, v25, v22
	v_mul_f32_e32 v24, v26, v22
	v_mul_f32_e32 v25, v27, v22
	v_fma_f32 v18, v102, v18, v8
	v_fma_f32 v19, v103, v19, v9
	v_fma_f32 v24, v110, v24, v10
	v_fma_f32 v25, v111, v25, v11
	v_cvt_pk_bf16_f32 v18, v18, v19
	v_cvt_pk_bf16_f32 v19, v24, v25
	v_mul_f32_e32 v24, 0x4b800000, v34
	v_cmp_gt_f32_e32 vcc, s12, v34
	global_store_dwordx4 v[20:21], v[16:19], off
	s_nop 0
	v_cndmask_b32_e32 v24, v34, v24, vcc
	v_mul_f32_e32 v16, v60, v22
	v_mul_f32_e32 v17, v61, v22
	v_mul_f32_e32 v18, v62, v22
	v_mul_f32_e32 v19, v63, v22
	v_fma_f32 v16, v106, v16, v4
	v_fma_f32 v17, v107, v17, v5
	v_fma_f32 v18, v108, v18, v6
	v_fma_f32 v19, v109, v19, v7
	v_rsq_f32_e32 v24, v24
	v_cvt_pk_bf16_f32 v16, v16, v17
	v_cvt_pk_bf16_f32 v17, v18, v19
	v_mul_f32_e32 v18, v56, v22
	v_mul_f32_e32 v19, v57, v22
	v_mul_f32_e32 v23, v59, v22
	v_mul_f32_e32 v22, v58, v22
	v_fma_f32 v18, v112, v18, v0
	v_fma_f32 v19, v113, v19, v1
	v_fma_f32 v22, v114, v22, v2
	v_fma_f32 v23, v115, v23, v3
	v_cvt_pk_bf16_f32 v18, v18, v19
	v_cvt_pk_bf16_f32 v19, v22, v23
	global_store_dwordx4 v[20:21], v[16:19], off offset:1024
	s_nop 1
	v_mul_f32_e32 v16, 0x45800000, v24
	v_cndmask_b32_e32 v16, v24, v16, vcc
	v_mul_f32_e32 v20, v52, v16
	v_mul_f32_e32 v21, v53, v16
	v_lshlrev_b64 v[18:19], 11, v[96:97]
	v_fmac_f32_e32 v12, v100, v20
	v_fmac_f32_e32 v13, v101, v21
	v_mul_f32_e32 v20, v54, v16
	v_mul_f32_e32 v21, v55, v16
	v_cvt_pk_bf16_f32 v12, v12, v13
	v_fmac_f32_e32 v14, v104, v20
	v_fmac_f32_e32 v15, v105, v21
	s_nop 0
	v_cvt_pk_bf16_f32 v13, v14, v15
	v_mul_f32_e32 v14, v48, v16
	v_mul_f32_e32 v15, v49, v16
	s_nop 0
	v_fmac_f32_e32 v8, v102, v14
	v_fmac_f32_e32 v9, v103, v15
	v_mul_f32_e32 v14, v50, v16
	v_mul_f32_e32 v15, v51, v16
	s_nop 0
	v_fmac_f32_e32 v10, v110, v14
	v_fmac_f32_e32 v11, v111, v15
	v_cvt_pk_bf16_f32 v14, v8, v9
	v_cvt_pk_bf16_f32 v15, v10, v11
	v_mul_f32_e32 v10, v44, v16
	v_mul_f32_e32 v11, v45, v16
	v_lshl_add_u64 v[8:9], v[86:87], 0, v[18:19]
	v_fmac_f32_e32 v4, v106, v10
	v_fmac_f32_e32 v5, v107, v11
	v_mul_f32_e32 v10, v46, v16
	v_mul_f32_e32 v11, v47, v16
	v_cvt_pk_bf16_f32 v4, v4, v5
	v_fmac_f32_e32 v6, v108, v10
	v_fmac_f32_e32 v7, v109, v11
	global_store_dwordx4 v[8:9], v[12:15], off
	v_cvt_pk_bf16_f32 v5, v6, v7
	v_mul_f32_e32 v6, v40, v16
	v_mul_f32_e32 v7, v41, v16
	s_nop 0
	v_fmac_f32_e32 v0, v112, v6
	v_fmac_f32_e32 v1, v113, v7
	v_mul_f32_e32 v6, v42, v16
	v_mul_f32_e32 v7, v43, v16
	s_nop 0
	v_fmac_f32_e32 v2, v114, v6
	v_fmac_f32_e32 v3, v115, v7
	v_cvt_pk_bf16_f32 v6, v0, v1
	v_cvt_pk_bf16_f32 v7, v2, v3
	global_store_dwordx4 v[8:9], v[4:7], off offset:1024
	s_cbranch_scc0 .LBB0_161
	s_branch .LBB0_158

; DI unsigned pk_bf16(float lo, float hi) { f32x2 v = {lo, hi}; bf2_t b = __builtin_convertvector(v, bf2_t); return __builtin_bit_cast(unsigned, b); }
; DI float silu_f(float v) { return v * __builtin_amdgcn_rcpf(1.f + fast_exp2(-v * LOG2E)); }
; template <int NI>
; DI void p2_store_group(const Params& p, const f32x16 (&a)[NI], int colg, int tok0, int b, int h) {
;     ...
;       bf16_t* d = base + (size_t)idx * stride + 8 * h;
; #pragma unroll
;       for (int q = 0; q < 2; ++q) {
;         u32x2 w[2];
; #pragma unroll
;         for (int gg = 0; gg < 2; ++gg) {
;           const int g = 2 * q + gg;
;           float v0 = a[ni][4 * g] * scale, v1 = a[ni][4 * g + 1] * scale, v2 = a[ni][4 * g + 2] * scale, v3 = a[ni][4 * g + 3] * scale;
;           if (mode == 1) { v0 = silu_f(v0); v1 = silu_f(v1); v2 = silu_f(v2); v3 = silu_f(v3); }
;           w[gg].x = pk_bf16(v0, v1); w[gg].y = pk_bf16(v2, v3);
;         }
;         *(u32x4*)(d + 16 * q) = widen_pair(w[0], w[1]);
;         __builtin_amdgcn_sched_barrier(0);
;       }
.LBB0_232:
	s_or_b64 exec, exec, s[36:37]
	v_mul_f32_e32 v16, v16, v32
	v_mul_f32_e32 v17, v17, v32
	v_mul_f32_e32 v18, v18, v32
	v_mul_f32_e32 v19, v19, v32
	s_and_saveexec_b64 s[36:37], s[2:3]
	s_cbranch_execz .LBB0_234
	v_mul_f32_e32 v33, 0xbfb8aa3b, v16
	v_exp_f32_e32 v33, v33
	v_mul_f32_e32 v38, 0xbfb8aa3b, v17
	v_exp_f32_e32 v38, v38
	v_mul_f32_e32 v40, 0xbfb8aa3b, v19
	v_add_f32_e32 v33, 1.0, v33
	v_exp_f32_e32 v41, v40
	v_add_f32_e32 v39, 1.0, v38
	v_rcp_f32_e32 v38, v33
	v_mul_f32_e32 v33, 0xbfb8aa3b, v18
	v_exp_f32_e32 v33, v33
	v_rcp_f32_e32 v39, v39
	v_add_f32_e32 v33, 1.0, v33
	v_rcp_f32_e32 v40, v33
	v_add_f32_e32 v33, 1.0, v41
	v_rcp_f32_e32 v41, v33
	v_mul_f32_e32 v16, v16, v38
	v_mul_f32_e32 v17, v17, v39
	v_mul_f32_e32 v18, v18, v40
	v_mul_f32_e32 v19, v19, v41
.LBB0_234:
	s_or_b64 exec, exec, s[36:37]
	v_mov_b32_e32 v33, v32
	v_mul_f32_e32 v20, v20, v32
	v_mul_f32_e32 v21, v21, v33
	v_mul_f32_e32 v22, v22, v32
	v_mul_f32_e32 v23, v23, v33
	s_and_saveexec_b64 s[36:37], s[2:3]
	s_cbranch_execz .LBB0_236
	v_mul_f32_e32 v38, 0xbfb8aa3b, v20
	v_mul_f32_e32 v39, 0xbfb8aa3b, v21
	v_mul_f32_e32 v40, 0xbfb8aa3b, v22
	v_mul_f32_e32 v41, 0xbfb8aa3b, v23
	v_exp_f32_e32 v38, v38
	v_exp_f32_e32 v39, v39
	v_exp_f32_e32 v40, v40
	v_exp_f32_e32 v41, v41
	v_add_f32_e32 v38, 1.0, v38
	v_add_f32_e32 v39, 1.0, v39
	v_add_f32_e32 v40, 1.0, v40
	v_add_f32_e32 v41, 1.0, v41
	v_rcp_f32_e32 v38, v38
	v_rcp_f32_e32 v39, v39
	v_rcp_f32_e32 v40, v40
	v_rcp_f32_e32 v41, v41
	v_mul_f32_e32 v20, v20, v38
	v_mul_f32_e32 v21, v21, v39
	v_mul_f32_e32 v22, v22, v40
	v_mul_f32_e32 v23, v23, v41
.LBB0_236:
	s_or_b64 exec, exec, s[36:37]
	v_lshlrev_b32_e32 v144, 1, v180
	v_cvt_pk_bf16_f32 v38, v16, v17
	v_cvt_pk_bf16_f32 v39, v18, v19
	v_lshl_add_u64 v[16:17], v[36:37], 0, v[144:145]
	v_mul_lo_u32 v36, v35, v132
	v_mul_lo_u32 v37, v34, v133
	v_mad_u64_u32 v[18:19], s[36:37], v34, v132, 0
	v_add3_u32 v19, v19, v37, v36
	v_cvt_pk_bf16_f32 v40, v20, v21
	v_cvt_pk_bf16_f32 v41, v22, v23
	v_lshl_add_u64 v[18:19], v[18:19], 1, v[16:17]
	v_permlane32_swap_b32_e32 v38, v40
	v_permlane32_swap_b32_e32 v39, v41
	global_store_dwordx4 v[18:19], v[38:41], off
	v_mul_f32_e32 v20, v24, v32
	v_mul_f32_e32 v21, v25, v33
	v_mul_f32_e32 v22, v26, v32
	v_mul_f32_e32 v23, v27, v33
	s_and_saveexec_b64 s[36:37], s[2:3]
	s_cbranch_execz .LBB0_238
	v_mul_f32_e32 v24, 0xbfb8aa3b, v20
	v_mul_f32_e32 v25, 0xbfb8aa3b, v21
	v_mul_f32_e32 v26, 0xbfb8aa3b, v22
	v_mul_f32_e32 v27, 0xbfb8aa3b, v23
	v_exp_f32_e32 v24, v24
	v_exp_f32_e32 v25, v25
	v_exp_f32_e32 v26, v26
	v_exp_f32_e32 v27, v27
	v_add_f32_e32 v24, 1.0, v24
	v_add_f32_e32 v25, 1.0, v25
	v_add_f32_e32 v26, 1.0, v26
	v_add_f32_e32 v27, 1.0, v27
	v_rcp_f32_e32 v24, v24
	v_rcp_f32_e32 v25, v25
	v_rcp_f32_e32 v26, v26
	v_rcp_f32_e32 v27, v27
	v_mul_f32_e32 v20, v20, v24
	v_mul_f32_e32 v21, v21, v25
	v_mul_f32_e32 v22, v22, v26
	v_mul_f32_e32 v23, v23, v27
.LBB0_238:
	s_or_b64 exec, exec, s[36:37]
	v_mul_f32_e32 v24, v28, v32
	v_mul_f32_e32 v25, v29, v33
	v_mul_f32_e32 v26, v30, v32
	v_mul_f32_e32 v27, v31, v33
	s_and_saveexec_b64 s[36:37], s[2:3]
	s_cbranch_execz .LBB0_240
	v_mul_f32_e32 v28, 0xbfb8aa3b, v24
	v_mul_f32_e32 v29, 0xbfb8aa3b, v25
	v_mul_f32_e32 v30, 0xbfb8aa3b, v26
	v_mul_f32_e32 v31, 0xbfb8aa3b, v27
	v_exp_f32_e32 v28, v28
	v_exp_f32_e32 v29, v29
	v_exp_f32_e32 v30, v30
	v_exp_f32_e32 v31, v31
	v_add_f32_e32 v28, 1.0, v28
	v_add_f32_e32 v29, 1.0, v29
	v_add_f32_e32 v30, 1.0, v30
	v_add_f32_e32 v31, 1.0, v31
	v_rcp_f32_e32 v28, v28
	v_rcp_f32_e32 v29, v29
	v_rcp_f32_e32 v30, v30
	v_rcp_f32_e32 v31, v31
	v_mul_f32_e32 v24, v24, v28
	v_mul_f32_e32 v25, v25, v29
	v_mul_f32_e32 v26, v26, v30
	v_mul_f32_e32 v27, v27, v31
.LBB0_240:
	s_or_b64 exec, exec, s[36:37]
	v_cvt_pk_bf16_f32 v20, v20, v21
	v_cvt_pk_bf16_f32 v21, v22, v23
	v_cvt_pk_bf16_f32 v22, v24, v25
	v_cvt_pk_bf16_f32 v23, v26, v27
	s_nop 0
	v_permlane32_swap_b32_e32 v20, v22
	v_permlane32_swap_b32_e32 v21, v23
	global_store_dwordx4 v[18:19], v[20:23], off offset:32
	v_mul_f32_e32 v0, v0, v32
	v_mul_f32_e32 v1, v1, v33
	v_mul_f32_e32 v2, v2, v32
	v_mul_f32_e32 v3, v3, v33
	s_and_saveexec_b64 s[36:37], s[2:3]
	s_cbranch_execz .LBB0_242
	v_mul_f32_e32 v18, 0xbfb8aa3b, v0
	v_mul_f32_e32 v19, 0xbfb8aa3b, v1
	v_mul_f32_e32 v20, 0xbfb8aa3b, v2
	v_mul_f32_e32 v21, 0xbfb8aa3b, v3
	v_exp_f32_e32 v18, v18
	v_exp_f32_e32 v19, v19
	v_exp_f32_e32 v20, v20
	v_exp_f32_e32 v21, v21
	v_add_f32_e32 v18, 1.0, v18
	v_add_f32_e32 v19, 1.0, v19
	v_add_f32_e32 v20, 1.0, v20
	v_add_f32_e32 v21, 1.0, v21
	v_rcp_f32_e32 v18, v18
	v_rcp_f32_e32 v19, v19
	v_rcp_f32_e32 v20, v20
	v_rcp_f32_e32 v21, v21
	v_mul_f32_e32 v0, v0, v18
	v_mul_f32_e32 v1, v1, v19
	v_mul_f32_e32 v2, v2, v20
	v_mul_f32_e32 v3, v3, v21
.LBB0_242:
	s_or_b64 exec, exec, s[36:37]
	v_mul_f32_e32 v4, v4, v32
	v_mul_f32_e32 v5, v5, v33
	v_mul_f32_e32 v6, v6, v32
	v_mul_f32_e32 v7, v7, v33
	s_and_saveexec_b64 s[36:37], s[2:3]
	s_cbranch_execz .LBB0_244
	v_mul_f32_e32 v18, 0xbfb8aa3b, v4
	v_mul_f32_e32 v19, 0xbfb8aa3b, v5
	v_mul_f32_e32 v20, 0xbfb8aa3b, v6
	v_mul_f32_e32 v21, 0xbfb8aa3b, v7
	v_exp_f32_e32 v18, v18
	v_exp_f32_e32 v19, v19
	v_exp_f32_e32 v20, v20
	v_exp_f32_e32 v21, v21
	v_add_f32_e32 v18, 1.0, v18
	v_add_f32_e32 v19, 1.0, v19
	v_add_f32_e32 v20, 1.0, v20
	v_add_f32_e32 v21, 1.0, v21
	v_rcp_f32_e32 v18, v18
	v_rcp_f32_e32 v19, v19
	v_rcp_f32_e32 v20, v20
	v_rcp_f32_e32 v21, v21
	v_mul_f32_e32 v4, v4, v18
	v_mul_f32_e32 v5, v5, v19
	v_mul_f32_e32 v6, v6, v20
	v_mul_f32_e32 v7, v7, v21
; DI unsigned pk_bf16(float lo, float hi) { f32x2 v = {lo, hi}; bf2_t b = __builtin_convertvector(v, bf2_t); return __builtin_bit_cast(unsigned, b); }
; DI float silu_f(float v) { return v * __builtin_amdgcn_rcpf(1.f + fast_exp2(-v * LOG2E)); }
; template <int NI>
; DI void p2_store_group(const Params& p, const f32x16 (&a)[NI], int colg, int tok0, int b, int h) {
;     ...
;       bf16_t* d = base + (size_t)idx * stride + 8 * h;
; #pragma unroll
;       for (int q = 0; q < 2; ++q) {
;         u32x2 w[2];
; #pragma unroll
;         for (int gg = 0; gg < 2; ++gg) {
;           const int g = 2 * q + gg;
;           float v0 = a[ni][4 * g] * scale, v1 = a[ni][4 * g + 1] * scale, v2 = a[ni][4 * g + 2] * scale, v3 = a[ni][4 * g + 3] * scale;
;           if (mode == 1) { v0 = silu_f(v0); v1 = silu_f(v1); v2 = silu_f(v2); v3 = silu_f(v3); }
;           w[gg].x = pk_bf16(v0, v1); w[gg].y = pk_bf16(v2, v3);
;         }
;         *(u32x4*)(d + 16 * q) = widen_pair(w[0], w[1]);
;         __builtin_amdgcn_sched_barrier(0);
;       }
.LBB0_244:
	s_or_b64 exec, exec, s[36:37]
	v_cvt_pk_bf16_f32 v18, v0, v1
	v_cndmask_b32_e32 v0, v152, v128, vcc
	v_ashrrev_i32_e32 v1, 31, v0
	v_cvt_pk_bf16_f32 v19, v2, v3
	v_mul_lo_u32 v2, v34, v1
	v_mul_lo_u32 v3, v35, v0
	v_mad_u64_u32 v[0:1], s[36:37], v34, v0, 0
	v_add3_u32 v1, v1, v2, v3
	v_cvt_pk_bf16_f32 v20, v4, v5
	v_cvt_pk_bf16_f32 v21, v6, v7
	v_lshl_add_u64 v[0:1], v[0:1], 1, v[16:17]
	v_permlane32_swap_b32_e32 v18, v20
	v_permlane32_swap_b32_e32 v19, v21
	global_store_dwordx4 v[0:1], v[18:21], off
	v_mul_f32_e32 v2, v8, v32
	v_mul_f32_e32 v3, v9, v33
	v_mul_f32_e32 v4, v10, v32
	v_mul_f32_e32 v5, v11, v33
	s_and_saveexec_b64 s[36:37], s[2:3]
	s_cbranch_execz .LBB0_246
	v_mul_f32_e32 v6, 0xbfb8aa3b, v2
	v_mul_f32_e32 v7, 0xbfb8aa3b, v3
	v_mul_f32_e32 v8, 0xbfb8aa3b, v4
	v_mul_f32_e32 v9, 0xbfb8aa3b, v5
	v_exp_f32_e32 v6, v6
	v_exp_f32_e32 v7, v7
	v_exp_f32_e32 v8, v8
	v_exp_f32_e32 v9, v9
	v_add_f32_e32 v6, 1.0, v6
	v_add_f32_e32 v7, 1.0, v7
	v_add_f32_e32 v8, 1.0, v8
	v_add_f32_e32 v9, 1.0, v9
	v_rcp_f32_e32 v6, v6
	v_rcp_f32_e32 v7, v7
	v_rcp_f32_e32 v8, v8
	v_rcp_f32_e32 v9, v9
	v_mul_f32_e32 v2, v2, v6
	v_mul_f32_e32 v3, v3, v7
	v_mul_f32_e32 v4, v4, v8
	v_mul_f32_e32 v5, v5, v9
.LBB0_246:
	s_or_b64 exec, exec, s[36:37]
	v_mul_f32_e32 v6, v12, v32
	v_mul_f32_e32 v7, v13, v33
	v_mul_f32_e32 v8, v14, v32
	v_mul_f32_e32 v9, v15, v33
	s_and_saveexec_b64 s[36:37], s[2:3]
	s_cbranch_execz .LBB0_185
	v_mul_f32_e32 v10, 0xbfb8aa3b, v6
	v_mul_f32_e32 v11, 0xbfb8aa3b, v7
	v_mul_f32_e32 v12, 0xbfb8aa3b, v8
	v_mul_f32_e32 v13, 0xbfb8aa3b, v9
	v_exp_f32_e32 v10, v10
	v_exp_f32_e32 v11, v11
	v_exp_f32_e32 v12, v12
	v_exp_f32_e32 v13, v13
	v_add_f32_e32 v10, 1.0, v10
	v_add_f32_e32 v11, 1.0, v11
	v_add_f32_e32 v12, 1.0, v12
	v_add_f32_e32 v13, 1.0, v13
	v_rcp_f32_e32 v10, v10
	v_rcp_f32_e32 v11, v11
	v_rcp_f32_e32 v12, v12
	v_rcp_f32_e32 v13, v13
	v_mul_f32_e32 v6, v6, v10
	v_mul_f32_e32 v7, v7, v11
	v_mul_f32_e32 v8, v8, v12
	v_mul_f32_e32 v9, v9, v13
	s_branch .LBB0_185
.LBB0_248:
	v_mul_f32_e32 v48, v48, v140
	v_mul_f32_e32 v49, v49, v140
	v_mul_f32_e32 v50, v50, v140
	v_mul_f32_e32 v51, v51, v140
	s_and_saveexec_b64 s[40:41], s[2:3]
	s_cbranch_execz .LBB0_250
	v_mul_f32_e32 v129, 0xbfb8aa3b, v48
	v_exp_f32_e32 v129, v129
	v_mul_f32_e32 v135, 0xbfb8aa3b, v49
	v_mul_f32_e32 v141, 0xbfb8aa3b, v51
	v_exp_f32_e32 v135, v135
	v_add_f32_e32 v129, 1.0, v129
	v_rcp_f32_e32 v154, v129
	v_mul_f32_e32 v129, 0xbfb8aa3b, v50
	v_exp_f32_e32 v129, v129
	v_exp_f32_e32 v141, v141
	v_add_f32_e32 v135, 1.0, v135
	v_rcp_f32_e32 v155, v135
	v_add_f32_e32 v129, 1.0, v129
	v_rcp_f32_e32 v172, v129
	v_add_f32_e32 v129, 1.0, v141
	v_rcp_f32_e32 v173, v129
	v_mul_f32_e32 v48, v48, v154
	v_mul_f32_e32 v49, v49, v155
	v_mul_f32_e32 v50, v50, v172
	v_mul_f32_e32 v51, v51, v173
.LBB0_250:
	s_or_b64 exec, exec, s[40:41]
	v_mov_b32_e32 v141, v140
	v_mul_f32_e32 v52, v52, v140
	v_mul_f32_e32 v53, v53, v141
	v_mul_f32_e32 v54, v54, v140
	v_mul_f32_e32 v55, v55, v141
	s_and_saveexec_b64 s[40:41], s[2:3]
	s_cbranch_execz .LBB0_252
	v_mul_f32_e32 v129, 0xbfb8aa3b, v52
	v_exp_f32_e32 v129, v129
	v_mul_f32_e32 v135, 0xbfb8aa3b, v53
	v_mul_f32_e32 v144, 0xbfb8aa3b, v55
	v_exp_f32_e32 v135, v135
	v_add_f32_e32 v129, 1.0, v129
	v_rcp_f32_e32 v154, v129
	v_mul_f32_e32 v129, 0xbfb8aa3b, v54
	v_exp_f32_e32 v129, v129
	v_exp_f32_e32 v144, v144
	v_add_f32_e32 v135, 1.0, v135
	v_rcp_f32_e32 v155, v135
	v_add_f32_e32 v129, 1.0, v129
	v_rcp_f32_e32 v172, v129
	v_add_f32_e32 v129, 1.0, v144
	v_rcp_f32_e32 v173, v129
	v_mul_f32_e32 v52, v52, v154
	v_mul_f32_e32 v53, v53, v155
	v_mul_f32_e32 v54, v54, v172
	v_mul_f32_e32 v55, v55, v173
.LBB0_252:
	s_or_b64 exec, exec, s[40:41]
	v_cvt_pk_bf16_f32 v172, v48, v49
	v_cndmask_b32_e32 v48, v132, v130, vcc
	v_ashrrev_i32_e32 v49, 31, v48
	v_cvt_pk_bf16_f32 v173, v50, v51
	v_mul_lo_u32 v50, v138, v49
	v_mul_lo_u32 v51, v139, v48
	v_mad_u64_u32 v[48:49], s[40:41], v138, v48, 0
	v_add3_u32 v49, v49, v50, v51
	v_cvt_pk_bf16_f32 v174, v52, v53
	v_cvt_pk_bf16_f32 v175, v54, v55
	v_lshl_add_u64 v[48:49], v[48:49], 1, v[142:143]
	v_permlane32_swap_b32_e32 v172, v174
	v_permlane32_swap_b32_e32 v173, v175
	global_store_dwordx4 v[48:49], v[172:175], off
	v_mul_f32_e32 v50, v56, v140
	v_mul_f32_e32 v51, v57, v141
	v_mul_f32_e32 v52, v58, v140
	v_mul_f32_e32 v53, v59, v141
	s_and_saveexec_b64 s[40:41], s[2:3]
	s_cbranch_execz .LBB0_254
	v_mul_f32_e32 v54, 0xbfb8aa3b, v50
	v_mul_f32_e32 v55, 0xbfb8aa3b, v51
	v_mul_f32_e32 v56, 0xbfb8aa3b, v52
	v_mul_f32_e32 v57, 0xbfb8aa3b, v53
	v_exp_f32_e32 v54, v54
	v_exp_f32_e32 v55, v55
	v_exp_f32_e32 v56, v56
	v_exp_f32_e32 v57, v57
	v_add_f32_e32 v54, 1.0, v54
	v_add_f32_e32 v55, 1.0, v55
	v_add_f32_e32 v56, 1.0, v56
	v_add_f32_e32 v57, 1.0, v57
	v_rcp_f32_e32 v54, v54
	v_rcp_f32_e32 v55, v55
	v_rcp_f32_e32 v56, v56
	v_rcp_f32_e32 v57, v57
	v_mul_f32_e32 v50, v50, v54
	v_mul_f32_e32 v51, v51, v55
	v_mul_f32_e32 v52, v52, v56
	v_mul_f32_e32 v53, v53, v57
.LBB0_254:
	s_or_b64 exec, exec, s[40:41]
	v_mul_f32_e32 v54, v60, v140
	v_mul_f32_e32 v55, v61, v141
	v_mul_f32_e32 v56, v62, v140
	v_mul_f32_e32 v57, v63, v141
	s_and_saveexec_b64 s[40:41], s[2:3]
	s_cbranch_execz .LBB0_256
	v_mul_f32_e32 v58, 0xbfb8aa3b, v54
	v_mul_f32_e32 v59, 0xbfb8aa3b, v55
	v_mul_f32_e32 v60, 0xbfb8aa3b, v56
	v_mul_f32_e32 v61, 0xbfb8aa3b, v57
	v_exp_f32_e32 v58, v58
	v_exp_f32_e32 v59, v59
	v_exp_f32_e32 v60, v60
	v_exp_f32_e32 v61, v61
	v_add_f32_e32 v58, 1.0, v58
	v_add_f32_e32 v59, 1.0, v59
	v_add_f32_e32 v60, 1.0, v60
	v_add_f32_e32 v61, 1.0, v61
	v_rcp_f32_e32 v58, v58
	v_rcp_f32_e32 v59, v59
	v_rcp_f32_e32 v60, v60
	v_rcp_f32_e32 v61, v61
	v_mul_f32_e32 v54, v54, v58
	v_mul_f32_e32 v55, v55, v59
	v_mul_f32_e32 v56, v56, v60
	v_mul_f32_e32 v57, v57, v61

; DI unsigned pk_bf16(float lo, float hi) { f32x2 v = {lo, hi}; bf2_t b = __builtin_convertvector(v, bf2_t); return __builtin_bit_cast(unsigned, b); }
; DI float silu_f(float v) { return v * __builtin_amdgcn_rcpf(1.f + fast_exp2(-v * LOG2E)); }
; template <int NI>
; DI void p2_store_group(const Params& p, const f32x16 (&a)[NI], int colg, int tok0, int b, int h) {
;     ...
;       bf16_t* d = base + (size_t)idx * stride + 8 * h;
; #pragma unroll
;       for (int q = 0; q < 2; ++q) {
;         u32x2 w[2];
; #pragma unroll
;         for (int gg = 0; gg < 2; ++gg) {
;           const int g = 2 * q + gg;
;           float v0 = a[ni][4 * g] * scale, v1 = a[ni][4 * g + 1] * scale, v2 = a[ni][4 * g + 2] * scale, v3 = a[ni][4 * g + 3] * scale;
;           if (mode == 1) { v0 = silu_f(v0); v1 = silu_f(v1); v2 = silu_f(v2); v3 = silu_f(v3); }
;           w[gg].x = pk_bf16(v0, v1); w[gg].y = pk_bf16(v2, v3);
;         }
;         *(u32x4*)(d + 16 * q) = widen_pair(w[0], w[1]);
;         __builtin_amdgcn_sched_barrier(0);
;       }
.LBB0_258:
	v_mul_f32_e32 v32, v32, v140
	v_mul_f32_e32 v33, v33, v140
	v_mul_f32_e32 v34, v34, v140
	v_mul_f32_e32 v35, v35, v140
	s_and_saveexec_b64 s[38:39], s[2:3]
	s_cbranch_execz .LBB0_260
	v_mul_f32_e32 v48, 0xbfb8aa3b, v32
	v_mul_f32_e32 v49, 0xbfb8aa3b, v33
	v_mul_f32_e32 v50, 0xbfb8aa3b, v34
	v_mul_f32_e32 v51, 0xbfb8aa3b, v35
	v_exp_f32_e32 v48, v48
	v_exp_f32_e32 v49, v49
	v_exp_f32_e32 v50, v50
	v_exp_f32_e32 v51, v51
	v_add_f32_e32 v48, 1.0, v48
	v_add_f32_e32 v49, 1.0, v49
	v_add_f32_e32 v50, 1.0, v50
	v_add_f32_e32 v51, 1.0, v51
	v_rcp_f32_e32 v48, v48
	v_rcp_f32_e32 v49, v49
	v_rcp_f32_e32 v50, v50
	v_rcp_f32_e32 v51, v51
	v_mul_f32_e32 v32, v32, v48
	v_mul_f32_e32 v33, v33, v49
	v_mul_f32_e32 v34, v34, v50
	v_mul_f32_e32 v35, v35, v51
.LBB0_260:
	s_or_b64 exec, exec, s[38:39]
	v_mov_b32_e32 v141, v140
	v_mul_f32_e32 v36, v36, v140
	v_mul_f32_e32 v37, v37, v141
	v_mul_f32_e32 v38, v38, v140
	v_mul_f32_e32 v39, v39, v141
	s_and_saveexec_b64 s[38:39], s[2:3]
	s_cbranch_execz .LBB0_262
	v_mul_f32_e32 v48, 0xbfb8aa3b, v36
	v_mul_f32_e32 v49, 0xbfb8aa3b, v37
	v_mul_f32_e32 v50, 0xbfb8aa3b, v38
	v_mul_f32_e32 v51, 0xbfb8aa3b, v39
	v_exp_f32_e32 v48, v48
	v_exp_f32_e32 v49, v49
	v_exp_f32_e32 v50, v50
	v_exp_f32_e32 v51, v51
	v_add_f32_e32 v48, 1.0, v48
	v_add_f32_e32 v49, 1.0, v49
	v_add_f32_e32 v50, 1.0, v50
	v_add_f32_e32 v51, 1.0, v51
	v_rcp_f32_e32 v48, v48
	v_rcp_f32_e32 v49, v49
	v_rcp_f32_e32 v50, v50
	v_rcp_f32_e32 v51, v51
	v_mul_f32_e32 v36, v36, v48
	v_mul_f32_e32 v37, v37, v49
	v_mul_f32_e32 v38, v38, v50
	v_mul_f32_e32 v39, v39, v51
.LBB0_262:
	s_or_b64 exec, exec, s[38:39]
	v_cvt_pk_bf16_f32 v48, v32, v33
	v_cndmask_b32_e32 v32, v152, v128, vcc
	v_ashrrev_i32_e32 v33, 31, v32
	v_cvt_pk_bf16_f32 v49, v34, v35
	v_mul_lo_u32 v34, v138, v33
	v_mul_lo_u32 v35, v139, v32
	v_mad_u64_u32 v[32:33], s[38:39], v138, v32, 0
	v_add3_u32 v33, v33, v34, v35
	v_cvt_pk_bf16_f32 v50, v36, v37
	v_cvt_pk_bf16_f32 v51, v38, v39
	v_lshl_add_u64 v[32:33], v[32:33], 1, v[142:143]
	v_permlane32_swap_b32_e32 v48, v50
	v_permlane32_swap_b32_e32 v49, v51
	global_store_dwordx4 v[32:33], v[48:51], off
	v_mul_f32_e32 v34, v40, v140
	v_mul_f32_e32 v35, v41, v141
	v_mul_f32_e32 v36, v42, v140
	v_mul_f32_e32 v37, v43, v141
	s_and_saveexec_b64 s[38:39], s[2:3]
	s_cbranch_execz .LBB0_264
	v_mul_f32_e32 v38, 0xbfb8aa3b, v34
	v_mul_f32_e32 v39, 0xbfb8aa3b, v35
	v_mul_f32_e32 v40, 0xbfb8aa3b, v36
	v_mul_f32_e32 v41, 0xbfb8aa3b, v37
	v_exp_f32_e32 v38, v38
	v_exp_f32_e32 v39, v39
	v_exp_f32_e32 v40, v40
	v_exp_f32_e32 v41, v41
	v_add_f32_e32 v38, 1.0, v38
	v_add_f32_e32 v39, 1.0, v39
	v_add_f32_e32 v40, 1.0, v40
	v_add_f32_e32 v41, 1.0, v41
	v_rcp_f32_e32 v38, v38
	v_rcp_f32_e32 v39, v39
	v_rcp_f32_e32 v40, v40
	v_rcp_f32_e32 v41, v41
	v_mul_f32_e32 v34, v34, v38
	v_mul_f32_e32 v35, v35, v39
	v_mul_f32_e32 v36, v36, v40
	v_mul_f32_e32 v37, v37, v41
.LBB0_264:
	s_or_b64 exec, exec, s[38:39]
	v_mul_f32_e32 v38, v44, v140
	v_mul_f32_e32 v39, v45, v141
	v_mul_f32_e32 v40, v46, v140
	v_mul_f32_e32 v41, v47, v141
	s_and_saveexec_b64 s[38:39], s[2:3]
	s_cbranch_execz .LBB0_266
	v_mul_f32_e32 v42, 0xbfb8aa3b, v38
	v_mul_f32_e32 v43, 0xbfb8aa3b, v39
	v_mul_f32_e32 v44, 0xbfb8aa3b, v40
	v_mul_f32_e32 v45, 0xbfb8aa3b, v41
	v_exp_f32_e32 v42, v42
	v_exp_f32_e32 v43, v43
	v_exp_f32_e32 v44, v44
	v_exp_f32_e32 v45, v45
	v_add_f32_e32 v42, 1.0, v42
	v_add_f32_e32 v43, 1.0, v43
	v_add_f32_e32 v44, 1.0, v44
	v_add_f32_e32 v45, 1.0, v45
	v_rcp_f32_e32 v42, v42
	v_rcp_f32_e32 v43, v43
	v_rcp_f32_e32 v44, v44
	v_rcp_f32_e32 v45, v45
	v_mul_f32_e32 v38, v38, v42
	v_mul_f32_e32 v39, v39, v43
	v_mul_f32_e32 v40, v40, v44
	v_mul_f32_e32 v41, v41, v45

; DI unsigned pk_bf16(float lo, float hi) { f32x2 v = {lo, hi}; bf2_t b = __builtin_convertvector(v, bf2_t); return __builtin_bit_cast(unsigned, b); }
; DI float silu_f(float v) { return v * __builtin_amdgcn_rcpf(1.f + fast_exp2(-v * LOG2E)); }
; template <int NI>
; DI void p2_store_group(const Params& p, const f32x16 (&a)[NI], int colg, int tok0, int b, int h) {
;     ...
;       bf16_t* d = base + (size_t)idx * stride + 8 * h;
; #pragma unroll
;       for (int q = 0; q < 2; ++q) {
;         u32x2 w[2];
; #pragma unroll
;         for (int gg = 0; gg < 2; ++gg) {
;           const int g = 2 * q + gg;
;           float v0 = a[ni][4 * g] * scale, v1 = a[ni][4 * g + 1] * scale, v2 = a[ni][4 * g + 2] * scale, v3 = a[ni][4 * g + 3] * scale;
;           if (mode == 1) { v0 = silu_f(v0); v1 = silu_f(v1); v2 = silu_f(v2); v3 = silu_f(v3); }
;           w[gg].x = pk_bf16(v0, v1); w[gg].y = pk_bf16(v2, v3);
;         }
;         *(u32x4*)(d + 16 * q) = widen_pair(w[0], w[1]);
;         __builtin_amdgcn_sched_barrier(0);
;       }
.LBB0_297:
	v_mul_f32_e32 v16, v16, v38
	v_mul_f32_e32 v17, v17, v38
	v_mul_f32_e32 v18, v18, v38
	v_mul_f32_e32 v19, v19, v38
	s_and_b64 vcc, exec, s[38:39]
	s_cbranch_vccz .LBB0_299
	v_mul_f32_e32 v35, 0xbfb8aa3b, v16
	v_exp_f32_e32 v35, v35
	v_mul_f32_e32 v39, 0xbfb8aa3b, v17
	v_mul_f32_e32 v43, 0xbfb8aa3b, v19
	v_exp_f32_e32 v39, v39
	v_add_f32_e32 v35, 1.0, v35
	v_rcp_f32_e32 v42, v35
	v_mul_f32_e32 v35, 0xbfb8aa3b, v18
	v_exp_f32_e32 v35, v35
	v_exp_f32_e32 v45, v43
	v_add_f32_e32 v39, 1.0, v39
	v_rcp_f32_e32 v43, v39
	v_add_f32_e32 v35, 1.0, v35
	v_rcp_f32_e32 v44, v35
	v_add_f32_e32 v35, 1.0, v45
	v_rcp_f32_e32 v45, v35
	v_mul_f32_e32 v16, v16, v42
	v_mul_f32_e32 v17, v17, v43
	v_mul_f32_e32 v18, v18, v44
	v_mul_f32_e32 v19, v19, v45
.LBB0_299:
	v_mov_b32_e32 v39, v38
	v_cndmask_b32_e64 v35, 0, 1, s[38:39]
	v_mul_f32_e32 v20, v20, v38
	v_mul_f32_e32 v21, v21, v39
	v_cmp_ne_u32_e64 s[8:9], 1, v35
	s_andn2_b64 vcc, exec, s[38:39]
	v_mul_f32_e32 v22, v22, v38
	v_mul_f32_e32 v23, v23, v39
	s_cbranch_vccnz .LBB0_301
	v_mul_f32_e32 v35, 0xbfb8aa3b, v20
	v_exp_f32_e32 v35, v35
	v_mul_f32_e32 v42, 0xbfb8aa3b, v21
	v_exp_f32_e32 v42, v42
	v_mul_f32_e32 v44, 0xbfb8aa3b, v23
	v_add_f32_e32 v35, 1.0, v35
	v_exp_f32_e32 v45, v44
	v_add_f32_e32 v43, 1.0, v42
	v_rcp_f32_e32 v42, v35
	v_mul_f32_e32 v35, 0xbfb8aa3b, v22
	v_exp_f32_e32 v35, v35
	v_rcp_f32_e32 v43, v43
	v_add_f32_e32 v35, 1.0, v35
	v_rcp_f32_e32 v44, v35
	v_add_f32_e32 v35, 1.0, v45
	v_rcp_f32_e32 v45, v35
	v_mul_f32_e32 v20, v20, v42
	v_mul_f32_e32 v21, v21, v43
	v_mul_f32_e32 v22, v22, v44
	v_mul_f32_e32 v23, v23, v45
.LBB0_301:
	v_cvt_pk_bf16_f32 v42, v16, v17
	v_cvt_pk_bf16_f32 v43, v18, v19
	v_mul_lo_u32 v18, s41, v40
	v_mul_lo_u32 v19, s40, v41
	v_mad_u64_u32 v[16:17], s[38:39], s40, v40, 0
	v_add3_u32 v17, v17, v19, v18
	v_lshl_add_u64 v[16:17], v[16:17], 1, s[36:37]
	v_lshlrev_b32_e32 v144, 1, v180
	v_cvt_pk_bf16_f32 v44, v20, v21
	v_cvt_pk_bf16_f32 v45, v22, v23
	v_lshl_add_u64 v[16:17], v[16:17], 0, v[144:145]
	v_permlane32_swap_b32_e32 v42, v44
	v_permlane32_swap_b32_e32 v43, v45
	global_store_dwordx4 v[16:17], v[42:45], off
	v_mul_f32_e32 v18, v24, v38
	v_mul_f32_e32 v19, v25, v39
	s_and_b64 vcc, exec, s[8:9]
	v_mul_f32_e32 v20, v26, v38
	v_mul_f32_e32 v21, v27, v39
	s_cbranch_vccnz .LBB0_303
	v_mul_f32_e32 v22, 0xbfb8aa3b, v18
	v_mul_f32_e32 v23, 0xbfb8aa3b, v19
	v_mul_f32_e32 v24, 0xbfb8aa3b, v20
	v_mul_f32_e32 v25, 0xbfb8aa3b, v21
	v_exp_f32_e32 v22, v22
	v_exp_f32_e32 v23, v23
	v_exp_f32_e32 v24, v24
	v_exp_f32_e32 v25, v25
	v_add_f32_e32 v22, 1.0, v22
	v_add_f32_e32 v23, 1.0, v23
	v_add_f32_e32 v24, 1.0, v24
	v_add_f32_e32 v25, 1.0, v25
	v_rcp_f32_e32 v22, v22
	v_rcp_f32_e32 v23, v23
	v_rcp_f32_e32 v24, v24
	v_rcp_f32_e32 v25, v25
	v_mul_f32_e32 v18, v18, v22
	v_mul_f32_e32 v19, v19, v23
	v_mul_f32_e32 v20, v20, v24
	v_mul_f32_e32 v21, v21, v25
.LBB0_303:
	v_mul_f32_e32 v22, v28, v38
	v_mul_f32_e32 v23, v29, v39
	s_and_b64 vcc, exec, s[8:9]
	v_mul_f32_e32 v24, v30, v38
	v_mul_f32_e32 v25, v31, v39
	s_cbranch_vccnz .LBB0_305
	v_mul_f32_e32 v26, 0xbfb8aa3b, v22
	v_mul_f32_e32 v27, 0xbfb8aa3b, v23
	v_mul_f32_e32 v28, 0xbfb8aa3b, v24
	v_mul_f32_e32 v29, 0xbfb8aa3b, v25
	v_exp_f32_e32 v26, v26
	v_exp_f32_e32 v27, v27
	v_exp_f32_e32 v28, v28
	v_exp_f32_e32 v29, v29
	v_add_f32_e32 v26, 1.0, v26
	v_add_f32_e32 v27, 1.0, v27
	v_add_f32_e32 v28, 1.0, v28
	v_add_f32_e32 v29, 1.0, v29
	v_rcp_f32_e32 v26, v26
	v_rcp_f32_e32 v27, v27
	v_rcp_f32_e32 v28, v28
	v_rcp_f32_e32 v29, v29
	v_mul_f32_e32 v22, v22, v26
	v_mul_f32_e32 v23, v23, v27
	v_mul_f32_e32 v24, v24, v28
	v_mul_f32_e32 v25, v25, v29

; DI unsigned pk_bf16(float lo, float hi) { f32x2 v = {lo, hi}; bf2_t b = __builtin_convertvector(v, bf2_t); return __builtin_bit_cast(unsigned, b); }
; DI float silu_f(float v) { return v * __builtin_amdgcn_rcpf(1.f + fast_exp2(-v * LOG2E)); }
; template <int NI>
; DI void p2_store_group(const Params& p, const f32x16 (&a)[NI], int colg, int tok0, int b, int h) {
;     ...
;       bf16_t* d = base + (size_t)idx * stride + 8 * h;
; #pragma unroll
;       for (int q = 0; q < 2; ++q) {
;         u32x2 w[2];
; #pragma unroll
;         for (int gg = 0; gg < 2; ++gg) {
;           const int g = 2 * q + gg;
;           float v0 = a[ni][4 * g] * scale, v1 = a[ni][4 * g + 1] * scale, v2 = a[ni][4 * g + 2] * scale, v3 = a[ni][4 * g + 3] * scale;
;           if (mode == 1) { v0 = silu_f(v0); v1 = silu_f(v1); v2 = silu_f(v2); v3 = silu_f(v3); }
;           w[gg].x = pk_bf16(v0, v1); w[gg].y = pk_bf16(v2, v3);
;         }
;         *(u32x4*)(d + 16 * q) = widen_pair(w[0], w[1]);
;         __builtin_amdgcn_sched_barrier(0);
;       }
.LBB0_327:
	v_mul_f32_e32 v0, v0, v16
	v_mul_f32_e32 v1, v1, v16
	v_cndmask_b32_e64 v17, 0, 1, s[36:37]
	v_cmp_ne_u32_e64 s[8:9], 1, v17
	s_andn2_b64 vcc, exec, s[36:37]
	v_mul_f32_e32 v2, v2, v16
	v_mul_f32_e32 v3, v3, v16
	s_cbranch_vccnz .LBB0_329
	v_mul_f32_e32 v17, 0xbfb8aa3b, v0
	v_exp_f32_e32 v17, v17
	v_mul_f32_e32 v18, 0xbfb8aa3b, v1
	v_exp_f32_e32 v18, v18
	v_mul_f32_e32 v20, 0xbfb8aa3b, v3
	v_add_f32_e32 v17, 1.0, v17
	v_exp_f32_e32 v21, v20
	v_add_f32_e32 v19, 1.0, v18
	v_rcp_f32_e32 v18, v17
	v_mul_f32_e32 v17, 0xbfb8aa3b, v2
	v_exp_f32_e32 v17, v17
	v_rcp_f32_e32 v19, v19
	v_add_f32_e32 v17, 1.0, v17
	v_rcp_f32_e32 v20, v17
	v_add_f32_e32 v17, 1.0, v21
	v_rcp_f32_e32 v21, v17
	v_mul_f32_e32 v0, v0, v18
	v_mul_f32_e32 v1, v1, v19
	v_mul_f32_e32 v2, v2, v20
	v_mul_f32_e32 v3, v3, v21
.LBB0_329:
	v_mov_b32_e32 v17, v16
	v_mul_f32_e32 v4, v4, v16
	v_mul_f32_e32 v5, v5, v17
	s_and_b64 vcc, exec, s[8:9]
	v_mul_f32_e32 v6, v6, v16
	v_mul_f32_e32 v7, v7, v17
	s_cbranch_vccnz .LBB0_331
	v_mul_f32_e32 v18, 0xbfb8aa3b, v4
	v_mul_f32_e32 v19, 0xbfb8aa3b, v5
	v_mul_f32_e32 v20, 0xbfb8aa3b, v6
	v_mul_f32_e32 v21, 0xbfb8aa3b, v7
	v_exp_f32_e32 v18, v18
	v_exp_f32_e32 v19, v19
	v_exp_f32_e32 v20, v20
	v_exp_f32_e32 v21, v21
	v_add_f32_e32 v18, 1.0, v18
	v_add_f32_e32 v19, 1.0, v19
	v_add_f32_e32 v20, 1.0, v20
	v_add_f32_e32 v21, 1.0, v21
	v_rcp_f32_e32 v18, v18
	v_rcp_f32_e32 v19, v19
	v_rcp_f32_e32 v20, v20
	v_rcp_f32_e32 v21, v21
	v_mul_f32_e32 v4, v4, v18
	v_mul_f32_e32 v5, v5, v19
	v_mul_f32_e32 v6, v6, v20
	v_mul_f32_e32 v7, v7, v21
.LBB0_331:
	v_cvt_pk_bf16_f32 v18, v0, v1
	v_cvt_pk_bf16_f32 v19, v2, v3
	v_mul_lo_u32 v2, s39, v32
	v_mul_lo_u32 v3, s38, v33
	v_mad_u64_u32 v[0:1], s[2:3], s38, v32, 0
	v_add3_u32 v1, v1, v3, v2
	v_lshl_add_u64 v[0:1], v[0:1], 1, s[34:35]
	v_lshlrev_b32_e32 v144, 1, v180
	v_cvt_pk_bf16_f32 v20, v4, v5
	v_cvt_pk_bf16_f32 v21, v6, v7
	v_lshl_add_u64 v[0:1], v[0:1], 0, v[144:145]
	v_permlane32_swap_b32_e32 v18, v20
	v_permlane32_swap_b32_e32 v19, v21
	global_store_dwordx4 v[0:1], v[18:21], off
	v_mul_f32_e32 v2, v8, v16
	v_mul_f32_e32 v3, v9, v17
	s_and_b64 vcc, exec, s[8:9]
	v_mul_f32_e32 v4, v10, v16
	v_mul_f32_e32 v5, v11, v17
	s_cbranch_vccnz .LBB0_333
	v_mul_f32_e32 v6, 0xbfb8aa3b, v2
	v_mul_f32_e32 v7, 0xbfb8aa3b, v3
	v_mul_f32_e32 v8, 0xbfb8aa3b, v4
	v_mul_f32_e32 v9, 0xbfb8aa3b, v5
	v_exp_f32_e32 v6, v6
	v_exp_f32_e32 v7, v7
	v_exp_f32_e32 v8, v8
	v_exp_f32_e32 v9, v9
	v_add_f32_e32 v6, 1.0, v6
	v_add_f32_e32 v7, 1.0, v7
	v_add_f32_e32 v8, 1.0, v8
	v_add_f32_e32 v9, 1.0, v9
	v_rcp_f32_e32 v6, v6
	v_rcp_f32_e32 v7, v7
	v_rcp_f32_e32 v8, v8
	v_rcp_f32_e32 v9, v9
	v_mul_f32_e32 v2, v2, v6
	v_mul_f32_e32 v3, v3, v7
	v_mul_f32_e32 v4, v4, v8
	v_mul_f32_e32 v5, v5, v9
.LBB0_333:
	v_mul_f32_e32 v6, v12, v16
	v_mul_f32_e32 v7, v13, v17
	s_and_b64 vcc, exec, s[8:9]
	v_mul_f32_e32 v8, v14, v16
	v_mul_f32_e32 v9, v15, v17
	s_cbranch_vccnz .LBB0_269
	v_mul_f32_e32 v10, 0xbfb8aa3b, v6
	v_mul_f32_e32 v11, 0xbfb8aa3b, v7
	v_mul_f32_e32 v12, 0xbfb8aa3b, v8
	v_mul_f32_e32 v13, 0xbfb8aa3b, v9
	v_exp_f32_e32 v10, v10
	v_exp_f32_e32 v11, v11
	v_exp_f32_e32 v12, v12
	v_exp_f32_e32 v13, v13
	v_add_f32_e32 v10, 1.0, v10
	v_add_f32_e32 v11, 1.0, v11
	v_add_f32_e32 v12, 1.0, v12
	v_add_f32_e32 v13, 1.0, v13
	v_rcp_f32_e32 v10, v10
	v_rcp_f32_e32 v11, v11
	v_rcp_f32_e32 v12, v12
	v_rcp_f32_e32 v13, v13
	v_mul_f32_e32 v6, v6, v10
	v_mul_f32_e32 v7, v7, v11
	v_mul_f32_e32 v8, v8, v12
	v_mul_f32_e32 v9, v9, v13
	s_branch .LBB0_269

; DI void phase3(const Params& p, char* smem, const Sched sc) {
;     ...
;       const float rstd = rsqrtf(sumsq[tl] * (1.f / 384) + 1e-6f);
;       float ssq = 0.f;
; #pragma unroll
;       for (int rb = 0; rb < 3; ++rb)
; #pragma unroll
;         for (int i = 0; i < 16; ++i) { const float v = acc[rb][0][i] * rstd; acc[rb][0][i] = v; ssq += v * v; }
;       ssq += other_half(ssq);
;       const float r2 = rsqrtf(ssq * (1.f / 96) + 1e-6f);
; #pragma unroll
;       for (int rb = 0; rb < 3; ++rb)
; #pragma unroll
;         for (int g = 0; g < 4; ++g) {
;           const f32x4 w4 = *(const f32x4*)(p.qhn + rb * 32 + 8 * g + 4 * h);
; #pragma unroll
;           for (int e = 0; e < 4; ++e) acc[rb][0][4 * g + e] *= r2 * w4[e];
;         }
; #pragma unroll
;       for (int g = 0; g < 2; ++g) {
;         const f32x4 c4 = *(const f32x4*)(p.cosT + (size_t)token * 16 + 8 * g + 4 * h), s4 = *(const f32x4*)(p.sinT + (size_t)token * 16 + 8 * g + 4 * h);
.LBB0_358:
	s_or_b64 exec, exec, s[4:5]
	s_waitcnt lgkmcnt(0)
	s_barrier
	ds_read_b32 v48, v231
	global_load_dwordx4 v[64:67], v[202:203], off
	global_load_dwordx4 v[68:71], v[202:203], off offset:32
	global_load_dwordx4 v[72:75], v[202:203], off offset:64
	global_load_dwordx4 v[76:79], v[202:203], off offset:96
	global_load_dwordx4 v[80:83], v[202:203], off offset:128
	global_load_dwordx4 v[84:87], v[202:203], off offset:160
	global_load_dwordx4 v[88:91], v[202:203], off offset:192
	global_load_dwordx4 v[92:95], v[202:203], off offset:224
	global_load_dwordx4 v[96:99], v[202:203], off offset:256
	global_load_dwordx4 v[100:103], v[202:203], off offset:288
	global_load_dwordx4 v[104:107], v[202:203], off offset:320
	global_load_dwordx4 v[108:111], v[202:203], off offset:352
	v_ashrrev_i32_e32 v209, 31, v208
	v_lshl_or_b32 v120, v240, 3, s25
	v_ashrrev_i32_e32 v121, 31, v120
	s_waitcnt lgkmcnt(0)
	v_fmamk_f32 v48, v48, 0x3b2aaaab, v233
	v_mul_f32_e32 v49, 0x4b800000, v48
	v_cmp_gt_f32_e32 vcc, s19, v48
	v_lshlrev_b64 v[120:121], 13, v[120:121]
	v_or_b32_e32 v120, v120, v239
	v_cndmask_b32_e32 v48, v48, v49, vcc
	v_rsq_f32_e32 v48, v48
	s_nop 0
	v_mul_f32_e32 v49, 0x45800000, v48
	v_cndmask_b32_e32 v112, v48, v49, vcc
	v_mul_f32_e32 v32, v32, v112
	v_mul_f32_e32 v33, v33, v112
	v_mul_f32_e32 v34, v34, v112
	v_mul_f32_e32 v35, v35, v112
	s_nop 0
	v_mul_f32_e32 v137, v33, v33
	s_nop 0
	s_nop 0
	v_fma_f32 v136, v32, v32, v137
	v_mul_f32_e32 v36, v36, v112
	v_mul_f32_e32 v37, v37, v112
	v_fma_f32 v134, v34, v34, v136
	s_nop 0
	s_nop 0
	v_fmac_f32_e32 v134, v35, v35
	v_mul_f32_e32 v60, v10, v112
	v_mul_f32_e32 v61, v11, v112
	v_lshlrev_b64 v[10:11], 6, v[208:209]
	v_mul_f32_e32 v38, v38, v112
	v_mul_f32_e32 v39, v39, v112
	v_fma_f32 v132, v36, v36, v134
	v_mul_f32_e32 v62, v12, v112
	v_mul_f32_e32 v63, v13, v112
	v_lshl_add_u64 v[12:13], v[192:193], 0, v[10:11]
	v_lshl_add_u64 v[48:49], v[194:195], 0, v[10:11]
	s_nop 0
	s_nop 0
	v_fmac_f32_e32 v132, v37, v37
	global_load_dwordx4 v[52:55], v[12:13], off
	s_nop 0
	global_load_dwordx4 v[10:13], v[12:13], off offset:32
	s_nop 0
	global_load_dwordx4 v[56:59], v[48:49], off
	s_nop 0
	global_load_dwordx4 v[48:51], v[48:49], off offset:32
	v_mul_f32_e32 v40, v40, v112
	v_mul_f32_e32 v41, v41, v112
	v_fma_f32 v130, v38, v38, v132
	s_nop 0
	s_nop 0
	v_fmac_f32_e32 v130, v39, v39
	v_mul_f32_e32 v42, v42, v112
	v_mul_f32_e32 v43, v43, v112
	v_fma_f32 v128, v40, v40, v130
	s_nop 0
	s_nop 0
	v_fmac_f32_e32 v128, v41, v41
	v_mul_f32_e32 v44, v44, v112
	v_mul_f32_e32 v45, v45, v112
	v_fma_f32 v126, v42, v42, v128
	s_nop 0
	s_nop 0
	v_fmac_f32_e32 v126, v43, v43
	v_mul_f32_e32 v46, v46, v112
	v_mul_f32_e32 v47, v47, v112
	v_fma_f32 v124, v44, v44, v126
	s_nop 0
	s_nop 0
	v_fmac_f32_e32 v124, v45, v45
	v_mul_f32_e32 v16, v16, v112
	v_mul_f32_e32 v17, v17, v112
	v_fma_f32 v122, v46, v46, v124
	s_nop 0
	s_nop 0
	v_fmac_f32_e32 v122, v47, v47
	v_mul_f32_e32 v18, v18, v112
	v_mul_f32_e32 v19, v19, v112
	v_fmac_f32_e32 v122, v16, v16
	s_nop 0
	s_nop 0
	v_fmac_f32_e32 v122, v17, v17
	v_mul_f32_e32 v20, v20, v112
	v_mul_f32_e32 v21, v21, v112
	v_fmac_f32_e32 v122, v18, v18
	s_nop 0
	s_nop 0
	v_fmac_f32_e32 v122, v19, v19
	v_mul_f32_e32 v22, v22, v112
	v_mul_f32_e32 v23, v23, v112
	v_fmac_f32_e32 v122, v20, v20
	s_nop 0
	s_nop 0
	v_fmac_f32_e32 v122, v21, v21
	v_mul_f32_e32 v24, v24, v112
	v_mul_f32_e32 v25, v25, v112
	v_fmac_f32_e32 v122, v22, v22
	s_nop 0
	s_nop 0
	v_fmac_f32_e32 v122, v23, v23
	v_mul_f32_e32 v26, v26, v112
	v_mul_f32_e32 v27, v27, v112
	v_fmac_f32_e32 v122, v24, v24
	s_nop 0
	s_nop 0
	v_fmac_f32_e32 v122, v25, v25
	v_mul_f32_e32 v28, v28, v112
	v_mul_f32_e32 v29, v29, v112
	v_fmac_f32_e32 v122, v26, v26
	s_nop 0
	s_nop 0
	v_fmac_f32_e32 v122, v27, v27
	v_mul_f32_e32 v30, v30, v112
	v_mul_f32_e32 v31, v31, v112
	v_fmac_f32_e32 v122, v28, v28
	s_nop 0
	s_nop 0
	v_fmac_f32_e32 v122, v29, v29
	v_mul_f32_e32 v0, v0, v112
	v_mul_f32_e32 v1, v1, v112
	v_fmac_f32_e32 v122, v30, v30
	s_nop 0
	s_nop 0
	v_fmac_f32_e32 v122, v31, v31
	v_mul_f32_e32 v2, v2, v112
	v_mul_f32_e32 v3, v3, v112
	v_fmac_f32_e32 v122, v0, v0
	s_nop 0
	s_nop 0
	v_fmac_f32_e32 v122, v1, v1
	v_mul_f32_e32 v4, v4, v112
	v_mul_f32_e32 v5, v5, v112
	v_fmac_f32_e32 v122, v2, v2
	s_nop 0
	s_nop 0
	v_fmac_f32_e32 v122, v3, v3
	v_mul_f32_e32 v6, v6, v112
	v_mul_f32_e32 v7, v7, v112
	v_fmac_f32_e32 v122, v4, v4
	s_nop 0
	s_nop 0
	v_fmac_f32_e32 v122, v5, v5
	v_mul_f32_e32 v8, v8, v112
	v_mul_f32_e32 v9, v9, v112
	v_fmac_f32_e32 v122, v6, v6
	v_mul_f32_e32 v14, v14, v112
	v_mul_f32_e32 v15, v15, v112
	s_nop 0
	s_nop 0
	v_fmac_f32_e32 v122, v7, v7
	v_fma_f32 v112, v8, v8, v122
	s_nop 0
	s_nop 0
	v_fmac_f32_e32 v112, v9, v9
	v_fmac_f32_e32 v112, v60, v60
	s_nop 0
	s_nop 0
	v_fmac_f32_e32 v112, v61, v61
	v_fmac_f32_e32 v112, v62, v62
	s_nop 0
	s_nop 0
	v_fmac_f32_e32 v112, v63, v63
	v_fmac_f32_e32 v112, v14, v14
	v_fmac_f32_e32 v112, v15, v15
	v_mov_b32_e32 v113, v112
	v_mov_b32_e32 v114, v112
	s_nop 1
	v_permlane32_swap_b32_e32 v113, v114
	v_cndmask_b32_e64 v113, v113, v114, s[8:9]
	v_add_f32_e32 v112, v112, v113
	v_fmamk_f32 v112, v112, 0x3c2aaaab, v233
	v_mul_f32_e32 v113, 0x4b800000, v112
	v_cmp_gt_f32_e32 vcc, s19, v112
	s_nop 1
	v_cndmask_b32_e32 v112, v112, v113, vcc
	v_rsq_f32_e32 v114, v112
	v_mad_u64_u32 v[112:113], s[4:5], v120, s20, v[204:205]
	v_mad_i32_i24 v113, v121, s20, v113
	v_mul_f32_e32 v115, 0x45800000, v114
	v_cndmask_b32_e32 v114, v114, v115, vcc
	s_waitcnt vmcnt(15)
	v_mul_f32_e32 v64, v64, v114
	v_mul_f32_e32 v65, v65, v114
	s_nop 0
	v_mul_f32_e32 v32, v32, v64
	v_mul_f32_e32 v33, v33, v65
	v_mul_f32_e32 v64, v66, v114
	v_mul_f32_e32 v65, v67, v114
	s_nop 0
	v_mul_f32_e32 v34, v34, v64
	v_mul_f32_e32 v35, v35, v65
	s_waitcnt vmcnt(14)
; DI unsigned pk_bf16(float lo, float hi) { f32x2 v = {lo, hi}; bf2_t b = __builtin_convertvector(v, bf2_t); return __builtin_bit_cast(unsigned, b); }
; DI void phase3(const Params& p, char* smem, const Sched sc) {
;     ...
; #pragma unroll
;       for (int rb = 0; rb < 3; ++rb)
; #pragma unroll
;         for (int g = 0; g < 4; ++g) {
;           const f32x4 w4 = *(const f32x4*)(p.qhn + rb * 32 + 8 * g + 4 * h);
; #pragma unroll
;           for (int e = 0; e < 4; ++e) acc[rb][0][4 * g + e] *= r2 * w4[e];
;         }
; #pragma unroll
;       for (int g = 0; g < 2; ++g) {
;         const f32x4 c4 = *(const f32x4*)(p.cosT + (size_t)token * 16 + 8 * g + 4 * h), s4 = *(const f32x4*)(p.sinT + (size_t)token * 16 + 8 * g + 4 * h);
; #pragma unroll
;         for (int e = 0; e < 4; ++e) {
;           const float x1 = acc[2][0][4 * g + e], x2 = acc[2][0][4 * (g + 2) + e];
;           acc[2][0][4 * g + e] = x1 * c4[e] - x2 * s4[e];
;           acc[2][0][4 * (g + 2) + e] = x2 * c4[e] + x1 * s4[e];
;         }
;       }
;       const float qs = LOG2E * 0.10206207261596577f;
;       bf16_t* dst = p.Qm + ((size_t)(b * 8 + head) * S_ + s) * 96;
; #pragma unroll
;       for (int rb = 0; rb < 3; ++rb) {
;         u32x2 w[4];
; #pragma unroll
;         for (int g = 0; g < 4; ++g) { w[g].x = pk_bf16(acc[rb][0][4 * g] * qs, acc[rb][0][4 * g + 1] * qs); w[g].y = pk_bf16(acc[rb][0][4 * g + 2] * qs, acc[rb][0][4 * g + 3] * qs); }
; #pragma unroll
;         for (int q = 0; q < 2; ++q) *(u32x4*)(dst + rb * 32 + 16 * q + 8 * h) = widen_pair(w[2 * q], w[2 * q + 1]);
;       }
	v_mul_f32_e32 v64, v68, v114
	v_mul_f32_e32 v65, v69, v114
	s_nop 0
	v_mul_f32_e32 v36, v36, v64
	v_mul_f32_e32 v37, v37, v65
	v_mul_f32_e32 v64, v70, v114
	v_mul_f32_e32 v65, v71, v114
	s_nop 0
	v_mul_f32_e32 v38, v38, v64
	v_mul_f32_e32 v39, v39, v65
	s_waitcnt vmcnt(13)
	v_mul_f32_e32 v64, v72, v114
	v_mul_f32_e32 v65, v73, v114
	s_nop 0
	v_mul_f32_e32 v40, v40, v64
	v_mul_f32_e32 v41, v41, v65
	v_mul_f32_e32 v64, v74, v114
	v_mul_f32_e32 v65, v75, v114
	s_nop 0
	v_mul_f32_e32 v42, v42, v64
	v_mul_f32_e32 v43, v43, v65
	s_waitcnt vmcnt(12)
	v_mul_f32_e32 v64, v76, v114
	v_mul_f32_e32 v65, v77, v114
	s_nop 0
	v_mul_f32_e32 v44, v44, v64
	v_mul_f32_e32 v45, v45, v65
	v_mul_f32_e32 v64, v78, v114
	v_mul_f32_e32 v65, v79, v114
	s_nop 0
	v_mul_f32_e32 v46, v46, v64
	v_mul_f32_e32 v47, v47, v65
	s_waitcnt vmcnt(11)
	v_mul_f32_e32 v64, v80, v114
	v_mul_f32_e32 v65, v81, v114
	s_nop 0
	v_mul_f32_e32 v16, v16, v64
	v_mul_f32_e32 v17, v17, v65
	v_mul_f32_e32 v64, v82, v114
	v_mul_f32_e32 v65, v83, v114
	s_nop 0
	v_mul_f32_e32 v18, v18, v64
	v_mul_f32_e32 v19, v19, v65
	s_waitcnt vmcnt(10)
	v_mul_f32_e32 v64, v84, v114
	v_mul_f32_e32 v65, v85, v114
	s_nop 0
	v_mul_f32_e32 v20, v20, v64
	v_mul_f32_e32 v21, v21, v65
	v_mul_f32_e32 v64, v86, v114
	v_mul_f32_e32 v65, v87, v114
	s_nop 0
	v_mul_f32_e32 v22, v22, v64
	v_mul_f32_e32 v23, v23, v65
	s_waitcnt vmcnt(9)
	v_mul_f32_e32 v64, v88, v114
	v_mul_f32_e32 v65, v89, v114
	s_nop 0
	v_mul_f32_e32 v24, v24, v64
	v_mul_f32_e32 v25, v25, v65
	v_mul_f32_e32 v64, v90, v114
	v_mul_f32_e32 v65, v91, v114
	s_nop 0
	v_mul_f32_e32 v26, v26, v64
	v_mul_f32_e32 v27, v27, v65
	s_waitcnt vmcnt(8)
	v_mul_f32_e32 v64, v92, v114
	v_mul_f32_e32 v65, v93, v114
	s_nop 0
	v_mul_f32_e32 v28, v28, v64
	v_mul_f32_e32 v29, v29, v65
	v_mul_f32_e32 v64, v94, v114
	v_mul_f32_e32 v65, v95, v114
	s_nop 0
	v_mul_f32_e32 v30, v30, v64
	v_mul_f32_e32 v31, v31, v65
	s_waitcnt vmcnt(7)
	v_mul_f32_e32 v64, v96, v114
	v_mul_f32_e32 v65, v97, v114
	s_nop 0
	v_mul_f32_e32 v64, v0, v64
	v_mul_f32_e32 v65, v1, v65
	v_mul_f32_e32 v0, v98, v114
	v_mul_f32_e32 v1, v99, v114
	s_nop 0
	v_mul_f32_e32 v66, v2, v0
	v_mul_f32_e32 v67, v3, v1
	s_waitcnt vmcnt(6)
	v_mul_f32_e32 v0, v100, v114
	v_mul_f32_e32 v1, v101, v114
	v_mul_f32_e32 v2, s2, v34
	v_mul_f32_e32 v3, s2, v35
	v_mul_f32_e32 v68, v4, v0
	v_mul_f32_e32 v69, v5, v1
	v_mul_f32_e32 v0, v102, v114
	v_mul_f32_e32 v1, v103, v114
	v_mul_f32_e32 v4, s2, v38
	v_mul_f32_e32 v5, s2, v39
	v_mul_f32_e32 v70, v6, v0
	v_mul_f32_e32 v71, v7, v1
	s_waitcnt vmcnt(5)
	v_mul_f32_e32 v0, v104, v114
	v_mul_f32_e32 v1, v105, v114
	v_mul_f32_e32 v6, s2, v42
	v_mul_f32_e32 v7, s2, v43
	v_mul_f32_e32 v8, v8, v0
	v_mul_f32_e32 v9, v9, v1
	v_mul_f32_e32 v0, v106, v114
	v_mul_f32_e32 v1, v107, v114
	s_nop 0
	v_mul_f32_e32 v60, v60, v0
	v_mul_f32_e32 v61, v61, v1
	s_waitcnt vmcnt(4)
	v_mul_f32_e32 v0, v108, v114
	v_mul_f32_e32 v1, v109, v114
	s_nop 0
	v_mul_f32_e32 v62, v62, v0
	v_mul_f32_e32 v63, v63, v1
	v_mul_f32_e32 v0, v110, v114
	v_mul_f32_e32 v1, v111, v114
	s_nop 0
	v_mul_f32_e32 v14, v14, v0
	v_mul_f32_e32 v15, v15, v1
	s_waitcnt vmcnt(1)
	v_mul_f32_e32 v0, v56, v64
	v_mul_f32_e32 v1, v57, v65
	s_nop 0
	v_fma_f32 v72, v52, v8, v0
	v_fma_f32 v73, v53, v9, v1
	v_mul_f32_e32 v0, v58, v66
	v_mul_f32_e32 v1, v59, v67
	s_nop 0
	v_fma_f32 v74, v54, v60, v0
	v_fma_f32 v75, v55, v61, v1
	s_waitcnt vmcnt(0)
	v_mul_f32_e32 v0, v48, v68
	v_mul_f32_e32 v1, v49, v69
	s_nop 0
	v_fma_f32 v76, v10, v62, v0
	v_fma_f32 v77, v11, v63, v1
	v_mul_f32_e32 v0, v50, v70
	v_mul_f32_e32 v1, v51, v71
	s_nop 0
	v_fma_f32 v78, v12, v14, v0
	v_fma_f32 v79, v13, v15, v1
	v_mul_f32_e32 v0, s2, v32
	v_mul_f32_e32 v1, s2, v33
	v_mul_f32_e32 v32, s2, v46
	v_mul_f32_e32 v33, s2, v47
	v_cvt_pk_bf16_f32 v0, v0, v1
	v_cvt_pk_bf16_f32 v1, v2, v3
	v_mul_f32_e32 v2, s2, v36
	v_mul_f32_e32 v3, s2, v37
	s_nop 0
	v_cvt_pk_bf16_f32 v2, v2, v3
	v_cvt_pk_bf16_f32 v3, v4, v5
	v_mul_f32_e32 v4, s2, v40
	v_mul_f32_e32 v5, s2, v41
	v_permlane32_swap_b32_e32 v0, v2
	v_cvt_pk_bf16_f32 v4, v4, v5
	v_cvt_pk_bf16_f32 v5, v6, v7
	v_mul_f32_e32 v6, s2, v44
	v_mul_f32_e32 v7, s2, v45
	v_permlane32_swap_b32_e32 v1, v3
	v_cvt_pk_bf16_f32 v6, v6, v7
	v_cvt_pk_bf16_f32 v7, v32, v33
	global_store_dwordx4 v[112:113], v[0:3], off
	v_permlane32_swap_b32_e32 v4, v6
	v_permlane32_swap_b32_e32 v5, v7
	v_mul_f32_e32 v0, s2, v16
	v_mul_f32_e32 v1, s2, v17
	v_mul_f32_e32 v2, s2, v18
	v_mul_f32_e32 v3, s2, v19
	global_store_dwordx4 v[112:113], v[4:7], off offset:32
	v_cvt_pk_bf16_f32 v0, v0, v1
	v_cvt_pk_bf16_f32 v1, v2, v3
	v_mul_f32_e32 v2, s2, v20
	v_mul_f32_e32 v3, s2, v21
	v_mul_f32_e32 v4, s2, v22
	v_mul_f32_e32 v5, s2, v23
	v_cvt_pk_bf16_f32 v2, v2, v3
	v_cvt_pk_bf16_f32 v3, v4, v5
	v_mul_f32_e32 v4, s2, v24
	v_mul_f32_e32 v5, s2, v25
	v_mul_f32_e32 v6, s2, v26
	v_mul_f32_e32 v7, s2, v27
	v_permlane32_swap_b32_e32 v0, v2
	v_permlane32_swap_b32_e32 v1, v3
	v_cvt_pk_bf16_f32 v4, v4, v5
	v_cvt_pk_bf16_f32 v5, v6, v7
	v_mul_f32_e32 v6, s2, v28
	v_mul_f32_e32 v7, s2, v29
	v_mul_f32_e32 v16, s2, v30
	v_mul_f32_e32 v17, s2, v31
	global_store_dwordx4 v[112:113], v[0:3], off offset:64
	v_cvt_pk_bf16_f32 v6, v6, v7
	v_cvt_pk_bf16_f32 v7, v16, v17
	v_mul_f32_e32 v0, v56, v8
	v_mul_f32_e32 v1, v57, v9
	v_mul_f32_e32 v2, v58, v60
	v_mul_f32_e32 v3, v59, v61
	v_fma_f32 v0, v52, v64, -v0
	v_fma_f32 v1, v53, v65, -v1
	v_fma_f32 v2, v54, v66, -v2
	v_fma_f32 v3, v55, v67, -v3
	v_permlane32_swap_b32_e32 v4, v6
	v_permlane32_swap_b32_e32 v5, v7
	v_mul_f32_e32 v0, s2, v0
	v_mul_f32_e32 v1, s2, v1
	v_mul_f32_e32 v2, s2, v2
	v_mul_f32_e32 v3, s2, v3
	global_store_dwordx4 v[112:113], v[4:7], off offset:96
	v_cvt_pk_bf16_f32 v0, v0, v1
	v_cvt_pk_bf16_f32 v1, v2, v3
	v_mul_f32_e32 v2, v48, v62
	v_mul_f32_e32 v3, v49, v63
	v_mul_f32_e32 v4, v50, v14
	v_mul_f32_e32 v5, v51, v15
	v_fma_f32 v2, v10, v68, -v2
	v_fma_f32 v3, v11, v69, -v3
	v_fma_f32 v4, v12, v70, -v4
	v_fma_f32 v5, v13, v71, -v5
	v_mul_f32_e32 v2, s2, v2
	v_mul_f32_e32 v3, s2, v3
	v_mul_f32_e32 v4, s2, v4
	v_mul_f32_e32 v5, s2, v5
	v_cvt_pk_bf16_f32 v2, v2, v3
	v_cvt_pk_bf16_f32 v3, v4, v5
	v_mul_f32_e32 v4, s2, v72
	v_mul_f32_e32 v5, s2, v73
	v_mul_f32_e32 v6, s2, v74
	v_mul_f32_e32 v7, s2, v75
	v_cvt_pk_bf16_f32 v4, v4, v5
	v_cvt_pk_bf16_f32 v5, v6, v7
	v_mul_f32_e32 v6, s2, v76
	v_mul_f32_e32 v7, s2, v77
	v_mul_f32_e32 v8, s2, v78
	v_mul_f32_e32 v9, s2, v79
	v_cvt_pk_bf16_f32 v6, v6, v7
	v_cvt_pk_bf16_f32 v7, v8, v9
	v_permlane32_swap_b32_e32 v0, v2
	v_permlane32_swap_b32_e32 v1, v3
	v_permlane32_swap_b32_e32 v4, v6
	v_permlane32_swap_b32_e32 v5, v7
	global_store_dwordx4 v[112:113], v[0:3], off offset:128
	global_store_dwordx4 v[112:113], v[4:7], off offset:160

; DI void phase3(const Params& p, char* smem, const Sched sc) {
;     ...
;       const float rstd = rsqrtf(sumsq[tl] * (1.f / 256) + 1e-6f);
;       float kr[16];
; #pragma unroll
;       for (int g = 0; g < 4; ++g) {
;         const f32x4 k4 = *(const f32x4*)(p.KR + (size_t)token * 32 + 8 * g + 4 * h);
; #pragma unroll
;         for (int e = 0; e < 4; ++e) kr[4 * g + e] = k4[e];
;       }
;       float ssq = 0.f;
; #pragma unroll
;       for (int rb = 0; rb < 2; ++rb)
; #pragma unroll
;         for (int i = 0; i < 16; ++i) { const float v = acc[rb][0][i] * rstd; acc[rb][0][i] = v; ssq += v * v; }
; #pragma unroll
;       for (int i = 0; i < 16; ++i) ssq += kr[i] * kr[i];
;       ssq += other_half(ssq);
;       const float r2 = rsqrtf(ssq * (1.f / 96) + 1e-6f);
.LBB0_370:
	s_or_b64 exec, exec, s[12:13]
	v_ashrrev_i32_e32 v209, 31, v208
	s_waitcnt lgkmcnt(0)
	v_lshlrev_b64 v[64:65], 7, v[208:209]
	v_lshl_add_u64 v[92:93], v[188:189], 0, v[64:65]
	s_barrier
	global_load_dwordx4 v[68:71], v[92:93], off offset:32
	global_load_dwordx4 v[72:75], v[92:93], off offset:64
	global_load_dwordx4 v[64:67], v[92:93], off offset:96
	ds_read_b32 v94, v231
	global_load_dwordx4 v[88:91], v[190:191], off
	global_load_dwordx4 v[84:87], v[190:191], off offset:32
	global_load_dwordx4 v[80:83], v[190:191], off offset:64
	global_load_dwordx4 v[76:79], v[190:191], off offset:96
	global_load_dwordx4 v[104:107], v[190:191], off offset:128
	global_load_dwordx4 v[96:99], v[190:191], off offset:160
	s_waitcnt lgkmcnt(0)
	v_fmamk_f32 v94, v94, 0x3b800000, v233
	v_mul_f32_e32 v95, 0x4b800000, v94
	v_cmp_gt_f32_e32 vcc, s19, v94
	s_waitcnt vmcnt(8)
	s_nop 0
	s_nop 0
	v_cndmask_b32_e32 v94, v94, v95, vcc
	v_rsq_f32_e32 v112, v94
	global_load_dwordx4 v[92:95], v[92:93], off
	s_nop 0
	global_load_dwordx4 v[108:111], v[190:191], off offset:192
	global_load_dwordx4 v[100:103], v[190:191], off offset:224
	s_waitcnt vmcnt(10)
	s_nop 0
	s_nop 0
	s_nop 0
	s_nop 0
	v_mul_f32_e32 v113, 0x45800000, v112
	v_cndmask_b32_e32 v112, v112, v113, vcc
	v_mul_f32_e32 v132, v48, v112
	v_mul_f32_e32 v133, v49, v112
	v_mul_f32_e32 v130, v50, v112
	v_mul_f32_e32 v131, v51, v112
	s_nop 0
	v_mul_f32_e32 v51, v133, v133
	s_nop 0
	s_nop 0
	v_fma_f32 v50, v132, v132, v51
	v_mul_f32_e32 v128, v52, v112
	v_mul_f32_e32 v129, v53, v112
	v_fma_f32 v48, v130, v130, v50
	v_mul_f32_e32 v134, v42, v112
	v_mul_f32_e32 v135, v43, v112
	s_nop 0
	s_nop 0
	v_fmac_f32_e32 v48, v131, v131
	v_mul_f32_e32 v126, v54, v112
	v_mul_f32_e32 v127, v55, v112
	v_fma_f32 v42, v128, v128, v48
	v_mul_f32_e32 v136, v40, v112
	v_mul_f32_e32 v137, v41, v112
	s_nop 0
	s_nop 0
	v_fmac_f32_e32 v42, v129, v129
	v_mul_f32_e32 v124, v56, v112
	v_mul_f32_e32 v125, v57, v112
	v_fma_f32 v40, v126, v126, v42
	v_mul_f32_e32 v138, v38, v112
	v_mul_f32_e32 v139, v39, v112
	s_nop 0
	s_nop 0
	v_fmac_f32_e32 v40, v127, v127
	v_mul_f32_e32 v122, v58, v112
	v_mul_f32_e32 v123, v59, v112
	v_fma_f32 v38, v124, v124, v40
	v_mul_f32_e32 v140, v36, v112
	v_mul_f32_e32 v141, v37, v112
	s_nop 0
	s_nop 0
	v_fmac_f32_e32 v38, v125, v125
	v_mul_f32_e32 v120, v60, v112
	v_mul_f32_e32 v121, v61, v112
	v_fma_f32 v36, v122, v122, v38
	v_mul_f32_e32 v142, v34, v112
	v_mul_f32_e32 v143, v35, v112
	s_nop 0
	s_nop 0
	v_fmac_f32_e32 v36, v123, v123
	v_mul_f32_e32 v118, v62, v112
	v_mul_f32_e32 v119, v63, v112
	v_fma_f32 v34, v120, v120, v36
	v_mul_f32_e32 v144, v32, v112
	v_mul_f32_e32 v145, v33, v112
	s_nop 0
	s_nop 0
	v_fmac_f32_e32 v34, v121, v121
	v_fma_f32 v32, v118, v118, v34
	s_nop 0
	s_nop 0
	v_fmac_f32_e32 v32, v119, v119
	v_fmac_f32_e32 v32, v144, v144
	s_nop 0
	s_nop 0
	v_fmac_f32_e32 v32, v145, v145
	v_fmac_f32_e32 v32, v142, v142
	s_nop 0
	s_nop 0
	v_fmac_f32_e32 v32, v143, v143
	v_fmac_f32_e32 v32, v140, v140
	s_nop 0
	s_nop 0
	v_fmac_f32_e32 v32, v141, v141
	v_fmac_f32_e32 v32, v138, v138
	s_nop 0
	s_nop 0
	v_fmac_f32_e32 v32, v139, v139
	v_fmac_f32_e32 v32, v136, v136
	s_nop 0
	s_nop 0
	v_fma_f32 v58, v137, v137, v32
	global_load_dwordx4 v[32:35], v[190:191], off offset:256
	global_load_dwordx4 v[36:39], v[190:191], off offset:320
	v_lshlrev_b64 v[40:41], 6, v[208:209]
	v_mul_f32_e32 v44, v44, v112
	v_mul_f32_e32 v45, v45, v112
	v_lshl_add_u64 v[60:61], v[194:195], 0, v[40:41]
	v_fma_f32 v56, v134, v134, v58
	s_nop 0
	s_nop 0
	v_lshl_add_u64 v[114:115], v[192:193], 0, v[40:41]
	global_load_dwordx4 v[40:43], v[60:61], off
	global_load_dwordx4 v[48:51], v[114:115], off
	v_fmac_f32_e32 v56, v135, v135
	v_mul_f32_e32 v46, v46, v112
	v_mul_f32_e32 v47, v47, v112
	v_fma_f32 v54, v44, v44, v56
	s_nop 0
	s_nop 0
	v_fmac_f32_e32 v54, v45, v45
	v_fma_f32 v52, v46, v46, v54
	v_fma_f32 v113, v47, v47, v52
	global_load_dwordx4 v[52:55], v[190:191], off offset:288
	global_load_dwordx4 v[56:59], v[190:191], off offset:352
	s_nop 0
	global_load_dwordx4 v[60:63], v[60:61], off offset:32
	s_nop 0
	global_load_dwordx4 v[114:117], v[114:115], off offset:32
	s_waitcnt vmcnt(17)
	s_nop 0
	s_nop 0
	s_nop 0
	s_nop 0
	s_waitcnt vmcnt(10)
	v_fmac_f32_e32 v113, v92, v92
	v_fmac_f32_e32 v113, v93, v93
	v_fmac_f32_e32 v113, v94, v94
	v_fmac_f32_e32 v113, v95, v95
	v_fmac_f32_e32 v113, v68, v68
	v_fmac_f32_e32 v113, v69, v69
	v_fmac_f32_e32 v113, v70, v70
	v_fmac_f32_e32 v113, v71, v71
	v_fmac_f32_e32 v113, v72, v72
	v_fmac_f32_e32 v113, v73, v73
	v_fmac_f32_e32 v113, v74, v74
	v_fmac_f32_e32 v113, v75, v75
	v_fmac_f32_e32 v113, v64, v64
	v_fmac_f32_e32 v113, v65, v65
	v_fmac_f32_e32 v113, v66, v66
	v_fmac_f32_e32 v113, v67, v67
	v_mov_b32_e32 v146, v113
	v_mov_b32_e32 v147, v113
	s_nop 1
	v_permlane32_swap_b32_e32 v146, v147
	v_cndmask_b32_e64 v146, v146, v147, s[8:9]
	v_add_f32_e32 v113, v113, v146
	v_fmamk_f32 v113, v113, 0x3c2aaaab, v233
	v_mul_f32_e32 v146, 0x4b800000, v113
	v_cmp_gt_f32_e32 vcc, s19, v113
	s_nop 1
	v_cndmask_b32_e32 v113, v113, v146, vcc
	v_rsq_f32_e32 v113, v113
	s_nop 0
	v_mul_f32_e32 v146, 0x45800000, v113
	v_cndmask_b32_e32 v146, v113, v146, vcc
	v_mul_f32_e32 v88, v88, v146
	v_mul_f32_e32 v89, v89, v146
	v_mul_f32_e32 v90, v90, v146
	v_mul_f32_e32 v91, v91, v146
	v_mul_f32_e32 v84, v84, v146
	v_mul_f32_e32 v85, v85, v146
	v_mul_f32_e32 v86, v86, v146
	v_mul_f32_e32 v87, v87, v146
	v_mul_f32_e32 v16, v16, v112
	v_mul_f32_e32 v17, v17, v112
	v_mul_f32_e32 v18, v18, v112
	v_mul_f32_e32 v19, v19, v112
	v_mul_f32_e32 v88, v132, v88
	v_mul_f32_e32 v89, v133, v89
	v_mul_f32_e32 v90, v130, v90
	v_mul_f32_e32 v91, v131, v91
	v_mul_f32_e32 v84, v128, v84
	v_mul_f32_e32 v85, v129, v85
	v_mul_f32_e32 v86, v126, v86
	v_mul_f32_e32 v87, v127, v87
	s_waitcnt vmcnt(8)
; DI void phase3(const Params& p, char* smem, const Sched sc) {
;     ...
; #pragma unroll
;       for (int rb = 0; rb < 2; ++rb)
; #pragma unroll
;         for (int g = 0; g < 4; ++g) {
;           const f32x4 w4 = *(const f32x4*)(p.khn + rb * 32 + 8 * g + 4 * h);
; #pragma unroll
;           for (int e = 0; e < 4; ++e) acc[rb][0][4 * g + e] *= r2 * w4[e];
;         }
; #pragma unroll
;       for (int g = 0; g < 4; ++g) {
;         const f32x4 w4 = *(const f32x4*)(p.khn + 64 + 8 * g + 4 * h);
; #pragma unroll
;         for (int e = 0; e < 4; ++e) kr[4 * g + e] *= r2 * w4[e];
;       }
; #pragma unroll
;       for (int g = 0; g < 2; ++g) {
;         const f32x4 c4 = *(const f32x4*)(p.cosT + (size_t)token * 16 + 8 * g + 4 * h), s4 = *(const f32x4*)(p.sinT + (size_t)token * 16 + 8 * g + 4 * h);
; #pragma unroll
;         for (int e = 0; e < 4; ++e) {
;           const float x1 = kr[4 * g + e], x2 = kr[4 * (g + 2) + e];
;           kr[4 * g + e] = x1 * c4[e] - x2 * s4[e];
;           kr[4 * (g + 2) + e] = x2 * c4[e] + x1 * s4[e];
;         }
;       }
	v_mul_f32_e32 v100, v100, v146
	v_mul_f32_e32 v101, v101, v146
	v_cvt_pk_bf16_f32 v16, v16, v17
	v_cvt_pk_bf16_f32 v17, v18, v19
	v_mul_f32_e32 v18, v20, v112
	v_mul_f32_e32 v19, v21, v112
	v_mul_f32_e32 v20, v22, v112
	v_mul_f32_e32 v21, v23, v112
	v_mul_f32_e32 v0, v0, v112
	v_mul_f32_e32 v1, v1, v112
	v_mul_f32_e32 v2, v2, v112
	v_mul_f32_e32 v3, v3, v112
	v_mul_f32_e32 v80, v80, v146
	v_mul_f32_e32 v81, v81, v146
	v_mul_f32_e32 v82, v82, v146
	v_mul_f32_e32 v83, v83, v146
	v_mul_f32_e32 v76, v76, v146
	v_mul_f32_e32 v77, v77, v146
	v_mul_f32_e32 v78, v78, v146
	v_mul_f32_e32 v79, v79, v146
	v_mul_f32_e32 v104, v104, v146
	v_mul_f32_e32 v105, v105, v146
	v_mul_f32_e32 v106, v106, v146
	v_mul_f32_e32 v107, v107, v146
	v_mul_f32_e32 v96, v96, v146
	v_mul_f32_e32 v97, v97, v146
	v_mul_f32_e32 v98, v98, v146
	v_mul_f32_e32 v99, v99, v146
	s_waitcnt vmcnt(7)
	v_mul_f32_e32 v32, v32, v146
	v_mul_f32_e32 v33, v33, v146
	s_waitcnt vmcnt(6)
	v_mul_f32_e32 v36, v36, v146
	v_mul_f32_e32 v37, v37, v146
	v_mul_f32_e32 v32, v92, v32
	v_mul_f32_e32 v33, v93, v33
	v_mul_f32_e32 v36, v72, v36
	v_mul_f32_e32 v37, v73, v37
	v_mul_f32_e32 v108, v108, v146
	v_mul_f32_e32 v109, v109, v146
	v_mul_f32_e32 v110, v110, v146
	v_mul_f32_e32 v111, v111, v146
	v_mul_f32_e32 v44, v44, v100
	v_mul_f32_e32 v45, v45, v101
	s_waitcnt vmcnt(5)
	v_mul_f32_e32 v72, v40, v36
	v_mul_f32_e32 v73, v41, v37
	s_waitcnt vmcnt(4)
	v_mul_f32_e32 v36, v48, v36
	v_mul_f32_e32 v37, v49, v37
	v_fma_f32 v72, v48, v32, -v72
	v_fma_f32 v73, v49, v33, -v73
	v_fmac_f32_e32 v36, v40, v32
	v_fmac_f32_e32 v37, v41, v33
	v_mul_f32_e32 v32, v34, v146
	v_mul_f32_e32 v33, v35, v146
	v_mul_f32_e32 v34, v38, v146
	v_mul_f32_e32 v35, v39, v146
	v_mul_f32_e32 v32, v94, v32
	v_mul_f32_e32 v33, v95, v33
	v_mul_f32_e32 v34, v74, v34
	v_mul_f32_e32 v35, v75, v35
	v_mul_f32_e32 v100, v102, v146
	v_mul_f32_e32 v101, v103, v146
	v_mul_f32_e32 v38, v42, v34
	v_mul_f32_e32 v39, v43, v35
	v_mul_f32_e32 v34, v50, v34
	v_mul_f32_e32 v35, v51, v35
	v_fma_f32 v38, v50, v32, -v38
	v_fma_f32 v39, v51, v33, -v39
	v_fma_f32 v40, v42, v32, v34
	v_fma_f32 v41, v43, v33, v35
	s_waitcnt vmcnt(2)
	v_mul_f32_e32 v34, v56, v146
	v_mul_f32_e32 v35, v57, v146
	v_mul_f32_e32 v32, v52, v146
	v_mul_f32_e32 v33, v53, v146
	v_mul_f32_e32 v34, v64, v34
	v_mul_f32_e32 v35, v65, v35
	v_mul_f32_e32 v32, v68, v32
	v_mul_f32_e32 v33, v69, v33
	s_waitcnt vmcnt(1)
	v_mul_f32_e32 v42, v60, v34
	v_mul_f32_e32 v43, v61, v35
	s_waitcnt vmcnt(0)
; DI unsigned pk_bf16(float lo, float hi) { f32x2 v = {lo, hi}; bf2_t b = __builtin_convertvector(v, bf2_t); return __builtin_bit_cast(unsigned, b); }
; DI void phase3(const Params& p, char* smem, const Sched sc) {
;     ...
;       for (int g = 0; g < 2; ++g) {
;         const f32x4 c4 = *(const f32x4*)(p.cosT + (size_t)token * 16 + 8 * g + 4 * h), s4 = *(const f32x4*)(p.sinT + (size_t)token * 16 + 8 * g + 4 * h);
; #pragma unroll
;         for (int e = 0; e < 4; ++e) {
;           const float x1 = kr[4 * g + e], x2 = kr[4 * (g + 2) + e];
;           kr[4 * g + e] = x1 * c4[e] - x2 * s4[e];
;           kr[4 * (g + 2) + e] = x2 * c4[e] + x1 * s4[e];
;         }
;       }
;       bf16_t* dk = p.Km + ((size_t)(b * 8 + head) * S_ + s) * 96;
;       bf16_t* dv = p.Vm + ((size_t)(b * 8 + head) * S_ + s) * 64;
; #pragma unroll
;       for (int rb = 0; rb < 2; ++rb) {
;         u32x2 w[4], u[4];
; #pragma unroll
;         for (int g = 0; g < 4; ++g) {
;           w[g].x = pk_bf16(acc[rb][0][4 * g], acc[rb][0][4 * g + 1]); w[g].y = pk_bf16(acc[rb][0][4 * g + 2], acc[rb][0][4 * g + 3]);
;           u[g].x = pk_bf16(acc[rb + 2][0][4 * g] * rstd, acc[rb + 2][0][4 * g + 1] * rstd); u[g].y = pk_bf16(acc[rb + 2][0][4 * g + 2] * rstd, acc[rb + 2][0][4 * g + 3] * rstd);
;         }
; #pragma unroll
;         for (int q = 0; q < 2; ++q) {
;           *(u32x4*)(dk + rb * 32 + 16 * q + 8 * h) = widen_pair(w[2 * q], w[2 * q + 1]);
;           *(u32x4*)(dv + rb * 32 + 16 * q + 8 * h) = widen_pair(u[2 * q], u[2 * q + 1]);
;         }
;       }
;       {
;         u32x2 w[4];
; #pragma unroll
;         for (int g = 0; g < 4; ++g) { w[g].x = pk_bf16(kr[4 * g], kr[4 * g + 1]); w[g].y = pk_bf16(kr[4 * g + 2], kr[4 * g + 3]); }
; #pragma unroll
;         for (int q = 0; q < 2; ++q) *(u32x4*)(dk + 64 + 16 * q + 8 * h) = widen_pair(w[2 * q], w[2 * q + 1]);
;       }
	v_mul_f32_e32 v34, v114, v34
	v_mul_f32_e32 v35, v115, v35
	v_fma_f32 v42, v114, v32, -v42
	v_fma_f32 v43, v115, v33, -v43
	v_fma_f32 v48, v60, v32, v34
	v_fma_f32 v49, v61, v33, v35
	v_mul_f32_e32 v34, v58, v146
	v_mul_f32_e32 v35, v59, v146
	v_mul_f32_e32 v32, v54, v146
	v_mul_f32_e32 v33, v55, v146
	v_mul_f32_e32 v34, v66, v34
	v_mul_f32_e32 v35, v67, v35
	v_mul_f32_e32 v32, v70, v32
	v_mul_f32_e32 v33, v71, v33
	v_mul_f32_e32 v50, v62, v34
	v_mul_f32_e32 v51, v63, v35
	v_mul_f32_e32 v34, v116, v34
	v_mul_f32_e32 v35, v117, v35
	v_fma_f32 v50, v116, v32, -v50
	v_fma_f32 v51, v117, v33, -v51
	v_fma_f32 v52, v62, v32, v34
	v_fma_f32 v53, v63, v33, v35
	v_lshl_or_b32 v32, v240, 3, s25
	v_ashrrev_i32_e32 v33, 31, v32
	v_lshlrev_b64 v[32:33], 13, v[32:33]
	v_or_b32_e32 v32, v32, v239
	v_lshlrev_b64 v[34:35], 7, v[32:33]
	v_mad_u64_u32 v[54:55], s[12:13], v32, s20, v[206:207]
	v_mad_i32_i24 v55, v33, s20, v55
	v_lshl_add_u64 v[56:57], v[196:197], 0, v[34:35]
	v_cvt_pk_bf16_f32 v32, v88, v89
	v_cvt_pk_bf16_f32 v33, v90, v91
	v_cvt_pk_bf16_f32 v34, v84, v85
	v_cvt_pk_bf16_f32 v35, v86, v87
	v_cvt_pk_bf16_f32 v18, v18, v19
	v_cvt_pk_bf16_f32 v19, v20, v21
	v_mul_f32_e32 v22, v24, v112
	v_mul_f32_e32 v23, v25, v112
	v_cvt_pk_bf16_f32 v0, v0, v1
	v_cvt_pk_bf16_f32 v1, v2, v3
	v_mul_f32_e32 v2, v4, v112
	v_mul_f32_e32 v3, v5, v112
	v_mul_f32_e32 v4, v6, v112
	v_mul_f32_e32 v5, v7, v112
	v_mul_f32_e32 v6, v8, v112
	v_mul_f32_e32 v7, v9, v112
	v_mul_f32_e32 v80, v124, v80
	v_mul_f32_e32 v81, v125, v81
	v_mul_f32_e32 v82, v122, v82
	v_mul_f32_e32 v83, v123, v83
	v_mul_f32_e32 v76, v120, v76
	v_mul_f32_e32 v77, v121, v77
	v_mul_f32_e32 v78, v118, v78
	v_mul_f32_e32 v79, v119, v79
	v_mul_f32_e32 v104, v144, v104
	v_mul_f32_e32 v105, v145, v105
	v_mul_f32_e32 v106, v142, v106
	v_mul_f32_e32 v107, v143, v107
	v_mul_f32_e32 v96, v140, v96
	v_mul_f32_e32 v97, v141, v97
	v_mul_f32_e32 v98, v138, v98
	v_mul_f32_e32 v99, v139, v99
	v_mul_f32_e32 v108, v136, v108
	v_mul_f32_e32 v109, v137, v109
	v_mul_f32_e32 v110, v134, v110
	v_mul_f32_e32 v111, v135, v111
	v_mul_f32_e32 v46, v46, v100
	v_mul_f32_e32 v47, v47, v101
	v_cvt_pk_bf16_f32 v24, v22, v23
	v_mul_f32_e32 v22, v26, v112
	v_mul_f32_e32 v23, v27, v112
	v_mul_f32_e32 v26, v28, v112
	v_mul_f32_e32 v27, v29, v112
	v_mul_f32_e32 v28, v30, v112
	v_mul_f32_e32 v29, v31, v112
	v_permlane32_swap_b32_e32 v32, v34
	v_permlane32_swap_b32_e32 v33, v35
	v_permlane32_swap_b32_e32 v16, v18
	v_permlane32_swap_b32_e32 v17, v19
	v_cvt_pk_bf16_f32 v8, v6, v7
	v_mul_f32_e32 v6, v10, v112
	v_mul_f32_e32 v7, v11, v112
	v_cvt_pk_bf16_f32 v20, v80, v81
	v_cvt_pk_bf16_f32 v21, v82, v83
	v_cvt_pk_bf16_f32 v25, v22, v23
	v_cvt_pk_bf16_f32 v22, v76, v77
	v_cvt_pk_bf16_f32 v23, v78, v79
	v_cvt_pk_bf16_f32 v26, v26, v27
	v_cvt_pk_bf16_f32 v27, v28, v29
	global_store_dwordx4 v[54:55], v[32:35], off
	global_store_dwordx4 v[56:57], v[16:19], off
	v_cvt_pk_bf16_f32 v2, v2, v3
	v_cvt_pk_bf16_f32 v3, v4, v5
	v_cvt_pk_bf16_f32 v16, v104, v105
	v_cvt_pk_bf16_f32 v17, v106, v107
	v_cvt_pk_bf16_f32 v18, v96, v97
	v_cvt_pk_bf16_f32 v19, v98, v99
	v_cvt_pk_bf16_f32 v4, v108, v109
	v_cvt_pk_bf16_f32 v5, v110, v111
	v_cvt_pk_bf16_f32 v9, v6, v7
	v_cvt_pk_bf16_f32 v6, v44, v45
	v_cvt_pk_bf16_f32 v7, v46, v47
	v_permlane32_swap_b32_e32 v20, v22
	v_permlane32_swap_b32_e32 v21, v23
	v_permlane32_swap_b32_e32 v24, v26
	v_permlane32_swap_b32_e32 v25, v27
	v_mul_f32_e32 v10, v12, v112
	v_mul_f32_e32 v11, v13, v112
	v_mul_f32_e32 v12, v14, v112
	v_mul_f32_e32 v13, v15, v112
	v_permlane32_swap_b32_e32 v16, v18
	v_permlane32_swap_b32_e32 v17, v19
	v_permlane32_swap_b32_e32 v0, v2
	v_permlane32_swap_b32_e32 v1, v3
	v_permlane32_swap_b32_e32 v4, v6
	v_permlane32_swap_b32_e32 v5, v7
	global_store_dwordx4 v[54:55], v[20:23], off offset:32
	global_store_dwordx4 v[56:57], v[24:27], off offset:32
	v_cvt_pk_bf16_f32 v10, v10, v11
	v_cvt_pk_bf16_f32 v11, v12, v13
	global_store_dwordx4 v[54:55], v[16:19], off offset:64
	global_store_dwordx4 v[56:57], v[0:3], off offset:64
	global_store_dwordx4 v[54:55], v[4:7], off offset:96
	v_permlane32_swap_b32_e32 v8, v10
	v_cvt_pk_bf16_f32 v0, v72, v73
	v_cvt_pk_bf16_f32 v1, v38, v39
	v_cvt_pk_bf16_f32 v2, v42, v43
	v_cvt_pk_bf16_f32 v3, v50, v51
	v_cvt_pk_bf16_f32 v4, v36, v37
	v_cvt_pk_bf16_f32 v5, v40, v41
	v_cvt_pk_bf16_f32 v6, v48, v49
	v_cvt_pk_bf16_f32 v7, v52, v53
	v_permlane32_swap_b32_e32 v9, v11
	v_permlane32_swap_b32_e32 v0, v2
	v_permlane32_swap_b32_e32 v1, v3
	v_permlane32_swap_b32_e32 v4, v6
	v_permlane32_swap_b32_e32 v5, v7
	global_store_dwordx4 v[56:57], v[8:11], off offset:96
	global_store_dwordx4 v[54:55], v[0:3], off offset:128
	global_store_dwordx4 v[54:55], v[4:7], off offset:160
	s_branch .LBB0_359

; DI unsigned pk_bf16(float lo, float hi) { f32x2 v = {lo, hi}; bf2_t b = __builtin_convertvector(v, bf2_t); return __builtin_bit_cast(unsigned, b); }
; DI float bf_lo(unsigned u) { return __uint_as_float(u << 16); }
; DI float bf_hi(unsigned u) { return __uint_as_float(u & 0xffff0000u); }
; template <int DQK, bool SB, bool SMAX>
; DI void attn_item(const Params& p, char* smem, int bh, int qb, float Mb) {
;     ...
;   float inv = 1.f;
;   if (!SB) { const float lt = lsum + other_half(lsum); inv = 1.f / lt; }
;   const size_t token = (size_t)(bh >> 3) * S_ + query;
;   const int colbase = (SB ? 0 : 512) + (bh & 7) * 64;
; #pragma unroll
;   for (int db = 0; db < 2; ++db) {
;     u32x2 w[4];
; #pragma unroll
;     for (int g = 0; g < 4; ++g) {
;       const int col = colbase + db * 32 + 8 * g + 4 * h;
;       const u32x2 gt = *(const u32x2*)(p.Gate + token * 1024 + col);
;       w[g].x = pk_bf16(O[db][4 * g] * inv * bf_lo(gt.x), O[db][4 * g + 1] * inv * bf_hi(gt.x));
;       w[g].y = pk_bf16(O[db][4 * g + 2] * inv * bf_lo(gt.y), O[db][4 * g + 3] * inv * bf_hi(gt.y));
;     }
; #pragma unroll
;     for (int q = 0; q < 2; ++q) *(u32x4*)(p.Mixed + token * 1024 + colbase + db * 32 + 16 * q + 8 * h) = widen_pair(w[2 * q], w[2 * q + 1]);
;   }
;   __syncthreads();
.LBB0_424:
	s_setprio 0
	s_lshl_b32 s0, s0, 6
	v_readlane_b32 s2, v255, 15
	s_and_b32 s0, s0, 0x1c0
	v_lshlrev_b64 v[48:49], 11, v[176:177]
	v_readlane_b32 s3, v255, 16
	v_or_b32_e32 v52, s0, v197
	v_lshlrev_b32_e32 v176, 1, v52
	v_lshl_add_u64 v[48:49], v[48:49], 0, s[2:3]
	v_lshl_add_u64 v[50:51], s[94:95], 0, v[48:49]
	v_lshl_add_u64 v[50:51], v[50:51], 0, v[176:177]
	global_load_dwordx2 v[52:53], v[50:51], off offset:1024
	global_load_dwordx2 v[54:55], v[50:51], off offset:1040
	global_load_dwordx2 v[56:57], v[50:51], off offset:1056
	global_load_dwordx2 v[58:59], v[50:51], off offset:1072
	v_mov_b32_e32 v60, v152
	v_mov_b32_e32 v61, v152
	s_nop 1
	v_permlane32_swap_b32_e32 v60, v61
	v_cndmask_b32_e64 v60, v60, v61, s[8:9]
	v_add_f32_e32 v60, v152, v60
	s_lshl_b32 s4, s0, 1
	v_div_scale_f32 v61, s[0:1], v60, v60, 1.0
	v_rcp_f32_e32 v62, v61
	v_div_scale_f32 v63, vcc, 1.0, v60, 1.0
	v_lshl_add_u64 v[48:49], s[86:87], 0, v[48:49]
	v_fma_f32 v64, -v61, v62, 1.0
	v_fmac_f32_e32 v62, v64, v62
	v_mul_f32_e32 v64, v63, v62
	v_fma_f32 v65, -v61, v64, v63
	v_fmac_f32_e32 v64, v65, v62
	v_fma_f32 v61, -v61, v64, v63
	v_div_fmas_f32 v61, v61, v62, v64
	v_div_fixup_f32 v60, v61, v60, 1.0
	v_mul_f32_e32 v32, v32, v60
	v_mul_f32_e32 v33, v33, v60
	v_mul_f32_e32 v34, v34, v60
	v_mul_f32_e32 v35, v35, v60
	v_mul_f32_e32 v36, v36, v60
	v_mul_f32_e32 v37, v37, v60
	v_mul_f32_e32 v38, v38, v60
	v_mul_f32_e32 v39, v39, v60
	v_mul_f32_e32 v40, v40, v60
	v_mul_f32_e32 v41, v41, v60
	v_mul_f32_e32 v42, v42, v60
	v_mul_f32_e32 v43, v43, v60
	v_mul_f32_e32 v44, v44, v60
	v_mul_f32_e32 v45, v45, v60
	v_mul_f32_e32 v46, v46, v60
	v_mul_f32_e32 v47, v47, v60
	v_mov_b32_e32 v181, v177
	v_lshl_add_u64 v[48:49], v[48:49], 0, s[4:5]
	v_lshl_add_u64 v[48:49], v[48:49], 0, v[180:181]
	v_mul_f32_e32 v16, v16, v60
	v_mul_f32_e32 v17, v17, v60
	v_mul_f32_e32 v18, v18, v60
	v_mul_f32_e32 v19, v19, v60
	v_mul_f32_e32 v20, v20, v60
	v_mul_f32_e32 v21, v21, v60
	v_mul_f32_e32 v22, v22, v60
	v_mul_f32_e32 v23, v23, v60
	v_mul_f32_e32 v24, v24, v60
	v_mul_f32_e32 v25, v25, v60
	v_mul_f32_e32 v26, v26, v60
	v_mul_f32_e32 v27, v27, v60
	v_mul_f32_e32 v28, v28, v60
	v_mul_f32_e32 v29, v29, v60
	v_mul_f32_e32 v30, v30, v60
	v_mul_f32_e32 v31, v31, v60
	s_waitcnt vmcnt(3)
	v_lshlrev_b32_e32 v62, 16, v52
	v_and_b32_e32 v63, 0xffff0000, v52
	v_lshlrev_b32_e32 v52, 16, v53
	v_and_b32_e32 v53, 0xffff0000, v53
	s_waitcnt vmcnt(2)
	v_lshlrev_b32_e32 v64, 16, v54
	v_and_b32_e32 v65, 0xffff0000, v54
	v_lshlrev_b32_e32 v54, 16, v55
	v_and_b32_e32 v55, 0xffff0000, v55
	s_waitcnt vmcnt(1)
	v_lshlrev_b32_e32 v66, 16, v56
	v_and_b32_e32 v67, 0xffff0000, v56
	v_lshlrev_b32_e32 v56, 16, v57
	v_and_b32_e32 v57, 0xffff0000, v57
	s_waitcnt vmcnt(0)
	v_lshlrev_b32_e32 v68, 16, v58
	v_and_b32_e32 v69, 0xffff0000, v58
	v_lshlrev_b32_e32 v58, 16, v59
	v_and_b32_e32 v59, 0xffff0000, v59
	v_mul_f32_e32 v32, v32, v62
	v_mul_f32_e32 v33, v33, v63
	v_mul_f32_e32 v34, v34, v52
	v_mul_f32_e32 v35, v35, v53
	v_mul_f32_e32 v36, v36, v64
	v_mul_f32_e32 v37, v37, v65
	v_mul_f32_e32 v38, v38, v54
	v_mul_f32_e32 v39, v39, v55
	v_mul_f32_e32 v40, v40, v66
	v_mul_f32_e32 v41, v41, v67
	v_mul_f32_e32 v42, v42, v56
	v_mul_f32_e32 v43, v43, v57
	v_mul_f32_e32 v44, v44, v68
	v_mul_f32_e32 v45, v45, v69
	v_mul_f32_e32 v46, v46, v58
	v_mul_f32_e32 v47, v47, v59
	v_cvt_pk_bf16_f32 v32, v32, v33
	v_cvt_pk_bf16_f32 v33, v34, v35
	v_cvt_pk_bf16_f32 v34, v36, v37
	v_cvt_pk_bf16_f32 v35, v38, v39
	v_cvt_pk_bf16_f32 v36, v40, v41
	v_cvt_pk_bf16_f32 v37, v42, v43
	v_cvt_pk_bf16_f32 v38, v44, v45
	v_cvt_pk_bf16_f32 v39, v46, v47
	v_permlane32_swap_b32_e32 v32, v34
	v_permlane32_swap_b32_e32 v33, v35
	v_permlane32_swap_b32_e32 v36, v38
	v_permlane32_swap_b32_e32 v37, v39
	global_store_dwordx4 v[48:49], v[32:35], off offset:1024
	global_store_dwordx4 v[48:49], v[36:39], off offset:1056
	global_load_dwordx2 v[32:33], v[50:51], off offset:1088
	s_nop 0
	global_load_dwordx2 v[34:35], v[50:51], off offset:1104
	global_load_dwordx2 v[36:37], v[50:51], off offset:1120
	global_load_dwordx2 v[38:39], v[50:51], off offset:1136
	s_waitcnt vmcnt(3)
	v_lshlrev_b32_e32 v40, 16, v32
	v_and_b32_e32 v41, 0xffff0000, v32
	v_lshlrev_b32_e32 v32, 16, v33
	v_and_b32_e32 v33, 0xffff0000, v33
	s_waitcnt vmcnt(2)
	v_lshlrev_b32_e32 v42, 16, v34
	v_and_b32_e32 v43, 0xffff0000, v34
	v_lshlrev_b32_e32 v34, 16, v35
	v_and_b32_e32 v35, 0xffff0000, v35
	s_waitcnt vmcnt(1)
	v_lshlrev_b32_e32 v44, 16, v36
	v_and_b32_e32 v45, 0xffff0000, v36
	v_lshlrev_b32_e32 v36, 16, v37
	v_and_b32_e32 v37, 0xffff0000, v37
	s_waitcnt vmcnt(0)
	v_lshlrev_b32_e32 v46, 16, v38
	v_and_b32_e32 v47, 0xffff0000, v38
	v_lshlrev_b32_e32 v38, 16, v39
	v_and_b32_e32 v39, 0xffff0000, v39
	v_mul_f32_e32 v16, v16, v40
	v_mul_f32_e32 v17, v17, v41
	v_mul_f32_e32 v18, v18, v32
	v_mul_f32_e32 v19, v19, v33
	v_mul_f32_e32 v20, v20, v42
	v_mul_f32_e32 v21, v21, v43
	v_mul_f32_e32 v22, v22, v34
	v_mul_f32_e32 v23, v23, v35
	v_mul_f32_e32 v24, v24, v44
	v_mul_f32_e32 v25, v25, v45
	v_mul_f32_e32 v26, v26, v36
	v_mul_f32_e32 v27, v27, v37
	v_mul_f32_e32 v28, v28, v46
	v_mul_f32_e32 v29, v29, v47
	v_mul_f32_e32 v30, v30, v38
	v_mul_f32_e32 v31, v31, v39
	v_cvt_pk_bf16_f32 v16, v16, v17
	v_cvt_pk_bf16_f32 v17, v18, v19
	v_cvt_pk_bf16_f32 v18, v20, v21
	v_cvt_pk_bf16_f32 v19, v22, v23
	v_cvt_pk_bf16_f32 v20, v24, v25
	v_cvt_pk_bf16_f32 v21, v26, v27
	v_cvt_pk_bf16_f32 v22, v28, v29
	v_cvt_pk_bf16_f32 v23, v30, v31
	v_permlane32_swap_b32_e32 v16, v18
	v_permlane32_swap_b32_e32 v17, v19
	v_permlane32_swap_b32_e32 v20, v22
	v_permlane32_swap_b32_e32 v21, v23
	global_store_dwordx4 v[48:49], v[16:19], off offset:1088
	global_store_dwordx4 v[48:49], v[20:23], off offset:1120
	s_barrier

; DI unsigned pk_bf16(float lo, float hi) { f32x2 v = {lo, hi}; bf2_t b = __builtin_convertvector(v, bf2_t); return __builtin_bit_cast(unsigned, b); }
; DI float bf_lo(unsigned u) { return __uint_as_float(u << 16); }
; DI float bf_hi(unsigned u) { return __uint_as_float(u & 0xffff0000u); }
; DI int crow(int i, int h) { return (i & 3) + 8 * (i >> 2) + 4 * h; }
; DI float fast_exp2(float x) { return __builtin_amdgcn_exp2f(x); }
; DI float fast_log2(float x) { return __builtin_amdgcn_logf(x); }
; template <int DQK, bool SB, bool SMAX>
; DI void attn_item(const Params& p, char* smem, int bh, int qb, float Mb) {
;     ...
;           for (int i2 = 0; i2 < 8; ++i2) {
;             float lk[2];
; #pragma unroll
;             for (int e = 0; e < 2; ++e) {
;               const int i = 2 * i2 + e;
;               const float z = fminf(st[kb][i], 100.f);
;               const int key = kb0 + kb * 32 + crow(i, h);
;               const bool valid = !diag || (key < query);
;               float l = -fast_log2(1.f + fast_exp2(z));
;               l = valid ? l : 0.f;
;               lk[e] = l;
;               tsum += l;
;               ca[kb][i] = z + carry;
;             }
;             const unsigned hp = pk_bf16(lk[0], lk[1]);
;             const unsigned lp = pk_bf16(lk[0] - bf_lo(hp), lk[1] - bf_hi(hp));
;             const int kk = kb * 2 + (i2 >> 2), w = i2 & 3;
;             hi[kk][2 * w] = (short)(hp & 0xffffu); hi[kk][2 * w + 1] = (short)(hp >> 16);
;             lo[kk][2 * w] = (short)(lp & 0xffffu); lo[kk][2 * w + 1] = (short)(lp >> 16);
;           }
.LBB0_435:
	s_or_b64 exec, exec, s[2:3]
	s_cmp_lt_u32 s4, s1
	s_cselect_b32 s2, s78, 0
	s_ashr_i32 s3, s2, 31
	s_lshl_b64 s[2:3], s[2:3], 7
	v_lshl_add_u64 v[80:81], v[148:149], 0, s[2:3]
	s_waitcnt vmcnt(3)
	ds_write_b128 v203, v[120:123] offset:9216
	s_waitcnt vmcnt(2)
	ds_write_b128 v204, v[124:127] offset:9216
	s_waitcnt vmcnt(1)
	ds_write_b128 v203, v[128:131] offset:27648
	s_waitcnt vmcnt(0)
	ds_write_b128 v204, v[132:135] offset:27648
	v_add_co_u32_e32 v82, vcc, 0x1000, v80
	s_nop 1
	v_addc_co_u32_e32 v83, vcc, 0, v81, vcc
	global_load_dwordx4 v[120:123], v[80:81], off
	global_load_dwordx4 v[124:127], v[82:83], off
	v_lshl_add_u64 v[80:81], v[150:151], 0, s[2:3]
	v_add_co_u32_e32 v82, vcc, 0x1000, v80
	s_nop 1
	v_addc_co_u32_e32 v83, vcc, 0, v81, vcc
	global_load_dwordx4 v[128:131], v[80:81], off
	global_load_dwordx4 v[132:135], v[82:83], off
	s_and_saveexec_b64 s[80:81], s[12:13]
	s_cbranch_execz .LBB0_437
	v_cmp_le_i32_e64 s[44:45], s14, v181
	s_nop 0
	s_cmp_eq_u64 s[44:45], exec
	s_cbranch_scc1 .Lsbf_1
	s_nop 0
	v_add_u32_e32 v143, s78, v197
	v_min_f32_e32 v84, 0x42c80000, v64
	s_nop 0
	v_exp_f32_e32 v64, v84
	v_min_f32_e32 v85, 0x42c80000, v65
	v_add_u32_e32 v65, 0x81, v143
	v_cmp_lt_i32_e64 s[2:3], v65, v176
	v_exp_f32_e32 v65, v85
	v_add_f32_e32 v64, 1.0, v64
	v_log_f32_e32 v64, v64
	v_add_u32_e32 v80, 0x80, v143
	v_add_f32_e32 v65, 1.0, v65
	v_log_f32_e32 v65, v65
	v_cmp_le_i32_e64 s[44:45], s14, v181
	v_cmp_lt_i32_e32 vcc, v80, v176
	s_or_b64 vcc, s[44:45], vcc
	s_or_b64 s[12:13], s[44:45], s[2:3]
	v_cndmask_b32_e64 v64, 0, -v64, vcc
	v_add_f32_e32 v80, 0, v64
	v_cndmask_b32_e64 v65, 0, -v65, s[12:13]
	v_add_f32_e32 v81, v65, v80
	v_cvt_pk_bf16_f32 v80, v64, v65
	v_lshlrev_b32_e32 v82, 16, v80
	v_sub_f32_e32 v64, v64, v82
	v_and_b32_e32 v82, 0xffff0000, v80
	v_sub_f32_e32 v65, v65, v82
	v_cvt_pk_bf16_f32 v64, v64, v65
	s_nop 0
	v_min_f32_e32 v86, 0x42c80000, v66
	v_add_u32_e32 v65, 0x82, v143
	s_nop 0
	v_cmp_lt_i32_e64 s[2:3], v65, v176
	v_min_f32_e32 v87, 0x42c80000, v67
	v_add_u32_e32 v67, 0x83, v143
	s_or_b64 s[14:15], s[44:45], s[2:3]
	v_exp_f32_e32 v65, v86
	v_cmp_lt_i32_e64 s[2:3], v67, v176
	v_exp_f32_e32 v67, v87
	s_or_b64 s[16:17], s[44:45], s[2:3]
	v_add_f32_e32 v65, 1.0, v65
	v_log_f32_e32 v65, v65
	v_add_f32_e32 v67, 1.0, v67
	v_log_f32_e32 v67, v67
	s_nop 0
	v_cndmask_b32_e64 v65, 0, -v65, s[14:15]
	v_add_f32_e32 v66, v65, v81
	v_cndmask_b32_e64 v67, 0, -v67, s[16:17]
	v_cvt_pk_bf16_f32 v81, v65, v67
	v_lshlrev_b32_e32 v82, 16, v81
	v_sub_f32_e32 v65, v65, v82
	v_and_b32_e32 v82, 0xffff0000, v81
	v_add_f32_e32 v66, v67, v66
	v_sub_f32_e32 v67, v67, v82
	v_cvt_pk_bf16_f32 v65, v65, v67
	s_nop 0
	v_min_f32_e32 v88, 0x42c80000, v68
	v_add_u32_e32 v67, 0x88, v143
	s_nop 0
	v_cmp_lt_i32_e64 s[2:3], v67, v176
	v_min_f32_e32 v89, 0x42c80000, v69
	v_add_u32_e32 v68, 0x89, v143
	s_or_b64 s[18:19], s[44:45], s[2:3]
	v_exp_f32_e32 v67, v88
	v_cmp_lt_i32_e64 s[2:3], v68, v176
	v_exp_f32_e32 v68, v89
	s_or_b64 s[20:21], s[44:45], s[2:3]
	v_add_f32_e32 v67, 1.0, v67
	v_log_f32_e32 v67, v67
	v_add_f32_e32 v68, 1.0, v68
	v_log_f32_e32 v68, v68
	s_nop 0
	v_cndmask_b32_e64 v67, 0, -v67, s[18:19]
	v_add_f32_e32 v66, v67, v66
	v_cndmask_b32_e64 v68, 0, -v68, s[20:21]
	v_cvt_pk_bf16_f32 v82, v67, v68
	v_add_f32_e32 v69, v68, v66
	v_lshlrev_b32_e32 v66, 16, v82
	v_sub_f32_e32 v66, v67, v66
	v_and_b32_e32 v67, 0xffff0000, v82
	v_sub_f32_e32 v67, v68, v67
	v_cvt_pk_bf16_f32 v66, v66, v67
	s_nop 0
	v_min_f32_e32 v90, 0x42c80000, v70
	v_add_u32_e32 v67, 0x8a, v143
	v_cmp_lt_i32_e64 s[2:3], v67, v176
	v_exp_f32_e32 v67, v90
	s_or_b64 s[22:23], s[44:45], s[2:3]
	v_min_f32_e32 v156, 0x42c80000, v48
	v_min_f32_e32 v157, 0x42c80000, v49
	v_add_f32_e32 v67, 1.0, v67
	v_log_f32_e32 v67, v67
	v_add_u32_e32 v49, 0xa1, v143
	v_exp_f32_e32 v48, v156
	s_mov_b32 s97, s96
	v_cndmask_b32_e64 v67, 0, -v67, s[22:23]
	v_add_f32_e32 v68, v67, v69
	s_nop 0
	v_min_f32_e32 v91, 0x42c80000, v71
	v_add_u32_e32 v69, 0x8b, v143
	v_cmp_lt_i32_e64 s[2:3], v69, v176
	v_exp_f32_e32 v69, v91
	s_or_b64 s[24:25], s[44:45], s[2:3]
	v_add_f32_e32 v48, 1.0, v48
	v_log_f32_e32 v48, v48
	v_add_f32_e32 v69, 1.0, v69
	v_log_f32_e32 v69, v69
	s_mov_b32 s98, s96
	s_mov_b32 s99, s96
	v_cndmask_b32_e64 v69, 0, -v69, s[24:25]
	v_cvt_pk_bf16_f32 v83, v67, v69
	v_lshlrev_b32_e32 v70, 16, v83
	v_sub_f32_e32 v67, v67, v70
	v_and_b32_e32 v70, 0xffff0000, v83
	v_add_f32_e32 v68, v69, v68
	v_sub_f32_e32 v69, v69, v70
	v_cvt_pk_bf16_f32 v67, v67, v69
	s_nop 0
	v_min_f32_e32 v92, 0x42c80000, v72
	v_add_u32_e32 v69, 0x90, v143
	s_nop 0
	v_cmp_lt_i32_e64 s[2:3], v69, v176
	v_min_f32_e32 v93, 0x42c80000, v73
	v_add_u32_e32 v70, 0x91, v143
	s_or_b64 s[26:27], s[44:45], s[2:3]
	v_exp_f32_e32 v69, v92
	v_cmp_lt_i32_e64 s[2:3], v70, v176
	v_exp_f32_e32 v70, v93
	s_or_b64 s[28:29], s[44:45], s[2:3]
	v_add_f32_e32 v69, 1.0, v69
	v_log_f32_e32 v69, v69
	v_add_f32_e32 v70, 1.0, v70
	v_log_f32_e32 v70, v70
	v_cndmask_b32_e64 v69, 0, -v69, s[26:27]
	v_add_f32_e32 v68, v69, v68
	v_cndmask_b32_e64 v70, 0, -v70, s[28:29]
	v_cvt_pk_bf16_f32 v72, v69, v70
	v_add_f32_e32 v71, v70, v68
	v_lshlrev_b32_e32 v68, 16, v72
	v_sub_f32_e32 v68, v69, v68
	v_and_b32_e32 v69, 0xffff0000, v72
	v_sub_f32_e32 v69, v70, v69
	v_cvt_pk_bf16_f32 v68, v68, v69
	s_nop 0
	v_min_f32_e32 v94, 0x42c80000, v74
	v_add_u32_e32 v69, 0x92, v143
	v_cmp_lt_i32_e64 s[2:3], v69, v176
	v_exp_f32_e32 v69, v94
	s_or_b64 s[30:31], s[44:45], s[2:3]
	v_add_f32_e32 v69, 1.0, v69
	v_log_f32_e32 v69, v69
	s_nop 0
	v_cndmask_b32_e64 v69, 0, -v69, s[30:31]
	v_add_f32_e32 v70, v69, v71
	s_nop 0
	v_min_f32_e32 v95, 0x42c80000, v75
	v_add_u32_e32 v71, 0x93, v143
; DI unsigned pk_bf16(float lo, float hi) { f32x2 v = {lo, hi}; bf2_t b = __builtin_convertvector(v, bf2_t); return __builtin_bit_cast(unsigned, b); }
; DI float bf_lo(unsigned u) { return __uint_as_float(u << 16); }
; DI float bf_hi(unsigned u) { return __uint_as_float(u & 0xffff0000u); }
; DI int crow(int i, int h) { return (i & 3) + 8 * (i >> 2) + 4 * h; }
; DI float fast_exp2(float x) { return __builtin_amdgcn_exp2f(x); }
; DI float fast_log2(float x) { return __builtin_amdgcn_logf(x); }
; template <int DQK, bool SB, bool SMAX>
; DI void attn_item(const Params& p, char* smem, int bh, int qb, float Mb) {
;     ...
;           for (int i2 = 0; i2 < 8; ++i2) {
;             float lk[2];
; #pragma unroll
;             for (int e = 0; e < 2; ++e) {
;               const int i = 2 * i2 + e;
;               const float z = fminf(st[kb][i], 100.f);
;               const int key = kb0 + kb * 32 + crow(i, h);
;               const bool valid = !diag || (key < query);
;               float l = -fast_log2(1.f + fast_exp2(z));
;               l = valid ? l : 0.f;
;               lk[e] = l;
;               tsum += l;
;               ca[kb][i] = z + carry;
;             }
;             const unsigned hp = pk_bf16(lk[0], lk[1]);
;             const unsigned lp = pk_bf16(lk[0] - bf_lo(hp), lk[1] - bf_hi(hp));
;             const int kk = kb * 2 + (i2 >> 2), w = i2 & 3;
;             hi[kk][2 * w] = (short)(hp & 0xffffu); hi[kk][2 * w + 1] = (short)(hp >> 16);
;             lo[kk][2 * w] = (short)(lp & 0xffffu); lo[kk][2 * w + 1] = (short)(lp >> 16);
;           }
	v_cmp_lt_i32_e64 s[2:3], v71, v176
	v_exp_f32_e32 v71, v95
	s_or_b64 s[34:35], s[44:45], s[2:3]
	v_add_f32_e32 v71, 1.0, v71
	v_log_f32_e32 v71, v71
	s_nop 0
	v_cndmask_b32_e64 v71, 0, -v71, s[34:35]
	v_cvt_pk_bf16_f32 v73, v69, v71
	v_lshlrev_b32_e32 v74, 16, v73
	v_sub_f32_e32 v69, v69, v74
	v_and_b32_e32 v74, 0xffff0000, v73
	v_add_f32_e32 v70, v71, v70
	v_sub_f32_e32 v71, v71, v74
	v_cvt_pk_bf16_f32 v69, v69, v71
	s_nop 0
	v_min_f32_e32 v154, 0x42c80000, v76
	v_add_u32_e32 v71, 0x98, v143
	s_nop 0
	v_cmp_lt_i32_e64 s[2:3], v71, v176
	v_min_f32_e32 v155, 0x42c80000, v77
	v_add_u32_e32 v74, 0x99, v143
	s_or_b64 s[36:37], s[44:45], s[2:3]
	v_exp_f32_e32 v71, v154
	v_cmp_lt_i32_e64 s[2:3], v74, v176
	v_exp_f32_e32 v74, v155
	s_or_b64 s[38:39], s[44:45], s[2:3]
	v_add_f32_e32 v71, 1.0, v71
	v_log_f32_e32 v71, v71
	v_add_f32_e32 v74, 1.0, v74
	v_log_f32_e32 v74, v74
	v_cndmask_b32_e64 v71, 0, -v71, s[36:37]
	v_add_f32_e32 v70, v71, v70
	v_cndmask_b32_e64 v75, 0, -v74, s[38:39]
	v_cvt_pk_bf16_f32 v74, v71, v75
	v_add_f32_e32 v76, v75, v70
	v_lshlrev_b32_e32 v70, 16, v74
	v_sub_f32_e32 v70, v71, v70
	v_and_b32_e32 v71, 0xffff0000, v74
	v_sub_f32_e32 v71, v75, v71
	v_cvt_pk_bf16_f32 v70, v70, v71
	s_nop 0
	v_min_f32_e32 v158, 0x42c80000, v78
	v_add_u32_e32 v71, 0x9a, v143
	v_cmp_lt_i32_e64 s[2:3], v71, v176
	v_exp_f32_e32 v71, v158
	s_or_b64 s[40:41], s[44:45], s[2:3]
	v_add_f32_e32 v71, 1.0, v71
	v_log_f32_e32 v71, v71
	s_nop 0
	v_cndmask_b32_e64 v71, 0, -v71, s[40:41]
	v_add_f32_e32 v75, v71, v76
	s_nop 0
	v_min_f32_e32 v159, 0x42c80000, v79
	v_add_u32_e32 v76, 0x9b, v143
	v_cmp_lt_i32_e64 s[2:3], v76, v176
	v_exp_f32_e32 v76, v159
	s_or_b64 s[42:43], s[44:45], s[2:3]
	v_add_f32_e32 v76, 1.0, v76
	v_log_f32_e32 v76, v76
	s_nop 0
	v_cndmask_b32_e64 v76, 0, -v76, s[42:43]
	v_add_f32_e32 v77, v76, v75
	v_cvt_pk_bf16_f32 v75, v71, v76
	v_lshlrev_b32_e32 v78, 16, v75
	v_sub_f32_e32 v71, v71, v78
	v_and_b32_e32 v78, 0xffff0000, v75
	v_sub_f32_e32 v76, v76, v78
	v_cvt_pk_bf16_f32 v71, v71, v76
	v_add_u32_e32 v76, 0xa0, v143
	v_cmp_lt_i32_e64 s[2:3], v76, v176
	s_or_b64 s[46:47], s[44:45], s[2:3]
	v_cmp_lt_i32_e64 s[2:3], v49, v176
	v_exp_f32_e32 v49, v157
	s_or_b64 s[48:49], s[44:45], s[2:3]
	v_cndmask_b32_e64 v48, 0, -v48, s[46:47]
	v_add_f32_e32 v76, v48, v77
	v_add_f32_e32 v49, 1.0, v49
	v_log_f32_e32 v49, v49
	s_nop 0
	v_cndmask_b32_e64 v49, 0, -v49, s[48:49]
	v_cvt_pk_bf16_f32 v136, v48, v49
	v_add_f32_e32 v77, v49, v76
	v_lshlrev_b32_e32 v76, 16, v136
	v_sub_f32_e32 v48, v48, v76
	v_and_b32_e32 v76, 0xffff0000, v136
	v_sub_f32_e32 v49, v49, v76
	v_cvt_pk_bf16_f32 v76, v48, v49
	s_nop 0
	v_min_f32_e32 v160, 0x42c80000, v50
	v_add_u32_e32 v48, 0xa2, v143
	s_nop 0
	v_cmp_lt_i32_e64 s[2:3], v48, v176
	v_min_f32_e32 v161, 0x42c80000, v51
	v_add_u32_e32 v50, 0xa3, v143
	s_or_b64 s[50:51], s[44:45], s[2:3]
	v_exp_f32_e32 v48, v160
	v_cmp_lt_i32_e64 s[2:3], v50, v176
	v_exp_f32_e32 v50, v161
	s_or_b64 s[52:53], s[44:45], s[2:3]
	v_add_f32_e32 v48, 1.0, v48
	v_log_f32_e32 v48, v48
	v_add_f32_e32 v50, 1.0, v50
	v_log_f32_e32 v50, v50
	v_cndmask_b32_e64 v48, 0, -v48, s[50:51]
	v_add_f32_e32 v49, v48, v77
	v_cndmask_b32_e64 v50, 0, -v50, s[52:53]
	v_cvt_pk_bf16_f32 v137, v48, v50
	v_lshlrev_b32_e32 v51, 16, v137
	v_sub_f32_e32 v48, v48, v51
	v_and_b32_e32 v51, 0xffff0000, v137
	v_add_f32_e32 v49, v50, v49
	v_sub_f32_e32 v50, v50, v51
	v_cvt_pk_bf16_f32 v77, v48, v50
	s_nop 0
	v_min_f32_e32 v162, 0x42c80000, v52
	v_add_u32_e32 v48, 0xa8, v143
	s_nop 0
	v_cmp_lt_i32_e64 s[2:3], v48, v176
	v_min_f32_e32 v163, 0x42c80000, v53
	v_add_u32_e32 v50, 0xa9, v143
	s_or_b64 s[54:55], s[44:45], s[2:3]
	v_exp_f32_e32 v48, v162
	v_cmp_lt_i32_e64 s[2:3], v50, v176
	v_exp_f32_e32 v50, v163
	s_or_b64 s[56:57], s[44:45], s[2:3]
	v_add_f32_e32 v48, 1.0, v48
	v_log_f32_e32 v48, v48
	v_add_f32_e32 v50, 1.0, v50
	v_log_f32_e32 v50, v50
	v_add_f32_e32 v52, v152, v88
	v_add_f32_e32 v53, v152, v89
	v_cndmask_b32_e64 v48, 0, -v48, s[54:55]
	v_add_f32_e32 v49, v48, v49
	v_cndmask_b32_e64 v50, 0, -v50, s[56:57]
	v_cvt_pk_bf16_f32 v138, v48, v50
	v_lshlrev_b32_e32 v51, 16, v138
	v_sub_f32_e32 v48, v48, v51
	v_and_b32_e32 v51, 0xffff0000, v138
	v_add_f32_e32 v49, v50, v49
	v_sub_f32_e32 v50, v50, v51
	v_cvt_pk_bf16_f32 v78, v48, v50
	s_nop 0
	v_min_f32_e32 v164, 0x42c80000, v54
	v_add_u32_e32 v48, 0xaa, v143
	s_nop 0
	v_cmp_lt_i32_e64 s[2:3], v48, v176
	v_min_f32_e32 v165, 0x42c80000, v55
	v_add_u32_e32 v50, 0xab, v143
	s_or_b64 s[58:59], s[44:45], s[2:3]
	v_exp_f32_e32 v48, v164
	v_cmp_lt_i32_e64 s[2:3], v50, v176
	v_exp_f32_e32 v50, v165
	s_or_b64 s[60:61], s[44:45], s[2:3]
	v_add_f32_e32 v48, 1.0, v48
	v_log_f32_e32 v48, v48
	v_add_f32_e32 v50, 1.0, v50
	v_log_f32_e32 v50, v50
	v_add_f32_e32 v54, v152, v90
	v_add_f32_e32 v55, v152, v91
	v_cndmask_b32_e64 v48, 0, -v48, s[58:59]
	v_add_f32_e32 v49, v48, v49
	v_cndmask_b32_e64 v50, 0, -v50, s[60:61]
	v_cvt_pk_bf16_f32 v139, v48, v50
	v_lshlrev_b32_e32 v51, 16, v139
	v_sub_f32_e32 v48, v48, v51
	v_and_b32_e32 v51, 0xffff0000, v139
	v_add_f32_e32 v49, v50, v49
	v_sub_f32_e32 v50, v50, v51
	v_cvt_pk_bf16_f32 v79, v48, v50
	s_nop 0
	v_min_f32_e32 v166, 0x42c80000, v56
	v_add_u32_e32 v48, 0xb0, v143
	s_nop 0
	v_cmp_lt_i32_e64 s[2:3], v48, v176
	v_min_f32_e32 v167, 0x42c80000, v57
	v_add_u32_e32 v50, 0xb1, v143
	s_or_b64 s[62:63], s[44:45], s[2:3]
	v_exp_f32_e32 v48, v166
	v_cmp_lt_i32_e64 s[2:3], v50, v176
	v_exp_f32_e32 v50, v167
	s_or_b64 s[64:65], s[44:45], s[2:3]
	v_add_f32_e32 v48, 1.0, v48
	v_log_f32_e32 v48, v48
	v_add_f32_e32 v50, 1.0, v50
	v_log_f32_e32 v50, v50
	v_add_f32_e32 v56, v152, v92
	v_add_f32_e32 v57, v152, v93
; #define MFMA32(a, b, c) __builtin_amdgcn_mfma_f32_32x32x16_bf16((a), (b), (c), 0, 0, 0)
; DI unsigned pk_bf16(float lo, float hi) { f32x2 v = {lo, hi}; bf2_t b = __builtin_convertvector(v, bf2_t); return __builtin_bit_cast(unsigned, b); }
; DI float bf_lo(unsigned u) { return __uint_as_float(u << 16); }
; DI float bf_hi(unsigned u) { return __uint_as_float(u & 0xffff0000u); }
; DI int crow(int i, int h) { return (i & 3) + 8 * (i >> 2) + 4 * h; }
; DI float fast_exp2(float x) { return __builtin_amdgcn_exp2f(x); }
; template <int DQK, bool SB, bool SMAX>
; DI void attn_item(const Params& p, char* smem, int bh, int qb, float Mb) {
;     ...
;               ca[kb][i] = z + carry;
;             }
;             const unsigned hp = pk_bf16(lk[0], lk[1]);
;             const unsigned lp = pk_bf16(lk[0] - bf_lo(hp), lk[1] - bf_hi(hp));
;             const int kk = kb * 2 + (i2 >> 2), w = i2 & 3;
;             hi[kk][2 * w] = (short)(hp & 0xffffu); hi[kk][2 * w + 1] = (short)(hp >> 16);
;             lo[kk][2 * w] = (short)(lp & 0xffffu); lo[kk][2 * w + 1] = (short)(lp >> 16);
;           }
;         tsum += other_half(tsum);
; #pragma unroll
;         for (int s = 0; s < 2; ++s) {
;           ca[0] = MFMA32(tri[s], hi[s], ca[0]);
;           ca[0] = MFMA32(tri[s], lo[s], ca[0]);
;           ca[0] = MFMA32(ones, hi[2 + s], ca[0]);
;           ca[0] = MFMA32(ones, lo[2 + s], ca[0]);
;           ca[1] = MFMA32(tri[s], hi[2 + s], ca[1]);
;           ca[1] = MFMA32(tri[s], lo[2 + s], ca[1]);
;         }
; #pragma unroll
;         for (int kb = 0; kb < 2; ++kb)
; #pragma unroll
;           for (int i = 0; i < 16; ++i) {
;             const int key = kb0 + kb * 32 + crow(i, h);
;             const bool valid = !diag || (key < query);
;             st[kb][i] = valid ? fast_exp2(ca[kb][i]) : 0.f;
;           }
;         carry += tsum;
	v_cndmask_b32_e64 v48, 0, -v48, s[62:63]
	v_add_f32_e32 v49, v48, v49
	v_cndmask_b32_e64 v50, 0, -v50, s[64:65]
	v_cvt_pk_bf16_f32 v140, v48, v50
	v_lshlrev_b32_e32 v51, 16, v140
	v_sub_f32_e32 v48, v48, v51
	v_and_b32_e32 v51, 0xffff0000, v140
	v_add_f32_e32 v49, v50, v49
	v_sub_f32_e32 v50, v50, v51
	v_cvt_pk_bf16_f32 v144, v48, v50
	s_nop 0
	v_min_f32_e32 v168, 0x42c80000, v58
	v_add_u32_e32 v48, 0xb2, v143
	s_nop 0
	v_cmp_lt_i32_e64 s[2:3], v48, v176
	v_min_f32_e32 v169, 0x42c80000, v59
	v_add_u32_e32 v50, 0xb3, v143
	s_or_b64 s[66:67], s[44:45], s[2:3]
	v_exp_f32_e32 v48, v168
	v_cmp_lt_i32_e64 s[2:3], v50, v176
	v_exp_f32_e32 v50, v169
	s_or_b64 s[68:69], s[44:45], s[2:3]
	v_add_f32_e32 v48, 1.0, v48
	v_log_f32_e32 v48, v48
	v_add_f32_e32 v50, 1.0, v50
	v_log_f32_e32 v50, v50
	v_add_f32_e32 v58, v152, v94
	v_add_f32_e32 v59, v152, v95
	v_cndmask_b32_e64 v48, 0, -v48, s[66:67]
	v_add_f32_e32 v49, v48, v49
	v_cndmask_b32_e64 v50, 0, -v50, s[68:69]
	v_cvt_pk_bf16_f32 v141, v48, v50
	v_lshlrev_b32_e32 v51, 16, v141
	v_sub_f32_e32 v48, v48, v51
	v_and_b32_e32 v51, 0xffff0000, v141
	v_add_f32_e32 v49, v50, v49
	v_sub_f32_e32 v50, v50, v51
	v_cvt_pk_bf16_f32 v145, v48, v50
	s_nop 0
	v_min_f32_e32 v170, 0x42c80000, v60
	v_add_u32_e32 v48, 0xb8, v143
	s_nop 0
	v_cmp_lt_i32_e64 s[2:3], v48, v176
	v_min_f32_e32 v171, 0x42c80000, v61
	v_add_u32_e32 v50, 0xb9, v143
	s_or_b64 s[70:71], s[44:45], s[2:3]
	v_exp_f32_e32 v48, v170
	v_cmp_lt_i32_e64 s[2:3], v50, v176
	v_exp_f32_e32 v50, v171
	s_or_b64 s[72:73], s[44:45], s[2:3]
	v_add_f32_e32 v48, 1.0, v48
	v_log_f32_e32 v48, v48
	v_add_f32_e32 v50, 1.0, v50
	v_log_f32_e32 v50, v50
	v_add_f32_e32 v60, v152, v154
	v_add_f32_e32 v61, v152, v155
	v_cndmask_b32_e64 v48, 0, -v48, s[70:71]
	v_add_f32_e32 v49, v48, v49
	v_cndmask_b32_e64 v50, 0, -v50, s[72:73]
	v_cvt_pk_bf16_f32 v142, v48, v50
	v_lshlrev_b32_e32 v51, 16, v142
	v_sub_f32_e32 v48, v48, v51
	v_and_b32_e32 v51, 0xffff0000, v142
	v_add_f32_e32 v49, v50, v49
	v_sub_f32_e32 v50, v50, v51
	v_cvt_pk_bf16_f32 v146, v48, v50
	s_nop 0
	v_min_f32_e32 v182, 0x42c80000, v62
	v_add_u32_e32 v48, 0xba, v143
	s_nop 0
	v_cmp_lt_i32_e64 s[2:3], v48, v176
	v_min_f32_e32 v183, 0x42c80000, v63
	v_add_u32_e32 v50, 0xbb, v143
	s_or_b64 s[74:75], s[44:45], s[2:3]
	v_exp_f32_e32 v48, v182
	v_cmp_lt_i32_e64 s[2:3], v50, v176
	v_exp_f32_e32 v50, v183
	s_or_b64 s[44:45], s[44:45], s[2:3]
	v_add_f32_e32 v48, 1.0, v48
	v_log_f32_e32 v48, v48
	v_add_f32_e32 v50, 1.0, v50
	v_log_f32_e32 v50, v50
	v_add_f32_e32 v62, v152, v158
	v_add_f32_e32 v63, v152, v159
	v_cndmask_b32_e64 v48, 0, -v48, s[74:75]
	v_add_f32_e32 v49, v48, v49
	v_cndmask_b32_e64 v50, 0, -v50, s[44:45]
	v_cvt_pk_bf16_f32 v143, v48, v50
	v_add_f32_e32 v184, v50, v49
	v_lshlrev_b32_e32 v49, 16, v143
	v_sub_f32_e32 v48, v48, v49
	v_and_b32_e32 v49, 0xffff0000, v143
	v_sub_f32_e32 v49, v50, v49
	v_cvt_pk_bf16_f32 v147, v48, v49
	v_mov_b32_e32 v48, v184
	v_mov_b32_e32 v49, v184
	s_nop 1
	v_permlane32_swap_b32_e32 v48, v49
	v_cndmask_b32_e64 v185, v48, v49, s[8:9]
	v_add_f32_e32 v50, v152, v86
	v_add_f32_e32 v51, v152, v87
	v_add_f32_e32 v48, v152, v84
	v_add_f32_e32 v49, v152, v85
	v_add_f32_e32 v94, v152, v182
	v_add_f32_e32 v95, v152, v183
	v_add_f32_e32 v92, v152, v170
	v_add_f32_e32 v93, v152, v171
	v_mfma_f32_32x32x16_bf16 v[48:63], v[96:99], v[80:83], v[48:63]
	v_add_f32_e32 v90, v152, v168
	v_add_f32_e32 v91, v152, v169
	v_add_f32_e32 v88, v152, v166
	v_add_f32_e32 v89, v152, v167
	v_add_f32_e32 v86, v152, v164
	v_add_f32_e32 v87, v152, v165
	v_add_f32_e32 v84, v152, v162
	v_add_f32_e32 v85, v152, v163
	v_add_f32_e32 v82, v152, v160
	v_add_f32_e32 v83, v152, v161
	v_add_f32_e32 v80, v152, v156
	v_add_f32_e32 v81, v152, v157
	v_mfma_f32_32x32x16_bf16 v[48:63], v[96:99], v[64:67], v[48:63]
	v_mov_b64_e32 v[64:65], s[96:97]
	v_mov_b64_e32 v[66:67], s[98:99]
	s_nop 1
	v_mfma_f32_32x32x16_bf16 v[48:63], v[64:67], v[136:139], v[48:63]
	v_mfma_f32_32x32x16_bf16 v[48:63], v[64:67], v[76:79], v[48:63]
	v_mfma_f32_32x32x16_bf16 v[48:63], v[100:103], v[72:75], v[48:63]
	v_mfma_f32_32x32x16_bf16 v[48:63], v[100:103], v[68:71], v[48:63]
	v_mfma_f32_32x32x16_bf16 v[48:63], v[64:67], v[140:143], v[48:63]
	v_mfma_f32_32x32x16_bf16 v[48:63], v[64:67], v[144:147], v[48:63]
	v_mfma_f32_32x32x16_bf16 v[80:95], v[96:99], v[136:139], v[80:95]
	s_nop 10
	v_exp_f32_e32 v48, v48
	s_nop 0
	v_cndmask_b32_e32 v64, 0, v48, vcc
	v_exp_f32_e32 v48, v49
	v_mfma_f32_32x32x16_bf16 v[80:95], v[96:99], v[76:79], v[80:95]
	v_cndmask_b32_e64 v65, 0, v48, s[12:13]
	v_exp_f32_e32 v48, v50
	s_nop 0
	v_cndmask_b32_e64 v66, 0, v48, s[14:15]
	v_exp_f32_e32 v48, v51
	v_mfma_f32_32x32x16_bf16 v[80:95], v[100:103], v[140:143], v[80:95]
	v_add_u32_e32 v141, v198, v200
	ds_read_b64_tr_b16 v[136:137], v141 offset:18432
	ds_read_b64_tr_b16 v[138:139], v141 offset:19584
	v_cndmask_b32_e64 v67, 0, v48, s[16:17]
	v_exp_f32_e32 v48, v52
	v_add_f32_e32 v140, v184, v185
	v_add_f32_e32 v152, v152, v140
	v_cndmask_b32_e64 v68, 0, v48, s[18:19]
	v_exp_f32_e32 v48, v53
	v_mfma_f32_32x32x16_bf16 v[80:95], v[100:103], v[144:147], v[80:95]
	v_cndmask_b32_e64 v69, 0, v48, s[20:21]
	v_exp_f32_e32 v48, v54
	s_nop 0
	v_cndmask_b32_e64 v70, 0, v48, s[22:23]
	v_exp_f32_e32 v48, v55
	s_nop 6
	v_exp_f32_e32 v49, v81
	v_exp_f32_e32 v50, v82
	v_exp_f32_e32 v51, v83
	v_cndmask_b32_e64 v71, 0, v48, s[24:25]
	v_exp_f32_e32 v48, v56
	v_exp_f32_e32 v56, v88
	v_exp_f32_e32 v52, v84
	v_exp_f32_e32 v53, v85
	v_cndmask_b32_e64 v72, 0, v48, s[26:27]
	v_exp_f32_e32 v48, v57
	v_exp_f32_e32 v57, v89
	v_exp_f32_e32 v54, v86
	v_exp_f32_e32 v55, v87
	v_cndmask_b32_e64 v73, 0, v48, s[28:29]
	v_exp_f32_e32 v48, v58
	v_exp_f32_e32 v58, v90
	v_cvt_pk_bf16_f32 v88, v72, v73
	v_cndmask_b32_e64 v49, 0, v49, s[48:49]
	v_cndmask_b32_e64 v74, 0, v48, s[30:31]
	v_exp_f32_e32 v48, v59
	v_exp_f32_e32 v59, v91
	v_cndmask_b32_e64 v50, 0, v50, s[50:51]
	v_cndmask_b32_e64 v51, 0, v51, s[52:53]
	v_cndmask_b32_e64 v75, 0, v48, s[34:35]
	v_exp_f32_e32 v48, v60
	v_exp_f32_e32 v60, v92
	v_cvt_pk_bf16_f32 v92, v64, v65
	v_cvt_pk_bf16_f32 v89, v74, v75
	v_cndmask_b32_e64 v76, 0, v48, s[36:37]
	v_exp_f32_e32 v48, v61
	v_exp_f32_e32 v61, v93
	v_cvt_pk_bf16_f32 v93, v66, v67
	v_cndmask_b32_e64 v52, 0, v52, s[54:55]
	v_cndmask_b32_e64 v77, 0, v48, s[38:39]
	v_exp_f32_e32 v48, v62
	v_exp_f32_e32 v62, v94
	v_cvt_pk_bf16_f32 v94, v68, v69
	v_cvt_pk_bf16_f32 v90, v76, v77
	v_cndmask_b32_e64 v78, 0, v48, s[40:41]
	v_exp_f32_e32 v48, v63
	v_exp_f32_e32 v63, v95
	v_cvt_pk_bf16_f32 v95, v70, v71
	v_cndmask_b32_e64 v53, 0, v53, s[56:57]
	v_cndmask_b32_e64 v79, 0, v48, s[42:43]
	s_waitcnt lgkmcnt(0)
; template <int DQK, bool SB, bool SMAX>
; DI void attn_item(const Params& p, char* smem, int bh, int qb, float Mb) {
;     ...
;           for (int i2 = 0; i2 < 8; ++i2) {
;             float lk[2];
; #pragma unroll
;             for (int e = 0; e < 2; ++e) {
;               const int i = 2 * i2 + e;
;               const float z = fminf(st[kb][i], 100.f);
;               const int key = kb0 + kb * 32 + crow(i, h);
;               const bool valid = !diag || (key < query);
;               float l = -fast_log2(1.f + fast_exp2(z));
;               l = valid ? l : 0.f;
;               lk[e] = l;
;               tsum += l;
;               ca[kb][i] = z + carry;
;             }
;             const unsigned hp = pk_bf16(lk[0], lk[1]);
;             const unsigned lp = pk_bf16(lk[0] - bf_lo(hp), lk[1] - bf_hi(hp));
;             const int kk = kb * 2 + (i2 >> 2), w = i2 & 3;
;             hi[kk][2 * w] = (short)(hp & 0xffffu); hi[kk][2 * w + 1] = (short)(hp >> 16);
;             lo[kk][2 * w] = (short)(lp & 0xffffu); lo[kk][2 * w + 1] = (short)(lp >> 16);
;           }
;         tsum += other_half(tsum);
; #pragma unroll
;         for (int s = 0; s < 2; ++s) {
;           ca[0] = MFMA32(tri[s], hi[s], ca[0]);
;           ca[0] = MFMA32(tri[s], lo[s], ca[0]);
;           ca[0] = MFMA32(ones, hi[2 + s], ca[0]);
;           ca[0] = MFMA32(ones, lo[2 + s], ca[0]);
;           ca[1] = MFMA32(tri[s], hi[2 + s], ca[1]);
;           ca[1] = MFMA32(tri[s], lo[2 + s], ca[1]);
;         }
; #pragma unroll
;         for (int kb = 0; kb < 2; ++kb)
; #pragma unroll
;           for (int i = 0; i < 16; ++i) {
;             const int key = kb0 + kb * 32 + crow(i, h);
;             const bool valid = !diag || (key < query);
;             st[kb][i] = valid ? fast_exp2(ca[kb][i]) : 0.f;
;           }
;         carry += tsum;
;       }
; #pragma unroll
;       for (int kb = 0; kb < 2; ++kb)
; #pragma unroll
;         for (int s = 0; s < 2; ++s) {
;           u32x4 w;
; #pragma unroll
;           for (int e = 0; e < 4; ++e) w[e] = pk_bf16(st[kb][8 * s + 2 * e], st[kb][8 * s + 2 * e + 1]);
;           pk[kb * 2 + s] = __builtin_bit_cast(bf16x8, w);
;         }
; #pragma unroll
;       for (int kk = 0; kk < 4; ++kk)
; #pragma unroll
;         for (int db = 0; db < 2; ++db) {
;           const s16x4 v0 = __builtin_amdgcn_ds_read_tr16_b64_v4i16((lds_s16x4*)(vc + voff + (16 * kk) * VSTR + 32 * db));
	v_mfma_f32_32x32x16_bf16 v[32:47], v[136:139], v[92:95], v[32:47]
	ds_read_b64_tr_b16 v[136:137], v141 offset:18496
	ds_read_b64_tr_b16 v[138:139], v141 offset:19648
	v_cvt_pk_bf16_f32 v91, v78, v79
	v_exp_f32_e32 v48, v80
	v_cndmask_b32_e64 v54, 0, v54, s[58:59]
	v_cndmask_b32_e64 v55, 0, v55, s[60:61]
	v_cvt_pk_bf16_f32 v85, v50, v51
	v_cndmask_b32_e64 v48, 0, v48, s[46:47]
	s_waitcnt lgkmcnt(0)
	v_mfma_f32_32x32x16_bf16 v[16:31], v[136:139], v[92:95], v[16:31]
	ds_read_b64_tr_b16 v[92:93], v141 offset:20736
	ds_read_b64_tr_b16 v[94:95], v141 offset:21888
	v_cvt_pk_bf16_f32 v84, v48, v49
	v_cvt_pk_bf16_f32 v86, v52, v53
	v_cvt_pk_bf16_f32 v87, v54, v55
	v_cndmask_b32_e64 v56, 0, v56, s[62:63]
	v_cndmask_b32_e64 v57, 0, v57, s[64:65]
	v_cndmask_b32_e64 v58, 0, v58, s[66:67]
	s_waitcnt lgkmcnt(0)
	v_mfma_f32_32x32x16_bf16 v[32:47], v[92:95], v[88:91], v[32:47]
	ds_read_b64_tr_b16 v[92:93], v141 offset:20800
	ds_read_b64_tr_b16 v[94:95], v141 offset:21952
	v_cndmask_b32_e64 v59, 0, v59, s[68:69]
	v_cndmask_b32_e64 v60, 0, v60, s[70:71]
	v_cndmask_b32_e64 v61, 0, v61, s[72:73]
	v_cndmask_b32_e64 v62, 0, v62, s[74:75]
	v_cndmask_b32_e64 v63, 0, v63, s[44:45]
	v_cvt_pk_bf16_f32 v80, v56, v57
	s_waitcnt lgkmcnt(0)
	v_mfma_f32_32x32x16_bf16 v[16:31], v[92:95], v[88:91], v[16:31]
	ds_read_b64_tr_b16 v[88:89], v141 offset:23040
	ds_read_b64_tr_b16 v[90:91], v141 offset:24192
	v_cvt_pk_bf16_f32 v81, v58, v59
	v_cvt_pk_bf16_f32 v82, v60, v61
	v_cvt_pk_bf16_f32 v83, v62, v63
	s_waitcnt lgkmcnt(0)
	v_mfma_f32_32x32x16_bf16 v[32:47], v[88:91], v[84:87], v[32:47]
	ds_read_b64_tr_b16 v[88:89], v141 offset:23104
	ds_read_b64_tr_b16 v[90:91], v141 offset:24256
	s_waitcnt lgkmcnt(0)
	v_mfma_f32_32x32x16_bf16 v[16:31], v[88:91], v[84:87], v[16:31]
	ds_read_b64_tr_b16 v[84:85], v141 offset:25344
	ds_read_b64_tr_b16 v[86:87], v141 offset:26496
	s_waitcnt lgkmcnt(0)
	v_mfma_f32_32x32x16_bf16 v[32:47], v[84:87], v[80:83], v[32:47]
	ds_read_b64_tr_b16 v[84:85], v141 offset:25408
	ds_read_b64_tr_b16 v[86:87], v141 offset:26560
	s_waitcnt lgkmcnt(0)
	v_mfma_f32_32x32x16_bf16 v[16:31], v[84:87], v[80:83], v[16:31]
	s_branch .LBB0_437
.Lsbf_1:
	s_nop 0
	v_add_u32_e32 v143, s78, v197
	v_min_f32_e32 v84, 0x42c80000, v64
	s_nop 0
	v_exp_f32_e32 v64, v84
	v_min_f32_e32 v85, 0x42c80000, v65
	s_nop 0
	s_nop 0
	v_exp_f32_e32 v65, v85
	v_add_f32_e32 v64, 1.0, v64
	v_log_f32_e32 v64, v64
	s_nop 0
	v_add_f32_e32 v65, 1.0, v65
	v_log_f32_e32 v65, v65
	s_nop 0
	s_nop 0
	s_nop 0
	s_nop 0
	v_xor_b32_e32 v64, 0x80000000, v64
	v_add_f32_e32 v80, 0, v64
	v_xor_b32_e32 v65, 0x80000000, v65
	v_add_f32_e32 v81, v65, v80
	v_cvt_pk_bf16_f32 v80, v64, v65
	v_lshlrev_b32_e32 v82, 16, v80
	v_sub_f32_e32 v64, v64, v82
	v_and_b32_e32 v82, 0xffff0000, v80
	v_sub_f32_e32 v65, v65, v82
	v_cvt_pk_bf16_f32 v64, v64, v65
	s_nop 0
	v_min_f32_e32 v86, 0x42c80000, v66
	s_nop 0
	s_nop 0
	s_nop 0
	v_min_f32_e32 v87, 0x42c80000, v67
	s_nop 0
	s_nop 0
	v_exp_f32_e32 v65, v86
	s_nop 0
	v_exp_f32_e32 v67, v87
	s_nop 0
	v_add_f32_e32 v65, 1.0, v65
	v_log_f32_e32 v65, v65
	v_add_f32_e32 v67, 1.0, v67
	v_log_f32_e32 v67, v67
	s_nop 0
	v_xor_b32_e32 v65, 0x80000000, v65
	v_add_f32_e32 v66, v65, v81
	v_xor_b32_e32 v67, 0x80000000, v67
	v_cvt_pk_bf16_f32 v81, v65, v67
	v_lshlrev_b32_e32 v82, 16, v81
	v_sub_f32_e32 v65, v65, v82
	v_and_b32_e32 v82, 0xffff0000, v81
	v_add_f32_e32 v66, v67, v66
	v_sub_f32_e32 v67, v67, v82
	v_cvt_pk_bf16_f32 v65, v65, v67
	s_nop 0
	v_min_f32_e32 v88, 0x42c80000, v68
	s_nop 0
	s_nop 0
	s_nop 0
	v_min_f32_e32 v89, 0x42c80000, v69
	s_nop 0
	s_nop 0
	v_exp_f32_e32 v67, v88
	s_nop 0
	v_exp_f32_e32 v68, v89
	s_nop 0
	v_add_f32_e32 v67, 1.0, v67
	v_log_f32_e32 v67, v67
	v_add_f32_e32 v68, 1.0, v68
	v_log_f32_e32 v68, v68
	s_nop 0
	v_xor_b32_e32 v67, 0x80000000, v67
	v_add_f32_e32 v66, v67, v66
	v_xor_b32_e32 v68, 0x80000000, v68
	v_cvt_pk_bf16_f32 v82, v67, v68
	v_add_f32_e32 v69, v68, v66
	v_lshlrev_b32_e32 v66, 16, v82
	v_sub_f32_e32 v66, v67, v66
	v_and_b32_e32 v67, 0xffff0000, v82
	v_sub_f32_e32 v67, v68, v67
	v_cvt_pk_bf16_f32 v66, v66, v67
	s_nop 0
	v_min_f32_e32 v90, 0x42c80000, v70
	s_nop 0
	s_nop 0
	v_exp_f32_e32 v67, v90
	s_nop 0
	v_min_f32_e32 v156, 0x42c80000, v48
	v_min_f32_e32 v157, 0x42c80000, v49
	v_add_f32_e32 v67, 1.0, v67
	v_log_f32_e32 v67, v67
	s_nop 0
	v_exp_f32_e32 v48, v156
	s_mov_b32 s97, s96
	v_xor_b32_e32 v67, 0x80000000, v67
	v_add_f32_e32 v68, v67, v69
	s_nop 0
	v_min_f32_e32 v91, 0x42c80000, v71
	s_nop 0
	s_nop 0
	v_exp_f32_e32 v69, v91
	s_nop 0
	v_add_f32_e32 v48, 1.0, v48
	v_log_f32_e32 v48, v48
	v_add_f32_e32 v69, 1.0, v69
	v_log_f32_e32 v69, v69
	s_mov_b32 s98, s96
	s_mov_b32 s99, s96
	v_xor_b32_e32 v69, 0x80000000, v69
	v_cvt_pk_bf16_f32 v83, v67, v69
	v_lshlrev_b32_e32 v70, 16, v83
	v_sub_f32_e32 v67, v67, v70
	v_and_b32_e32 v70, 0xffff0000, v83
	v_add_f32_e32 v68, v69, v68
	v_sub_f32_e32 v69, v69, v70
	v_cvt_pk_bf16_f32 v67, v67, v69
	s_nop 0
	v_min_f32_e32 v92, 0x42c80000, v72
	s_nop 0
	s_nop 0
	s_nop 0
	v_min_f32_e32 v93, 0x42c80000, v73
	s_nop 0
	s_nop 0
	v_exp_f32_e32 v69, v92
	s_nop 0
	v_exp_f32_e32 v70, v93
	s_nop 0
	v_add_f32_e32 v69, 1.0, v69
	v_log_f32_e32 v69, v69
	v_add_f32_e32 v70, 1.0, v70
	v_log_f32_e32 v70, v70
	v_xor_b32_e32 v69, 0x80000000, v69
	v_add_f32_e32 v68, v69, v68
	v_xor_b32_e32 v70, 0x80000000, v70
	v_cvt_pk_bf16_f32 v72, v69, v70
	v_add_f32_e32 v71, v70, v68
	v_lshlrev_b32_e32 v68, 16, v72
	v_sub_f32_e32 v68, v69, v68
	v_and_b32_e32 v69, 0xffff0000, v72
	v_sub_f32_e32 v69, v70, v69
	v_cvt_pk_bf16_f32 v68, v68, v69
	s_nop 0
	v_min_f32_e32 v94, 0x42c80000, v74
	s_nop 0
	s_nop 0
	v_exp_f32_e32 v69, v94
	s_nop 0
; DI unsigned pk_bf16(float lo, float hi) { f32x2 v = {lo, hi}; bf2_t b = __builtin_convertvector(v, bf2_t); return __builtin_bit_cast(unsigned, b); }
; DI float bf_lo(unsigned u) { return __uint_as_float(u << 16); }
; DI float bf_hi(unsigned u) { return __uint_as_float(u & 0xffff0000u); }
; DI int crow(int i, int h) { return (i & 3) + 8 * (i >> 2) + 4 * h; }
; DI float fast_exp2(float x) { return __builtin_amdgcn_exp2f(x); }
; DI float fast_log2(float x) { return __builtin_amdgcn_logf(x); }
; template <int DQK, bool SB, bool SMAX>
; DI void attn_item(const Params& p, char* smem, int bh, int qb, float Mb) {
;     ...
;           for (int i2 = 0; i2 < 8; ++i2) {
;             float lk[2];
; #pragma unroll
;             for (int e = 0; e < 2; ++e) {
;               const int i = 2 * i2 + e;
;               const float z = fminf(st[kb][i], 100.f);
;               const int key = kb0 + kb * 32 + crow(i, h);
;               const bool valid = !diag || (key < query);
;               float l = -fast_log2(1.f + fast_exp2(z));
;               l = valid ? l : 0.f;
;               lk[e] = l;
;               tsum += l;
;               ca[kb][i] = z + carry;
;             }
;             const unsigned hp = pk_bf16(lk[0], lk[1]);
;             const unsigned lp = pk_bf16(lk[0] - bf_lo(hp), lk[1] - bf_hi(hp));
;             const int kk = kb * 2 + (i2 >> 2), w = i2 & 3;
;             hi[kk][2 * w] = (short)(hp & 0xffffu); hi[kk][2 * w + 1] = (short)(hp >> 16);
;             lo[kk][2 * w] = (short)(lp & 0xffffu); lo[kk][2 * w + 1] = (short)(lp >> 16);
;           }
	v_add_f32_e32 v69, 1.0, v69
	v_log_f32_e32 v69, v69
	s_nop 0
	v_xor_b32_e32 v69, 0x80000000, v69
	v_add_f32_e32 v70, v69, v71
	s_nop 0
	v_min_f32_e32 v95, 0x42c80000, v75
	s_nop 0
	s_nop 0
	v_exp_f32_e32 v71, v95
	s_nop 0
	v_add_f32_e32 v71, 1.0, v71
	v_log_f32_e32 v71, v71
	s_nop 0
	v_xor_b32_e32 v71, 0x80000000, v71
	v_cvt_pk_bf16_f32 v73, v69, v71
	v_lshlrev_b32_e32 v74, 16, v73
	v_sub_f32_e32 v69, v69, v74
	v_and_b32_e32 v74, 0xffff0000, v73
	v_add_f32_e32 v70, v71, v70
	v_sub_f32_e32 v71, v71, v74
	v_cvt_pk_bf16_f32 v69, v69, v71
	s_nop 0
	v_min_f32_e32 v154, 0x42c80000, v76
	s_nop 0
	s_nop 0
	s_nop 0
	v_min_f32_e32 v155, 0x42c80000, v77
	s_nop 0
	s_nop 0
	v_exp_f32_e32 v71, v154
	s_nop 0
	v_exp_f32_e32 v74, v155
	s_nop 0
	v_add_f32_e32 v71, 1.0, v71
	v_log_f32_e32 v71, v71
	v_add_f32_e32 v74, 1.0, v74
	v_log_f32_e32 v74, v74
	v_xor_b32_e32 v71, 0x80000000, v71
	v_add_f32_e32 v70, v71, v70
	v_xor_b32_e32 v75, 0x80000000, v74
	v_cvt_pk_bf16_f32 v74, v71, v75
	v_add_f32_e32 v76, v75, v70
	v_lshlrev_b32_e32 v70, 16, v74
	v_sub_f32_e32 v70, v71, v70
	v_and_b32_e32 v71, 0xffff0000, v74
	v_sub_f32_e32 v71, v75, v71
	v_cvt_pk_bf16_f32 v70, v70, v71
	s_nop 0
	v_min_f32_e32 v158, 0x42c80000, v78
	s_nop 0
	s_nop 0
	v_exp_f32_e32 v71, v158
	s_nop 0
	v_add_f32_e32 v71, 1.0, v71
	v_log_f32_e32 v71, v71
	s_nop 0
	v_xor_b32_e32 v71, 0x80000000, v71
	v_add_f32_e32 v75, v71, v76
	s_nop 0
	v_min_f32_e32 v159, 0x42c80000, v79
	s_nop 0
	s_nop 0
	v_exp_f32_e32 v76, v159
	s_nop 0
	v_add_f32_e32 v76, 1.0, v76
	v_log_f32_e32 v76, v76
	s_nop 0
	v_xor_b32_e32 v76, 0x80000000, v76
	v_add_f32_e32 v77, v76, v75
	v_cvt_pk_bf16_f32 v75, v71, v76
	v_lshlrev_b32_e32 v78, 16, v75
	v_sub_f32_e32 v71, v71, v78
	v_and_b32_e32 v78, 0xffff0000, v75
	v_sub_f32_e32 v76, v76, v78
	v_cvt_pk_bf16_f32 v71, v71, v76
	s_nop 0
	s_nop 0
	s_nop 0
	s_nop 0
	v_exp_f32_e32 v49, v157
	s_nop 0
	v_xor_b32_e32 v48, 0x80000000, v48
	v_add_f32_e32 v76, v48, v77
	v_add_f32_e32 v49, 1.0, v49
	v_log_f32_e32 v49, v49
	s_nop 0
	v_xor_b32_e32 v49, 0x80000000, v49
	v_cvt_pk_bf16_f32 v136, v48, v49
	v_add_f32_e32 v77, v49, v76
	v_lshlrev_b32_e32 v76, 16, v136
	v_sub_f32_e32 v48, v48, v76
	v_and_b32_e32 v76, 0xffff0000, v136
	v_sub_f32_e32 v49, v49, v76
	v_cvt_pk_bf16_f32 v76, v48, v49
	s_nop 0
	v_min_f32_e32 v160, 0x42c80000, v50
	s_nop 0
	s_nop 0
	s_nop 0
	v_min_f32_e32 v161, 0x42c80000, v51
	s_nop 0
	s_nop 0
	v_exp_f32_e32 v48, v160
	s_nop 0
	v_exp_f32_e32 v50, v161
	s_nop 0
	v_add_f32_e32 v48, 1.0, v48
	v_log_f32_e32 v48, v48
	v_add_f32_e32 v50, 1.0, v50
	v_log_f32_e32 v50, v50
	v_xor_b32_e32 v48, 0x80000000, v48
	v_add_f32_e32 v49, v48, v77
	v_xor_b32_e32 v50, 0x80000000, v50
	v_cvt_pk_bf16_f32 v137, v48, v50
	v_lshlrev_b32_e32 v51, 16, v137
	v_sub_f32_e32 v48, v48, v51
	v_and_b32_e32 v51, 0xffff0000, v137
	v_add_f32_e32 v49, v50, v49
	v_sub_f32_e32 v50, v50, v51
	v_cvt_pk_bf16_f32 v77, v48, v50
	s_nop 0
	v_min_f32_e32 v162, 0x42c80000, v52
	s_nop 0
	s_nop 0
	s_nop 0
	v_min_f32_e32 v163, 0x42c80000, v53
	s_nop 0
	s_nop 0
	v_exp_f32_e32 v48, v162
	s_nop 0
	v_exp_f32_e32 v50, v163
	s_nop 0
	v_add_f32_e32 v48, 1.0, v48
	v_log_f32_e32 v48, v48
	v_add_f32_e32 v50, 1.0, v50
	v_log_f32_e32 v50, v50
	v_add_f32_e32 v52, v152, v88
	v_add_f32_e32 v53, v152, v89
	v_xor_b32_e32 v48, 0x80000000, v48
	v_add_f32_e32 v49, v48, v49
	v_xor_b32_e32 v50, 0x80000000, v50
	v_cvt_pk_bf16_f32 v138, v48, v50
	v_lshlrev_b32_e32 v51, 16, v138
	v_sub_f32_e32 v48, v48, v51
	v_and_b32_e32 v51, 0xffff0000, v138
	v_add_f32_e32 v49, v50, v49
	v_sub_f32_e32 v50, v50, v51
	v_cvt_pk_bf16_f32 v78, v48, v50
	s_nop 0
	v_min_f32_e32 v164, 0x42c80000, v54
	s_nop 0
	s_nop 0
	s_nop 0
	v_min_f32_e32 v165, 0x42c80000, v55
	s_nop 0
	s_nop 0
	v_exp_f32_e32 v48, v164
	s_nop 0
	v_exp_f32_e32 v50, v165
	s_nop 0
	v_add_f32_e32 v48, 1.0, v48
	v_log_f32_e32 v48, v48
	v_add_f32_e32 v50, 1.0, v50
	v_log_f32_e32 v50, v50
	v_add_f32_e32 v54, v152, v90
	v_add_f32_e32 v55, v152, v91
	v_xor_b32_e32 v48, 0x80000000, v48
	v_add_f32_e32 v49, v48, v49
	v_xor_b32_e32 v50, 0x80000000, v50
	v_cvt_pk_bf16_f32 v139, v48, v50
	v_lshlrev_b32_e32 v51, 16, v139
	v_sub_f32_e32 v48, v48, v51
	v_and_b32_e32 v51, 0xffff0000, v139
	v_add_f32_e32 v49, v50, v49
	v_sub_f32_e32 v50, v50, v51
	v_cvt_pk_bf16_f32 v79, v48, v50
	s_nop 0
	v_min_f32_e32 v166, 0x42c80000, v56
	s_nop 0
	s_nop 0
	s_nop 0
	v_min_f32_e32 v167, 0x42c80000, v57
	s_nop 0
	s_nop 0
	v_exp_f32_e32 v48, v166
	s_nop 0
	v_exp_f32_e32 v50, v167
	s_nop 0
	v_add_f32_e32 v48, 1.0, v48
	v_log_f32_e32 v48, v48
	v_add_f32_e32 v50, 1.0, v50
	v_log_f32_e32 v50, v50
	v_add_f32_e32 v56, v152, v92
	v_add_f32_e32 v57, v152, v93
	v_xor_b32_e32 v48, 0x80000000, v48
	v_add_f32_e32 v49, v48, v49
	v_xor_b32_e32 v50, 0x80000000, v50
	v_cvt_pk_bf16_f32 v140, v48, v50
	v_lshlrev_b32_e32 v51, 16, v140
	v_sub_f32_e32 v48, v48, v51
	v_and_b32_e32 v51, 0xffff0000, v140
	v_add_f32_e32 v49, v50, v49
	v_sub_f32_e32 v50, v50, v51
	v_cvt_pk_bf16_f32 v144, v48, v50
	s_nop 0
	v_min_f32_e32 v168, 0x42c80000, v58
	s_nop 0
	s_nop 0
	s_nop 0
	v_min_f32_e32 v169, 0x42c80000, v59
	s_nop 0
	s_nop 0
	v_exp_f32_e32 v48, v168
	s_nop 0
	v_exp_f32_e32 v50, v169
	s_nop 0
	v_add_f32_e32 v48, 1.0, v48
	v_log_f32_e32 v48, v48
	v_add_f32_e32 v50, 1.0, v50
	v_log_f32_e32 v50, v50
	v_add_f32_e32 v58, v152, v94
	v_add_f32_e32 v59, v152, v95
	v_xor_b32_e32 v48, 0x80000000, v48
	v_add_f32_e32 v49, v48, v49
	v_xor_b32_e32 v50, 0x80000000, v50
	v_cvt_pk_bf16_f32 v141, v48, v50
	v_lshlrev_b32_e32 v51, 16, v141
	v_sub_f32_e32 v48, v48, v51
	v_and_b32_e32 v51, 0xffff0000, v141
	v_add_f32_e32 v49, v50, v49
	v_sub_f32_e32 v50, v50, v51
	v_cvt_pk_bf16_f32 v145, v48, v50
; template <int DQK, bool SB, bool SMAX>
; DI void attn_item(const Params& p, char* smem, int bh, int qb, float Mb) {
;     ...
;           for (int i2 = 0; i2 < 8; ++i2) {
;             float lk[2];
; #pragma unroll
;             for (int e = 0; e < 2; ++e) {
;               const int i = 2 * i2 + e;
;               const float z = fminf(st[kb][i], 100.f);
;               const int key = kb0 + kb * 32 + crow(i, h);
;               const bool valid = !diag || (key < query);
;               float l = -fast_log2(1.f + fast_exp2(z));
;               l = valid ? l : 0.f;
;               lk[e] = l;
;               tsum += l;
;               ca[kb][i] = z + carry;
;             }
;             const unsigned hp = pk_bf16(lk[0], lk[1]);
;             const unsigned lp = pk_bf16(lk[0] - bf_lo(hp), lk[1] - bf_hi(hp));
;             const int kk = kb * 2 + (i2 >> 2), w = i2 & 3;
;             hi[kk][2 * w] = (short)(hp & 0xffffu); hi[kk][2 * w + 1] = (short)(hp >> 16);
;             lo[kk][2 * w] = (short)(lp & 0xffffu); lo[kk][2 * w + 1] = (short)(lp >> 16);
;           }
;         tsum += other_half(tsum);
; #pragma unroll
;         for (int s = 0; s < 2; ++s) {
;           ca[0] = MFMA32(tri[s], hi[s], ca[0]);
;           ca[0] = MFMA32(tri[s], lo[s], ca[0]);
;           ca[0] = MFMA32(ones, hi[2 + s], ca[0]);
;           ca[0] = MFMA32(ones, lo[2 + s], ca[0]);
;           ca[1] = MFMA32(tri[s], hi[2 + s], ca[1]);
;           ca[1] = MFMA32(tri[s], lo[2 + s], ca[1]);
;         }
; #pragma unroll
;         for (int kb = 0; kb < 2; ++kb)
; #pragma unroll
;           for (int i = 0; i < 16; ++i) {
;             const int key = kb0 + kb * 32 + crow(i, h);
;             const bool valid = !diag || (key < query);
;             st[kb][i] = valid ? fast_exp2(ca[kb][i]) : 0.f;
;           }
;         carry += tsum;
;       }
; #pragma unroll
;       for (int kb = 0; kb < 2; ++kb)
; #pragma unroll
;         for (int s = 0; s < 2; ++s) {
;           u32x4 w;
; #pragma unroll
;           for (int e = 0; e < 4; ++e) w[e] = pk_bf16(st[kb][8 * s + 2 * e], st[kb][8 * s + 2 * e + 1]);
;           pk[kb * 2 + s] = __builtin_bit_cast(bf16x8, w);
;         }
; #pragma unroll
;       for (int kk = 0; kk < 4; ++kk)
; #pragma unroll
;         for (int db = 0; db < 2; ++db) {
;           const s16x4 v0 = __builtin_amdgcn_ds_read_tr16_b64_v4i16((lds_s16x4*)(vc + voff + (16 * kk) * VSTR + 32 * db));
	s_nop 0
	v_min_f32_e32 v170, 0x42c80000, v60
	s_nop 0
	s_nop 0
	s_nop 0
	v_min_f32_e32 v171, 0x42c80000, v61
	s_nop 0
	s_nop 0
	v_exp_f32_e32 v48, v170
	s_nop 0
	v_exp_f32_e32 v50, v171
	s_nop 0
	v_add_f32_e32 v48, 1.0, v48
	v_log_f32_e32 v48, v48
	v_add_f32_e32 v50, 1.0, v50
	v_log_f32_e32 v50, v50
	v_add_f32_e32 v60, v152, v154
	v_add_f32_e32 v61, v152, v155
	v_xor_b32_e32 v48, 0x80000000, v48
	v_add_f32_e32 v49, v48, v49
	v_xor_b32_e32 v50, 0x80000000, v50
	v_cvt_pk_bf16_f32 v142, v48, v50
	v_lshlrev_b32_e32 v51, 16, v142
	v_sub_f32_e32 v48, v48, v51
	v_and_b32_e32 v51, 0xffff0000, v142
	v_add_f32_e32 v49, v50, v49
	v_sub_f32_e32 v50, v50, v51
	v_cvt_pk_bf16_f32 v146, v48, v50
	s_nop 0
	v_min_f32_e32 v182, 0x42c80000, v62
	s_nop 0
	s_nop 0
	s_nop 0
	v_min_f32_e32 v183, 0x42c80000, v63
	s_nop 0
	s_nop 0
	v_exp_f32_e32 v48, v182
	s_nop 0
	v_exp_f32_e32 v50, v183
	s_nop 0
	v_add_f32_e32 v48, 1.0, v48
	v_log_f32_e32 v48, v48
	v_add_f32_e32 v50, 1.0, v50
	v_log_f32_e32 v50, v50
	v_add_f32_e32 v62, v152, v158
	v_add_f32_e32 v63, v152, v159
	v_xor_b32_e32 v48, 0x80000000, v48
	v_add_f32_e32 v49, v48, v49
	v_xor_b32_e32 v50, 0x80000000, v50
	v_cvt_pk_bf16_f32 v143, v48, v50
	v_add_f32_e32 v184, v50, v49
	v_lshlrev_b32_e32 v49, 16, v143
	v_sub_f32_e32 v48, v48, v49
	v_and_b32_e32 v49, 0xffff0000, v143
	v_sub_f32_e32 v49, v50, v49
	v_cvt_pk_bf16_f32 v147, v48, v49
	v_mov_b32_e32 v48, v184
	v_mov_b32_e32 v49, v184
	s_nop 1
	v_permlane32_swap_b32_e32 v48, v49
	v_cndmask_b32_e64 v185, v48, v49, s[8:9]
	v_add_f32_e32 v50, v152, v86
	v_add_f32_e32 v51, v152, v87
	v_add_f32_e32 v48, v152, v84
	v_add_f32_e32 v49, v152, v85
	v_add_f32_e32 v94, v152, v182
	v_add_f32_e32 v95, v152, v183
	v_add_f32_e32 v92, v152, v170
	v_add_f32_e32 v93, v152, v171
	v_mfma_f32_32x32x16_bf16 v[48:63], v[96:99], v[80:83], v[48:63]
	v_add_f32_e32 v90, v152, v168
	v_add_f32_e32 v91, v152, v169
	v_add_f32_e32 v88, v152, v166
	v_add_f32_e32 v89, v152, v167
	v_add_f32_e32 v86, v152, v164
	v_add_f32_e32 v87, v152, v165
	v_add_f32_e32 v84, v152, v162
	v_add_f32_e32 v85, v152, v163
	v_add_f32_e32 v82, v152, v160
	v_add_f32_e32 v83, v152, v161
	v_add_f32_e32 v80, v152, v156
	v_add_f32_e32 v81, v152, v157
	v_mfma_f32_32x32x16_bf16 v[48:63], v[96:99], v[64:67], v[48:63]
	v_mov_b64_e32 v[64:65], s[96:97]
	v_mov_b64_e32 v[66:67], s[98:99]
	s_nop 1
	v_mfma_f32_32x32x16_bf16 v[48:63], v[64:67], v[136:139], v[48:63]
	v_mfma_f32_32x32x16_bf16 v[48:63], v[64:67], v[76:79], v[48:63]
	v_mfma_f32_32x32x16_bf16 v[48:63], v[100:103], v[72:75], v[48:63]
	v_mfma_f32_32x32x16_bf16 v[48:63], v[100:103], v[68:71], v[48:63]
	v_mfma_f32_32x32x16_bf16 v[48:63], v[64:67], v[140:143], v[48:63]
	v_mfma_f32_32x32x16_bf16 v[48:63], v[64:67], v[144:147], v[48:63]
	v_mfma_f32_32x32x16_bf16 v[80:95], v[96:99], v[136:139], v[80:95]
	s_nop 10
	v_exp_f32_e32 v64, v48
	s_nop 0
	s_nop 0
	v_exp_f32_e32 v65, v49
	v_mfma_f32_32x32x16_bf16 v[80:95], v[96:99], v[76:79], v[80:95]
	s_nop 0
	v_exp_f32_e32 v66, v50
	s_nop 0
	s_nop 0
	v_exp_f32_e32 v67, v51
	v_mfma_f32_32x32x16_bf16 v[80:95], v[100:103], v[140:143], v[80:95]
	v_add_u32_e32 v141, v198, v200
	ds_read_b64_tr_b16 v[136:137], v141 offset:18432
	ds_read_b64_tr_b16 v[138:139], v141 offset:19584
	s_nop 0
	v_exp_f32_e32 v68, v52
	v_add_f32_e32 v140, v184, v185
	v_add_f32_e32 v152, v152, v140
	s_nop 0
	v_exp_f32_e32 v69, v53
	v_mfma_f32_32x32x16_bf16 v[80:95], v[100:103], v[144:147], v[80:95]
	s_nop 0
	v_exp_f32_e32 v70, v54
	s_nop 0
	s_nop 0
	v_exp_f32_e32 v71, v55
	s_nop 6
	v_exp_f32_e32 v49, v81
	v_exp_f32_e32 v50, v82
	v_exp_f32_e32 v51, v83
	s_nop 0
	v_exp_f32_e32 v72, v56
	v_exp_f32_e32 v56, v88
	v_exp_f32_e32 v52, v84
	v_exp_f32_e32 v53, v85
	s_nop 0
	v_exp_f32_e32 v73, v57
	v_exp_f32_e32 v57, v89
	v_exp_f32_e32 v54, v86
	v_exp_f32_e32 v55, v87
	s_nop 0
	v_exp_f32_e32 v74, v58
	v_exp_f32_e32 v58, v90
	v_cvt_pk_bf16_f32 v88, v72, v73
	s_nop 0
	s_nop 0
	v_exp_f32_e32 v75, v59
	v_exp_f32_e32 v59, v91
	s_nop 0
	s_nop 0
	s_nop 0
	v_exp_f32_e32 v76, v60
	v_exp_f32_e32 v60, v92
	v_cvt_pk_bf16_f32 v92, v64, v65
	v_cvt_pk_bf16_f32 v89, v74, v75
	s_nop 0
	v_exp_f32_e32 v77, v61
	v_exp_f32_e32 v61, v93
	v_cvt_pk_bf16_f32 v93, v66, v67
	s_nop 0
	s_nop 0
	v_exp_f32_e32 v78, v62
	v_exp_f32_e32 v62, v94
	v_cvt_pk_bf16_f32 v94, v68, v69
	v_cvt_pk_bf16_f32 v90, v76, v77
	s_nop 0
	v_exp_f32_e32 v79, v63
	v_exp_f32_e32 v63, v95
	v_cvt_pk_bf16_f32 v95, v70, v71
	s_nop 0
	s_nop 0
	s_waitcnt lgkmcnt(0)
	v_mfma_f32_32x32x16_bf16 v[32:47], v[136:139], v[92:95], v[32:47]
	ds_read_b64_tr_b16 v[136:137], v141 offset:18496
	ds_read_b64_tr_b16 v[138:139], v141 offset:19648
	v_cvt_pk_bf16_f32 v91, v78, v79
	v_exp_f32_e32 v48, v80
	s_nop 0
	s_nop 0
	v_cvt_pk_bf16_f32 v85, v50, v51
	s_nop 0
	s_waitcnt lgkmcnt(0)
	v_mfma_f32_32x32x16_bf16 v[16:31], v[136:139], v[92:95], v[16:31]
	ds_read_b64_tr_b16 v[92:93], v141 offset:20736
	ds_read_b64_tr_b16 v[94:95], v141 offset:21888
	v_cvt_pk_bf16_f32 v84, v48, v49
	v_cvt_pk_bf16_f32 v86, v52, v53
	v_cvt_pk_bf16_f32 v87, v54, v55
	s_nop 0
	s_nop 0
	s_nop 0
	s_waitcnt lgkmcnt(0)
	v_mfma_f32_32x32x16_bf16 v[32:47], v[92:95], v[88:91], v[32:47]
	ds_read_b64_tr_b16 v[92:93], v141 offset:20800
	ds_read_b64_tr_b16 v[94:95], v141 offset:21952
	s_nop 0
	s_nop 0
	s_nop 0
	s_nop 0
	s_nop 0
	v_cvt_pk_bf16_f32 v80, v56, v57
	s_waitcnt lgkmcnt(0)
	v_mfma_f32_32x32x16_bf16 v[16:31], v[92:95], v[88:91], v[16:31]
	ds_read_b64_tr_b16 v[88:89], v141 offset:23040
	ds_read_b64_tr_b16 v[90:91], v141 offset:24192
	v_cvt_pk_bf16_f32 v81, v58, v59
	v_cvt_pk_bf16_f32 v82, v60, v61
	v_cvt_pk_bf16_f32 v83, v62, v63
	s_waitcnt lgkmcnt(0)
	v_mfma_f32_32x32x16_bf16 v[32:47], v[88:91], v[84:87], v[32:47]
	ds_read_b64_tr_b16 v[88:89], v141 offset:23104
	ds_read_b64_tr_b16 v[90:91], v141 offset:24256
	s_waitcnt lgkmcnt(0)
	v_mfma_f32_32x32x16_bf16 v[16:31], v[88:91], v[84:87], v[16:31]
	ds_read_b64_tr_b16 v[84:85], v141 offset:25344
	ds_read_b64_tr_b16 v[86:87], v141 offset:26496
	s_waitcnt lgkmcnt(0)
	v_mfma_f32_32x32x16_bf16 v[32:47], v[84:87], v[80:83], v[32:47]
	ds_read_b64_tr_b16 v[84:85], v141 offset:25408
	ds_read_b64_tr_b16 v[86:87], v141 offset:26560
	s_waitcnt lgkmcnt(0)
	v_mfma_f32_32x32x16_bf16 v[16:31], v[84:87], v[80:83], v[16:31]

; DI unsigned pk_bf16(float lo, float hi) { f32x2 v = {lo, hi}; bf2_t b = __builtin_convertvector(v, bf2_t); return __builtin_bit_cast(unsigned, b); }
; DI float bf_lo(unsigned u) { return __uint_as_float(u << 16); }
; DI float bf_hi(unsigned u) { return __uint_as_float(u & 0xffff0000u); }
; DI int crow(int i, int h) { return (i & 3) + 8 * (i >> 2) + 4 * h; }
; DI float fast_exp2(float x) { return __builtin_amdgcn_exp2f(x); }
; DI float fast_log2(float x) { return __builtin_amdgcn_logf(x); }
; template <int DQK, bool SB, bool SMAX>
; DI void attn_item(const Params& p, char* smem, int bh, int qb, float Mb) {
;     ...
;           for (int i2 = 0; i2 < 8; ++i2) {
;             float lk[2];
; #pragma unroll
;             for (int e = 0; e < 2; ++e) {
;               const int i = 2 * i2 + e;
;               const float z = fminf(st[kb][i], 100.f);
;               const int key = kb0 + kb * 32 + crow(i, h);
;               const bool valid = !diag || (key < query);
;               float l = -fast_log2(1.f + fast_exp2(z));
;               l = valid ? l : 0.f;
;               lk[e] = l;
;               tsum += l;
;               ca[kb][i] = z + carry;
;             }
;             const unsigned hp = pk_bf16(lk[0], lk[1]);
;             const unsigned lp = pk_bf16(lk[0] - bf_lo(hp), lk[1] - bf_hi(hp));
;             const int kk = kb * 2 + (i2 >> 2), w = i2 & 3;
;             hi[kk][2 * w] = (short)(hp & 0xffffu); hi[kk][2 * w + 1] = (short)(hp >> 16);
;             lo[kk][2 * w] = (short)(lp & 0xffffu); lo[kk][2 * w + 1] = (short)(lp >> 16);
;           }
.LBB0_442:
	s_or_b64 exec, exec, s[2:3]
	s_add_i32 s2, s4, 1
	s_xor_b32 s3, s4, 0x3fffffe
	s_add_i32 s3, s3, s1
	s_lshl_b32 s3, s3, 6
	s_cmp_lt_u32 s2, s1
	s_cselect_b32 s2, s3, 0
	s_ashr_i32 s3, s2, 31
	s_lshl_b64 s[2:3], s[2:3], 7
	v_lshl_add_u64 v[80:81], v[148:149], 0, s[2:3]
	s_waitcnt vmcnt(3)
	ds_write_b128 v203, v[120:123]
	s_waitcnt vmcnt(2)
	ds_write_b128 v204, v[124:127]
	s_waitcnt vmcnt(1)
	ds_write_b128 v203, v[128:131] offset:18432
	s_waitcnt vmcnt(0)
	ds_write_b128 v204, v[132:135] offset:18432
	v_add_co_u32_e32 v82, vcc, s7, v80
	s_nop 1
	v_addc_co_u32_e32 v83, vcc, 0, v81, vcc
	global_load_dwordx4 v[120:123], v[80:81], off
	global_load_dwordx4 v[124:127], v[82:83], off
	v_lshl_add_u64 v[80:81], v[150:151], 0, s[2:3]
	v_add_co_u32_e32 v82, vcc, 0x1000, v80
	s_nop 1
	v_addc_co_u32_e32 v83, vcc, 0, v81, vcc
	global_load_dwordx4 v[128:131], v[80:81], off
	global_load_dwordx4 v[132:135], v[82:83], off
	s_and_saveexec_b64 s[80:81], s[12:13]
	s_cbranch_execz .LBB0_444
	v_cmp_le_i32_e64 s[44:45], s14, v181
	s_nop 0
	s_cmp_eq_u64 s[44:45], exec
	s_cbranch_scc1 .Lsbf_2
	s_nop 0
	v_add_u32_e32 v143, s78, v197
	v_min_f32_e32 v84, 0x42c80000, v64
	s_nop 0
	v_exp_f32_e32 v64, v84
	v_min_f32_e32 v85, 0x42c80000, v65
	v_add_u32_e32 v65, 0x41, v143
	v_cmp_lt_i32_e64 s[2:3], v65, v176
	v_exp_f32_e32 v65, v85
	v_add_f32_e32 v64, 1.0, v64
	v_log_f32_e32 v64, v64
	v_add_u32_e32 v80, 64, v143
	v_add_f32_e32 v65, 1.0, v65
	v_log_f32_e32 v65, v65
	v_cmp_le_i32_e64 s[44:45], s14, v181
	v_cmp_lt_i32_e32 vcc, v80, v176
	s_or_b64 vcc, s[44:45], vcc
	s_or_b64 s[12:13], s[44:45], s[2:3]
	v_cndmask_b32_e64 v64, 0, -v64, vcc
	v_add_f32_e32 v80, 0, v64
	v_cndmask_b32_e64 v65, 0, -v65, s[12:13]
	v_add_f32_e32 v81, v65, v80
	v_cvt_pk_bf16_f32 v80, v64, v65
	v_lshlrev_b32_e32 v82, 16, v80
	v_sub_f32_e32 v64, v64, v82
	v_and_b32_e32 v82, 0xffff0000, v80
	v_sub_f32_e32 v65, v65, v82
	v_cvt_pk_bf16_f32 v64, v64, v65
	s_nop 0
	v_min_f32_e32 v86, 0x42c80000, v66
	v_add_u32_e32 v65, 0x42, v143
	s_nop 0
	v_cmp_lt_i32_e64 s[2:3], v65, v176
	v_min_f32_e32 v87, 0x42c80000, v67
	v_add_u32_e32 v67, 0x43, v143
	s_or_b64 s[14:15], s[44:45], s[2:3]
	v_exp_f32_e32 v65, v86
	v_cmp_lt_i32_e64 s[2:3], v67, v176
	v_exp_f32_e32 v67, v87
	s_or_b64 s[16:17], s[44:45], s[2:3]
	v_add_f32_e32 v65, 1.0, v65
	v_log_f32_e32 v65, v65
	v_add_f32_e32 v67, 1.0, v67
	v_log_f32_e32 v67, v67
	s_nop 0
	v_cndmask_b32_e64 v65, 0, -v65, s[14:15]
	v_add_f32_e32 v66, v65, v81
	v_cndmask_b32_e64 v67, 0, -v67, s[16:17]
	v_cvt_pk_bf16_f32 v81, v65, v67
	v_lshlrev_b32_e32 v82, 16, v81
	v_sub_f32_e32 v65, v65, v82
	v_and_b32_e32 v82, 0xffff0000, v81
	v_add_f32_e32 v66, v67, v66
	v_sub_f32_e32 v67, v67, v82
	v_cvt_pk_bf16_f32 v65, v65, v67
	s_nop 0
	v_min_f32_e32 v88, 0x42c80000, v68
	v_add_u32_e32 v67, 0x48, v143
	s_nop 0
	v_cmp_lt_i32_e64 s[2:3], v67, v176
	v_min_f32_e32 v89, 0x42c80000, v69
	v_add_u32_e32 v68, 0x49, v143
	s_or_b64 s[18:19], s[44:45], s[2:3]
	v_exp_f32_e32 v67, v88
	v_cmp_lt_i32_e64 s[2:3], v68, v176
	v_exp_f32_e32 v68, v89
	s_or_b64 s[20:21], s[44:45], s[2:3]
	v_add_f32_e32 v67, 1.0, v67
	v_log_f32_e32 v67, v67
	v_add_f32_e32 v68, 1.0, v68
	v_log_f32_e32 v68, v68
	s_nop 0
	v_cndmask_b32_e64 v67, 0, -v67, s[18:19]
	v_add_f32_e32 v66, v67, v66
	v_cndmask_b32_e64 v68, 0, -v68, s[20:21]
	v_cvt_pk_bf16_f32 v82, v67, v68
	v_add_f32_e32 v69, v68, v66
	v_lshlrev_b32_e32 v66, 16, v82
	v_sub_f32_e32 v66, v67, v66
	v_and_b32_e32 v67, 0xffff0000, v82
	v_sub_f32_e32 v67, v68, v67
	v_cvt_pk_bf16_f32 v66, v66, v67
	s_nop 0
	v_min_f32_e32 v90, 0x42c80000, v70
	v_add_u32_e32 v67, 0x4a, v143
	v_cmp_lt_i32_e64 s[2:3], v67, v176
	v_exp_f32_e32 v67, v90
	s_or_b64 s[22:23], s[44:45], s[2:3]
	v_min_f32_e32 v156, 0x42c80000, v48
	v_min_f32_e32 v157, 0x42c80000, v49
	v_add_f32_e32 v67, 1.0, v67
	v_log_f32_e32 v67, v67
	v_add_u32_e32 v49, 0x61, v143
	v_exp_f32_e32 v48, v156
	s_mov_b32 s97, s96
	v_cndmask_b32_e64 v67, 0, -v67, s[22:23]
	v_add_f32_e32 v68, v67, v69
	s_nop 0
	v_min_f32_e32 v91, 0x42c80000, v71
	v_add_u32_e32 v69, 0x4b, v143
	v_cmp_lt_i32_e64 s[2:3], v69, v176
	v_exp_f32_e32 v69, v91
	s_or_b64 s[24:25], s[44:45], s[2:3]
	v_add_f32_e32 v48, 1.0, v48
	v_log_f32_e32 v48, v48
	v_add_f32_e32 v69, 1.0, v69
	v_log_f32_e32 v69, v69
	s_mov_b32 s98, s96
	s_mov_b32 s99, s96
	v_cndmask_b32_e64 v69, 0, -v69, s[24:25]
	v_cvt_pk_bf16_f32 v83, v67, v69
	v_lshlrev_b32_e32 v70, 16, v83
	v_sub_f32_e32 v67, v67, v70
	v_and_b32_e32 v70, 0xffff0000, v83
	v_add_f32_e32 v68, v69, v68
	v_sub_f32_e32 v69, v69, v70
	v_cvt_pk_bf16_f32 v67, v67, v69
	s_nop 0
	v_min_f32_e32 v92, 0x42c80000, v72
	v_add_u32_e32 v69, 0x50, v143
	s_nop 0
	v_cmp_lt_i32_e64 s[2:3], v69, v176
	v_min_f32_e32 v93, 0x42c80000, v73
	v_add_u32_e32 v70, 0x51, v143
	s_or_b64 s[26:27], s[44:45], s[2:3]
	v_exp_f32_e32 v69, v92
	v_cmp_lt_i32_e64 s[2:3], v70, v176
	v_exp_f32_e32 v70, v93
	s_or_b64 s[28:29], s[44:45], s[2:3]
	v_add_f32_e32 v69, 1.0, v69
	v_log_f32_e32 v69, v69
	v_add_f32_e32 v70, 1.0, v70
	v_log_f32_e32 v70, v70
	v_cndmask_b32_e64 v69, 0, -v69, s[26:27]
	v_add_f32_e32 v68, v69, v68
	v_cndmask_b32_e64 v70, 0, -v70, s[28:29]
	v_cvt_pk_bf16_f32 v72, v69, v70
	v_add_f32_e32 v71, v70, v68
	v_lshlrev_b32_e32 v68, 16, v72
	v_sub_f32_e32 v68, v69, v68
	v_and_b32_e32 v69, 0xffff0000, v72
	v_sub_f32_e32 v69, v70, v69
	v_cvt_pk_bf16_f32 v68, v68, v69
	s_nop 0
	v_min_f32_e32 v94, 0x42c80000, v74
	v_add_u32_e32 v69, 0x52, v143
	v_cmp_lt_i32_e64 s[2:3], v69, v176
	v_exp_f32_e32 v69, v94
	s_or_b64 s[30:31], s[44:45], s[2:3]
	v_add_f32_e32 v69, 1.0, v69
	v_log_f32_e32 v69, v69
	s_nop 0
	v_cndmask_b32_e64 v69, 0, -v69, s[30:31]
	v_add_f32_e32 v70, v69, v71
; DI unsigned pk_bf16(float lo, float hi) { f32x2 v = {lo, hi}; bf2_t b = __builtin_convertvector(v, bf2_t); return __builtin_bit_cast(unsigned, b); }
; DI float bf_lo(unsigned u) { return __uint_as_float(u << 16); }
; DI float bf_hi(unsigned u) { return __uint_as_float(u & 0xffff0000u); }
; DI int crow(int i, int h) { return (i & 3) + 8 * (i >> 2) + 4 * h; }
; DI float fast_exp2(float x) { return __builtin_amdgcn_exp2f(x); }
; DI float fast_log2(float x) { return __builtin_amdgcn_logf(x); }
; template <int DQK, bool SB, bool SMAX>
; DI void attn_item(const Params& p, char* smem, int bh, int qb, float Mb) {
;     ...
;           for (int i2 = 0; i2 < 8; ++i2) {
;             float lk[2];
; #pragma unroll
;             for (int e = 0; e < 2; ++e) {
;               const int i = 2 * i2 + e;
;               const float z = fminf(st[kb][i], 100.f);
;               const int key = kb0 + kb * 32 + crow(i, h);
;               const bool valid = !diag || (key < query);
;               float l = -fast_log2(1.f + fast_exp2(z));
;               l = valid ? l : 0.f;
;               lk[e] = l;
;               tsum += l;
;               ca[kb][i] = z + carry;
;             }
;             const unsigned hp = pk_bf16(lk[0], lk[1]);
;             const unsigned lp = pk_bf16(lk[0] - bf_lo(hp), lk[1] - bf_hi(hp));
;             const int kk = kb * 2 + (i2 >> 2), w = i2 & 3;
;             hi[kk][2 * w] = (short)(hp & 0xffffu); hi[kk][2 * w + 1] = (short)(hp >> 16);
;             lo[kk][2 * w] = (short)(lp & 0xffffu); lo[kk][2 * w + 1] = (short)(lp >> 16);
;           }
	s_nop 0
	v_min_f32_e32 v95, 0x42c80000, v75
	v_add_u32_e32 v71, 0x53, v143
	v_cmp_lt_i32_e64 s[2:3], v71, v176
	v_exp_f32_e32 v71, v95
	s_or_b64 s[34:35], s[44:45], s[2:3]
	v_add_f32_e32 v71, 1.0, v71
	v_log_f32_e32 v71, v71
	s_nop 0
	v_cndmask_b32_e64 v71, 0, -v71, s[34:35]
	v_cvt_pk_bf16_f32 v73, v69, v71
	v_lshlrev_b32_e32 v74, 16, v73
	v_sub_f32_e32 v69, v69, v74
	v_and_b32_e32 v74, 0xffff0000, v73
	v_add_f32_e32 v70, v71, v70
	v_sub_f32_e32 v71, v71, v74
	v_cvt_pk_bf16_f32 v69, v69, v71
	s_nop 0
	v_min_f32_e32 v154, 0x42c80000, v76
	v_add_u32_e32 v71, 0x58, v143
	s_nop 0
	v_cmp_lt_i32_e64 s[2:3], v71, v176
	v_min_f32_e32 v155, 0x42c80000, v77
	v_add_u32_e32 v74, 0x59, v143
	s_or_b64 s[36:37], s[44:45], s[2:3]
	v_exp_f32_e32 v71, v154
	v_cmp_lt_i32_e64 s[2:3], v74, v176
	v_exp_f32_e32 v74, v155
	s_or_b64 s[38:39], s[44:45], s[2:3]
	v_add_f32_e32 v71, 1.0, v71
	v_log_f32_e32 v71, v71
	v_add_f32_e32 v74, 1.0, v74
	v_log_f32_e32 v74, v74
	v_cndmask_b32_e64 v71, 0, -v71, s[36:37]
	v_add_f32_e32 v70, v71, v70
	v_cndmask_b32_e64 v75, 0, -v74, s[38:39]
	v_cvt_pk_bf16_f32 v74, v71, v75
	v_add_f32_e32 v76, v75, v70
	v_lshlrev_b32_e32 v70, 16, v74
	v_sub_f32_e32 v70, v71, v70
	v_and_b32_e32 v71, 0xffff0000, v74
	v_sub_f32_e32 v71, v75, v71
	v_cvt_pk_bf16_f32 v70, v70, v71
	s_nop 0
	v_min_f32_e32 v158, 0x42c80000, v78
	v_add_u32_e32 v71, 0x5a, v143
	v_cmp_lt_i32_e64 s[2:3], v71, v176
	v_exp_f32_e32 v71, v158
	s_or_b64 s[40:41], s[44:45], s[2:3]
	v_add_f32_e32 v71, 1.0, v71
	v_log_f32_e32 v71, v71
	s_nop 0
	v_cndmask_b32_e64 v71, 0, -v71, s[40:41]
	v_add_f32_e32 v75, v71, v76
	s_nop 0
	v_min_f32_e32 v159, 0x42c80000, v79
	v_add_u32_e32 v76, 0x5b, v143
	v_cmp_lt_i32_e64 s[2:3], v76, v176
	v_exp_f32_e32 v76, v159
	s_or_b64 s[42:43], s[44:45], s[2:3]
	v_add_f32_e32 v76, 1.0, v76
	v_log_f32_e32 v76, v76
	s_nop 0
	v_cndmask_b32_e64 v76, 0, -v76, s[42:43]
	v_add_f32_e32 v77, v76, v75
	v_cvt_pk_bf16_f32 v75, v71, v76
	v_lshlrev_b32_e32 v78, 16, v75
	v_sub_f32_e32 v71, v71, v78
	v_and_b32_e32 v78, 0xffff0000, v75
	v_sub_f32_e32 v76, v76, v78
	v_cvt_pk_bf16_f32 v71, v71, v76
	v_add_u32_e32 v76, 0x60, v143
	v_cmp_lt_i32_e64 s[2:3], v76, v176
	s_or_b64 s[46:47], s[44:45], s[2:3]
	v_cmp_lt_i32_e64 s[2:3], v49, v176
	v_exp_f32_e32 v49, v157
	s_or_b64 s[48:49], s[44:45], s[2:3]
	v_cndmask_b32_e64 v48, 0, -v48, s[46:47]
	v_add_f32_e32 v76, v48, v77
	v_add_f32_e32 v49, 1.0, v49
	v_log_f32_e32 v49, v49
	s_nop 0
	v_cndmask_b32_e64 v49, 0, -v49, s[48:49]
	v_cvt_pk_bf16_f32 v136, v48, v49
	v_add_f32_e32 v77, v49, v76
	v_lshlrev_b32_e32 v76, 16, v136
	v_sub_f32_e32 v48, v48, v76
	v_and_b32_e32 v76, 0xffff0000, v136
	v_sub_f32_e32 v49, v49, v76
	v_cvt_pk_bf16_f32 v76, v48, v49
	s_nop 0
	v_min_f32_e32 v160, 0x42c80000, v50
	v_add_u32_e32 v48, 0x62, v143
	s_nop 0
	v_cmp_lt_i32_e64 s[2:3], v48, v176
	v_min_f32_e32 v161, 0x42c80000, v51
	v_add_u32_e32 v50, 0x63, v143
	s_or_b64 s[50:51], s[44:45], s[2:3]
	v_exp_f32_e32 v48, v160
	v_cmp_lt_i32_e64 s[2:3], v50, v176
	v_exp_f32_e32 v50, v161
	s_or_b64 s[52:53], s[44:45], s[2:3]
	v_add_f32_e32 v48, 1.0, v48
	v_log_f32_e32 v48, v48
	v_add_f32_e32 v50, 1.0, v50
	v_log_f32_e32 v50, v50
	v_cndmask_b32_e64 v48, 0, -v48, s[50:51]
	v_add_f32_e32 v49, v48, v77
	v_cndmask_b32_e64 v50, 0, -v50, s[52:53]
	v_cvt_pk_bf16_f32 v137, v48, v50
	v_lshlrev_b32_e32 v51, 16, v137
	v_sub_f32_e32 v48, v48, v51
	v_and_b32_e32 v51, 0xffff0000, v137
	v_add_f32_e32 v49, v50, v49
	v_sub_f32_e32 v50, v50, v51
	v_cvt_pk_bf16_f32 v77, v48, v50
	s_nop 0
	v_min_f32_e32 v162, 0x42c80000, v52
	v_add_u32_e32 v48, 0x68, v143
	s_nop 0
	v_cmp_lt_i32_e64 s[2:3], v48, v176
	v_min_f32_e32 v163, 0x42c80000, v53
	v_add_u32_e32 v50, 0x69, v143
	s_or_b64 s[54:55], s[44:45], s[2:3]
	v_exp_f32_e32 v48, v162
	v_cmp_lt_i32_e64 s[2:3], v50, v176
	v_exp_f32_e32 v50, v163
	s_or_b64 s[56:57], s[44:45], s[2:3]
	v_add_f32_e32 v48, 1.0, v48
	v_log_f32_e32 v48, v48
	v_add_f32_e32 v50, 1.0, v50
	v_log_f32_e32 v50, v50
	v_add_f32_e32 v52, v152, v88
	v_add_f32_e32 v53, v152, v89
	v_cndmask_b32_e64 v48, 0, -v48, s[54:55]
	v_add_f32_e32 v49, v48, v49
	v_cndmask_b32_e64 v50, 0, -v50, s[56:57]
	v_cvt_pk_bf16_f32 v138, v48, v50
	v_lshlrev_b32_e32 v51, 16, v138
	v_sub_f32_e32 v48, v48, v51
	v_and_b32_e32 v51, 0xffff0000, v138
	v_add_f32_e32 v49, v50, v49
	v_sub_f32_e32 v50, v50, v51
	v_cvt_pk_bf16_f32 v78, v48, v50
	s_nop 0
	v_min_f32_e32 v164, 0x42c80000, v54
	v_add_u32_e32 v48, 0x6a, v143
	s_nop 0
	v_cmp_lt_i32_e64 s[2:3], v48, v176
	v_min_f32_e32 v165, 0x42c80000, v55
	v_add_u32_e32 v50, 0x6b, v143
	s_or_b64 s[58:59], s[44:45], s[2:3]
	v_exp_f32_e32 v48, v164
	v_cmp_lt_i32_e64 s[2:3], v50, v176
	v_exp_f32_e32 v50, v165
	s_or_b64 s[60:61], s[44:45], s[2:3]
	v_add_f32_e32 v48, 1.0, v48
	v_log_f32_e32 v48, v48
	v_add_f32_e32 v50, 1.0, v50
	v_log_f32_e32 v50, v50
	v_add_f32_e32 v54, v152, v90
	v_add_f32_e32 v55, v152, v91
	v_cndmask_b32_e64 v48, 0, -v48, s[58:59]
	v_add_f32_e32 v49, v48, v49
	v_cndmask_b32_e64 v50, 0, -v50, s[60:61]
	v_cvt_pk_bf16_f32 v139, v48, v50
	v_lshlrev_b32_e32 v51, 16, v139
	v_sub_f32_e32 v48, v48, v51
	v_and_b32_e32 v51, 0xffff0000, v139
	v_add_f32_e32 v49, v50, v49
	v_sub_f32_e32 v50, v50, v51
	v_cvt_pk_bf16_f32 v79, v48, v50
	s_nop 0
	v_min_f32_e32 v166, 0x42c80000, v56
	v_add_u32_e32 v48, 0x70, v143
	s_nop 0
	v_cmp_lt_i32_e64 s[2:3], v48, v176
	v_min_f32_e32 v167, 0x42c80000, v57
	v_add_u32_e32 v50, 0x71, v143
	s_or_b64 s[62:63], s[44:45], s[2:3]
	v_exp_f32_e32 v48, v166
	v_cmp_lt_i32_e64 s[2:3], v50, v176
	v_exp_f32_e32 v50, v167
	s_or_b64 s[64:65], s[44:45], s[2:3]
	v_add_f32_e32 v48, 1.0, v48
	v_log_f32_e32 v48, v48
	v_add_f32_e32 v50, 1.0, v50
; template <int DQK, bool SB, bool SMAX>
; DI void attn_item(const Params& p, char* smem, int bh, int qb, float Mb) {
;     ...
;           for (int i2 = 0; i2 < 8; ++i2) {
;             float lk[2];
; #pragma unroll
;             for (int e = 0; e < 2; ++e) {
;               const int i = 2 * i2 + e;
;               const float z = fminf(st[kb][i], 100.f);
;               const int key = kb0 + kb * 32 + crow(i, h);
;               const bool valid = !diag || (key < query);
;               float l = -fast_log2(1.f + fast_exp2(z));
;               l = valid ? l : 0.f;
;               lk[e] = l;
;               tsum += l;
;               ca[kb][i] = z + carry;
;             }
;             const unsigned hp = pk_bf16(lk[0], lk[1]);
;             const unsigned lp = pk_bf16(lk[0] - bf_lo(hp), lk[1] - bf_hi(hp));
;             const int kk = kb * 2 + (i2 >> 2), w = i2 & 3;
;             hi[kk][2 * w] = (short)(hp & 0xffffu); hi[kk][2 * w + 1] = (short)(hp >> 16);
;             lo[kk][2 * w] = (short)(lp & 0xffffu); lo[kk][2 * w + 1] = (short)(lp >> 16);
;           }
;         tsum += other_half(tsum);
; #pragma unroll
;         for (int s = 0; s < 2; ++s) {
;           ca[0] = MFMA32(tri[s], hi[s], ca[0]);
;           ca[0] = MFMA32(tri[s], lo[s], ca[0]);
;           ca[0] = MFMA32(ones, hi[2 + s], ca[0]);
;           ca[0] = MFMA32(ones, lo[2 + s], ca[0]);
;           ca[1] = MFMA32(tri[s], hi[2 + s], ca[1]);
;           ca[1] = MFMA32(tri[s], lo[2 + s], ca[1]);
;         }
; #pragma unroll
;         for (int kb = 0; kb < 2; ++kb)
; #pragma unroll
;           for (int i = 0; i < 16; ++i) {
;             const int key = kb0 + kb * 32 + crow(i, h);
;             const bool valid = !diag || (key < query);
;             st[kb][i] = valid ? fast_exp2(ca[kb][i]) : 0.f;
;           }
;         carry += tsum;
;       }
; #pragma unroll
;       for (int kb = 0; kb < 2; ++kb)
; #pragma unroll
;         for (int s = 0; s < 2; ++s) {
;           u32x4 w;
; #pragma unroll
;           for (int e = 0; e < 4; ++e) w[e] = pk_bf16(st[kb][8 * s + 2 * e], st[kb][8 * s + 2 * e + 1]);
;           pk[kb * 2 + s] = __builtin_bit_cast(bf16x8, w);
;         }
; #pragma unroll
;       for (int kk = 0; kk < 4; ++kk)
; #pragma unroll
;         for (int db = 0; db < 2; ++db) {
;           const s16x4 v0 = __builtin_amdgcn_ds_read_tr16_b64_v4i16((lds_s16x4*)(vc + voff + (16 * kk) * VSTR + 32 * db));
	v_log_f32_e32 v50, v50
	v_add_f32_e32 v56, v152, v92
	v_add_f32_e32 v57, v152, v93
	v_cndmask_b32_e64 v48, 0, -v48, s[62:63]
	v_add_f32_e32 v49, v48, v49
	v_cndmask_b32_e64 v50, 0, -v50, s[64:65]
	v_cvt_pk_bf16_f32 v140, v48, v50
	v_lshlrev_b32_e32 v51, 16, v140
	v_sub_f32_e32 v48, v48, v51
	v_and_b32_e32 v51, 0xffff0000, v140
	v_add_f32_e32 v49, v50, v49
	v_sub_f32_e32 v50, v50, v51
	v_cvt_pk_bf16_f32 v144, v48, v50
	s_nop 0
	v_min_f32_e32 v168, 0x42c80000, v58
	v_add_u32_e32 v48, 0x72, v143
	s_nop 0
	v_cmp_lt_i32_e64 s[2:3], v48, v176
	v_min_f32_e32 v169, 0x42c80000, v59
	v_add_u32_e32 v50, 0x73, v143
	s_or_b64 s[66:67], s[44:45], s[2:3]
	v_exp_f32_e32 v48, v168
	v_cmp_lt_i32_e64 s[2:3], v50, v176
	v_exp_f32_e32 v50, v169
	s_or_b64 s[68:69], s[44:45], s[2:3]
	v_add_f32_e32 v48, 1.0, v48
	v_log_f32_e32 v48, v48
	v_add_f32_e32 v50, 1.0, v50
	v_log_f32_e32 v50, v50
	v_add_f32_e32 v58, v152, v94
	v_add_f32_e32 v59, v152, v95
	v_cndmask_b32_e64 v48, 0, -v48, s[66:67]
	v_add_f32_e32 v49, v48, v49
	v_cndmask_b32_e64 v50, 0, -v50, s[68:69]
	v_cvt_pk_bf16_f32 v141, v48, v50
	v_lshlrev_b32_e32 v51, 16, v141
	v_sub_f32_e32 v48, v48, v51
	v_and_b32_e32 v51, 0xffff0000, v141
	v_add_f32_e32 v49, v50, v49
	v_sub_f32_e32 v50, v50, v51
	v_cvt_pk_bf16_f32 v145, v48, v50
	s_nop 0
	v_min_f32_e32 v170, 0x42c80000, v60
	v_add_u32_e32 v48, 0x78, v143
	s_nop 0
	v_cmp_lt_i32_e64 s[2:3], v48, v176
	v_min_f32_e32 v171, 0x42c80000, v61
	v_add_u32_e32 v50, 0x79, v143
	s_or_b64 s[70:71], s[44:45], s[2:3]
	v_exp_f32_e32 v48, v170
	v_cmp_lt_i32_e64 s[2:3], v50, v176
	v_exp_f32_e32 v50, v171
	s_or_b64 s[72:73], s[44:45], s[2:3]
	v_add_f32_e32 v48, 1.0, v48
	v_log_f32_e32 v48, v48
	v_add_f32_e32 v50, 1.0, v50
	v_log_f32_e32 v50, v50
	v_add_f32_e32 v60, v152, v154
	v_add_f32_e32 v61, v152, v155
	v_cndmask_b32_e64 v48, 0, -v48, s[70:71]
	v_add_f32_e32 v49, v48, v49
	v_cndmask_b32_e64 v50, 0, -v50, s[72:73]
	v_cvt_pk_bf16_f32 v142, v48, v50
	v_lshlrev_b32_e32 v51, 16, v142
	v_sub_f32_e32 v48, v48, v51
	v_and_b32_e32 v51, 0xffff0000, v142
	v_add_f32_e32 v49, v50, v49
	v_sub_f32_e32 v50, v50, v51
	v_cvt_pk_bf16_f32 v146, v48, v50
	s_nop 0
	v_min_f32_e32 v182, 0x42c80000, v62
	v_add_u32_e32 v48, 0x7a, v143
	s_nop 0
	v_cmp_lt_i32_e64 s[2:3], v48, v176
	v_min_f32_e32 v183, 0x42c80000, v63
	v_add_u32_e32 v50, 0x7b, v143
	s_or_b64 s[74:75], s[44:45], s[2:3]
	v_exp_f32_e32 v48, v182
	v_cmp_lt_i32_e64 s[2:3], v50, v176
	v_exp_f32_e32 v50, v183
	s_or_b64 s[44:45], s[44:45], s[2:3]
	v_add_f32_e32 v48, 1.0, v48
	v_log_f32_e32 v48, v48
	v_add_f32_e32 v50, 1.0, v50
	v_log_f32_e32 v50, v50
	v_add_f32_e32 v62, v152, v158
	v_add_f32_e32 v63, v152, v159
	v_cndmask_b32_e64 v48, 0, -v48, s[74:75]
	v_add_f32_e32 v49, v48, v49
	v_cndmask_b32_e64 v50, 0, -v50, s[44:45]
	v_cvt_pk_bf16_f32 v143, v48, v50
	v_add_f32_e32 v184, v50, v49
	v_lshlrev_b32_e32 v49, 16, v143
	v_sub_f32_e32 v48, v48, v49
	v_and_b32_e32 v49, 0xffff0000, v143
	v_sub_f32_e32 v49, v50, v49
	v_cvt_pk_bf16_f32 v147, v48, v49
	v_mov_b32_e32 v48, v184
	v_mov_b32_e32 v49, v184
	s_nop 1
	v_permlane32_swap_b32_e32 v48, v49
	v_cndmask_b32_e64 v185, v48, v49, s[8:9]
	v_add_f32_e32 v50, v152, v86
	v_add_f32_e32 v51, v152, v87
	v_add_f32_e32 v48, v152, v84
	v_add_f32_e32 v49, v152, v85
	v_add_f32_e32 v94, v152, v182
	v_add_f32_e32 v95, v152, v183
	v_add_f32_e32 v92, v152, v170
	v_add_f32_e32 v93, v152, v171
	v_mfma_f32_32x32x16_bf16 v[48:63], v[96:99], v[80:83], v[48:63]
	v_add_f32_e32 v90, v152, v168
	v_add_f32_e32 v91, v152, v169
	v_add_f32_e32 v88, v152, v166
	v_add_f32_e32 v89, v152, v167
	v_add_f32_e32 v86, v152, v164
	v_add_f32_e32 v87, v152, v165
	v_add_f32_e32 v84, v152, v162
	v_add_f32_e32 v85, v152, v163
	v_add_f32_e32 v82, v152, v160
	v_add_f32_e32 v83, v152, v161
	v_add_f32_e32 v80, v152, v156
	v_add_f32_e32 v81, v152, v157
	v_mfma_f32_32x32x16_bf16 v[48:63], v[96:99], v[64:67], v[48:63]
	v_mov_b64_e32 v[64:65], s[96:97]
	v_mov_b64_e32 v[66:67], s[98:99]
	s_nop 1
	v_mfma_f32_32x32x16_bf16 v[48:63], v[64:67], v[136:139], v[48:63]
	v_mfma_f32_32x32x16_bf16 v[48:63], v[64:67], v[76:79], v[48:63]
	v_mfma_f32_32x32x16_bf16 v[48:63], v[100:103], v[72:75], v[48:63]
	v_mfma_f32_32x32x16_bf16 v[48:63], v[100:103], v[68:71], v[48:63]
	v_mfma_f32_32x32x16_bf16 v[48:63], v[64:67], v[140:143], v[48:63]
	v_mfma_f32_32x32x16_bf16 v[48:63], v[64:67], v[144:147], v[48:63]
	v_mfma_f32_32x32x16_bf16 v[80:95], v[96:99], v[136:139], v[80:95]
	s_nop 10
	v_exp_f32_e32 v48, v48
	s_nop 0
	v_cndmask_b32_e32 v64, 0, v48, vcc
	v_exp_f32_e32 v48, v49
	v_mfma_f32_32x32x16_bf16 v[80:95], v[96:99], v[76:79], v[80:95]
	v_cndmask_b32_e64 v65, 0, v48, s[12:13]
	v_exp_f32_e32 v48, v50
	s_nop 0
	v_cndmask_b32_e64 v66, 0, v48, s[14:15]
	v_exp_f32_e32 v48, v51
	v_mfma_f32_32x32x16_bf16 v[80:95], v[100:103], v[140:143], v[80:95]
	v_cndmask_b32_e64 v67, 0, v48, s[16:17]
	v_exp_f32_e32 v48, v52
	s_nop 0
	v_cndmask_b32_e64 v68, 0, v48, s[18:19]
	v_exp_f32_e32 v48, v53
	v_mfma_f32_32x32x16_bf16 v[80:95], v[100:103], v[144:147], v[80:95]
	v_cndmask_b32_e64 v69, 0, v48, s[20:21]
	v_exp_f32_e32 v48, v54
	s_nop 0
	v_cndmask_b32_e64 v70, 0, v48, s[22:23]
	v_exp_f32_e32 v48, v55
	s_nop 6
	v_exp_f32_e32 v53, v85
	v_add_u32_e32 v85, v198, v200
	ds_read_b64_tr_b16 v[140:141], v85 offset:27648
	ds_read_b64_tr_b16 v[142:143], v85 offset:28800
	v_cndmask_b32_e64 v71, 0, v48, s[24:25]
	v_exp_f32_e32 v48, v56
	v_exp_f32_e32 v54, v86
	v_exp_f32_e32 v55, v87
	v_exp_f32_e32 v56, v88
	v_cndmask_b32_e64 v72, 0, v48, s[26:27]
	v_exp_f32_e32 v48, v57
	v_exp_f32_e32 v57, v89
	v_cvt_pk_bf16_f32 v86, v64, v65
	v_cvt_pk_bf16_f32 v87, v66, v67
	v_cndmask_b32_e64 v73, 0, v48, s[28:29]
	v_exp_f32_e32 v48, v58
	v_cvt_pk_bf16_f32 v88, v68, v69
	v_cvt_pk_bf16_f32 v89, v70, v71
	v_exp_f32_e32 v58, v90
	v_cndmask_b32_e64 v74, 0, v48, s[30:31]
	v_exp_f32_e32 v48, v59
	s_waitcnt lgkmcnt(0)
; #define MFMA32(a, b, c) __builtin_amdgcn_mfma_f32_32x32x16_bf16((a), (b), (c), 0, 0, 0)
; DI unsigned pk_bf16(float lo, float hi) { f32x2 v = {lo, hi}; bf2_t b = __builtin_convertvector(v, bf2_t); return __builtin_bit_cast(unsigned, b); }
; DI float bf_lo(unsigned u) { return __uint_as_float(u << 16); }
; DI float bf_hi(unsigned u) { return __uint_as_float(u & 0xffff0000u); }
; DI int crow(int i, int h) { return (i & 3) + 8 * (i >> 2) + 4 * h; }
; template <int DQK, bool SB, bool SMAX>
; DI void attn_item(const Params& p, char* smem, int bh, int qb, float Mb) {
;     ...
;           for (int i2 = 0; i2 < 8; ++i2) {
;             float lk[2];
; #pragma unroll
;             for (int e = 0; e < 2; ++e) {
;               const int i = 2 * i2 + e;
;               const float z = fminf(st[kb][i], 100.f);
;               const int key = kb0 + kb * 32 + crow(i, h);
;               const bool valid = !diag || (key < query);
;               float l = -fast_log2(1.f + fast_exp2(z));
;               l = valid ? l : 0.f;
;               lk[e] = l;
;               tsum += l;
;               ca[kb][i] = z + carry;
;             }
;             const unsigned hp = pk_bf16(lk[0], lk[1]);
;             const unsigned lp = pk_bf16(lk[0] - bf_lo(hp), lk[1] - bf_hi(hp));
;             const int kk = kb * 2 + (i2 >> 2), w = i2 & 3;
;             hi[kk][2 * w] = (short)(hp & 0xffffu); hi[kk][2 * w + 1] = (short)(hp >> 16);
;             lo[kk][2 * w] = (short)(lp & 0xffffu); lo[kk][2 * w + 1] = (short)(lp >> 16);
;           }
;     ...
;         carry += tsum;
;       }
; #pragma unroll
;       for (int kb = 0; kb < 2; ++kb)
; #pragma unroll
;         for (int s = 0; s < 2; ++s) {
;           u32x4 w;
; #pragma unroll
;           for (int e = 0; e < 4; ++e) w[e] = pk_bf16(st[kb][8 * s + 2 * e], st[kb][8 * s + 2 * e + 1]);
;           pk[kb * 2 + s] = __builtin_bit_cast(bf16x8, w);
;         }
; #pragma unroll
;       for (int kk = 0; kk < 4; ++kk)
; #pragma unroll
;         for (int db = 0; db < 2; ++db) {
;           const s16x4 v0 = __builtin_amdgcn_ds_read_tr16_b64_v4i16((lds_s16x4*)(vc + voff + (16 * kk) * VSTR + 32 * db));
;           const s16x4 v1 = __builtin_amdgcn_ds_read_tr16_b64_v4i16((lds_s16x4*)(vc + voff + (16 * kk + 8) * VSTR + 32 * db));
;           const bf16x8 vf = __builtin_shufflevector(v0, v1, 0, 1, 2, 3, 4, 5, 6, 7);
;           O[db] = MFMA32(vf, pk[kk], O[db]);
;         }
	v_mfma_f32_32x32x16_bf16 v[32:47], v[140:143], v[86:89], v[32:47]
	ds_read_b64_tr_b16 v[140:141], v85 offset:27712
	ds_read_b64_tr_b16 v[142:143], v85 offset:28864
	v_exp_f32_e32 v59, v91
	v_cndmask_b32_e64 v75, 0, v48, s[34:35]
	v_exp_f32_e32 v48, v60
	v_exp_f32_e32 v60, v92
	v_cvt_pk_bf16_f32 v90, v72, v73
	v_cvt_pk_bf16_f32 v91, v74, v75
	v_cndmask_b32_e64 v76, 0, v48, s[36:37]
	v_exp_f32_e32 v48, v61
	s_waitcnt lgkmcnt(0)
	v_mfma_f32_32x32x16_bf16 v[16:31], v[140:143], v[86:89], v[16:31]
	ds_read_b64_tr_b16 v[86:87], v85 offset:29952
	ds_read_b64_tr_b16 v[88:89], v85 offset:31104
	v_exp_f32_e32 v61, v93
	v_cndmask_b32_e64 v77, 0, v48, s[38:39]
	v_exp_f32_e32 v48, v62
	v_cvt_pk_bf16_f32 v92, v76, v77
	v_exp_f32_e32 v49, v81
	v_exp_f32_e32 v50, v82
	v_cndmask_b32_e64 v78, 0, v48, s[40:41]
	v_exp_f32_e32 v48, v63
	v_exp_f32_e32 v51, v83
	v_exp_f32_e32 v52, v84
	v_cndmask_b32_e64 v49, 0, v49, s[48:49]
	v_cndmask_b32_e64 v79, 0, v48, s[42:43]
	v_cvt_pk_bf16_f32 v93, v78, v79
	v_exp_f32_e32 v48, v80
	v_cndmask_b32_e64 v50, 0, v50, s[50:51]
	s_waitcnt lgkmcnt(0)
	v_mfma_f32_32x32x16_bf16 v[32:47], v[86:89], v[90:93], v[32:47]
	ds_read_b64_tr_b16 v[86:87], v85 offset:30016
	ds_read_b64_tr_b16 v[88:89], v85 offset:31168
	v_cndmask_b32_e64 v48, 0, v48, s[46:47]
	v_cndmask_b32_e64 v51, 0, v51, s[52:53]
	v_cndmask_b32_e64 v52, 0, v52, s[54:55]
	v_cndmask_b32_e64 v53, 0, v53, s[56:57]
	v_cndmask_b32_e64 v54, 0, v54, s[58:59]
	v_cndmask_b32_e64 v55, 0, v55, s[60:61]
	s_waitcnt lgkmcnt(0)
	v_mfma_f32_32x32x16_bf16 v[16:31], v[86:89], v[90:93], v[16:31]
	ds_read_b64_tr_b16 v[86:87], v85 offset:32256
	ds_read_b64_tr_b16 v[88:89], v85 offset:33408
	v_cvt_pk_bf16_f32 v136, v48, v49
	v_cvt_pk_bf16_f32 v137, v50, v51
	v_cvt_pk_bf16_f32 v138, v52, v53
	v_cvt_pk_bf16_f32 v139, v54, v55
	v_exp_f32_e32 v62, v94
	v_exp_f32_e32 v63, v95
	s_waitcnt lgkmcnt(0)
	v_mfma_f32_32x32x16_bf16 v[32:47], v[86:89], v[136:139], v[32:47]
	ds_read_b64_tr_b16 v[86:87], v85 offset:32320
	ds_read_b64_tr_b16 v[88:89], v85 offset:33472
	v_cndmask_b32_e64 v56, 0, v56, s[62:63]
	v_cndmask_b32_e64 v57, 0, v57, s[64:65]
	v_cndmask_b32_e64 v58, 0, v58, s[66:67]
	v_cndmask_b32_e64 v59, 0, v59, s[68:69]
	v_cndmask_b32_e64 v60, 0, v60, s[70:71]
	v_cndmask_b32_e64 v61, 0, v61, s[72:73]
	s_waitcnt lgkmcnt(0)
	v_mfma_f32_32x32x16_bf16 v[16:31], v[86:89], v[136:139], v[16:31]
	ds_read_b64_tr_b16 v[86:87], v85 offset:34560
	ds_read_b64_tr_b16 v[88:89], v85 offset:35712
	v_cndmask_b32_e64 v62, 0, v62, s[74:75]
	v_cndmask_b32_e64 v63, 0, v63, s[44:45]
	v_cvt_pk_bf16_f32 v80, v56, v57
	v_cvt_pk_bf16_f32 v81, v58, v59
	v_cvt_pk_bf16_f32 v82, v60, v61
	v_cvt_pk_bf16_f32 v83, v62, v63
	v_add_f32_e32 v84, v184, v185
	v_add_f32_e32 v152, v152, v84
	s_waitcnt lgkmcnt(0)
	v_mfma_f32_32x32x16_bf16 v[32:47], v[86:89], v[80:83], v[32:47]
	ds_read_b64_tr_b16 v[86:87], v85 offset:34624
	ds_read_b64_tr_b16 v[88:89], v85 offset:35776
	s_waitcnt lgkmcnt(0)
	v_mfma_f32_32x32x16_bf16 v[16:31], v[86:89], v[80:83], v[16:31]
	s_branch .LBB0_444
.Lsbf_2:
	s_nop 0
	v_add_u32_e32 v143, s78, v197
	v_min_f32_e32 v84, 0x42c80000, v64
	s_nop 0
	v_exp_f32_e32 v64, v84
	v_min_f32_e32 v85, 0x42c80000, v65
	s_nop 0
	s_nop 0
	v_exp_f32_e32 v65, v85
	v_add_f32_e32 v64, 1.0, v64
	v_log_f32_e32 v64, v64
	s_nop 0
	v_add_f32_e32 v65, 1.0, v65
	v_log_f32_e32 v65, v65
	s_nop 0
	s_nop 0
	s_nop 0
	s_nop 0
	v_xor_b32_e32 v64, 0x80000000, v64
	v_add_f32_e32 v80, 0, v64
	v_xor_b32_e32 v65, 0x80000000, v65
	v_add_f32_e32 v81, v65, v80
	v_cvt_pk_bf16_f32 v80, v64, v65
	v_lshlrev_b32_e32 v82, 16, v80
	v_sub_f32_e32 v64, v64, v82
	v_and_b32_e32 v82, 0xffff0000, v80
	v_sub_f32_e32 v65, v65, v82
	v_cvt_pk_bf16_f32 v64, v64, v65
	s_nop 0
	v_min_f32_e32 v86, 0x42c80000, v66
	s_nop 0
	s_nop 0
	s_nop 0
	v_min_f32_e32 v87, 0x42c80000, v67
	s_nop 0
	s_nop 0
	v_exp_f32_e32 v65, v86
	s_nop 0
	v_exp_f32_e32 v67, v87
	s_nop 0
	v_add_f32_e32 v65, 1.0, v65
	v_log_f32_e32 v65, v65
	v_add_f32_e32 v67, 1.0, v67
	v_log_f32_e32 v67, v67
	s_nop 0
	v_xor_b32_e32 v65, 0x80000000, v65
	v_add_f32_e32 v66, v65, v81
	v_xor_b32_e32 v67, 0x80000000, v67
	v_cvt_pk_bf16_f32 v81, v65, v67
	v_lshlrev_b32_e32 v82, 16, v81
	v_sub_f32_e32 v65, v65, v82
	v_and_b32_e32 v82, 0xffff0000, v81
	v_add_f32_e32 v66, v67, v66
	v_sub_f32_e32 v67, v67, v82
	v_cvt_pk_bf16_f32 v65, v65, v67
	s_nop 0
	v_min_f32_e32 v88, 0x42c80000, v68
	s_nop 0
	s_nop 0
	s_nop 0
	v_min_f32_e32 v89, 0x42c80000, v69
	s_nop 0
	s_nop 0
	v_exp_f32_e32 v67, v88
	s_nop 0
	v_exp_f32_e32 v68, v89
	s_nop 0
	v_add_f32_e32 v67, 1.0, v67
	v_log_f32_e32 v67, v67
	v_add_f32_e32 v68, 1.0, v68
	v_log_f32_e32 v68, v68
	s_nop 0
	v_xor_b32_e32 v67, 0x80000000, v67
	v_add_f32_e32 v66, v67, v66
	v_xor_b32_e32 v68, 0x80000000, v68
	v_cvt_pk_bf16_f32 v82, v67, v68
	v_add_f32_e32 v69, v68, v66
	v_lshlrev_b32_e32 v66, 16, v82
	v_sub_f32_e32 v66, v67, v66
	v_and_b32_e32 v67, 0xffff0000, v82
	v_sub_f32_e32 v67, v68, v67
	v_cvt_pk_bf16_f32 v66, v66, v67
	s_nop 0
	v_min_f32_e32 v90, 0x42c80000, v70
	s_nop 0
	s_nop 0
	v_exp_f32_e32 v67, v90
	s_nop 0
	v_min_f32_e32 v156, 0x42c80000, v48
	v_min_f32_e32 v157, 0x42c80000, v49
	v_add_f32_e32 v67, 1.0, v67
	v_log_f32_e32 v67, v67
	s_nop 0
	v_exp_f32_e32 v48, v156
	s_mov_b32 s97, s96
	v_xor_b32_e32 v67, 0x80000000, v67
	v_add_f32_e32 v68, v67, v69
	s_nop 0
	v_min_f32_e32 v91, 0x42c80000, v71
	s_nop 0
	s_nop 0
	v_exp_f32_e32 v69, v91
	s_nop 0
	v_add_f32_e32 v48, 1.0, v48
	v_log_f32_e32 v48, v48
	v_add_f32_e32 v69, 1.0, v69
	v_log_f32_e32 v69, v69
	s_mov_b32 s98, s96
	s_mov_b32 s99, s96
	v_xor_b32_e32 v69, 0x80000000, v69
	v_cvt_pk_bf16_f32 v83, v67, v69
	v_lshlrev_b32_e32 v70, 16, v83
; DI unsigned pk_bf16(float lo, float hi) { f32x2 v = {lo, hi}; bf2_t b = __builtin_convertvector(v, bf2_t); return __builtin_bit_cast(unsigned, b); }
; DI float bf_lo(unsigned u) { return __uint_as_float(u << 16); }
; DI float bf_hi(unsigned u) { return __uint_as_float(u & 0xffff0000u); }
; DI int crow(int i, int h) { return (i & 3) + 8 * (i >> 2) + 4 * h; }
; DI float fast_exp2(float x) { return __builtin_amdgcn_exp2f(x); }
; DI float fast_log2(float x) { return __builtin_amdgcn_logf(x); }
; template <int DQK, bool SB, bool SMAX>
; DI void attn_item(const Params& p, char* smem, int bh, int qb, float Mb) {
;     ...
;           for (int i2 = 0; i2 < 8; ++i2) {
;             float lk[2];
; #pragma unroll
;             for (int e = 0; e < 2; ++e) {
;               const int i = 2 * i2 + e;
;               const float z = fminf(st[kb][i], 100.f);
;               const int key = kb0 + kb * 32 + crow(i, h);
;               const bool valid = !diag || (key < query);
;               float l = -fast_log2(1.f + fast_exp2(z));
;               l = valid ? l : 0.f;
;               lk[e] = l;
;               tsum += l;
;               ca[kb][i] = z + carry;
;             }
;             const unsigned hp = pk_bf16(lk[0], lk[1]);
;             const unsigned lp = pk_bf16(lk[0] - bf_lo(hp), lk[1] - bf_hi(hp));
;             const int kk = kb * 2 + (i2 >> 2), w = i2 & 3;
;             hi[kk][2 * w] = (short)(hp & 0xffffu); hi[kk][2 * w + 1] = (short)(hp >> 16);
;             lo[kk][2 * w] = (short)(lp & 0xffffu); lo[kk][2 * w + 1] = (short)(lp >> 16);
;           }
	v_sub_f32_e32 v67, v67, v70
	v_and_b32_e32 v70, 0xffff0000, v83
	v_add_f32_e32 v68, v69, v68
	v_sub_f32_e32 v69, v69, v70
	v_cvt_pk_bf16_f32 v67, v67, v69
	s_nop 0
	v_min_f32_e32 v92, 0x42c80000, v72
	s_nop 0
	s_nop 0
	s_nop 0
	v_min_f32_e32 v93, 0x42c80000, v73
	s_nop 0
	s_nop 0
	v_exp_f32_e32 v69, v92
	s_nop 0
	v_exp_f32_e32 v70, v93
	s_nop 0
	v_add_f32_e32 v69, 1.0, v69
	v_log_f32_e32 v69, v69
	v_add_f32_e32 v70, 1.0, v70
	v_log_f32_e32 v70, v70
	v_xor_b32_e32 v69, 0x80000000, v69
	v_add_f32_e32 v68, v69, v68
	v_xor_b32_e32 v70, 0x80000000, v70
	v_cvt_pk_bf16_f32 v72, v69, v70
	v_add_f32_e32 v71, v70, v68
	v_lshlrev_b32_e32 v68, 16, v72
	v_sub_f32_e32 v68, v69, v68
	v_and_b32_e32 v69, 0xffff0000, v72
	v_sub_f32_e32 v69, v70, v69
	v_cvt_pk_bf16_f32 v68, v68, v69
	s_nop 0
	v_min_f32_e32 v94, 0x42c80000, v74
	s_nop 0
	s_nop 0
	v_exp_f32_e32 v69, v94
	s_nop 0
	v_add_f32_e32 v69, 1.0, v69
	v_log_f32_e32 v69, v69
	s_nop 0
	v_xor_b32_e32 v69, 0x80000000, v69
	v_add_f32_e32 v70, v69, v71
	s_nop 0
	v_min_f32_e32 v95, 0x42c80000, v75
	s_nop 0
	s_nop 0
	v_exp_f32_e32 v71, v95
	s_nop 0
	v_add_f32_e32 v71, 1.0, v71
	v_log_f32_e32 v71, v71
	s_nop 0
	v_xor_b32_e32 v71, 0x80000000, v71
	v_cvt_pk_bf16_f32 v73, v69, v71
	v_lshlrev_b32_e32 v74, 16, v73
	v_sub_f32_e32 v69, v69, v74
	v_and_b32_e32 v74, 0xffff0000, v73
	v_add_f32_e32 v70, v71, v70
	v_sub_f32_e32 v71, v71, v74
	v_cvt_pk_bf16_f32 v69, v69, v71
	s_nop 0
	v_min_f32_e32 v154, 0x42c80000, v76
	s_nop 0
	s_nop 0
	s_nop 0
	v_min_f32_e32 v155, 0x42c80000, v77
	s_nop 0
	s_nop 0
	v_exp_f32_e32 v71, v154
	s_nop 0
	v_exp_f32_e32 v74, v155
	s_nop 0
	v_add_f32_e32 v71, 1.0, v71
	v_log_f32_e32 v71, v71
	v_add_f32_e32 v74, 1.0, v74
	v_log_f32_e32 v74, v74
	v_xor_b32_e32 v71, 0x80000000, v71
	v_add_f32_e32 v70, v71, v70
	v_xor_b32_e32 v75, 0x80000000, v74
	v_cvt_pk_bf16_f32 v74, v71, v75
	v_add_f32_e32 v76, v75, v70
	v_lshlrev_b32_e32 v70, 16, v74
	v_sub_f32_e32 v70, v71, v70
	v_and_b32_e32 v71, 0xffff0000, v74
	v_sub_f32_e32 v71, v75, v71
	v_cvt_pk_bf16_f32 v70, v70, v71
	s_nop 0
	v_min_f32_e32 v158, 0x42c80000, v78
	s_nop 0
	s_nop 0
	v_exp_f32_e32 v71, v158
	s_nop 0
	v_add_f32_e32 v71, 1.0, v71
	v_log_f32_e32 v71, v71
	s_nop 0
	v_xor_b32_e32 v71, 0x80000000, v71
	v_add_f32_e32 v75, v71, v76
	s_nop 0
	v_min_f32_e32 v159, 0x42c80000, v79
	s_nop 0
	s_nop 0
	v_exp_f32_e32 v76, v159
	s_nop 0
	v_add_f32_e32 v76, 1.0, v76
	v_log_f32_e32 v76, v76
	s_nop 0
	v_xor_b32_e32 v76, 0x80000000, v76
	v_add_f32_e32 v77, v76, v75
	v_cvt_pk_bf16_f32 v75, v71, v76
	v_lshlrev_b32_e32 v78, 16, v75
	v_sub_f32_e32 v71, v71, v78
	v_and_b32_e32 v78, 0xffff0000, v75
	v_sub_f32_e32 v76, v76, v78
	v_cvt_pk_bf16_f32 v71, v71, v76
	s_nop 0
	s_nop 0
	s_nop 0
	s_nop 0
	v_exp_f32_e32 v49, v157
	s_nop 0
	v_xor_b32_e32 v48, 0x80000000, v48
	v_add_f32_e32 v76, v48, v77
	v_add_f32_e32 v49, 1.0, v49
	v_log_f32_e32 v49, v49
	s_nop 0
	v_xor_b32_e32 v49, 0x80000000, v49
	v_cvt_pk_bf16_f32 v136, v48, v49
	v_add_f32_e32 v77, v49, v76
	v_lshlrev_b32_e32 v76, 16, v136
	v_sub_f32_e32 v48, v48, v76
	v_and_b32_e32 v76, 0xffff0000, v136
	v_sub_f32_e32 v49, v49, v76
	v_cvt_pk_bf16_f32 v76, v48, v49
	s_nop 0
	v_min_f32_e32 v160, 0x42c80000, v50
	s_nop 0
	s_nop 0
	s_nop 0
	v_min_f32_e32 v161, 0x42c80000, v51
	s_nop 0
	s_nop 0
	v_exp_f32_e32 v48, v160
	s_nop 0
	v_exp_f32_e32 v50, v161
	s_nop 0
	v_add_f32_e32 v48, 1.0, v48
	v_log_f32_e32 v48, v48
	v_add_f32_e32 v50, 1.0, v50
	v_log_f32_e32 v50, v50
	v_xor_b32_e32 v48, 0x80000000, v48
	v_add_f32_e32 v49, v48, v77
	v_xor_b32_e32 v50, 0x80000000, v50
	v_cvt_pk_bf16_f32 v137, v48, v50
	v_lshlrev_b32_e32 v51, 16, v137
	v_sub_f32_e32 v48, v48, v51
	v_and_b32_e32 v51, 0xffff0000, v137
	v_add_f32_e32 v49, v50, v49
	v_sub_f32_e32 v50, v50, v51
	v_cvt_pk_bf16_f32 v77, v48, v50
	s_nop 0
	v_min_f32_e32 v162, 0x42c80000, v52
	s_nop 0
	s_nop 0
	s_nop 0
	v_min_f32_e32 v163, 0x42c80000, v53
	s_nop 0
	s_nop 0
	v_exp_f32_e32 v48, v162
	s_nop 0
	v_exp_f32_e32 v50, v163
	s_nop 0
	v_add_f32_e32 v48, 1.0, v48
	v_log_f32_e32 v48, v48
	v_add_f32_e32 v50, 1.0, v50
	v_log_f32_e32 v50, v50
	v_add_f32_e32 v52, v152, v88
	v_add_f32_e32 v53, v152, v89
	v_xor_b32_e32 v48, 0x80000000, v48
	v_add_f32_e32 v49, v48, v49
	v_xor_b32_e32 v50, 0x80000000, v50
	v_cvt_pk_bf16_f32 v138, v48, v50
	v_lshlrev_b32_e32 v51, 16, v138
	v_sub_f32_e32 v48, v48, v51
	v_and_b32_e32 v51, 0xffff0000, v138
	v_add_f32_e32 v49, v50, v49
	v_sub_f32_e32 v50, v50, v51
	v_cvt_pk_bf16_f32 v78, v48, v50
	s_nop 0
	v_min_f32_e32 v164, 0x42c80000, v54
	s_nop 0
	s_nop 0
	s_nop 0
	v_min_f32_e32 v165, 0x42c80000, v55
	s_nop 0
	s_nop 0
	v_exp_f32_e32 v48, v164
	s_nop 0
	v_exp_f32_e32 v50, v165
	s_nop 0
	v_add_f32_e32 v48, 1.0, v48
	v_log_f32_e32 v48, v48
	v_add_f32_e32 v50, 1.0, v50
	v_log_f32_e32 v50, v50
	v_add_f32_e32 v54, v152, v90
	v_add_f32_e32 v55, v152, v91
	v_xor_b32_e32 v48, 0x80000000, v48
	v_add_f32_e32 v49, v48, v49
	v_xor_b32_e32 v50, 0x80000000, v50
	v_cvt_pk_bf16_f32 v139, v48, v50
	v_lshlrev_b32_e32 v51, 16, v139
	v_sub_f32_e32 v48, v48, v51
	v_and_b32_e32 v51, 0xffff0000, v139
	v_add_f32_e32 v49, v50, v49
	v_sub_f32_e32 v50, v50, v51
	v_cvt_pk_bf16_f32 v79, v48, v50
	s_nop 0
	v_min_f32_e32 v166, 0x42c80000, v56
	s_nop 0
	s_nop 0
	s_nop 0
	v_min_f32_e32 v167, 0x42c80000, v57
	s_nop 0
	s_nop 0
	v_exp_f32_e32 v48, v166
	s_nop 0
	v_exp_f32_e32 v50, v167
	s_nop 0
	v_add_f32_e32 v48, 1.0, v48
	v_log_f32_e32 v48, v48
	v_add_f32_e32 v50, 1.0, v50
	v_log_f32_e32 v50, v50
	v_add_f32_e32 v56, v152, v92
	v_add_f32_e32 v57, v152, v93
	v_xor_b32_e32 v48, 0x80000000, v48
	v_add_f32_e32 v49, v48, v49
	v_xor_b32_e32 v50, 0x80000000, v50
	v_cvt_pk_bf16_f32 v140, v48, v50
; template <int DQK, bool SB, bool SMAX>
; DI void attn_item(const Params& p, char* smem, int bh, int qb, float Mb) {
;     ...
;           for (int i2 = 0; i2 < 8; ++i2) {
;             float lk[2];
; #pragma unroll
;             for (int e = 0; e < 2; ++e) {
;               const int i = 2 * i2 + e;
;               const float z = fminf(st[kb][i], 100.f);
;               const int key = kb0 + kb * 32 + crow(i, h);
;               const bool valid = !diag || (key < query);
;               float l = -fast_log2(1.f + fast_exp2(z));
;               l = valid ? l : 0.f;
;               lk[e] = l;
;               tsum += l;
;               ca[kb][i] = z + carry;
;             }
;             const unsigned hp = pk_bf16(lk[0], lk[1]);
;             const unsigned lp = pk_bf16(lk[0] - bf_lo(hp), lk[1] - bf_hi(hp));
;             const int kk = kb * 2 + (i2 >> 2), w = i2 & 3;
;             hi[kk][2 * w] = (short)(hp & 0xffffu); hi[kk][2 * w + 1] = (short)(hp >> 16);
;             lo[kk][2 * w] = (short)(lp & 0xffffu); lo[kk][2 * w + 1] = (short)(lp >> 16);
;           }
;         tsum += other_half(tsum);
; #pragma unroll
;         for (int s = 0; s < 2; ++s) {
;           ca[0] = MFMA32(tri[s], hi[s], ca[0]);
;           ca[0] = MFMA32(tri[s], lo[s], ca[0]);
;           ca[0] = MFMA32(ones, hi[2 + s], ca[0]);
;           ca[0] = MFMA32(ones, lo[2 + s], ca[0]);
;           ca[1] = MFMA32(tri[s], hi[2 + s], ca[1]);
;           ca[1] = MFMA32(tri[s], lo[2 + s], ca[1]);
;         }
; #pragma unroll
;         for (int kb = 0; kb < 2; ++kb)
; #pragma unroll
;           for (int i = 0; i < 16; ++i) {
;             const int key = kb0 + kb * 32 + crow(i, h);
;             const bool valid = !diag || (key < query);
;             st[kb][i] = valid ? fast_exp2(ca[kb][i]) : 0.f;
;           }
;         carry += tsum;
;       }
; #pragma unroll
;       for (int kb = 0; kb < 2; ++kb)
; #pragma unroll
;         for (int s = 0; s < 2; ++s) {
;           u32x4 w;
; #pragma unroll
;           for (int e = 0; e < 4; ++e) w[e] = pk_bf16(st[kb][8 * s + 2 * e], st[kb][8 * s + 2 * e + 1]);
;           pk[kb * 2 + s] = __builtin_bit_cast(bf16x8, w);
;         }
; #pragma unroll
;       for (int kk = 0; kk < 4; ++kk)
; #pragma unroll
;         for (int db = 0; db < 2; ++db) {
;           const s16x4 v0 = __builtin_amdgcn_ds_read_tr16_b64_v4i16((lds_s16x4*)(vc + voff + (16 * kk) * VSTR + 32 * db));
	v_lshlrev_b32_e32 v51, 16, v140
	v_sub_f32_e32 v48, v48, v51
	v_and_b32_e32 v51, 0xffff0000, v140
	v_add_f32_e32 v49, v50, v49
	v_sub_f32_e32 v50, v50, v51
	v_cvt_pk_bf16_f32 v144, v48, v50
	s_nop 0
	v_min_f32_e32 v168, 0x42c80000, v58
	s_nop 0
	s_nop 0
	s_nop 0
	v_min_f32_e32 v169, 0x42c80000, v59
	s_nop 0
	s_nop 0
	v_exp_f32_e32 v48, v168
	s_nop 0
	v_exp_f32_e32 v50, v169
	s_nop 0
	v_add_f32_e32 v48, 1.0, v48
	v_log_f32_e32 v48, v48
	v_add_f32_e32 v50, 1.0, v50
	v_log_f32_e32 v50, v50
	v_add_f32_e32 v58, v152, v94
	v_add_f32_e32 v59, v152, v95
	v_xor_b32_e32 v48, 0x80000000, v48
	v_add_f32_e32 v49, v48, v49
	v_xor_b32_e32 v50, 0x80000000, v50
	v_cvt_pk_bf16_f32 v141, v48, v50
	v_lshlrev_b32_e32 v51, 16, v141
	v_sub_f32_e32 v48, v48, v51
	v_and_b32_e32 v51, 0xffff0000, v141
	v_add_f32_e32 v49, v50, v49
	v_sub_f32_e32 v50, v50, v51
	v_cvt_pk_bf16_f32 v145, v48, v50
	s_nop 0
	v_min_f32_e32 v170, 0x42c80000, v60
	s_nop 0
	s_nop 0
	s_nop 0
	v_min_f32_e32 v171, 0x42c80000, v61
	s_nop 0
	s_nop 0
	v_exp_f32_e32 v48, v170
	s_nop 0
	v_exp_f32_e32 v50, v171
	s_nop 0
	v_add_f32_e32 v48, 1.0, v48
	v_log_f32_e32 v48, v48
	v_add_f32_e32 v50, 1.0, v50
	v_log_f32_e32 v50, v50
	v_add_f32_e32 v60, v152, v154
	v_add_f32_e32 v61, v152, v155
	v_xor_b32_e32 v48, 0x80000000, v48
	v_add_f32_e32 v49, v48, v49
	v_xor_b32_e32 v50, 0x80000000, v50
	v_cvt_pk_bf16_f32 v142, v48, v50
	v_lshlrev_b32_e32 v51, 16, v142
	v_sub_f32_e32 v48, v48, v51
	v_and_b32_e32 v51, 0xffff0000, v142
	v_add_f32_e32 v49, v50, v49
	v_sub_f32_e32 v50, v50, v51
	v_cvt_pk_bf16_f32 v146, v48, v50
	s_nop 0
	v_min_f32_e32 v182, 0x42c80000, v62
	s_nop 0
	s_nop 0
	s_nop 0
	v_min_f32_e32 v183, 0x42c80000, v63
	s_nop 0
	s_nop 0
	v_exp_f32_e32 v48, v182
	s_nop 0
	v_exp_f32_e32 v50, v183
	s_nop 0
	v_add_f32_e32 v48, 1.0, v48
	v_log_f32_e32 v48, v48
	v_add_f32_e32 v50, 1.0, v50
	v_log_f32_e32 v50, v50
	v_add_f32_e32 v62, v152, v158
	v_add_f32_e32 v63, v152, v159
	v_xor_b32_e32 v48, 0x80000000, v48
	v_add_f32_e32 v49, v48, v49
	v_xor_b32_e32 v50, 0x80000000, v50
	v_cvt_pk_bf16_f32 v143, v48, v50
	v_add_f32_e32 v184, v50, v49
	v_lshlrev_b32_e32 v49, 16, v143
	v_sub_f32_e32 v48, v48, v49
	v_and_b32_e32 v49, 0xffff0000, v143
	v_sub_f32_e32 v49, v50, v49
	v_cvt_pk_bf16_f32 v147, v48, v49
	v_mov_b32_e32 v48, v184
	v_mov_b32_e32 v49, v184
	s_nop 1
	v_permlane32_swap_b32_e32 v48, v49
	v_cndmask_b32_e64 v185, v48, v49, s[8:9]
	v_add_f32_e32 v50, v152, v86
	v_add_f32_e32 v51, v152, v87
	v_add_f32_e32 v48, v152, v84
	v_add_f32_e32 v49, v152, v85
	v_add_f32_e32 v94, v152, v182
	v_add_f32_e32 v95, v152, v183
	v_add_f32_e32 v92, v152, v170
	v_add_f32_e32 v93, v152, v171
	v_mfma_f32_32x32x16_bf16 v[48:63], v[96:99], v[80:83], v[48:63]
	v_add_f32_e32 v90, v152, v168
	v_add_f32_e32 v91, v152, v169
	v_add_f32_e32 v88, v152, v166
	v_add_f32_e32 v89, v152, v167
	v_add_f32_e32 v86, v152, v164
	v_add_f32_e32 v87, v152, v165
	v_add_f32_e32 v84, v152, v162
	v_add_f32_e32 v85, v152, v163
	v_add_f32_e32 v82, v152, v160
	v_add_f32_e32 v83, v152, v161
	v_add_f32_e32 v80, v152, v156
	v_add_f32_e32 v81, v152, v157
	v_mfma_f32_32x32x16_bf16 v[48:63], v[96:99], v[64:67], v[48:63]
	v_mov_b64_e32 v[64:65], s[96:97]
	v_mov_b64_e32 v[66:67], s[98:99]
	s_nop 1
	v_mfma_f32_32x32x16_bf16 v[48:63], v[64:67], v[136:139], v[48:63]
	v_mfma_f32_32x32x16_bf16 v[48:63], v[64:67], v[76:79], v[48:63]
	v_mfma_f32_32x32x16_bf16 v[48:63], v[100:103], v[72:75], v[48:63]
	v_mfma_f32_32x32x16_bf16 v[48:63], v[100:103], v[68:71], v[48:63]
	v_mfma_f32_32x32x16_bf16 v[48:63], v[64:67], v[140:143], v[48:63]
	v_mfma_f32_32x32x16_bf16 v[48:63], v[64:67], v[144:147], v[48:63]
	v_mfma_f32_32x32x16_bf16 v[80:95], v[96:99], v[136:139], v[80:95]
	s_nop 10
	v_exp_f32_e32 v64, v48
	s_nop 0
	s_nop 0
	v_exp_f32_e32 v65, v49
	v_mfma_f32_32x32x16_bf16 v[80:95], v[96:99], v[76:79], v[80:95]
	s_nop 0
	v_exp_f32_e32 v66, v50
	s_nop 0
	s_nop 0
	v_exp_f32_e32 v67, v51
	v_mfma_f32_32x32x16_bf16 v[80:95], v[100:103], v[140:143], v[80:95]
	s_nop 0
	v_exp_f32_e32 v68, v52
	s_nop 0
	s_nop 0
	v_exp_f32_e32 v69, v53
	v_mfma_f32_32x32x16_bf16 v[80:95], v[100:103], v[144:147], v[80:95]
	s_nop 0
	v_exp_f32_e32 v70, v54
	s_nop 0
	s_nop 0
	v_exp_f32_e32 v71, v55
	s_nop 6
	v_exp_f32_e32 v53, v85
	v_add_u32_e32 v85, v198, v200
	ds_read_b64_tr_b16 v[140:141], v85 offset:27648
	ds_read_b64_tr_b16 v[142:143], v85 offset:28800
	s_nop 0
	v_exp_f32_e32 v72, v56
	v_exp_f32_e32 v54, v86
	v_exp_f32_e32 v55, v87
	v_exp_f32_e32 v56, v88
	s_nop 0
	v_exp_f32_e32 v73, v57
	v_exp_f32_e32 v57, v89
	v_cvt_pk_bf16_f32 v86, v64, v65
	v_cvt_pk_bf16_f32 v87, v66, v67
	s_nop 0
	v_exp_f32_e32 v74, v58
	v_cvt_pk_bf16_f32 v88, v68, v69
	v_cvt_pk_bf16_f32 v89, v70, v71
	v_exp_f32_e32 v58, v90
	s_nop 0
	v_exp_f32_e32 v75, v59
	s_waitcnt lgkmcnt(0)
; #define MFMA32(a, b, c) __builtin_amdgcn_mfma_f32_32x32x16_bf16((a), (b), (c), 0, 0, 0)
; DI unsigned pk_bf16(float lo, float hi) { f32x2 v = {lo, hi}; bf2_t b = __builtin_convertvector(v, bf2_t); return __builtin_bit_cast(unsigned, b); }
; template <int DQK, bool SB, bool SMAX>
; DI void attn_item(const Params& p, char* smem, int bh, int qb, float Mb) {
;     ...
;         carry += tsum;
;       }
; #pragma unroll
;       for (int kb = 0; kb < 2; ++kb)
; #pragma unroll
;         for (int s = 0; s < 2; ++s) {
;           u32x4 w;
; #pragma unroll
;           for (int e = 0; e < 4; ++e) w[e] = pk_bf16(st[kb][8 * s + 2 * e], st[kb][8 * s + 2 * e + 1]);
;           pk[kb * 2 + s] = __builtin_bit_cast(bf16x8, w);
;         }
; #pragma unroll
;       for (int kk = 0; kk < 4; ++kk)
; #pragma unroll
;         for (int db = 0; db < 2; ++db) {
;           const s16x4 v0 = __builtin_amdgcn_ds_read_tr16_b64_v4i16((lds_s16x4*)(vc + voff + (16 * kk) * VSTR + 32 * db));
;           const s16x4 v1 = __builtin_amdgcn_ds_read_tr16_b64_v4i16((lds_s16x4*)(vc + voff + (16 * kk + 8) * VSTR + 32 * db));
;           const bf16x8 vf = __builtin_shufflevector(v0, v1, 0, 1, 2, 3, 4, 5, 6, 7);
;           O[db] = MFMA32(vf, pk[kk], O[db]);
;         }
	v_mfma_f32_32x32x16_bf16 v[32:47], v[140:143], v[86:89], v[32:47]
	ds_read_b64_tr_b16 v[140:141], v85 offset:27712
	ds_read_b64_tr_b16 v[142:143], v85 offset:28864
	v_exp_f32_e32 v59, v91
	s_nop 0
	v_exp_f32_e32 v76, v60
	v_exp_f32_e32 v60, v92
	v_cvt_pk_bf16_f32 v90, v72, v73
	v_cvt_pk_bf16_f32 v91, v74, v75
	s_nop 0
	v_exp_f32_e32 v77, v61
	s_waitcnt lgkmcnt(0)
	v_mfma_f32_32x32x16_bf16 v[16:31], v[140:143], v[86:89], v[16:31]
	ds_read_b64_tr_b16 v[86:87], v85 offset:29952
	ds_read_b64_tr_b16 v[88:89], v85 offset:31104
	v_exp_f32_e32 v61, v93
	s_nop 0
	v_exp_f32_e32 v78, v62
	v_cvt_pk_bf16_f32 v92, v76, v77
	v_exp_f32_e32 v49, v81
	v_exp_f32_e32 v50, v82
	s_nop 0
	v_exp_f32_e32 v79, v63
	v_exp_f32_e32 v51, v83
	v_exp_f32_e32 v52, v84
	s_nop 0
	s_nop 0
	v_cvt_pk_bf16_f32 v93, v78, v79
	v_exp_f32_e32 v48, v80
	s_nop 0
	s_waitcnt lgkmcnt(0)
	v_mfma_f32_32x32x16_bf16 v[32:47], v[86:89], v[90:93], v[32:47]
	ds_read_b64_tr_b16 v[86:87], v85 offset:30016
	ds_read_b64_tr_b16 v[88:89], v85 offset:31168
	s_nop 0
	s_nop 0
	s_nop 0
	s_nop 0
	s_nop 0
	s_nop 0
	s_waitcnt lgkmcnt(0)
	v_mfma_f32_32x32x16_bf16 v[16:31], v[86:89], v[90:93], v[16:31]
	ds_read_b64_tr_b16 v[86:87], v85 offset:32256
	ds_read_b64_tr_b16 v[88:89], v85 offset:33408
	v_cvt_pk_bf16_f32 v136, v48, v49
	v_cvt_pk_bf16_f32 v137, v50, v51
	v_cvt_pk_bf16_f32 v138, v52, v53
	v_cvt_pk_bf16_f32 v139, v54, v55
	v_exp_f32_e32 v62, v94
	v_exp_f32_e32 v63, v95
	s_waitcnt lgkmcnt(0)
	v_mfma_f32_32x32x16_bf16 v[32:47], v[86:89], v[136:139], v[32:47]
	ds_read_b64_tr_b16 v[86:87], v85 offset:32320
	ds_read_b64_tr_b16 v[88:89], v85 offset:33472
	s_nop 0
	s_nop 0
	s_nop 0
	s_nop 0
	s_nop 0
	s_nop 0
	s_waitcnt lgkmcnt(0)
	v_mfma_f32_32x32x16_bf16 v[16:31], v[86:89], v[136:139], v[16:31]
	ds_read_b64_tr_b16 v[86:87], v85 offset:34560
	ds_read_b64_tr_b16 v[88:89], v85 offset:35712
	s_nop 0
	s_nop 0
	v_cvt_pk_bf16_f32 v80, v56, v57
	v_cvt_pk_bf16_f32 v81, v58, v59
	v_cvt_pk_bf16_f32 v82, v60, v61
	v_cvt_pk_bf16_f32 v83, v62, v63
	v_add_f32_e32 v84, v184, v185
	v_add_f32_e32 v152, v152, v84
	s_waitcnt lgkmcnt(0)
	v_mfma_f32_32x32x16_bf16 v[32:47], v[86:89], v[80:83], v[32:47]
	ds_read_b64_tr_b16 v[86:87], v85 offset:34624
	ds_read_b64_tr_b16 v[88:89], v85 offset:35776
	s_waitcnt lgkmcnt(0)
	v_mfma_f32_32x32x16_bf16 v[16:31], v[86:89], v[80:83], v[16:31]

; DI unsigned pk_bf16(float lo, float hi) { f32x2 v = {lo, hi}; bf2_t b = __builtin_convertvector(v, bf2_t); return __builtin_bit_cast(unsigned, b); }
; DI float bf_lo(unsigned u) { return __uint_as_float(u << 16); }
; DI float bf_hi(unsigned u) { return __uint_as_float(u & 0xffff0000u); }
; template <int DQK, bool SB, bool SMAX>
; DI void attn_item(const Params& p, char* smem, int bh, int qb, float Mb) {
;     ...
;   float inv = 1.f;
;   if (!SB) { const float lt = lsum + other_half(lsum); inv = 1.f / lt; }
;   const size_t token = (size_t)(bh >> 3) * S_ + query;
;   const int colbase = (SB ? 0 : 512) + (bh & 7) * 64;
; #pragma unroll
;   for (int db = 0; db < 2; ++db) {
;     u32x2 w[4];
; #pragma unroll
;     for (int g = 0; g < 4; ++g) {
;       const int col = colbase + db * 32 + 8 * g + 4 * h;
;       const u32x2 gt = *(const u32x2*)(p.Gate + token * 1024 + col);
;       w[g].x = pk_bf16(O[db][4 * g] * inv * bf_lo(gt.x), O[db][4 * g + 1] * inv * bf_hi(gt.x));
;       w[g].y = pk_bf16(O[db][4 * g + 2] * inv * bf_lo(gt.y), O[db][4 * g + 3] * inv * bf_hi(gt.y));
;     }
; #pragma unroll
;     for (int q = 0; q < 2; ++q) *(u32x4*)(p.Mixed + token * 1024 + colbase + db * 32 + 16 * q + 8 * h) = widen_pair(w[2 * q], w[2 * q + 1]);
;   }
.LBB0_450:
	s_lshl_b32 s0, s0, 6
	v_readlane_b32 s2, v255, 15
	s_and_b32 s0, s0, 0x1c0
	v_lshlrev_b64 v[48:49], 11, v[176:177]
	v_readlane_b32 s3, v255, 16
	v_or_b32_e32 v52, s0, v197
	v_lshlrev_b32_e32 v176, 1, v52
	v_lshl_add_u64 v[48:49], v[48:49], 0, s[2:3]
	v_lshl_add_u64 v[50:51], s[94:95], 0, v[48:49]
	v_lshl_add_u64 v[50:51], v[50:51], 0, v[176:177]
	global_load_dwordx2 v[52:53], v[50:51], off
	global_load_dwordx2 v[54:55], v[50:51], off offset:16
	global_load_dwordx2 v[56:57], v[50:51], off offset:32
	global_load_dwordx2 v[58:59], v[50:51], off offset:48
	v_lshl_add_u64 v[48:49], s[86:87], 0, v[48:49]
	s_lshl_b32 s4, s0, 1
	v_mov_b32_e32 v181, v177
	v_lshl_add_u64 v[48:49], v[48:49], 0, s[4:5]
	v_lshl_add_u64 v[48:49], v[48:49], 0, v[180:181]
	v_readlane_b32 s72, v255, 2
	s_mov_b64 s[0:1], 0
	v_readlane_b32 s73, v255, 3
	s_mov_b32 s24, s79
	s_waitcnt vmcnt(3)
	v_lshlrev_b32_e32 v60, 16, v52
	v_and_b32_e32 v61, 0xffff0000, v52
	v_lshlrev_b32_e32 v52, 16, v53
	v_and_b32_e32 v53, 0xffff0000, v53
	s_waitcnt vmcnt(2)
	v_lshlrev_b32_e32 v62, 16, v54
	v_and_b32_e32 v63, 0xffff0000, v54
	v_lshlrev_b32_e32 v54, 16, v55
	v_and_b32_e32 v55, 0xffff0000, v55
	s_waitcnt vmcnt(1)
	v_lshlrev_b32_e32 v64, 16, v56
	v_and_b32_e32 v65, 0xffff0000, v56
	v_lshlrev_b32_e32 v56, 16, v57
	v_and_b32_e32 v57, 0xffff0000, v57
	s_waitcnt vmcnt(0)
	v_lshlrev_b32_e32 v66, 16, v58
	v_and_b32_e32 v67, 0xffff0000, v58
	v_lshlrev_b32_e32 v58, 16, v59
	v_and_b32_e32 v59, 0xffff0000, v59
	v_mul_f32_e32 v32, v32, v60
	v_mul_f32_e32 v33, v33, v61
	v_mul_f32_e32 v34, v34, v52
	v_mul_f32_e32 v35, v35, v53
	v_mul_f32_e32 v36, v36, v62
	v_mul_f32_e32 v37, v37, v63
	v_mul_f32_e32 v38, v38, v54
	v_mul_f32_e32 v39, v39, v55
	v_mul_f32_e32 v40, v40, v64
	v_mul_f32_e32 v41, v41, v65
	v_mul_f32_e32 v42, v42, v56
	v_mul_f32_e32 v43, v43, v57
	v_mul_f32_e32 v44, v44, v66
	v_mul_f32_e32 v45, v45, v67
	v_mul_f32_e32 v46, v46, v58
	v_mul_f32_e32 v47, v47, v59
	v_cvt_pk_bf16_f32 v32, v32, v33
	v_cvt_pk_bf16_f32 v33, v34, v35
	v_cvt_pk_bf16_f32 v34, v36, v37
	v_cvt_pk_bf16_f32 v35, v38, v39
	v_cvt_pk_bf16_f32 v36, v40, v41
	v_cvt_pk_bf16_f32 v37, v42, v43
	v_cvt_pk_bf16_f32 v38, v44, v45
	v_cvt_pk_bf16_f32 v39, v46, v47
	v_permlane32_swap_b32_e32 v32, v34
	v_permlane32_swap_b32_e32 v33, v35
	v_permlane32_swap_b32_e32 v36, v38
	v_permlane32_swap_b32_e32 v37, v39
	global_store_dwordx4 v[48:49], v[32:35], off
	global_store_dwordx4 v[48:49], v[36:39], off offset:32
	global_load_dwordx2 v[32:33], v[50:51], off offset:64
	s_nop 0
	global_load_dwordx2 v[34:35], v[50:51], off offset:80
	global_load_dwordx2 v[36:37], v[50:51], off offset:96
	global_load_dwordx2 v[38:39], v[50:51], off offset:112
	s_waitcnt vmcnt(3)
	v_lshlrev_b32_e32 v40, 16, v32
	v_and_b32_e32 v41, 0xffff0000, v32
	v_lshlrev_b32_e32 v32, 16, v33
	v_and_b32_e32 v33, 0xffff0000, v33
	s_waitcnt vmcnt(2)
	v_lshlrev_b32_e32 v42, 16, v34
	v_and_b32_e32 v43, 0xffff0000, v34
	v_lshlrev_b32_e32 v34, 16, v35
	v_and_b32_e32 v35, 0xffff0000, v35
	s_waitcnt vmcnt(1)
	v_lshlrev_b32_e32 v44, 16, v36
	v_and_b32_e32 v45, 0xffff0000, v36
	v_lshlrev_b32_e32 v36, 16, v37
	v_and_b32_e32 v37, 0xffff0000, v37
	s_waitcnt vmcnt(0)
	v_lshlrev_b32_e32 v46, 16, v38
	v_and_b32_e32 v47, 0xffff0000, v38
	v_lshlrev_b32_e32 v38, 16, v39
	v_and_b32_e32 v39, 0xffff0000, v39
	v_mul_f32_e32 v16, v16, v40
	v_mul_f32_e32 v17, v17, v41
	v_mul_f32_e32 v18, v18, v32
	v_mul_f32_e32 v19, v19, v33
	v_mul_f32_e32 v20, v20, v42
	v_mul_f32_e32 v21, v21, v43
	v_mul_f32_e32 v22, v22, v34
	v_mul_f32_e32 v23, v23, v35
	v_mul_f32_e32 v24, v24, v44
	v_mul_f32_e32 v25, v25, v45
	v_mul_f32_e32 v26, v26, v36
	v_mul_f32_e32 v27, v27, v37
	v_mul_f32_e32 v28, v28, v46
	v_mul_f32_e32 v29, v29, v47
	v_mul_f32_e32 v30, v30, v38
	v_mul_f32_e32 v31, v31, v39
	v_cvt_pk_bf16_f32 v16, v16, v17
	v_cvt_pk_bf16_f32 v17, v18, v19
	v_cvt_pk_bf16_f32 v18, v20, v21
	v_cvt_pk_bf16_f32 v19, v22, v23
	v_cvt_pk_bf16_f32 v20, v24, v25
	v_cvt_pk_bf16_f32 v21, v26, v27
	v_cvt_pk_bf16_f32 v22, v28, v29
	v_cvt_pk_bf16_f32 v23, v30, v31
	v_permlane32_swap_b32_e32 v16, v18
	v_permlane32_swap_b32_e32 v17, v19
	v_permlane32_swap_b32_e32 v20, v22
	v_permlane32_swap_b32_e32 v21, v23
	global_store_dwordx4 v[48:49], v[16:19], off offset:64
	global_store_dwordx4 v[48:49], v[20:23], off offset:96
	s_barrier

; #define MFMA32(a, b, c) __builtin_amdgcn_mfma_f32_32x32x16_bf16((a), (b), (c), 0, 0, 0)
; DI unsigned pk_bf16(float lo, float hi) { f32x2 v = {lo, hi}; bf2_t b = __builtin_convertvector(v, bf2_t); return __builtin_bit_cast(unsigned, b); }
; DI float fast_exp2(float x) { return __builtin_amdgcn_exp2f(x); }
; template <int DQK, bool SB, bool SMAX>
; DI void attn_item(const Params& p, char* smem, int bh, int qb, float Mb) {
;     ...
;         float mx = st[0][0];
; #pragma unroll
;         for (int kb = 0; kb < 2; ++kb)
; #pragma unroll
;           for (int i = 0; i < 16; ++i) mx = fmaxf(mx, st[kb][i]);
;         mx = fmaxf(mx, other_half(mx));
;         const float mnew = fmaxf(m, mx);
;         const float alpha = fast_exp2(m - mnew);
;         m = mnew;
;         float ps = 0.f;
; #pragma unroll
;         for (int kb = 0; kb < 2; ++kb)
; #pragma unroll
;           for (int i = 0; i < 16; ++i) { const float pv = fast_exp2(st[kb][i] - mnew); st[kb][i] = pv; ps += pv; }
;         lsum = lsum * alpha + ps;
; #pragma unroll
;         for (int db = 0; db < 2; ++db)
; #pragma unroll
;           for (int i = 0; i < 16; ++i) O[db][i] *= alpha;
;         }
;     ...
; #pragma unroll
;       for (int kb = 0; kb < 2; ++kb)
; #pragma unroll
;         for (int s = 0; s < 2; ++s) {
;           u32x4 w;
; #pragma unroll
;           for (int e = 0; e < 4; ++e) w[e] = pk_bf16(st[kb][8 * s + 2 * e], st[kb][8 * s + 2 * e + 1]);
;           pk[kb * 2 + s] = __builtin_bit_cast(bf16x8, w);
;         }
; #pragma unroll
;       for (int kk = 0; kk < 4; ++kk)
; #pragma unroll
;         for (int db = 0; db < 2; ++db) {
;           const s16x4 v0 = __builtin_amdgcn_ds_read_tr16_b64_v4i16((lds_s16x4*)(vc + voff + (16 * kk) * VSTR + 32 * db));
;           const s16x4 v1 = __builtin_amdgcn_ds_read_tr16_b64_v4i16((lds_s16x4*)(vc + voff + (16 * kk + 8) * VSTR + 32 * db));
;           const bf16x8 vf = __builtin_shufflevector(v0, v1, 0, 1, 2, 3, 4, 5, 6, 7);
;           O[db] = MFMA32(vf, pk[kk], O[db]);
;         }
.LBB0_455:
	s_or_b64 exec, exec, s[14:15]
	v_max_f32_e32 v152, v49, v49
	v_max_f32_e32 v153, v48, v48
	v_max_f32_e32 v152, v153, v152
	v_max3_f32 v152, v152, v50, v51
	v_max3_f32 v152, v152, v52, v53
	v_max3_f32 v152, v152, v54, v55
	v_max3_f32 v152, v152, v56, v57
	v_max3_f32 v152, v152, v58, v59
	v_max3_f32 v152, v152, v60, v61
	v_max3_f32 v152, v152, v62, v63
	v_max3_f32 v152, v152, v64, v65
	v_max3_f32 v152, v152, v66, v67
	v_max3_f32 v152, v152, v68, v69
	v_max3_f32 v152, v152, v70, v71
	v_max3_f32 v152, v152, v72, v73
	v_max3_f32 v152, v152, v74, v75
	v_max3_f32 v152, v152, v76, v77
	v_max3_f32 v152, v152, v78, v79
	v_mov_b32_e32 v153, v152
	v_mov_b32_e32 v154, v152
	s_nop 1
	v_permlane32_swap_b32_e32 v153, v154
	v_cndmask_b32_e64 v153, v153, v154, s[8:9]
	v_max3_f32 v165, v181, v152, v153
	v_sub_f32_e32 v48, v48, v165
	v_exp_f32_e32 v48, v48
	v_sub_f32_e32 v49, v49, v165
	v_exp_f32_e32 v49, v49
	v_sub_f32_e32 v50, v50, v165
	v_exp_f32_e32 v50, v50
	v_sub_f32_e32 v51, v51, v165
	v_exp_f32_e32 v51, v51
	v_sub_f32_e32 v52, v52, v165
	v_add_f32_e32 v153, 0, v48
	v_exp_f32_e32 v52, v52
	v_sub_f32_e32 v53, v53, v165
	v_add_f32_e32 v153, v49, v153
	v_exp_f32_e32 v53, v53
	v_sub_f32_e32 v54, v54, v165
	v_add_f32_e32 v153, v50, v153
	v_exp_f32_e32 v54, v54
	v_sub_f32_e32 v55, v55, v165
	v_add_f32_e32 v153, v51, v153
	v_exp_f32_e32 v55, v55
	v_sub_f32_e32 v56, v56, v165
	v_add_f32_e32 v153, v52, v153
	v_exp_f32_e32 v56, v56
	v_sub_f32_e32 v57, v57, v165
	v_add_f32_e32 v153, v53, v153
	v_exp_f32_e32 v57, v57
	v_sub_f32_e32 v58, v58, v165
	v_add_f32_e32 v153, v54, v153
	v_exp_f32_e32 v58, v58
	v_sub_f32_e32 v59, v59, v165
	v_add_f32_e32 v153, v55, v153
	v_exp_f32_e32 v59, v59
	v_sub_f32_e32 v60, v60, v165
	v_add_f32_e32 v153, v56, v153
	v_exp_f32_e32 v60, v60
	v_sub_f32_e32 v61, v61, v165
	v_add_f32_e32 v153, v57, v153
	v_exp_f32_e32 v61, v61
	v_sub_f32_e32 v62, v62, v165
	v_add_f32_e32 v153, v58, v153
	v_exp_f32_e32 v62, v62
	v_sub_f32_e32 v63, v63, v165
	v_add_f32_e32 v153, v59, v153
	v_exp_f32_e32 v63, v63
	v_add_f32_e32 v153, v60, v153
	v_add_f32_e32 v153, v61, v153
	v_sub_f32_e32 v152, v181, v165
	v_add_f32_e32 v153, v62, v153
	v_add_u32_e32 v167, v198, v200
	v_add_f32_e32 v166, v63, v153
	v_exp_f32_e32 v164, v152
	ds_read_b64_tr_b16 v[152:153], v167 offset:35840
	ds_read_b64_tr_b16 v[154:155], v167 offset:36992
	ds_read_b64_tr_b16 v[162:163], v167 offset:37056
	ds_read_b64_tr_b16 v[160:161], v167 offset:35904
	v_cvt_pk_bf16_f32 v156, v48, v49
	v_mul_f32_e32 v46, v46, v164
	v_mul_f32_e32 v47, v47, v164
	v_mul_f32_e32 v44, v44, v164
	v_mul_f32_e32 v45, v45, v164
	v_mul_f32_e32 v42, v42, v164
	v_mul_f32_e32 v43, v43, v164
	v_mul_f32_e32 v40, v40, v164
	v_mul_f32_e32 v41, v41, v164
	v_mul_f32_e32 v38, v38, v164
	v_mul_f32_e32 v39, v39, v164
	v_mul_f32_e32 v36, v36, v164
	v_mul_f32_e32 v37, v37, v164
	v_mul_f32_e32 v34, v34, v164
	v_mul_f32_e32 v35, v35, v164
	v_mul_f32_e32 v32, v32, v164
	v_mul_f32_e32 v33, v33, v164
	v_cvt_pk_bf16_f32 v157, v50, v51
	v_cvt_pk_bf16_f32 v158, v52, v53
	v_cvt_pk_bf16_f32 v159, v54, v55
	v_mul_f32_e32 v30, v30, v164
	v_mul_f32_e32 v31, v31, v164
	v_mul_f32_e32 v28, v28, v164
	v_mul_f32_e32 v29, v29, v164
	s_waitcnt lgkmcnt(2)
	v_mfma_f32_32x32x16_bf16 v[32:47], v[152:155], v[156:159], v[32:47]
	v_mul_f32_e32 v26, v26, v164
	v_mul_f32_e32 v27, v27, v164
	v_mul_f32_e32 v24, v24, v164
	v_mul_f32_e32 v25, v25, v164
	v_mul_f32_e32 v22, v22, v164
	v_mul_f32_e32 v23, v23, v164
	v_mul_f32_e32 v20, v20, v164
	v_mul_f32_e32 v21, v21, v164
	v_mul_f32_e32 v18, v18, v164
	v_mul_f32_e32 v19, v19, v164
	v_mul_f32_e32 v16, v16, v164
	v_mul_f32_e32 v17, v17, v164
	ds_read_b64_tr_b16 v[152:153], v167 offset:38144
	ds_read_b64_tr_b16 v[154:155], v167 offset:39296
	s_waitcnt lgkmcnt(2)
	v_mfma_f32_32x32x16_bf16 v[16:31], v[160:163], v[156:159], v[16:31]
	v_sub_f32_e32 v64, v64, v165
	ds_read_b64_tr_b16 v[162:163], v167 offset:39360
	ds_read_b64_tr_b16 v[160:161], v167 offset:38208
	v_exp_f32_e32 v64, v64
	v_sub_f32_e32 v65, v65, v165
	v_exp_f32_e32 v65, v65
	v_cvt_pk_bf16_f32 v156, v56, v57
	v_cvt_pk_bf16_f32 v157, v58, v59
	v_cvt_pk_bf16_f32 v158, v60, v61
	v_cvt_pk_bf16_f32 v159, v62, v63
	v_sub_f32_e32 v66, v66, v165
	v_sub_f32_e32 v67, v67, v165
	s_waitcnt lgkmcnt(2)
	v_mfma_f32_32x32x16_bf16 v[32:47], v[152:155], v[156:159], v[32:47]
	v_sub_f32_e32 v68, v68, v165
	v_sub_f32_e32 v69, v69, v165
	v_sub_f32_e32 v70, v70, v165
	v_sub_f32_e32 v71, v71, v165
	v_add_f32_e32 v152, v64, v166
	v_exp_f32_e32 v66, v66
	v_exp_f32_e32 v67, v67
	s_waitcnt lgkmcnt(0)
	v_mfma_f32_32x32x16_bf16 v[16:31], v[160:163], v[156:159], v[16:31]
	v_exp_f32_e32 v68, v68
	v_exp_f32_e32 v69, v69
	v_exp_f32_e32 v70, v70
	v_exp_f32_e32 v71, v71
	v_add_f32_e32 v166, v65, v152
	ds_read_b64_tr_b16 v[152:153], v167 offset:40448
	ds_read_b64_tr_b16 v[154:155], v167 offset:41600
	ds_read_b64_tr_b16 v[162:163], v167 offset:41664
	ds_read_b64_tr_b16 v[160:161], v167 offset:40512
	v_add_f32_e32 v166, v66, v166
	v_cvt_pk_bf16_f32 v156, v64, v65
	v_cvt_pk_bf16_f32 v157, v66, v67
	v_cvt_pk_bf16_f32 v158, v68, v69
	v_cvt_pk_bf16_f32 v159, v70, v71
	v_sub_f32_e32 v72, v72, v165
	v_sub_f32_e32 v73, v73, v165
	s_waitcnt lgkmcnt(2)
	v_mfma_f32_32x32x16_bf16 v[32:47], v[152:155], v[156:159], v[32:47]
	v_add_f32_e32 v152, v67, v166
	v_add_f32_e32 v152, v68, v152
	v_add_f32_e32 v152, v69, v152
	v_sub_f32_e32 v74, v74, v165
	v_sub_f32_e32 v75, v75, v165
	v_sub_f32_e32 v76, v76, v165
	v_sub_f32_e32 v77, v77, v165
	s_waitcnt lgkmcnt(0)
	v_mfma_f32_32x32x16_bf16 v[16:31], v[160:163], v[156:159], v[16:31]
	v_sub_f32_e32 v78, v78, v165
	v_sub_f32_e32 v79, v79, v165
	v_add_f32_e32 v152, v70, v152
	v_exp_f32_e32 v72, v72
	v_exp_f32_e32 v73, v73
	v_exp_f32_e32 v74, v74
	v_exp_f32_e32 v75, v75
	v_exp_f32_e32 v76, v76
	v_exp_f32_e32 v77, v77
	v_exp_f32_e32 v78, v78
	v_exp_f32_e32 v79, v79
	v_add_f32_e32 v166, v71, v152
	ds_read_b64_tr_b16 v[152:153], v167 offset:42752
	ds_read_b64_tr_b16 v[154:155], v167 offset:43904
	ds_read_b64_tr_b16 v[162:163], v167 offset:43968
	ds_read_b64_tr_b16 v[160:161], v167 offset:42816
	v_add_f32_e32 v166, v72, v166
	v_cvt_pk_bf16_f32 v156, v72, v73
	v_cvt_pk_bf16_f32 v157, v74, v75
	v_cvt_pk_bf16_f32 v158, v76, v77
	v_cvt_pk_bf16_f32 v159, v78, v79
	v_mov_b32_e32 v181, v165
	s_waitcnt lgkmcnt(2)
	v_mfma_f32_32x32x16_bf16 v[32:47], v[152:155], v[156:159], v[32:47]
	v_add_f32_e32 v152, v73, v166
	v_add_f32_e32 v152, v74, v152
	v_add_f32_e32 v152, v75, v152
	v_add_f32_e32 v152, v76, v152
	v_add_f32_e32 v152, v77, v152
	v_add_f32_e32 v152, v78, v152
	v_add_f32_e32 v152, v79, v152
	s_waitcnt lgkmcnt(0)
	v_mfma_f32_32x32x16_bf16 v[16:31], v[160:163], v[156:159], v[16:31]
	v_fmac_f32_e32 v152, v212, v164
	v_mov_b32_e32 v212, v152

; #define MFMA32(a, b, c) __builtin_amdgcn_mfma_f32_32x32x16_bf16((a), (b), (c), 0, 0, 0)
; DI unsigned pk_bf16(float lo, float hi) { f32x2 v = {lo, hi}; bf2_t b = __builtin_convertvector(v, bf2_t); return __builtin_bit_cast(unsigned, b); }
; DI float fast_exp2(float x) { return __builtin_amdgcn_exp2f(x); }
; template <int DQK, bool SB, bool SMAX>
; DI void attn_item(const Params& p, char* smem, int bh, int qb, float Mb) {
;     ...
;         float mx = st[0][0];
; #pragma unroll
;         for (int kb = 0; kb < 2; ++kb)
; #pragma unroll
;           for (int i = 0; i < 16; ++i) mx = fmaxf(mx, st[kb][i]);
;         mx = fmaxf(mx, other_half(mx));
;         const float mnew = fmaxf(m, mx);
;         const float alpha = fast_exp2(m - mnew);
;         m = mnew;
;         float ps = 0.f;
; #pragma unroll
;         for (int kb = 0; kb < 2; ++kb)
; #pragma unroll
;           for (int i = 0; i < 16; ++i) { const float pv = fast_exp2(st[kb][i] - mnew); st[kb][i] = pv; ps += pv; }
;         lsum = lsum * alpha + ps;
; #pragma unroll
;         for (int db = 0; db < 2; ++db)
; #pragma unroll
;           for (int i = 0; i < 16; ++i) O[db][i] *= alpha;
;         }
;     ...
; #pragma unroll
;       for (int kb = 0; kb < 2; ++kb)
; #pragma unroll
;         for (int s = 0; s < 2; ++s) {
;           u32x4 w;
; #pragma unroll
;           for (int e = 0; e < 4; ++e) w[e] = pk_bf16(st[kb][8 * s + 2 * e], st[kb][8 * s + 2 * e + 1]);
;           pk[kb * 2 + s] = __builtin_bit_cast(bf16x8, w);
;         }
; #pragma unroll
;       for (int kk = 0; kk < 4; ++kk)
; #pragma unroll
;         for (int db = 0; db < 2; ++db) {
;           const s16x4 v0 = __builtin_amdgcn_ds_read_tr16_b64_v4i16((lds_s16x4*)(vc + voff + (16 * kk) * VSTR + 32 * db));
;           const s16x4 v1 = __builtin_amdgcn_ds_read_tr16_b64_v4i16((lds_s16x4*)(vc + voff + (16 * kk + 8) * VSTR + 32 * db));
;           const bf16x8 vf = __builtin_shufflevector(v0, v1, 0, 1, 2, 3, 4, 5, 6, 7);
;           O[db] = MFMA32(vf, pk[kk], O[db]);
;         }
.LBB0_462:
	s_or_b64 exec, exec, s[14:15]
	v_max_f32_e32 v132, v49, v49
	v_max_f32_e32 v133, v48, v48
	v_max_f32_e32 v132, v133, v132
	v_max3_f32 v132, v132, v50, v51
	v_max3_f32 v132, v132, v52, v53
	v_max3_f32 v132, v132, v54, v55
	v_max3_f32 v132, v132, v56, v57
	v_max3_f32 v132, v132, v58, v59
	v_max3_f32 v132, v132, v60, v61
	v_max3_f32 v132, v132, v62, v63
	v_max3_f32 v132, v132, v64, v65
	v_max3_f32 v132, v132, v66, v67
	v_max3_f32 v132, v132, v68, v69
	v_max3_f32 v132, v132, v70, v71
	v_max3_f32 v132, v132, v72, v73
	v_max3_f32 v132, v132, v74, v75
	v_max3_f32 v132, v132, v76, v77
	v_max3_f32 v132, v132, v78, v79
	v_mov_b32_e32 v133, v132
	v_mov_b32_e32 v134, v132
	s_nop 1
	v_permlane32_swap_b32_e32 v133, v134
	v_cndmask_b32_e64 v133, v133, v134, s[8:9]
	v_max3_f32 v145, v181, v132, v133
	v_sub_f32_e32 v48, v48, v145
	v_exp_f32_e32 v48, v48
	v_sub_f32_e32 v49, v49, v145
	v_exp_f32_e32 v49, v49
	v_sub_f32_e32 v50, v50, v145
	v_exp_f32_e32 v50, v50
	v_sub_f32_e32 v51, v51, v145
	v_exp_f32_e32 v51, v51
	v_sub_f32_e32 v52, v52, v145
	v_add_f32_e32 v133, 0, v48
	v_exp_f32_e32 v52, v52
	v_sub_f32_e32 v53, v53, v145
	v_add_f32_e32 v133, v49, v133
	v_exp_f32_e32 v53, v53
	v_sub_f32_e32 v54, v54, v145
	v_add_f32_e32 v133, v50, v133
	v_exp_f32_e32 v54, v54
	v_sub_f32_e32 v55, v55, v145
	v_add_f32_e32 v133, v51, v133
	v_exp_f32_e32 v55, v55
	v_sub_f32_e32 v56, v56, v145
	v_add_f32_e32 v133, v52, v133
	v_exp_f32_e32 v56, v56
	v_sub_f32_e32 v57, v57, v145
	v_add_f32_e32 v133, v53, v133
	v_exp_f32_e32 v57, v57
	v_sub_f32_e32 v58, v58, v145
	v_add_f32_e32 v133, v54, v133
	v_exp_f32_e32 v58, v58
	v_sub_f32_e32 v59, v59, v145
	v_add_f32_e32 v133, v55, v133
	v_exp_f32_e32 v59, v59
	v_sub_f32_e32 v60, v60, v145
	v_add_f32_e32 v133, v56, v133
	v_exp_f32_e32 v60, v60
	v_sub_f32_e32 v61, v61, v145
	v_add_f32_e32 v133, v57, v133
	v_exp_f32_e32 v61, v61
	v_sub_f32_e32 v62, v62, v145
	v_add_f32_e32 v133, v58, v133
	v_exp_f32_e32 v62, v62
	v_sub_f32_e32 v63, v63, v145
	v_add_f32_e32 v133, v59, v133
	v_exp_f32_e32 v63, v63
	v_add_f32_e32 v133, v60, v133
	v_add_f32_e32 v133, v61, v133
	v_sub_f32_e32 v132, v181, v145
	v_add_f32_e32 v133, v62, v133
	v_add_u32_e32 v147, v198, v200
	v_add_f32_e32 v146, v63, v133
	v_exp_f32_e32 v144, v132
	ds_read_b64_tr_b16 v[132:133], v147 offset:26624
	ds_read_b64_tr_b16 v[134:135], v147 offset:27776
	ds_read_b64_tr_b16 v[142:143], v147 offset:27840
	ds_read_b64_tr_b16 v[140:141], v147 offset:26688
	v_cvt_pk_bf16_f32 v136, v48, v49
	v_mul_f32_e32 v46, v46, v144
	v_mul_f32_e32 v47, v47, v144
	v_mul_f32_e32 v44, v44, v144
	v_mul_f32_e32 v45, v45, v144
	v_mul_f32_e32 v42, v42, v144
	v_mul_f32_e32 v43, v43, v144
	v_mul_f32_e32 v40, v40, v144
	v_mul_f32_e32 v41, v41, v144
	v_mul_f32_e32 v38, v38, v144
	v_mul_f32_e32 v39, v39, v144
	v_mul_f32_e32 v36, v36, v144
	v_mul_f32_e32 v37, v37, v144
	v_mul_f32_e32 v34, v34, v144
	v_mul_f32_e32 v35, v35, v144
	v_mul_f32_e32 v32, v32, v144
	v_mul_f32_e32 v33, v33, v144
	v_cvt_pk_bf16_f32 v137, v50, v51
	v_cvt_pk_bf16_f32 v138, v52, v53
	v_cvt_pk_bf16_f32 v139, v54, v55
	v_mul_f32_e32 v30, v30, v144
	v_mul_f32_e32 v31, v31, v144
	v_mul_f32_e32 v28, v28, v144
	v_mul_f32_e32 v29, v29, v144
	s_waitcnt lgkmcnt(2)
	v_mfma_f32_32x32x16_bf16 v[32:47], v[132:135], v[136:139], v[32:47]
	v_mul_f32_e32 v26, v26, v144
	v_mul_f32_e32 v27, v27, v144
	v_mul_f32_e32 v24, v24, v144
	v_mul_f32_e32 v25, v25, v144
	v_mul_f32_e32 v22, v22, v144
	v_mul_f32_e32 v23, v23, v144
	v_mul_f32_e32 v20, v20, v144
	v_mul_f32_e32 v21, v21, v144
	v_mul_f32_e32 v18, v18, v144
	v_mul_f32_e32 v19, v19, v144
	v_mul_f32_e32 v16, v16, v144
	v_mul_f32_e32 v17, v17, v144
	ds_read_b64_tr_b16 v[132:133], v147 offset:28928
	ds_read_b64_tr_b16 v[134:135], v147 offset:30080
	s_waitcnt lgkmcnt(2)
	v_mfma_f32_32x32x16_bf16 v[16:31], v[140:143], v[136:139], v[16:31]
	v_sub_f32_e32 v64, v64, v145
	ds_read_b64_tr_b16 v[142:143], v147 offset:30144
	ds_read_b64_tr_b16 v[140:141], v147 offset:28992
	v_exp_f32_e32 v64, v64
	v_sub_f32_e32 v65, v65, v145
	v_exp_f32_e32 v65, v65
	v_cvt_pk_bf16_f32 v136, v56, v57
	v_cvt_pk_bf16_f32 v137, v58, v59
	v_cvt_pk_bf16_f32 v138, v60, v61
	v_cvt_pk_bf16_f32 v139, v62, v63
	v_sub_f32_e32 v66, v66, v145
	v_sub_f32_e32 v67, v67, v145
	s_waitcnt lgkmcnt(2)
	v_mfma_f32_32x32x16_bf16 v[32:47], v[132:135], v[136:139], v[32:47]
	v_sub_f32_e32 v68, v68, v145
	v_sub_f32_e32 v69, v69, v145
	v_sub_f32_e32 v70, v70, v145
	v_sub_f32_e32 v71, v71, v145
	v_add_f32_e32 v132, v64, v146
	v_exp_f32_e32 v66, v66
	v_exp_f32_e32 v67, v67
	s_waitcnt lgkmcnt(0)
	v_mfma_f32_32x32x16_bf16 v[16:31], v[140:143], v[136:139], v[16:31]
	v_exp_f32_e32 v68, v68
	v_exp_f32_e32 v69, v69
	v_exp_f32_e32 v70, v70
	v_exp_f32_e32 v71, v71
	v_add_f32_e32 v146, v65, v132
	ds_read_b64_tr_b16 v[132:133], v147 offset:31232
	ds_read_b64_tr_b16 v[134:135], v147 offset:32384
	ds_read_b64_tr_b16 v[142:143], v147 offset:32448
	ds_read_b64_tr_b16 v[140:141], v147 offset:31296
	v_add_f32_e32 v146, v66, v146
	v_cvt_pk_bf16_f32 v136, v64, v65
	v_cvt_pk_bf16_f32 v137, v66, v67
	v_cvt_pk_bf16_f32 v138, v68, v69
	v_cvt_pk_bf16_f32 v139, v70, v71
	v_sub_f32_e32 v72, v72, v145
	v_sub_f32_e32 v73, v73, v145
	s_waitcnt lgkmcnt(2)
	v_mfma_f32_32x32x16_bf16 v[32:47], v[132:135], v[136:139], v[32:47]
	v_add_f32_e32 v132, v67, v146
	v_add_f32_e32 v132, v68, v132
	v_add_f32_e32 v132, v69, v132
	v_sub_f32_e32 v74, v74, v145
	v_sub_f32_e32 v75, v75, v145
	v_sub_f32_e32 v76, v76, v145
	v_sub_f32_e32 v77, v77, v145
	s_waitcnt lgkmcnt(0)
	v_mfma_f32_32x32x16_bf16 v[16:31], v[140:143], v[136:139], v[16:31]
	v_sub_f32_e32 v78, v78, v145
	v_sub_f32_e32 v79, v79, v145
	v_add_f32_e32 v132, v70, v132
	v_exp_f32_e32 v72, v72
	v_exp_f32_e32 v73, v73
	v_exp_f32_e32 v74, v74
	v_exp_f32_e32 v75, v75
	v_exp_f32_e32 v76, v76
	v_exp_f32_e32 v77, v77
	v_exp_f32_e32 v78, v78
	v_exp_f32_e32 v79, v79
	v_add_f32_e32 v146, v71, v132
	ds_read_b64_tr_b16 v[132:133], v147 offset:33536
	ds_read_b64_tr_b16 v[134:135], v147 offset:34688
	ds_read_b64_tr_b16 v[142:143], v147 offset:34752
	ds_read_b64_tr_b16 v[140:141], v147 offset:33600
	v_add_f32_e32 v146, v72, v146
	v_cvt_pk_bf16_f32 v136, v72, v73
	v_cvt_pk_bf16_f32 v137, v74, v75
	v_cvt_pk_bf16_f32 v138, v76, v77
	v_cvt_pk_bf16_f32 v139, v78, v79
	v_mov_b32_e32 v181, v145
	s_waitcnt lgkmcnt(2)
	v_mfma_f32_32x32x16_bf16 v[32:47], v[132:135], v[136:139], v[32:47]
	v_add_f32_e32 v132, v73, v146
	v_add_f32_e32 v132, v74, v132
	v_add_f32_e32 v132, v75, v132
	v_add_f32_e32 v132, v76, v132
	v_add_f32_e32 v132, v77, v132
	v_add_f32_e32 v132, v78, v132
	v_add_f32_e32 v132, v79, v132
	s_waitcnt lgkmcnt(0)
	v_mfma_f32_32x32x16_bf16 v[16:31], v[140:143], v[136:139], v[16:31]
	v_fmac_f32_e32 v132, v212, v144
	v_mov_b32_e32 v212, v132

; DI unsigned pk_bf16(float lo, float hi) { f32x2 v = {lo, hi}; bf2_t b = __builtin_convertvector(v, bf2_t); return __builtin_bit_cast(unsigned, b); }
; DI float bf_lo(unsigned u) { return __uint_as_float(u << 16); }
; DI float bf_hi(unsigned u) { return __uint_as_float(u & 0xffff0000u); }
; template <int DQK, bool SB, bool SMAX>
; DI void attn_item(const Params& p, char* smem, int bh, int qb, float Mb) {
;     ...
;   float inv = 1.f;
;   if (!SB) { const float lt = lsum + other_half(lsum); inv = 1.f / lt; }
;   const size_t token = (size_t)(bh >> 3) * S_ + query;
;   const int colbase = (SB ? 0 : 512) + (bh & 7) * 64;
; #pragma unroll
;   for (int db = 0; db < 2; ++db) {
;     u32x2 w[4];
; #pragma unroll
;     for (int g = 0; g < 4; ++g) {
;       const int col = colbase + db * 32 + 8 * g + 4 * h;
;       const u32x2 gt = *(const u32x2*)(p.Gate + token * 1024 + col);
;       w[g].x = pk_bf16(O[db][4 * g] * inv * bf_lo(gt.x), O[db][4 * g + 1] * inv * bf_hi(gt.x));
;       w[g].y = pk_bf16(O[db][4 * g + 2] * inv * bf_lo(gt.y), O[db][4 * g + 3] * inv * bf_hi(gt.y));
;     }
; #pragma unroll
;     for (int q = 0; q < 2; ++q) *(u32x4*)(p.Mixed + token * 1024 + colbase + db * 32 + 16 * q + 8 * h) = widen_pair(w[2 * q], w[2 * q + 1]);
;   }
.LBB0_469:
	s_lshl_b32 s2, s0, 6
	v_readlane_b32 s14, v255, 15
	s_and_b32 s2, s2, 0x1c0
	v_lshlrev_b64 v[48:49], 11, v[176:177]
	v_readlane_b32 s15, v255, 16
	v_or_b32_e32 v52, s2, v197
	v_lshlrev_b32_e32 v52, 1, v52
	v_lshl_add_u64 v[48:49], v[48:49], 0, s[14:15]
	v_lshl_add_u64 v[50:51], s[94:95], 0, v[48:49]
	v_mov_b32_e32 v53, v177
	v_lshl_add_u64 v[50:51], v[50:51], 0, v[52:53]
	global_load_dwordx2 v[52:53], v[50:51], off offset:1024
	global_load_dwordx2 v[54:55], v[50:51], off offset:1040
	global_load_dwordx2 v[56:57], v[50:51], off offset:1056
	global_load_dwordx2 v[58:59], v[50:51], off offset:1072
	v_mov_b32_e32 v60, v212
	v_mov_b32_e32 v61, v212
	s_nop 1
	v_permlane32_swap_b32_e32 v60, v61
	v_cndmask_b32_e64 v60, v60, v61, s[8:9]
	v_add_f32_e32 v60, v212, v60
	s_lshl_b32 s4, s2, 1
	v_div_scale_f32 v61, s[2:3], v60, v60, 1.0
	v_rcp_f32_e32 v62, v61
	v_div_scale_f32 v63, vcc, 1.0, v60, 1.0
	v_lshl_add_u64 v[48:49], s[86:87], 0, v[48:49]
	v_fma_f32 v64, -v61, v62, 1.0
	v_fmac_f32_e32 v62, v64, v62
	v_mul_f32_e32 v64, v63, v62
	v_fma_f32 v65, -v61, v64, v63
	v_fmac_f32_e32 v64, v65, v62
	v_fma_f32 v61, -v61, v64, v63
	v_div_fmas_f32 v61, v61, v62, v64
	v_div_fixup_f32 v60, v61, v60, 1.0
	v_mul_f32_e32 v32, v32, v60
	v_mul_f32_e32 v33, v33, v60
	v_mul_f32_e32 v34, v34, v60
	v_mul_f32_e32 v35, v35, v60
	v_mul_f32_e32 v36, v36, v60
	v_mul_f32_e32 v37, v37, v60
	v_mul_f32_e32 v38, v38, v60
	v_mul_f32_e32 v39, v39, v60
	v_mul_f32_e32 v40, v40, v60
	v_mul_f32_e32 v41, v41, v60
	v_mul_f32_e32 v42, v42, v60
	v_mul_f32_e32 v43, v43, v60
	v_mul_f32_e32 v44, v44, v60
	v_mul_f32_e32 v45, v45, v60
	v_mul_f32_e32 v46, v46, v60
	v_mul_f32_e32 v47, v47, v60
	v_mov_b32_e32 v181, v177
	v_lshl_add_u64 v[48:49], v[48:49], 0, s[4:5]
	v_lshl_add_u64 v[48:49], v[48:49], 0, v[180:181]
	v_mul_f32_e32 v16, v16, v60
	v_mul_f32_e32 v17, v17, v60
	v_mul_f32_e32 v18, v18, v60
	v_mul_f32_e32 v19, v19, v60
	v_mul_f32_e32 v20, v20, v60
	v_mul_f32_e32 v21, v21, v60
	v_mul_f32_e32 v22, v22, v60
	v_mul_f32_e32 v23, v23, v60
	v_mul_f32_e32 v24, v24, v60
	v_mul_f32_e32 v25, v25, v60
	v_mul_f32_e32 v26, v26, v60
	v_mul_f32_e32 v27, v27, v60
	v_mul_f32_e32 v28, v28, v60
	v_mul_f32_e32 v29, v29, v60
	v_mul_f32_e32 v30, v30, v60
	v_mul_f32_e32 v31, v31, v60
	s_mov_b64 s[2:3], 0
	s_waitcnt vmcnt(3)
	v_lshlrev_b32_e32 v62, 16, v52
	v_and_b32_e32 v63, 0xffff0000, v52
	v_lshlrev_b32_e32 v52, 16, v53
	v_and_b32_e32 v53, 0xffff0000, v53
	s_waitcnt vmcnt(2)
	v_lshlrev_b32_e32 v64, 16, v54
	v_and_b32_e32 v65, 0xffff0000, v54
	v_lshlrev_b32_e32 v54, 16, v55
	v_and_b32_e32 v55, 0xffff0000, v55
	s_waitcnt vmcnt(1)
	v_lshlrev_b32_e32 v66, 16, v56
	v_and_b32_e32 v67, 0xffff0000, v56
	v_lshlrev_b32_e32 v56, 16, v57
	v_and_b32_e32 v57, 0xffff0000, v57
	s_waitcnt vmcnt(0)
	v_lshlrev_b32_e32 v68, 16, v58
	v_and_b32_e32 v69, 0xffff0000, v58
	v_lshlrev_b32_e32 v58, 16, v59
	v_and_b32_e32 v59, 0xffff0000, v59
	v_mul_f32_e32 v32, v32, v62
	v_mul_f32_e32 v33, v33, v63
	v_mul_f32_e32 v34, v34, v52
	v_mul_f32_e32 v35, v35, v53
	v_mul_f32_e32 v36, v36, v64
	v_mul_f32_e32 v37, v37, v65
	v_mul_f32_e32 v38, v38, v54
	v_mul_f32_e32 v39, v39, v55
	v_mul_f32_e32 v40, v40, v66
	v_mul_f32_e32 v41, v41, v67
	v_mul_f32_e32 v42, v42, v56
	v_mul_f32_e32 v43, v43, v57
	v_mul_f32_e32 v44, v44, v68
	v_mul_f32_e32 v45, v45, v69
	v_mul_f32_e32 v46, v46, v58
	v_mul_f32_e32 v47, v47, v59
	v_cvt_pk_bf16_f32 v32, v32, v33
	v_cvt_pk_bf16_f32 v33, v34, v35
	v_cvt_pk_bf16_f32 v34, v36, v37
	v_cvt_pk_bf16_f32 v35, v38, v39
	v_cvt_pk_bf16_f32 v36, v40, v41
	v_cvt_pk_bf16_f32 v37, v42, v43
	v_cvt_pk_bf16_f32 v38, v44, v45
	v_cvt_pk_bf16_f32 v39, v46, v47
	v_permlane32_swap_b32_e32 v32, v34
	v_permlane32_swap_b32_e32 v33, v35
	v_permlane32_swap_b32_e32 v36, v38
	v_permlane32_swap_b32_e32 v37, v39
	global_store_dwordx4 v[48:49], v[32:35], off offset:1024
	global_store_dwordx4 v[48:49], v[36:39], off offset:1056
	global_load_dwordx2 v[32:33], v[50:51], off offset:1088
	s_nop 0
	global_load_dwordx2 v[34:35], v[50:51], off offset:1104
	global_load_dwordx2 v[36:37], v[50:51], off offset:1120
	global_load_dwordx2 v[38:39], v[50:51], off offset:1136
	s_waitcnt vmcnt(3)
	v_lshlrev_b32_e32 v40, 16, v32
	v_and_b32_e32 v41, 0xffff0000, v32
	v_lshlrev_b32_e32 v32, 16, v33
	v_and_b32_e32 v33, 0xffff0000, v33
	s_waitcnt vmcnt(2)
	v_lshlrev_b32_e32 v42, 16, v34
	v_and_b32_e32 v43, 0xffff0000, v34
	v_lshlrev_b32_e32 v34, 16, v35
	v_and_b32_e32 v35, 0xffff0000, v35
	s_waitcnt vmcnt(1)
	v_lshlrev_b32_e32 v44, 16, v36
	v_and_b32_e32 v45, 0xffff0000, v36
	v_lshlrev_b32_e32 v36, 16, v37
	v_and_b32_e32 v37, 0xffff0000, v37
	s_waitcnt vmcnt(0)
	v_lshlrev_b32_e32 v46, 16, v38
	v_and_b32_e32 v47, 0xffff0000, v38
	v_lshlrev_b32_e32 v38, 16, v39
	v_and_b32_e32 v39, 0xffff0000, v39
	v_mul_f32_e32 v16, v16, v40
	v_mul_f32_e32 v17, v17, v41
	v_mul_f32_e32 v18, v18, v32
	v_mul_f32_e32 v19, v19, v33
	v_mul_f32_e32 v20, v20, v42
	v_mul_f32_e32 v21, v21, v43
	v_mul_f32_e32 v22, v22, v34
	v_mul_f32_e32 v23, v23, v35
	v_mul_f32_e32 v24, v24, v44
	v_mul_f32_e32 v25, v25, v45
	v_mul_f32_e32 v26, v26, v36
	v_mul_f32_e32 v27, v27, v37
	v_mul_f32_e32 v28, v28, v46
	v_mul_f32_e32 v29, v29, v47
	v_mul_f32_e32 v30, v30, v38
	v_mul_f32_e32 v31, v31, v39
	v_cvt_pk_bf16_f32 v16, v16, v17
	v_cvt_pk_bf16_f32 v17, v18, v19
	v_cvt_pk_bf16_f32 v18, v20, v21
	v_cvt_pk_bf16_f32 v19, v22, v23
	v_cvt_pk_bf16_f32 v20, v24, v25
	v_cvt_pk_bf16_f32 v21, v26, v27
	v_cvt_pk_bf16_f32 v22, v28, v29
	v_cvt_pk_bf16_f32 v23, v30, v31
	v_permlane32_swap_b32_e32 v16, v18
	v_permlane32_swap_b32_e32 v17, v19
	v_permlane32_swap_b32_e32 v20, v22
	v_permlane32_swap_b32_e32 v21, v23
	global_store_dwordx4 v[48:49], v[16:19], off offset:1088
	global_store_dwordx4 v[48:49], v[20:23], off offset:1120
	s_barrier

;     ...
;   if (cold) {
;     GT_LOAD(0, 0)
;     GT_LOAD(1, 1)
;     GT_WRITE(0, lds, true)
;     GT_LOAD(0, (2 < nk) ? 2 : nk - 1)
;     __syncthreads();
;   }
;   for (int kt2 = 0; kt2 < nk; kt2 += 2) {
; #pragma unroll
;     for (int st = 0; st < 2; ++st) {
;       const int kt = kt2 + st;
;       const bf16_t* cur = lds + st * BUFE;
;       bf16_t* oth = lds + (st ^ 1) * BUFE;
;       const long k0r = (kt + 3 < nk) ? (long)(kt + 3) * BK : dR + (long)(kt + 3 - nk) * BK;
;       const long k0c = (kt + 3 < nk) ? (long)(kt + 3) * BK : dC + (long)(kt + 3 - nk) * BK;
;       const bool cnt = kt + 1 < nk;
;       const bf16_t* abase = cur + (wr * (RM / WR) + r) * STR + h * 8;
;       const bf16_t* bbase = cur + (RM + wc * (CN / WC) + r) * STR + h * 8;
;       bf16x8 af[2][MI], bfr[2][NI];
;       if (FDB) {
; #pragma unroll
;         for (int mi = 0; mi < MI; ++mi) af[0][mi] = *(const bf16x8*)(abase + mi * 32 * STR);
; #pragma unroll
;         for (int ni = 0; ni < NI; ++ni) bfr[0][ni] = *(const bf16x8*)(bbase + ni * 32 * STR);
;       }
; #pragma unroll
;       for (int ks = 0; ks < KS; ++ks) {
;         if (!FDB) {
; #pragma unroll
;           for (int mi = 0; mi < MI; ++mi) af[ks & 1][mi] = *(const bf16x8*)(abase + mi * 32 * STR + ks * 16);
; #pragma unroll
;           for (int ni = 0; ni < NI; ++ni) bfr[ks & 1][ni] = *(const bf16x8*)(bbase + ni * 32 * STR + ks * 16);
;         }
; #pragma unroll
;         for (int c = ks; c < RCH; c += KS) *(u32x4*)(oth + (srow + RPP * c) * STR + skc) = rr[st ^ 1][c];
; #pragma unroll
;         for (int c = ks; c < CCH; c += KS) {
;           *(u32x4*)(oth + (RM + srow + RPP * c) * STR + skc) = cr[st ^ 1][c];
;           if (SUMSQ && cnt) {
; #pragma unroll
;             for (int e = 0; e < 4; ++e) { const float a_ = bf_lo(cr[st ^ 1][c][e]), b_ = bf_hi(cr[st ^ 1][c][e]); ss[c] += a_ * a_ + b_ * b_; }
;           }
;         }
; #pragma unroll
;         for (int c = ks; c < RCH; c += KS) rr[st ^ 1][c] = *(const u32x4*)(rp + (size_t)(RPP * c) * ldr + k0r);
; #pragma unroll
;         for (int c = ks; c < CCH; c += KS) cr[st ^ 1][c] = *(const u32x4*)(cp + (size_t)(RPP * c) * ldc + k0c);
;         __builtin_amdgcn_sched_barrier(0);
;         if (FDB && ks + 1 < KS) {
; #pragma unroll
;           for (int mi = 0; mi < MI; ++mi) af[(ks + 1) & 1][mi] = *(const bf16x8*)(abase + mi * 32 * STR + (ks + 1) * 16);
; #pragma unroll
.LBB0_529:
	s_ashr_i32 s2, s25, 3
	s_and_b32 s27, s2, -8
	s_add_i32 s27, s27, s23
	s_and_b32 s2, s25, 7
	s_or_b32 s2, s27, s2
	s_and_b32 s26, s24, 0x380
	s_lshl_b32 s8, s2, 7
	s_lshl_b32 s2, s26, 11
	v_lshl_add_u64 v[116:117], v[98:99], 0, s[2:3]
	v_add_co_u32_e32 v112, vcc, s12, v116
	s_ashr_i32 s9, s8, 31
	s_nop 0
	v_addc_co_u32_e32 v113, vcc, 0, v117, vcc
	v_add_co_u32_e32 v108, vcc, s13, v116
	s_lshl_b64 s[28:29], s[8:9], 11
	s_nop 0
	v_addc_co_u32_e32 v109, vcc, 0, v117, vcc
	v_add_co_u32_e32 v104, vcc, s14, v116
	v_lshl_add_u64 v[118:119], v[100:101], 0, s[28:29]
	s_nop 0
	v_addc_co_u32_e32 v105, vcc, 0, v117, vcc
	v_add_co_u32_e32 v114, vcc, s12, v118
	global_load_dwordx4 v[84:87], v[116:117], off
	s_nop 0
	v_addc_co_u32_e32 v115, vcc, 0, v119, vcc
	v_add_co_u32_e32 v110, vcc, s13, v118
	global_load_dwordx4 v[80:83], v[112:113], off
	global_load_dwordx4 v[68:71], v[108:109], off
	v_addc_co_u32_e32 v111, vcc, 0, v119, vcc
	v_add_co_u32_e32 v106, vcc, s14, v118
	global_load_dwordx4 v[64:67], v[104:105], off
	global_load_dwordx4 v[92:95], v[118:119], off
	global_load_dwordx4 v[88:91], v[114:115], off
	global_load_dwordx4 v[76:79], v[110:111], off
	v_addc_co_u32_e32 v107, vcc, 0, v119, vcc
	global_load_dwordx4 v[72:75], v[106:107], off
	global_load_dwordx4 v[0:3], v[116:117], off offset:128
	global_load_dwordx4 v[4:7], v[112:113], off offset:128
	global_load_dwordx4 v[142:145], v[108:109], off offset:128
	global_load_dwordx4 v[146:149], v[104:105], off offset:128
	global_load_dwordx4 v[8:11], v[118:119], off offset:128
	global_load_dwordx4 v[12:15], v[114:115], off offset:128
	global_load_dwordx4 v[150:153], v[110:111], off offset:128
	global_load_dwordx4 v[154:157], v[106:107], off offset:128
	global_load_dwordx4 v[158:161], v[116:117], off offset:256
	global_load_dwordx4 v[162:165], v[112:113], off offset:256
	global_load_dwordx4 v[166:169], v[108:109], off offset:256
	global_load_dwordx4 v[170:173], v[104:105], off offset:256
	global_load_dwordx4 v[174:177], v[118:119], off offset:256
	global_load_dwordx4 v[178:181], v[114:115], off offset:256
	global_load_dwordx4 v[182:185], v[110:111], off offset:256
	global_load_dwordx4 v[186:189], v[106:107], off offset:256
	s_waitcnt vmcnt(23)
	ds_write_b128 v120, v[84:87]
	s_waitcnt vmcnt(22)
	ds_write_b128 v120, v[80:83] offset:4608
	s_waitcnt vmcnt(21)
	ds_write_b128 v120, v[68:71] offset:9216
	s_waitcnt vmcnt(20)
	ds_write_b128 v120, v[64:67] offset:13824
	s_waitcnt vmcnt(19)
	ds_write_b128 v120, v[92:95] offset:18432
	s_waitcnt vmcnt(18)
	ds_write_b128 v120, v[88:91] offset:23040
	s_waitcnt vmcnt(17)
	ds_write_b128 v120, v[76:79] offset:27648
	s_waitcnt vmcnt(16)
	ds_write_b128 v120, v[72:75] offset:32256
	s_waitcnt lgkmcnt(0)
	s_barrier
	global_load_dwordx4 v[190:193], v[116:117], off offset:384
	global_load_dwordx4 v[194:197], v[118:119], off offset:384
	ds_read_b128 v[16:19], v121
	ds_read_b128 v[198:201], v121 offset:4608
	ds_read_b128 v[20:23], v122 offset:18432
	ds_read_b128 v[202:205], v122 offset:23040
	s_waitcnt vmcnt(17)
	ds_write_b128 v120, v[0:3] offset:36864
	s_waitcnt vmcnt(13)
	ds_write_b128 v120, v[8:11] offset:55296
	global_load_dwordx4 v[206:209], v[112:113], off offset:384
	global_load_dwordx4 v[210:213], v[114:115], off offset:384
	ds_read_b128 v[214:217], v121 offset:32
	ds_read_b128 v[218:221], v121 offset:4640
	ds_read_b128 v[222:225], v122 offset:18464
	ds_read_b128 v[226:229], v122 offset:23072
	s_waitcnt lgkmcnt(7)
	v_mfma_f32_32x32x16_bf16 v[48:63], v[16:19], v[20:23], 0
	ds_write_b128 v120, v[4:7] offset:41472
	s_waitcnt vmcnt(14)
	ds_write_b128 v120, v[12:15] offset:59904
	s_waitcnt lgkmcnt(8)
	v_mfma_f32_32x32x16_bf16 v[32:47], v[16:19], v[202:205], 0
	v_mfma_f32_32x32x16_bf16 v[16:31], v[198:201], v[20:23], 0
	v_mfma_f32_32x32x16_bf16 v[0:15], v[198:201], v[202:205], 0
	global_load_dwordx4 v[198:201], v[108:109], off offset:384
	global_load_dwordx4 v[202:205], v[110:111], off offset:384
	s_waitcnt lgkmcnt(3)
	v_mfma_f32_32x32x16_bf16 v[48:63], v[214:217], v[222:225], v[48:63]
	s_waitcnt lgkmcnt(2)
	v_mfma_f32_32x32x16_bf16 v[32:47], v[214:217], v[226:229], v[32:47]
	v_mfma_f32_32x32x16_bf16 v[16:31], v[218:221], v[222:225], v[16:31]
	ds_read_b128 v[214:217], v121 offset:64
	ds_read_b128 v[222:225], v121 offset:4672
	ds_read_b128 v[230:233], v122 offset:18496
	ds_read_b128 v[234:237], v122 offset:23104
	ds_write_b128 v120, v[142:145] offset:46080
	s_waitcnt vmcnt(15)
	ds_write_b128 v120, v[150:153] offset:64512
	v_mfma_f32_32x32x16_bf16 v[0:15], v[218:221], v[226:229], v[0:15]
	global_load_dwordx4 v[142:145], v[104:105], off offset:384
	global_load_dwordx4 v[150:153], v[106:107], off offset:384
	s_waitcnt lgkmcnt(3)
	v_mfma_f32_32x32x16_bf16 v[48:63], v[214:217], v[230:233], v[48:63]
	s_waitcnt lgkmcnt(2)
	v_mfma_f32_32x32x16_bf16 v[32:47], v[214:217], v[234:237], v[32:47]
	v_mfma_f32_32x32x16_bf16 v[16:31], v[222:225], v[230:233], v[16:31]
	ds_read_b128 v[214:217], v121 offset:96
	ds_read_b128 v[218:221], v121 offset:4704
	ds_read_b128 v[226:229], v122 offset:18528
	ds_read_b128 v[230:233], v122 offset:23136
	ds_write_b128 v120, v[146:149] offset:50688
	s_waitcnt vmcnt(16)
	ds_write_b128 v123, v[154:157] offset:13824
	v_mfma_f32_32x32x16_bf16 v[0:15], v[222:225], v[234:237], v[0:15]
	s_waitcnt lgkmcnt(0)
	s_barrier
;     ...
;   for (int kt2 = 0; kt2 < nk; kt2 += 2) {
; #pragma unroll
;     for (int st = 0; st < 2; ++st) {
;       const int kt = kt2 + st;
;       const bf16_t* cur = lds + st * BUFE;
;       bf16_t* oth = lds + (st ^ 1) * BUFE;
;       const long k0r = (kt + 3 < nk) ? (long)(kt + 3) * BK : dR + (long)(kt + 3 - nk) * BK;
;       const long k0c = (kt + 3 < nk) ? (long)(kt + 3) * BK : dC + (long)(kt + 3 - nk) * BK;
;       const bool cnt = kt + 1 < nk;
;       const bf16_t* abase = cur + (wr * (RM / WR) + r) * STR + h * 8;
;       const bf16_t* bbase = cur + (RM + wc * (CN / WC) + r) * STR + h * 8;
;       bf16x8 af[2][MI], bfr[2][NI];
;       if (FDB) {
; #pragma unroll
;         for (int mi = 0; mi < MI; ++mi) af[0][mi] = *(const bf16x8*)(abase + mi * 32 * STR);
; #pragma unroll
;         for (int ni = 0; ni < NI; ++ni) bfr[0][ni] = *(const bf16x8*)(bbase + ni * 32 * STR);
;       }
; #pragma unroll
;       for (int ks = 0; ks < KS; ++ks) {
;         if (!FDB) {
; #pragma unroll
;           for (int mi = 0; mi < MI; ++mi) af[ks & 1][mi] = *(const bf16x8*)(abase + mi * 32 * STR + ks * 16);
; #pragma unroll
;           for (int ni = 0; ni < NI; ++ni) bfr[ks & 1][ni] = *(const bf16x8*)(bbase + ni * 32 * STR + ks * 16);
;         }
; #pragma unroll
;         for (int c = ks; c < RCH; c += KS) *(u32x4*)(oth + (srow + RPP * c) * STR + skc) = rr[st ^ 1][c];
; #pragma unroll
;         for (int c = ks; c < CCH; c += KS) {
;           *(u32x4*)(oth + (RM + srow + RPP * c) * STR + skc) = cr[st ^ 1][c];
;           if (SUMSQ && cnt) {
; #pragma unroll
;             for (int e = 0; e < 4; ++e) { const float a_ = bf_lo(cr[st ^ 1][c][e]), b_ = bf_hi(cr[st ^ 1][c][e]); ss[c] += a_ * a_ + b_ * b_; }
;           }
;         }
; #pragma unroll
;         for (int c = ks; c < RCH; c += KS) rr[st ^ 1][c] = *(const u32x4*)(rp + (size_t)(RPP * c) * ldr + k0r);
; #pragma unroll
;         for (int c = ks; c < CCH; c += KS) cr[st ^ 1][c] = *(const u32x4*)(cp + (size_t)(RPP * c) * ldc + k0c);
;         __builtin_amdgcn_sched_barrier(0);
;         if (FDB && ks + 1 < KS) {
; #pragma unroll
;           for (int mi = 0; mi < MI; ++mi) af[(ks + 1) & 1][mi] = *(const bf16x8*)(abase + mi * 32 * STR + (ks + 1) * 16);
; #pragma unroll
;           for (int ni = 0; ni < NI; ++ni) bfr[(ks + 1) & 1][ni] = *(const bf16x8*)(bbase + ni * 32 * STR + (ks + 1) * 16);
;         }
; #pragma unroll
	global_load_dwordx4 v[146:149], v[116:117], off offset:512
	global_load_dwordx4 v[154:157], v[118:119], off offset:512
	v_mfma_f32_32x32x16_bf16 v[48:63], v[214:217], v[226:229], v[48:63]
	v_mfma_f32_32x32x16_bf16 v[32:47], v[214:217], v[230:233], v[32:47]
	v_mfma_f32_32x32x16_bf16 v[16:31], v[218:221], v[226:229], v[16:31]
	ds_read_b128 v[214:217], v121 offset:36864
	ds_read_b128 v[222:225], v121 offset:41472
	ds_read_b128 v[226:229], v122 offset:55296
	ds_read_b128 v[234:237], v122 offset:59904
	s_waitcnt vmcnt(17)
	ds_write_b128 v120, v[158:161]
	s_waitcnt vmcnt(13)
	ds_write_b128 v120, v[174:177] offset:18432
	v_mfma_f32_32x32x16_bf16 v[0:15], v[218:221], v[230:233], v[0:15]
	global_load_dwordx4 v[158:161], v[112:113], off offset:512
	global_load_dwordx4 v[174:177], v[114:115], off offset:512
	s_waitcnt lgkmcnt(3)
	v_mfma_f32_32x32x16_bf16 v[48:63], v[214:217], v[226:229], v[48:63]
	s_waitcnt lgkmcnt(2)
	v_mfma_f32_32x32x16_bf16 v[32:47], v[214:217], v[234:237], v[32:47]
	v_mfma_f32_32x32x16_bf16 v[16:31], v[222:225], v[226:229], v[16:31]
	ds_read_b128 v[214:217], v121 offset:36896
	ds_read_b128 v[218:221], v121 offset:41504
	ds_read_b128 v[226:229], v122 offset:55328
	ds_read_b128 v[230:233], v122 offset:59936
	ds_write_b128 v120, v[162:165] offset:4608
	s_waitcnt vmcnt(14)
	ds_write_b128 v120, v[178:181] offset:23040
	v_mfma_f32_32x32x16_bf16 v[0:15], v[222:225], v[234:237], v[0:15]
	global_load_dwordx4 v[162:165], v[108:109], off offset:512
	global_load_dwordx4 v[178:181], v[110:111], off offset:512
	s_waitcnt lgkmcnt(3)
	v_mfma_f32_32x32x16_bf16 v[48:63], v[214:217], v[226:229], v[48:63]
	s_waitcnt lgkmcnt(2)
	v_mfma_f32_32x32x16_bf16 v[32:47], v[214:217], v[230:233], v[32:47]
	v_mfma_f32_32x32x16_bf16 v[16:31], v[218:221], v[226:229], v[16:31]
	ds_read_b128 v[214:217], v121 offset:36928
	ds_read_b128 v[222:225], v121 offset:41536
	ds_read_b128 v[226:229], v122 offset:55360
	ds_read_b128 v[234:237], v122 offset:59968
	ds_write_b128 v120, v[166:169] offset:9216
	s_waitcnt vmcnt(15)
	ds_write_b128 v120, v[182:185] offset:27648
	v_mfma_f32_32x32x16_bf16 v[0:15], v[218:221], v[230:233], v[0:15]
	global_load_dwordx4 v[166:169], v[104:105], off offset:512
	global_load_dwordx4 v[182:185], v[106:107], off offset:512
	s_waitcnt lgkmcnt(3)
	v_mfma_f32_32x32x16_bf16 v[48:63], v[214:217], v[226:229], v[48:63]
	s_waitcnt lgkmcnt(2)
	v_mfma_f32_32x32x16_bf16 v[32:47], v[214:217], v[234:237], v[32:47]
	v_mfma_f32_32x32x16_bf16 v[16:31], v[222:225], v[226:229], v[16:31]
	ds_read_b128 v[214:217], v121 offset:36960
	ds_read_b128 v[218:221], v121 offset:41568
	ds_read_b128 v[226:229], v122 offset:55392
	ds_read_b128 v[230:233], v122 offset:60000
	ds_write_b128 v120, v[170:173] offset:13824
	s_waitcnt vmcnt(16)
	ds_write_b128 v120, v[186:189] offset:32256
	v_mfma_f32_32x32x16_bf16 v[0:15], v[222:225], v[234:237], v[0:15]
	s_waitcnt lgkmcnt(0)
	s_barrier
	global_load_dwordx4 v[170:173], v[116:117], off offset:640
	global_load_dwordx4 v[186:189], v[118:119], off offset:640
	v_mfma_f32_32x32x16_bf16 v[48:63], v[214:217], v[226:229], v[48:63]
	v_mfma_f32_32x32x16_bf16 v[32:47], v[214:217], v[230:233], v[32:47]
	v_mfma_f32_32x32x16_bf16 v[16:31], v[218:221], v[226:229], v[16:31]
	ds_read_b128 v[214:217], v121
	ds_read_b128 v[222:225], v121 offset:4608
	ds_read_b128 v[226:229], v122 offset:18432
	ds_read_b128 v[234:237], v122 offset:23040
	s_waitcnt vmcnt(17)
	ds_write_b128 v120, v[190:193] offset:36864
	s_waitcnt vmcnt(16)
	ds_write_b128 v120, v[194:197] offset:55296
	v_mfma_f32_32x32x16_bf16 v[0:15], v[218:221], v[230:233], v[0:15]
	global_load_dwordx4 v[190:193], v[112:113], off offset:640
	global_load_dwordx4 v[194:197], v[114:115], off offset:640
	s_waitcnt lgkmcnt(3)
	v_mfma_f32_32x32x16_bf16 v[48:63], v[214:217], v[226:229], v[48:63]
	s_waitcnt lgkmcnt(2)
	v_mfma_f32_32x32x16_bf16 v[32:47], v[214:217], v[234:237], v[32:47]
	v_mfma_f32_32x32x16_bf16 v[16:31], v[222:225], v[226:229], v[16:31]
	ds_read_b128 v[214:217], v121 offset:32
	ds_read_b128 v[218:221], v121 offset:4640
	ds_read_b128 v[226:229], v122 offset:18464
	ds_read_b128 v[230:233], v122 offset:23072
	s_waitcnt vmcnt(17)
	ds_write_b128 v120, v[206:209] offset:41472
	s_waitcnt vmcnt(16)
	ds_write_b128 v120, v[210:213] offset:59904
	v_mfma_f32_32x32x16_bf16 v[0:15], v[222:225], v[234:237], v[0:15]
	global_load_dwordx4 v[206:209], v[108:109], off offset:640
	global_load_dwordx4 v[210:213], v[110:111], off offset:640
	s_waitcnt lgkmcnt(3)
	v_mfma_f32_32x32x16_bf16 v[48:63], v[214:217], v[226:229], v[48:63]
	s_waitcnt lgkmcnt(2)
	v_mfma_f32_32x32x16_bf16 v[32:47], v[214:217], v[230:233], v[32:47]
	v_mfma_f32_32x32x16_bf16 v[16:31], v[218:221], v[226:229], v[16:31]
	ds_read_b128 v[214:217], v121 offset:64
	ds_read_b128 v[222:225], v121 offset:4672
	ds_read_b128 v[226:229], v122 offset:18496
	ds_read_b128 v[234:237], v122 offset:23104
	s_waitcnt vmcnt(17)
	ds_write_b128 v120, v[198:201] offset:46080
	s_waitcnt vmcnt(16)
	ds_write_b128 v120, v[202:205] offset:64512
	v_mfma_f32_32x32x16_bf16 v[0:15], v[218:221], v[230:233], v[0:15]
	global_load_dwordx4 v[198:201], v[104:105], off offset:640
	global_load_dwordx4 v[202:205], v[106:107], off offset:640
	s_waitcnt lgkmcnt(3)
	v_mfma_f32_32x32x16_bf16 v[48:63], v[214:217], v[226:229], v[48:63]
	s_waitcnt lgkmcnt(2)
	v_mfma_f32_32x32x16_bf16 v[32:47], v[214:217], v[234:237], v[32:47]
	v_mfma_f32_32x32x16_bf16 v[16:31], v[222:225], v[226:229], v[16:31]
	ds_read_b128 v[214:217], v121 offset:96
	ds_read_b128 v[218:221], v121 offset:4704
	ds_read_b128 v[226:229], v122 offset:18528
	ds_read_b128 v[230:233], v122 offset:23136
	s_waitcnt vmcnt(17)
	ds_write_b128 v120, v[142:145] offset:50688
	s_waitcnt vmcnt(16)
	ds_write_b128 v123, v[150:153] offset:13824
	v_mfma_f32_32x32x16_bf16 v[0:15], v[222:225], v[234:237], v[0:15]
	s_waitcnt lgkmcnt(0)
	s_barrier
;     ...
;   for (int kt2 = 0; kt2 < nk; kt2 += 2) {
; #pragma unroll
;     for (int st = 0; st < 2; ++st) {
;       const int kt = kt2 + st;
;       const bf16_t* cur = lds + st * BUFE;
;       bf16_t* oth = lds + (st ^ 1) * BUFE;
;       const long k0r = (kt + 3 < nk) ? (long)(kt + 3) * BK : dR + (long)(kt + 3 - nk) * BK;
;       const long k0c = (kt + 3 < nk) ? (long)(kt + 3) * BK : dC + (long)(kt + 3 - nk) * BK;
;       const bool cnt = kt + 1 < nk;
;       const bf16_t* abase = cur + (wr * (RM / WR) + r) * STR + h * 8;
;       const bf16_t* bbase = cur + (RM + wc * (CN / WC) + r) * STR + h * 8;
;       bf16x8 af[2][MI], bfr[2][NI];
;       if (FDB) {
; #pragma unroll
;         for (int mi = 0; mi < MI; ++mi) af[0][mi] = *(const bf16x8*)(abase + mi * 32 * STR);
; #pragma unroll
;         for (int ni = 0; ni < NI; ++ni) bfr[0][ni] = *(const bf16x8*)(bbase + ni * 32 * STR);
;       }
; #pragma unroll
;       for (int ks = 0; ks < KS; ++ks) {
;         if (!FDB) {
; #pragma unroll
;           for (int mi = 0; mi < MI; ++mi) af[ks & 1][mi] = *(const bf16x8*)(abase + mi * 32 * STR + ks * 16);
; #pragma unroll
;           for (int ni = 0; ni < NI; ++ni) bfr[ks & 1][ni] = *(const bf16x8*)(bbase + ni * 32 * STR + ks * 16);
;         }
; #pragma unroll
;         for (int c = ks; c < RCH; c += KS) *(u32x4*)(oth + (srow + RPP * c) * STR + skc) = rr[st ^ 1][c];
; #pragma unroll
;         for (int c = ks; c < CCH; c += KS) {
;           *(u32x4*)(oth + (RM + srow + RPP * c) * STR + skc) = cr[st ^ 1][c];
;           if (SUMSQ && cnt) {
; #pragma unroll
;             for (int e = 0; e < 4; ++e) { const float a_ = bf_lo(cr[st ^ 1][c][e]), b_ = bf_hi(cr[st ^ 1][c][e]); ss[c] += a_ * a_ + b_ * b_; }
;           }
;         }
; #pragma unroll
;         for (int c = ks; c < RCH; c += KS) rr[st ^ 1][c] = *(const u32x4*)(rp + (size_t)(RPP * c) * ldr + k0r);
; #pragma unroll
;         for (int c = ks; c < CCH; c += KS) cr[st ^ 1][c] = *(const u32x4*)(cp + (size_t)(RPP * c) * ldc + k0c);
;         __builtin_amdgcn_sched_barrier(0);
;         if (FDB && ks + 1 < KS) {
; #pragma unroll
;           for (int mi = 0; mi < MI; ++mi) af[(ks + 1) & 1][mi] = *(const bf16x8*)(abase + mi * 32 * STR + (ks + 1) * 16);
; #pragma unroll
;           for (int ni = 0; ni < NI; ++ni) bfr[(ks + 1) & 1][ni] = *(const bf16x8*)(bbase + ni * 32 * STR + (ks + 1) * 16);
;         }
; #pragma unroll
	global_load_dwordx4 v[142:145], v[116:117], off offset:768
	global_load_dwordx4 v[150:153], v[118:119], off offset:768
	v_mfma_f32_32x32x16_bf16 v[48:63], v[214:217], v[226:229], v[48:63]
	v_mfma_f32_32x32x16_bf16 v[32:47], v[214:217], v[230:233], v[32:47]
	v_mfma_f32_32x32x16_bf16 v[16:31], v[218:221], v[226:229], v[16:31]
	ds_read_b128 v[214:217], v121 offset:36864
	ds_read_b128 v[222:225], v121 offset:41472
	ds_read_b128 v[226:229], v122 offset:55296
	ds_read_b128 v[234:237], v122 offset:59904
	s_waitcnt vmcnt(17)
	ds_write_b128 v120, v[146:149]
	s_waitcnt vmcnt(16)
	ds_write_b128 v120, v[154:157] offset:18432
	v_mfma_f32_32x32x16_bf16 v[0:15], v[218:221], v[230:233], v[0:15]
	global_load_dwordx4 v[146:149], v[112:113], off offset:768
	global_load_dwordx4 v[154:157], v[114:115], off offset:768
	s_waitcnt lgkmcnt(3)
	v_mfma_f32_32x32x16_bf16 v[48:63], v[214:217], v[226:229], v[48:63]
	s_waitcnt lgkmcnt(2)
	v_mfma_f32_32x32x16_bf16 v[32:47], v[214:217], v[234:237], v[32:47]
	v_mfma_f32_32x32x16_bf16 v[16:31], v[222:225], v[226:229], v[16:31]
	ds_read_b128 v[214:217], v121 offset:36896
	ds_read_b128 v[218:221], v121 offset:41504
	ds_read_b128 v[226:229], v122 offset:55328
	ds_read_b128 v[230:233], v122 offset:59936
	s_waitcnt vmcnt(17)
	ds_write_b128 v120, v[158:161] offset:4608
	s_waitcnt vmcnt(16)
	ds_write_b128 v120, v[174:177] offset:23040
	v_mfma_f32_32x32x16_bf16 v[0:15], v[222:225], v[234:237], v[0:15]
	global_load_dwordx4 v[158:161], v[108:109], off offset:768
	global_load_dwordx4 v[174:177], v[110:111], off offset:768
	s_waitcnt lgkmcnt(3)
	v_mfma_f32_32x32x16_bf16 v[48:63], v[214:217], v[226:229], v[48:63]
	s_waitcnt lgkmcnt(2)
	v_mfma_f32_32x32x16_bf16 v[32:47], v[214:217], v[230:233], v[32:47]
	v_mfma_f32_32x32x16_bf16 v[16:31], v[218:221], v[226:229], v[16:31]
	ds_read_b128 v[214:217], v121 offset:36928
	ds_read_b128 v[222:225], v121 offset:41536
	ds_read_b128 v[226:229], v122 offset:55360
	ds_read_b128 v[234:237], v122 offset:59968
	s_waitcnt vmcnt(17)
	ds_write_b128 v120, v[162:165] offset:9216
	s_waitcnt vmcnt(16)
	ds_write_b128 v120, v[178:181] offset:27648
	v_mfma_f32_32x32x16_bf16 v[0:15], v[218:221], v[230:233], v[0:15]
	global_load_dwordx4 v[162:165], v[104:105], off offset:768
	global_load_dwordx4 v[178:181], v[106:107], off offset:768
	s_waitcnt lgkmcnt(3)
	v_mfma_f32_32x32x16_bf16 v[48:63], v[214:217], v[226:229], v[48:63]
	s_waitcnt lgkmcnt(2)
	v_mfma_f32_32x32x16_bf16 v[32:47], v[214:217], v[234:237], v[32:47]
	v_mfma_f32_32x32x16_bf16 v[16:31], v[222:225], v[226:229], v[16:31]
	ds_read_b128 v[214:217], v121 offset:36960
	ds_read_b128 v[218:221], v121 offset:41568
	ds_read_b128 v[226:229], v122 offset:55392
	ds_read_b128 v[230:233], v122 offset:60000
	s_waitcnt vmcnt(17)
	ds_write_b128 v120, v[166:169] offset:13824
	s_waitcnt vmcnt(16)
	ds_write_b128 v120, v[182:185] offset:32256
	v_mfma_f32_32x32x16_bf16 v[0:15], v[222:225], v[234:237], v[0:15]
	s_waitcnt lgkmcnt(0)
	s_barrier
	global_load_dwordx4 v[166:169], v[116:117], off offset:896
	global_load_dwordx4 v[182:185], v[118:119], off offset:896
	v_mfma_f32_32x32x16_bf16 v[48:63], v[214:217], v[226:229], v[48:63]
	v_mfma_f32_32x32x16_bf16 v[32:47], v[214:217], v[230:233], v[32:47]
	v_mfma_f32_32x32x16_bf16 v[16:31], v[218:221], v[226:229], v[16:31]
	ds_read_b128 v[214:217], v121
	ds_read_b128 v[222:225], v121 offset:4608
	ds_read_b128 v[226:229], v122 offset:18432
	ds_read_b128 v[234:237], v122 offset:23040
	s_waitcnt vmcnt(17)
	ds_write_b128 v120, v[170:173] offset:36864
	s_waitcnt vmcnt(16)
	ds_write_b128 v120, v[186:189] offset:55296
	v_mfma_f32_32x32x16_bf16 v[0:15], v[218:221], v[230:233], v[0:15]
	global_load_dwordx4 v[170:173], v[112:113], off offset:896
	global_load_dwordx4 v[186:189], v[114:115], off offset:896
	s_waitcnt lgkmcnt(3)
	v_mfma_f32_32x32x16_bf16 v[48:63], v[214:217], v[226:229], v[48:63]
	s_waitcnt lgkmcnt(2)
	v_mfma_f32_32x32x16_bf16 v[32:47], v[214:217], v[234:237], v[32:47]
	v_mfma_f32_32x32x16_bf16 v[16:31], v[222:225], v[226:229], v[16:31]
	ds_read_b128 v[214:217], v121 offset:32
	ds_read_b128 v[218:221], v121 offset:4640
	ds_read_b128 v[226:229], v122 offset:18464
	ds_read_b128 v[230:233], v122 offset:23072
	s_waitcnt vmcnt(17)
	ds_write_b128 v120, v[190:193] offset:41472
	s_waitcnt vmcnt(16)
	ds_write_b128 v120, v[194:197] offset:59904
	v_mfma_f32_32x32x16_bf16 v[0:15], v[222:225], v[234:237], v[0:15]
	global_load_dwordx4 v[190:193], v[108:109], off offset:896
	global_load_dwordx4 v[194:197], v[110:111], off offset:896
	s_waitcnt lgkmcnt(3)
	v_mfma_f32_32x32x16_bf16 v[48:63], v[214:217], v[226:229], v[48:63]
	s_waitcnt lgkmcnt(2)
	v_mfma_f32_32x32x16_bf16 v[32:47], v[214:217], v[230:233], v[32:47]
	v_mfma_f32_32x32x16_bf16 v[16:31], v[218:221], v[226:229], v[16:31]
	ds_read_b128 v[214:217], v121 offset:64
	ds_read_b128 v[222:225], v121 offset:4672
	ds_read_b128 v[226:229], v122 offset:18496
	ds_read_b128 v[234:237], v122 offset:23104
	s_waitcnt vmcnt(17)
	ds_write_b128 v120, v[206:209] offset:46080
	s_waitcnt vmcnt(16)
	ds_write_b128 v120, v[210:213] offset:64512
	v_mfma_f32_32x32x16_bf16 v[0:15], v[218:221], v[230:233], v[0:15]
	global_load_dwordx4 v[206:209], v[104:105], off offset:896
	global_load_dwordx4 v[210:213], v[106:107], off offset:896
	s_waitcnt lgkmcnt(3)
	v_mfma_f32_32x32x16_bf16 v[48:63], v[214:217], v[226:229], v[48:63]
	s_waitcnt lgkmcnt(2)
	v_mfma_f32_32x32x16_bf16 v[32:47], v[214:217], v[234:237], v[32:47]
	v_mfma_f32_32x32x16_bf16 v[16:31], v[222:225], v[226:229], v[16:31]
	ds_read_b128 v[214:217], v121 offset:96
	ds_read_b128 v[218:221], v121 offset:4704
	ds_read_b128 v[226:229], v122 offset:18528
	ds_read_b128 v[230:233], v122 offset:23136
	s_waitcnt vmcnt(17)
	ds_write_b128 v120, v[198:201] offset:50688
	s_waitcnt vmcnt(16)
	ds_write_b128 v123, v[202:205] offset:13824
	v_mfma_f32_32x32x16_bf16 v[0:15], v[222:225], v[234:237], v[0:15]
	s_waitcnt lgkmcnt(0)
	s_barrier
;     ...
;   for (int kt2 = 0; kt2 < nk; kt2 += 2) {
; #pragma unroll
;     for (int st = 0; st < 2; ++st) {
;       const int kt = kt2 + st;
;       const bf16_t* cur = lds + st * BUFE;
;       bf16_t* oth = lds + (st ^ 1) * BUFE;
;       const long k0r = (kt + 3 < nk) ? (long)(kt + 3) * BK : dR + (long)(kt + 3 - nk) * BK;
;       const long k0c = (kt + 3 < nk) ? (long)(kt + 3) * BK : dC + (long)(kt + 3 - nk) * BK;
;       const bool cnt = kt + 1 < nk;
;       const bf16_t* abase = cur + (wr * (RM / WR) + r) * STR + h * 8;
;       const bf16_t* bbase = cur + (RM + wc * (CN / WC) + r) * STR + h * 8;
;       bf16x8 af[2][MI], bfr[2][NI];
;       if (FDB) {
; #pragma unroll
;         for (int mi = 0; mi < MI; ++mi) af[0][mi] = *(const bf16x8*)(abase + mi * 32 * STR);
; #pragma unroll
;         for (int ni = 0; ni < NI; ++ni) bfr[0][ni] = *(const bf16x8*)(bbase + ni * 32 * STR);
;       }
; #pragma unroll
;       for (int ks = 0; ks < KS; ++ks) {
;         if (!FDB) {
; #pragma unroll
;           for (int mi = 0; mi < MI; ++mi) af[ks & 1][mi] = *(const bf16x8*)(abase + mi * 32 * STR + ks * 16);
; #pragma unroll
;           for (int ni = 0; ni < NI; ++ni) bfr[ks & 1][ni] = *(const bf16x8*)(bbase + ni * 32 * STR + ks * 16);
;         }
; #pragma unroll
;         for (int c = ks; c < RCH; c += KS) *(u32x4*)(oth + (srow + RPP * c) * STR + skc) = rr[st ^ 1][c];
; #pragma unroll
;         for (int c = ks; c < CCH; c += KS) {
;           *(u32x4*)(oth + (RM + srow + RPP * c) * STR + skc) = cr[st ^ 1][c];
;           if (SUMSQ && cnt) {
; #pragma unroll
;             for (int e = 0; e < 4; ++e) { const float a_ = bf_lo(cr[st ^ 1][c][e]), b_ = bf_hi(cr[st ^ 1][c][e]); ss[c] += a_ * a_ + b_ * b_; }
;           }
;         }
; #pragma unroll
;         for (int c = ks; c < RCH; c += KS) rr[st ^ 1][c] = *(const u32x4*)(rp + (size_t)(RPP * c) * ldr + k0r);
; #pragma unroll
;         for (int c = ks; c < CCH; c += KS) cr[st ^ 1][c] = *(const u32x4*)(cp + (size_t)(RPP * c) * ldc + k0c);
;         __builtin_amdgcn_sched_barrier(0);
;         if (FDB && ks + 1 < KS) {
; #pragma unroll
;           for (int mi = 0; mi < MI; ++mi) af[(ks + 1) & 1][mi] = *(const bf16x8*)(abase + mi * 32 * STR + (ks + 1) * 16);
; #pragma unroll
;           for (int ni = 0; ni < NI; ++ni) bfr[(ks + 1) & 1][ni] = *(const bf16x8*)(bbase + ni * 32 * STR + (ks + 1) * 16);
;         }
; #pragma unroll
	global_load_dwordx4 v[198:201], v[116:117], off offset:1024
	global_load_dwordx4 v[202:205], v[118:119], off offset:1024
	v_mfma_f32_32x32x16_bf16 v[48:63], v[214:217], v[226:229], v[48:63]
	v_mfma_f32_32x32x16_bf16 v[32:47], v[214:217], v[230:233], v[32:47]
	v_mfma_f32_32x32x16_bf16 v[16:31], v[218:221], v[226:229], v[16:31]
	ds_read_b128 v[214:217], v121 offset:36864
	ds_read_b128 v[222:225], v121 offset:41472
	ds_read_b128 v[226:229], v122 offset:55296
	ds_read_b128 v[234:237], v122 offset:59904
	s_waitcnt vmcnt(17)
	ds_write_b128 v120, v[142:145]
	s_waitcnt vmcnt(16)
	ds_write_b128 v120, v[150:153] offset:18432
	v_mfma_f32_32x32x16_bf16 v[0:15], v[218:221], v[230:233], v[0:15]
	global_load_dwordx4 v[142:145], v[112:113], off offset:1024
	global_load_dwordx4 v[150:153], v[114:115], off offset:1024
	s_waitcnt lgkmcnt(3)
	v_mfma_f32_32x32x16_bf16 v[48:63], v[214:217], v[226:229], v[48:63]
	s_waitcnt lgkmcnt(2)
	v_mfma_f32_32x32x16_bf16 v[32:47], v[214:217], v[234:237], v[32:47]
	v_mfma_f32_32x32x16_bf16 v[16:31], v[222:225], v[226:229], v[16:31]
	ds_read_b128 v[214:217], v121 offset:36896
	ds_read_b128 v[218:221], v121 offset:41504
	ds_read_b128 v[226:229], v122 offset:55328
	ds_read_b128 v[230:233], v122 offset:59936
	s_waitcnt vmcnt(17)
	ds_write_b128 v120, v[146:149] offset:4608
	s_waitcnt vmcnt(16)
	ds_write_b128 v120, v[154:157] offset:23040
	v_mfma_f32_32x32x16_bf16 v[0:15], v[222:225], v[234:237], v[0:15]
	global_load_dwordx4 v[146:149], v[108:109], off offset:1024
	global_load_dwordx4 v[154:157], v[110:111], off offset:1024
	s_waitcnt lgkmcnt(3)
	v_mfma_f32_32x32x16_bf16 v[48:63], v[214:217], v[226:229], v[48:63]
	s_waitcnt lgkmcnt(2)
	v_mfma_f32_32x32x16_bf16 v[32:47], v[214:217], v[230:233], v[32:47]
	v_mfma_f32_32x32x16_bf16 v[16:31], v[218:221], v[226:229], v[16:31]
	ds_read_b128 v[214:217], v121 offset:36928
	ds_read_b128 v[222:225], v121 offset:41536
	ds_read_b128 v[226:229], v122 offset:55360
	ds_read_b128 v[234:237], v122 offset:59968
	s_waitcnt vmcnt(17)
	ds_write_b128 v120, v[158:161] offset:9216
	s_waitcnt vmcnt(16)
	ds_write_b128 v120, v[174:177] offset:27648
	v_mfma_f32_32x32x16_bf16 v[0:15], v[218:221], v[230:233], v[0:15]
	global_load_dwordx4 v[158:161], v[104:105], off offset:1024
	global_load_dwordx4 v[174:177], v[106:107], off offset:1024
	s_waitcnt lgkmcnt(3)
	v_mfma_f32_32x32x16_bf16 v[48:63], v[214:217], v[226:229], v[48:63]
	s_waitcnt lgkmcnt(2)
	v_mfma_f32_32x32x16_bf16 v[32:47], v[214:217], v[234:237], v[32:47]
	v_mfma_f32_32x32x16_bf16 v[16:31], v[222:225], v[226:229], v[16:31]
	ds_read_b128 v[214:217], v121 offset:36960
	ds_read_b128 v[218:221], v121 offset:41568
	ds_read_b128 v[226:229], v122 offset:55392
	ds_read_b128 v[230:233], v122 offset:60000
	s_waitcnt vmcnt(17)
	ds_write_b128 v120, v[162:165] offset:13824
	s_waitcnt vmcnt(16)
	ds_write_b128 v120, v[178:181] offset:32256
	v_mfma_f32_32x32x16_bf16 v[0:15], v[222:225], v[234:237], v[0:15]
	s_waitcnt lgkmcnt(0)
	s_barrier
	global_load_dwordx4 v[162:165], v[116:117], off offset:1152
	global_load_dwordx4 v[178:181], v[118:119], off offset:1152
	v_mfma_f32_32x32x16_bf16 v[48:63], v[214:217], v[226:229], v[48:63]
	v_mfma_f32_32x32x16_bf16 v[32:47], v[214:217], v[230:233], v[32:47]
	v_mfma_f32_32x32x16_bf16 v[16:31], v[218:221], v[226:229], v[16:31]
	ds_read_b128 v[214:217], v121
	ds_read_b128 v[222:225], v121 offset:4608
	ds_read_b128 v[226:229], v122 offset:18432
	ds_read_b128 v[234:237], v122 offset:23040
	s_waitcnt vmcnt(17)
	ds_write_b128 v120, v[166:169] offset:36864
	s_waitcnt vmcnt(16)
	ds_write_b128 v120, v[182:185] offset:55296
	v_mfma_f32_32x32x16_bf16 v[0:15], v[218:221], v[230:233], v[0:15]
	global_load_dwordx4 v[166:169], v[112:113], off offset:1152
	global_load_dwordx4 v[182:185], v[114:115], off offset:1152
	s_waitcnt lgkmcnt(3)
	v_mfma_f32_32x32x16_bf16 v[48:63], v[214:217], v[226:229], v[48:63]
	s_waitcnt lgkmcnt(2)
	v_mfma_f32_32x32x16_bf16 v[32:47], v[214:217], v[234:237], v[32:47]
	v_mfma_f32_32x32x16_bf16 v[16:31], v[222:225], v[226:229], v[16:31]
	ds_read_b128 v[214:217], v121 offset:32
	ds_read_b128 v[218:221], v121 offset:4640
	ds_read_b128 v[226:229], v122 offset:18464
	ds_read_b128 v[230:233], v122 offset:23072
	s_waitcnt vmcnt(17)
	ds_write_b128 v120, v[170:173] offset:41472
	s_waitcnt vmcnt(16)
	ds_write_b128 v120, v[186:189] offset:59904
	v_mfma_f32_32x32x16_bf16 v[0:15], v[222:225], v[234:237], v[0:15]
	global_load_dwordx4 v[170:173], v[108:109], off offset:1152
	global_load_dwordx4 v[186:189], v[110:111], off offset:1152
	s_waitcnt lgkmcnt(3)
	v_mfma_f32_32x32x16_bf16 v[48:63], v[214:217], v[226:229], v[48:63]
	s_waitcnt lgkmcnt(2)
	v_mfma_f32_32x32x16_bf16 v[32:47], v[214:217], v[230:233], v[32:47]
	v_mfma_f32_32x32x16_bf16 v[16:31], v[218:221], v[226:229], v[16:31]
	ds_read_b128 v[214:217], v121 offset:64
	ds_read_b128 v[222:225], v121 offset:4672
	ds_read_b128 v[226:229], v122 offset:18496
	ds_read_b128 v[234:237], v122 offset:23104
	s_waitcnt vmcnt(17)
	ds_write_b128 v120, v[190:193] offset:46080
	s_waitcnt vmcnt(16)
	ds_write_b128 v120, v[194:197] offset:64512
	v_mfma_f32_32x32x16_bf16 v[0:15], v[218:221], v[230:233], v[0:15]
	global_load_dwordx4 v[190:193], v[104:105], off offset:1152
	global_load_dwordx4 v[194:197], v[106:107], off offset:1152
	s_waitcnt lgkmcnt(3)
	v_mfma_f32_32x32x16_bf16 v[48:63], v[214:217], v[226:229], v[48:63]
	s_waitcnt lgkmcnt(2)
	v_mfma_f32_32x32x16_bf16 v[32:47], v[214:217], v[234:237], v[32:47]
	v_mfma_f32_32x32x16_bf16 v[16:31], v[222:225], v[226:229], v[16:31]
	ds_read_b128 v[214:217], v121 offset:96
	ds_read_b128 v[218:221], v121 offset:4704
	ds_read_b128 v[226:229], v122 offset:18528
	ds_read_b128 v[230:233], v122 offset:23136
	s_waitcnt vmcnt(17)
	ds_write_b128 v120, v[206:209] offset:50688
	s_waitcnt vmcnt(16)
	ds_write_b128 v123, v[210:213] offset:13824
	v_mfma_f32_32x32x16_bf16 v[0:15], v[222:225], v[234:237], v[0:15]
	s_waitcnt lgkmcnt(0)
	s_barrier
;     ...
;   for (int kt2 = 0; kt2 < nk; kt2 += 2) {
; #pragma unroll
;     for (int st = 0; st < 2; ++st) {
;       const int kt = kt2 + st;
;       const bf16_t* cur = lds + st * BUFE;
;       bf16_t* oth = lds + (st ^ 1) * BUFE;
;       const long k0r = (kt + 3 < nk) ? (long)(kt + 3) * BK : dR + (long)(kt + 3 - nk) * BK;
;       const long k0c = (kt + 3 < nk) ? (long)(kt + 3) * BK : dC + (long)(kt + 3 - nk) * BK;
;       const bool cnt = kt + 1 < nk;
;       const bf16_t* abase = cur + (wr * (RM / WR) + r) * STR + h * 8;
;       const bf16_t* bbase = cur + (RM + wc * (CN / WC) + r) * STR + h * 8;
;       bf16x8 af[2][MI], bfr[2][NI];
;       if (FDB) {
; #pragma unroll
;         for (int mi = 0; mi < MI; ++mi) af[0][mi] = *(const bf16x8*)(abase + mi * 32 * STR);
; #pragma unroll
;         for (int ni = 0; ni < NI; ++ni) bfr[0][ni] = *(const bf16x8*)(bbase + ni * 32 * STR);
;       }
; #pragma unroll
;       for (int ks = 0; ks < KS; ++ks) {
;         if (!FDB) {
; #pragma unroll
;           for (int mi = 0; mi < MI; ++mi) af[ks & 1][mi] = *(const bf16x8*)(abase + mi * 32 * STR + ks * 16);
; #pragma unroll
;           for (int ni = 0; ni < NI; ++ni) bfr[ks & 1][ni] = *(const bf16x8*)(bbase + ni * 32 * STR + ks * 16);
;         }
; #pragma unroll
;         for (int c = ks; c < RCH; c += KS) *(u32x4*)(oth + (srow + RPP * c) * STR + skc) = rr[st ^ 1][c];
; #pragma unroll
;         for (int c = ks; c < CCH; c += KS) {
;           *(u32x4*)(oth + (RM + srow + RPP * c) * STR + skc) = cr[st ^ 1][c];
;           if (SUMSQ && cnt) {
; #pragma unroll
;             for (int e = 0; e < 4; ++e) { const float a_ = bf_lo(cr[st ^ 1][c][e]), b_ = bf_hi(cr[st ^ 1][c][e]); ss[c] += a_ * a_ + b_ * b_; }
;           }
;         }
; #pragma unroll
;         for (int c = ks; c < RCH; c += KS) rr[st ^ 1][c] = *(const u32x4*)(rp + (size_t)(RPP * c) * ldr + k0r);
; #pragma unroll
;         for (int c = ks; c < CCH; c += KS) cr[st ^ 1][c] = *(const u32x4*)(cp + (size_t)(RPP * c) * ldc + k0c);
;         __builtin_amdgcn_sched_barrier(0);
;         if (FDB && ks + 1 < KS) {
; #pragma unroll
;           for (int mi = 0; mi < MI; ++mi) af[(ks + 1) & 1][mi] = *(const bf16x8*)(abase + mi * 32 * STR + (ks + 1) * 16);
; #pragma unroll
;           for (int ni = 0; ni < NI; ++ni) bfr[(ks + 1) & 1][ni] = *(const bf16x8*)(bbase + ni * 32 * STR + (ks + 1) * 16);
;         }
; #pragma unroll
	global_load_dwordx4 v[206:209], v[116:117], off offset:1280
	global_load_dwordx4 v[210:213], v[118:119], off offset:1280
	v_mfma_f32_32x32x16_bf16 v[48:63], v[214:217], v[226:229], v[48:63]
	v_mfma_f32_32x32x16_bf16 v[32:47], v[214:217], v[230:233], v[32:47]
	v_mfma_f32_32x32x16_bf16 v[16:31], v[218:221], v[226:229], v[16:31]
	ds_read_b128 v[214:217], v121 offset:36864
	ds_read_b128 v[222:225], v121 offset:41472
	ds_read_b128 v[226:229], v122 offset:55296
	ds_read_b128 v[234:237], v122 offset:59904
	s_waitcnt vmcnt(17)
	ds_write_b128 v120, v[198:201]
	s_waitcnt vmcnt(16)
	ds_write_b128 v120, v[202:205] offset:18432
	v_mfma_f32_32x32x16_bf16 v[0:15], v[218:221], v[230:233], v[0:15]
	global_load_dwordx4 v[198:201], v[112:113], off offset:1280
	global_load_dwordx4 v[202:205], v[114:115], off offset:1280
	s_waitcnt lgkmcnt(3)
	v_mfma_f32_32x32x16_bf16 v[48:63], v[214:217], v[226:229], v[48:63]
	s_waitcnt lgkmcnt(2)
	v_mfma_f32_32x32x16_bf16 v[32:47], v[214:217], v[234:237], v[32:47]
	v_mfma_f32_32x32x16_bf16 v[16:31], v[222:225], v[226:229], v[16:31]
	ds_read_b128 v[214:217], v121 offset:36896
	ds_read_b128 v[218:221], v121 offset:41504
	ds_read_b128 v[226:229], v122 offset:55328
	ds_read_b128 v[230:233], v122 offset:59936
	s_waitcnt vmcnt(17)
	ds_write_b128 v120, v[142:145] offset:4608
	s_waitcnt vmcnt(16)
	ds_write_b128 v120, v[150:153] offset:23040
	v_mfma_f32_32x32x16_bf16 v[0:15], v[222:225], v[234:237], v[0:15]
	global_load_dwordx4 v[142:145], v[108:109], off offset:1280
	global_load_dwordx4 v[150:153], v[110:111], off offset:1280
	s_waitcnt lgkmcnt(3)
	v_mfma_f32_32x32x16_bf16 v[48:63], v[214:217], v[226:229], v[48:63]
	s_waitcnt lgkmcnt(2)
	v_mfma_f32_32x32x16_bf16 v[32:47], v[214:217], v[230:233], v[32:47]
	v_mfma_f32_32x32x16_bf16 v[16:31], v[218:221], v[226:229], v[16:31]
	ds_read_b128 v[214:217], v121 offset:36928
	ds_read_b128 v[222:225], v121 offset:41536
	ds_read_b128 v[226:229], v122 offset:55360
	ds_read_b128 v[234:237], v122 offset:59968
	s_waitcnt vmcnt(17)
	ds_write_b128 v120, v[146:149] offset:9216
	s_waitcnt vmcnt(16)
	ds_write_b128 v120, v[154:157] offset:27648
	v_mfma_f32_32x32x16_bf16 v[0:15], v[218:221], v[230:233], v[0:15]
	global_load_dwordx4 v[146:149], v[104:105], off offset:1280
	global_load_dwordx4 v[154:157], v[106:107], off offset:1280
	s_waitcnt lgkmcnt(3)
	v_mfma_f32_32x32x16_bf16 v[48:63], v[214:217], v[226:229], v[48:63]
	s_waitcnt lgkmcnt(2)
	v_mfma_f32_32x32x16_bf16 v[32:47], v[214:217], v[234:237], v[32:47]
	v_mfma_f32_32x32x16_bf16 v[16:31], v[222:225], v[226:229], v[16:31]
	ds_read_b128 v[214:217], v121 offset:36960
	ds_read_b128 v[218:221], v121 offset:41568
	ds_read_b128 v[226:229], v122 offset:55392
	ds_read_b128 v[230:233], v122 offset:60000
	s_waitcnt vmcnt(17)
	ds_write_b128 v120, v[158:161] offset:13824
	s_waitcnt vmcnt(16)
	ds_write_b128 v120, v[174:177] offset:32256
	v_mfma_f32_32x32x16_bf16 v[0:15], v[222:225], v[234:237], v[0:15]
	s_waitcnt lgkmcnt(0)
	s_barrier
	global_load_dwordx4 v[158:161], v[116:117], off offset:1408
	global_load_dwordx4 v[174:177], v[118:119], off offset:1408
	v_mfma_f32_32x32x16_bf16 v[48:63], v[214:217], v[226:229], v[48:63]
	v_mfma_f32_32x32x16_bf16 v[32:47], v[214:217], v[230:233], v[32:47]
	v_mfma_f32_32x32x16_bf16 v[16:31], v[218:221], v[226:229], v[16:31]
	ds_read_b128 v[214:217], v121
	ds_read_b128 v[222:225], v121 offset:4608
	ds_read_b128 v[226:229], v122 offset:18432
	ds_read_b128 v[234:237], v122 offset:23040
	s_waitcnt vmcnt(17)
	ds_write_b128 v120, v[162:165] offset:36864
	s_waitcnt vmcnt(16)
	ds_write_b128 v120, v[178:181] offset:55296
	v_mfma_f32_32x32x16_bf16 v[0:15], v[218:221], v[230:233], v[0:15]
	global_load_dwordx4 v[162:165], v[112:113], off offset:1408
	global_load_dwordx4 v[178:181], v[114:115], off offset:1408
	s_waitcnt lgkmcnt(3)
	v_mfma_f32_32x32x16_bf16 v[48:63], v[214:217], v[226:229], v[48:63]
	s_waitcnt lgkmcnt(2)
	v_mfma_f32_32x32x16_bf16 v[32:47], v[214:217], v[234:237], v[32:47]
	v_mfma_f32_32x32x16_bf16 v[16:31], v[222:225], v[226:229], v[16:31]
	ds_read_b128 v[214:217], v121 offset:32
	ds_read_b128 v[218:221], v121 offset:4640
	ds_read_b128 v[226:229], v122 offset:18464
	ds_read_b128 v[230:233], v122 offset:23072
	s_waitcnt vmcnt(17)
	ds_write_b128 v120, v[166:169] offset:41472
	s_waitcnt vmcnt(16)
	ds_write_b128 v120, v[182:185] offset:59904
	v_mfma_f32_32x32x16_bf16 v[0:15], v[222:225], v[234:237], v[0:15]
	global_load_dwordx4 v[166:169], v[108:109], off offset:1408
	global_load_dwordx4 v[182:185], v[110:111], off offset:1408
	s_waitcnt lgkmcnt(3)
	v_mfma_f32_32x32x16_bf16 v[48:63], v[214:217], v[226:229], v[48:63]
	s_waitcnt lgkmcnt(2)
	v_mfma_f32_32x32x16_bf16 v[32:47], v[214:217], v[230:233], v[32:47]
	v_mfma_f32_32x32x16_bf16 v[16:31], v[218:221], v[226:229], v[16:31]
	ds_read_b128 v[214:217], v121 offset:64
	ds_read_b128 v[222:225], v121 offset:4672
	ds_read_b128 v[226:229], v122 offset:18496
	ds_read_b128 v[234:237], v122 offset:23104
	s_waitcnt vmcnt(17)
	ds_write_b128 v120, v[170:173] offset:46080
	s_waitcnt vmcnt(16)
	ds_write_b128 v120, v[186:189] offset:64512
	v_mfma_f32_32x32x16_bf16 v[0:15], v[218:221], v[230:233], v[0:15]
	global_load_dwordx4 v[170:173], v[104:105], off offset:1408
	global_load_dwordx4 v[186:189], v[106:107], off offset:1408
	s_waitcnt lgkmcnt(3)
	v_mfma_f32_32x32x16_bf16 v[48:63], v[214:217], v[226:229], v[48:63]
	s_waitcnt lgkmcnt(2)
	v_mfma_f32_32x32x16_bf16 v[32:47], v[214:217], v[234:237], v[32:47]
	v_mfma_f32_32x32x16_bf16 v[16:31], v[222:225], v[226:229], v[16:31]
	ds_read_b128 v[214:217], v121 offset:96
	ds_read_b128 v[218:221], v121 offset:4704
	ds_read_b128 v[226:229], v122 offset:18528
	ds_read_b128 v[230:233], v122 offset:23136
	s_waitcnt vmcnt(17)
	ds_write_b128 v120, v[190:193] offset:50688
	s_waitcnt vmcnt(16)
	ds_write_b128 v123, v[194:197] offset:13824
	v_mfma_f32_32x32x16_bf16 v[0:15], v[222:225], v[234:237], v[0:15]
	s_waitcnt lgkmcnt(0)
	s_barrier
;     ...
;   for (int kt2 = 0; kt2 < nk; kt2 += 2) {
; #pragma unroll
;     for (int st = 0; st < 2; ++st) {
;       const int kt = kt2 + st;
;       const bf16_t* cur = lds + st * BUFE;
;       bf16_t* oth = lds + (st ^ 1) * BUFE;
;       const long k0r = (kt + 3 < nk) ? (long)(kt + 3) * BK : dR + (long)(kt + 3 - nk) * BK;
;       const long k0c = (kt + 3 < nk) ? (long)(kt + 3) * BK : dC + (long)(kt + 3 - nk) * BK;
;       const bool cnt = kt + 1 < nk;
;       const bf16_t* abase = cur + (wr * (RM / WR) + r) * STR + h * 8;
;       const bf16_t* bbase = cur + (RM + wc * (CN / WC) + r) * STR + h * 8;
;       bf16x8 af[2][MI], bfr[2][NI];
;       if (FDB) {
; #pragma unroll
;         for (int mi = 0; mi < MI; ++mi) af[0][mi] = *(const bf16x8*)(abase + mi * 32 * STR);
; #pragma unroll
;         for (int ni = 0; ni < NI; ++ni) bfr[0][ni] = *(const bf16x8*)(bbase + ni * 32 * STR);
;       }
; #pragma unroll
;       for (int ks = 0; ks < KS; ++ks) {
;         if (!FDB) {
; #pragma unroll
;           for (int mi = 0; mi < MI; ++mi) af[ks & 1][mi] = *(const bf16x8*)(abase + mi * 32 * STR + ks * 16);
; #pragma unroll
;           for (int ni = 0; ni < NI; ++ni) bfr[ks & 1][ni] = *(const bf16x8*)(bbase + ni * 32 * STR + ks * 16);
;         }
; #pragma unroll
;         for (int c = ks; c < RCH; c += KS) *(u32x4*)(oth + (srow + RPP * c) * STR + skc) = rr[st ^ 1][c];
; #pragma unroll
;         for (int c = ks; c < CCH; c += KS) {
;           *(u32x4*)(oth + (RM + srow + RPP * c) * STR + skc) = cr[st ^ 1][c];
;           if (SUMSQ && cnt) {
; #pragma unroll
;             for (int e = 0; e < 4; ++e) { const float a_ = bf_lo(cr[st ^ 1][c][e]), b_ = bf_hi(cr[st ^ 1][c][e]); ss[c] += a_ * a_ + b_ * b_; }
;           }
;         }
; #pragma unroll
;         for (int c = ks; c < RCH; c += KS) rr[st ^ 1][c] = *(const u32x4*)(rp + (size_t)(RPP * c) * ldr + k0r);
; #pragma unroll
;         for (int c = ks; c < CCH; c += KS) cr[st ^ 1][c] = *(const u32x4*)(cp + (size_t)(RPP * c) * ldc + k0c);
;         __builtin_amdgcn_sched_barrier(0);
;         if (FDB && ks + 1 < KS) {
; #pragma unroll
;           for (int mi = 0; mi < MI; ++mi) af[(ks + 1) & 1][mi] = *(const bf16x8*)(abase + mi * 32 * STR + (ks + 1) * 16);
; #pragma unroll
;           for (int ni = 0; ni < NI; ++ni) bfr[(ks + 1) & 1][ni] = *(const bf16x8*)(bbase + ni * 32 * STR + (ks + 1) * 16);
;         }
; #pragma unroll
	global_load_dwordx4 v[190:193], v[116:117], off offset:1536
	global_load_dwordx4 v[194:197], v[118:119], off offset:1536
	v_mfma_f32_32x32x16_bf16 v[48:63], v[214:217], v[226:229], v[48:63]
	v_mfma_f32_32x32x16_bf16 v[32:47], v[214:217], v[230:233], v[32:47]
	v_mfma_f32_32x32x16_bf16 v[16:31], v[218:221], v[226:229], v[16:31]
	ds_read_b128 v[214:217], v121 offset:36864
	ds_read_b128 v[222:225], v121 offset:41472
	ds_read_b128 v[226:229], v122 offset:55296
	ds_read_b128 v[234:237], v122 offset:59904
	s_waitcnt vmcnt(17)
	ds_write_b128 v120, v[206:209]
	s_waitcnt vmcnt(16)
	ds_write_b128 v120, v[210:213] offset:18432
	v_mfma_f32_32x32x16_bf16 v[0:15], v[218:221], v[230:233], v[0:15]
	global_load_dwordx4 v[206:209], v[112:113], off offset:1536
	global_load_dwordx4 v[210:213], v[114:115], off offset:1536
	s_waitcnt lgkmcnt(3)
	v_mfma_f32_32x32x16_bf16 v[48:63], v[214:217], v[226:229], v[48:63]
	s_waitcnt lgkmcnt(2)
	v_mfma_f32_32x32x16_bf16 v[32:47], v[214:217], v[234:237], v[32:47]
	v_mfma_f32_32x32x16_bf16 v[16:31], v[222:225], v[226:229], v[16:31]
	ds_read_b128 v[214:217], v121 offset:36896
	ds_read_b128 v[218:221], v121 offset:41504
	ds_read_b128 v[226:229], v122 offset:55328
	ds_read_b128 v[230:233], v122 offset:59936
	s_waitcnt vmcnt(17)
	ds_write_b128 v120, v[198:201] offset:4608
	s_waitcnt vmcnt(16)
	ds_write_b128 v120, v[202:205] offset:23040
	v_mfma_f32_32x32x16_bf16 v[0:15], v[222:225], v[234:237], v[0:15]
	global_load_dwordx4 v[198:201], v[108:109], off offset:1536
	global_load_dwordx4 v[202:205], v[110:111], off offset:1536
	s_waitcnt lgkmcnt(3)
	v_mfma_f32_32x32x16_bf16 v[48:63], v[214:217], v[226:229], v[48:63]
	s_waitcnt lgkmcnt(2)
	v_mfma_f32_32x32x16_bf16 v[32:47], v[214:217], v[230:233], v[32:47]
	v_mfma_f32_32x32x16_bf16 v[16:31], v[218:221], v[226:229], v[16:31]
	ds_read_b128 v[214:217], v121 offset:36928
	ds_read_b128 v[222:225], v121 offset:41536
	ds_read_b128 v[226:229], v122 offset:55360
	ds_read_b128 v[234:237], v122 offset:59968
	s_waitcnt vmcnt(17)
	ds_write_b128 v120, v[142:145] offset:9216
	s_waitcnt vmcnt(16)
	ds_write_b128 v120, v[150:153] offset:27648
	v_mfma_f32_32x32x16_bf16 v[0:15], v[218:221], v[230:233], v[0:15]
	global_load_dwordx4 v[142:145], v[104:105], off offset:1536
	global_load_dwordx4 v[150:153], v[106:107], off offset:1536
	s_waitcnt lgkmcnt(3)
	v_mfma_f32_32x32x16_bf16 v[48:63], v[214:217], v[226:229], v[48:63]
	s_waitcnt lgkmcnt(2)
	v_mfma_f32_32x32x16_bf16 v[32:47], v[214:217], v[234:237], v[32:47]
	v_mfma_f32_32x32x16_bf16 v[16:31], v[222:225], v[226:229], v[16:31]
	ds_read_b128 v[214:217], v121 offset:36960
	ds_read_b128 v[218:221], v121 offset:41568
	ds_read_b128 v[226:229], v122 offset:55392
	ds_read_b128 v[230:233], v122 offset:60000
	s_waitcnt vmcnt(17)
	ds_write_b128 v120, v[146:149] offset:13824
	s_waitcnt vmcnt(16)
	ds_write_b128 v120, v[154:157] offset:32256
	v_mfma_f32_32x32x16_bf16 v[0:15], v[222:225], v[234:237], v[0:15]
	s_waitcnt lgkmcnt(0)
	s_barrier
	global_load_dwordx4 v[146:149], v[116:117], off offset:1664
	global_load_dwordx4 v[154:157], v[118:119], off offset:1664
	v_mfma_f32_32x32x16_bf16 v[48:63], v[214:217], v[226:229], v[48:63]
	v_mfma_f32_32x32x16_bf16 v[32:47], v[214:217], v[230:233], v[32:47]
	v_mfma_f32_32x32x16_bf16 v[16:31], v[218:221], v[226:229], v[16:31]
	ds_read_b128 v[214:217], v121
	ds_read_b128 v[222:225], v121 offset:4608
	ds_read_b128 v[226:229], v122 offset:18432
	ds_read_b128 v[234:237], v122 offset:23040
	s_waitcnt vmcnt(17)
	ds_write_b128 v120, v[158:161] offset:36864
	s_waitcnt vmcnt(16)
	ds_write_b128 v120, v[174:177] offset:55296
	v_mfma_f32_32x32x16_bf16 v[0:15], v[218:221], v[230:233], v[0:15]
	global_load_dwordx4 v[158:161], v[112:113], off offset:1664
	global_load_dwordx4 v[174:177], v[114:115], off offset:1664
	s_waitcnt lgkmcnt(3)
	v_mfma_f32_32x32x16_bf16 v[48:63], v[214:217], v[226:229], v[48:63]
	s_waitcnt lgkmcnt(2)
	v_mfma_f32_32x32x16_bf16 v[32:47], v[214:217], v[234:237], v[32:47]
	v_mfma_f32_32x32x16_bf16 v[16:31], v[222:225], v[226:229], v[16:31]
	ds_read_b128 v[214:217], v121 offset:32
	ds_read_b128 v[218:221], v121 offset:4640
	ds_read_b128 v[226:229], v122 offset:18464
	ds_read_b128 v[230:233], v122 offset:23072
	s_waitcnt vmcnt(17)
	ds_write_b128 v120, v[162:165] offset:41472
	s_waitcnt vmcnt(16)
	ds_write_b128 v120, v[178:181] offset:59904
	v_mfma_f32_32x32x16_bf16 v[0:15], v[222:225], v[234:237], v[0:15]
	global_load_dwordx4 v[162:165], v[108:109], off offset:1664
	global_load_dwordx4 v[178:181], v[110:111], off offset:1664
	s_waitcnt lgkmcnt(3)
	v_mfma_f32_32x32x16_bf16 v[48:63], v[214:217], v[226:229], v[48:63]
	s_waitcnt lgkmcnt(2)
	v_mfma_f32_32x32x16_bf16 v[32:47], v[214:217], v[230:233], v[32:47]
	v_mfma_f32_32x32x16_bf16 v[16:31], v[218:221], v[226:229], v[16:31]
	ds_read_b128 v[214:217], v121 offset:64
	ds_read_b128 v[222:225], v121 offset:4672
	ds_read_b128 v[226:229], v122 offset:18496
	ds_read_b128 v[234:237], v122 offset:23104
	s_waitcnt vmcnt(17)
	ds_write_b128 v120, v[166:169] offset:46080
	s_waitcnt vmcnt(16)
	ds_write_b128 v120, v[182:185] offset:64512
	v_mfma_f32_32x32x16_bf16 v[0:15], v[218:221], v[230:233], v[0:15]
	global_load_dwordx4 v[166:169], v[104:105], off offset:1664
	global_load_dwordx4 v[182:185], v[106:107], off offset:1664
	s_waitcnt lgkmcnt(3)
	v_mfma_f32_32x32x16_bf16 v[48:63], v[214:217], v[226:229], v[48:63]
	s_waitcnt lgkmcnt(2)
	v_mfma_f32_32x32x16_bf16 v[32:47], v[214:217], v[234:237], v[32:47]
	v_mfma_f32_32x32x16_bf16 v[16:31], v[222:225], v[226:229], v[16:31]
	ds_read_b128 v[214:217], v121 offset:96
	ds_read_b128 v[218:221], v121 offset:4704
	ds_read_b128 v[226:229], v122 offset:18528
	ds_read_b128 v[230:233], v122 offset:23136
	s_waitcnt vmcnt(17)
	ds_write_b128 v120, v[170:173] offset:50688
	s_waitcnt vmcnt(16)
	ds_write_b128 v123, v[186:189] offset:13824
	v_mfma_f32_32x32x16_bf16 v[0:15], v[222:225], v[234:237], v[0:15]
	s_waitcnt lgkmcnt(0)
	s_barrier
; #define MFMA32(a, b, c) __builtin_amdgcn_mfma_f32_32x32x16_bf16((a), (b), (c), 0, 0, 0)
; DI float bf_lo(unsigned u) { return __uint_as_float(u << 16); }
; DI float bf_hi(unsigned u) { return __uint_as_float(u & 0xffff0000u); }
;     ...
;       for (int ks = 0; ks < KS; ++ks) {
;         if (!FDB) {
; #pragma unroll
;           for (int mi = 0; mi < MI; ++mi) af[ks & 1][mi] = *(const bf16x8*)(abase + mi * 32 * STR + ks * 16);
; #pragma unroll
;           for (int ni = 0; ni < NI; ++ni) bfr[ks & 1][ni] = *(const bf16x8*)(bbase + ni * 32 * STR + ks * 16);
;         }
; #pragma unroll
;         for (int c = ks; c < RCH; c += KS) *(u32x4*)(oth + (srow + RPP * c) * STR + skc) = rr[st ^ 1][c];
; #pragma unroll
;         for (int c = ks; c < CCH; c += KS) {
;           *(u32x4*)(oth + (RM + srow + RPP * c) * STR + skc) = cr[st ^ 1][c];
;           if (SUMSQ && cnt) {
; #pragma unroll
;             for (int e = 0; e < 4; ++e) { const float a_ = bf_lo(cr[st ^ 1][c][e]), b_ = bf_hi(cr[st ^ 1][c][e]); ss[c] += a_ * a_ + b_ * b_; }
;           }
;         }
; #pragma unroll
;         for (int c = ks; c < RCH; c += KS) rr[st ^ 1][c] = *(const u32x4*)(rp + (size_t)(RPP * c) * ldr + k0r);
; #pragma unroll
;         for (int c = ks; c < CCH; c += KS) cr[st ^ 1][c] = *(const u32x4*)(cp + (size_t)(RPP * c) * ldc + k0c);
;         __builtin_amdgcn_sched_barrier(0);
;         if (FDB && ks + 1 < KS) {
; #pragma unroll
;           for (int mi = 0; mi < MI; ++mi) af[(ks + 1) & 1][mi] = *(const bf16x8*)(abase + mi * 32 * STR + (ks + 1) * 16);
; #pragma unroll
;           for (int ni = 0; ni < NI; ++ni) bfr[(ks + 1) & 1][ni] = *(const bf16x8*)(bbase + ni * 32 * STR + (ks + 1) * 16);
;         }
; #pragma unroll
;         for (int mi = 0; mi < MI; ++mi)
; #pragma unroll
;           for (int ni = 0; ni < NI; ++ni) acc[mi][ni] = MFMA32(af[ks & 1][mi], bfr[ks & 1][ni], acc[mi][ni]);
;       }
;       __syncthreads();
	global_load_dwordx4 v[170:173], v[116:117], off offset:1792
	global_load_dwordx4 v[186:189], v[118:119], off offset:1792
	v_mfma_f32_32x32x16_bf16 v[48:63], v[214:217], v[226:229], v[48:63]
	v_mfma_f32_32x32x16_bf16 v[32:47], v[214:217], v[230:233], v[32:47]
	v_mfma_f32_32x32x16_bf16 v[16:31], v[218:221], v[226:229], v[16:31]
	ds_read_b128 v[214:217], v121 offset:36864
	ds_read_b128 v[222:225], v121 offset:41472
	ds_read_b128 v[226:229], v122 offset:55296
	ds_read_b128 v[234:237], v122 offset:59904
	s_waitcnt vmcnt(17)
	ds_write_b128 v120, v[190:193]
	s_waitcnt vmcnt(16)
	ds_write_b128 v120, v[194:197] offset:18432
	v_mfma_f32_32x32x16_bf16 v[0:15], v[218:221], v[230:233], v[0:15]
	global_load_dwordx4 v[190:193], v[112:113], off offset:1792
	global_load_dwordx4 v[194:197], v[114:115], off offset:1792
	s_waitcnt lgkmcnt(3)
	v_mfma_f32_32x32x16_bf16 v[48:63], v[214:217], v[226:229], v[48:63]
	s_waitcnt lgkmcnt(2)
	v_mfma_f32_32x32x16_bf16 v[32:47], v[214:217], v[234:237], v[32:47]
	v_mfma_f32_32x32x16_bf16 v[16:31], v[222:225], v[226:229], v[16:31]
	ds_read_b128 v[214:217], v121 offset:36896
	ds_read_b128 v[218:221], v121 offset:41504
	ds_read_b128 v[226:229], v122 offset:55328
	ds_read_b128 v[230:233], v122 offset:59936
	s_waitcnt vmcnt(17)
	ds_write_b128 v120, v[206:209] offset:4608
	s_waitcnt vmcnt(16)
	ds_write_b128 v120, v[210:213] offset:23040
	v_mfma_f32_32x32x16_bf16 v[0:15], v[222:225], v[234:237], v[0:15]
	global_load_dwordx4 v[206:209], v[108:109], off offset:1792
	global_load_dwordx4 v[210:213], v[110:111], off offset:1792
	s_waitcnt lgkmcnt(3)
	v_mfma_f32_32x32x16_bf16 v[48:63], v[214:217], v[226:229], v[48:63]
	s_waitcnt lgkmcnt(2)
	v_mfma_f32_32x32x16_bf16 v[32:47], v[214:217], v[230:233], v[32:47]
	v_mfma_f32_32x32x16_bf16 v[16:31], v[218:221], v[226:229], v[16:31]
	ds_read_b128 v[214:217], v121 offset:36928
	ds_read_b128 v[222:225], v121 offset:41536
	ds_read_b128 v[226:229], v122 offset:55360
	ds_read_b128 v[234:237], v122 offset:59968
	s_waitcnt vmcnt(17)
	ds_write_b128 v120, v[198:201] offset:9216
	s_waitcnt vmcnt(16)
	ds_write_b128 v120, v[202:205] offset:27648
	v_mfma_f32_32x32x16_bf16 v[0:15], v[218:221], v[230:233], v[0:15]
	global_load_dwordx4 v[198:201], v[104:105], off offset:1792
	global_load_dwordx4 v[202:205], v[106:107], off offset:1792
	s_waitcnt lgkmcnt(3)
	v_mfma_f32_32x32x16_bf16 v[48:63], v[214:217], v[226:229], v[48:63]
	s_waitcnt lgkmcnt(2)
	v_mfma_f32_32x32x16_bf16 v[32:47], v[214:217], v[234:237], v[32:47]
	v_mfma_f32_32x32x16_bf16 v[16:31], v[222:225], v[226:229], v[16:31]
	ds_read_b128 v[214:217], v121 offset:36960
	ds_read_b128 v[218:221], v121 offset:41568
	ds_read_b128 v[226:229], v122 offset:55392
	ds_read_b128 v[230:233], v122 offset:60000
	s_waitcnt vmcnt(17)
	ds_write_b128 v120, v[142:145] offset:13824
	s_waitcnt vmcnt(16)
	ds_write_b128 v120, v[150:153] offset:32256
	v_mfma_f32_32x32x16_bf16 v[0:15], v[222:225], v[234:237], v[0:15]
	s_waitcnt lgkmcnt(0)
	s_barrier
	global_load_dwordx4 v[142:145], v[116:117], off offset:1920
	s_nop 0
	global_load_dwordx4 v[116:119], v[118:119], off offset:1920
	v_mfma_f32_32x32x16_bf16 v[48:63], v[214:217], v[226:229], v[48:63]
	v_mfma_f32_32x32x16_bf16 v[32:47], v[214:217], v[230:233], v[32:47]
	v_mfma_f32_32x32x16_bf16 v[16:31], v[218:221], v[226:229], v[16:31]
	ds_read_b128 v[150:153], v121
	ds_read_b128 v[214:217], v121 offset:4608
	ds_read_b128 v[222:225], v122 offset:18432
	ds_read_b128 v[226:229], v122 offset:23040
	s_waitcnt vmcnt(17)
	ds_write_b128 v120, v[146:149] offset:36864
	s_waitcnt vmcnt(16)
	ds_write_b128 v120, v[154:157] offset:55296
	v_mfma_f32_32x32x16_bf16 v[0:15], v[218:221], v[230:233], v[0:15]
	global_load_dwordx4 v[146:149], v[112:113], off offset:1920
	s_nop 0
	global_load_dwordx4 v[112:115], v[114:115], off offset:1920
	s_waitcnt lgkmcnt(3)
	v_mfma_f32_32x32x16_bf16 v[48:63], v[150:153], v[222:225], v[48:63]
	s_waitcnt lgkmcnt(2)
	v_mfma_f32_32x32x16_bf16 v[32:47], v[150:153], v[226:229], v[32:47]
	v_mfma_f32_32x32x16_bf16 v[16:31], v[214:217], v[222:225], v[16:31]
	ds_read_b128 v[150:153], v121 offset:32
	ds_read_b128 v[154:157], v121 offset:4640
	ds_read_b128 v[218:221], v122 offset:18464
	ds_read_b128 v[222:225], v122 offset:23072
	s_waitcnt vmcnt(17)
	ds_write_b128 v120, v[158:161] offset:41472
	s_waitcnt vmcnt(16)
	ds_write_b128 v120, v[174:177] offset:59904
	v_mfma_f32_32x32x16_bf16 v[0:15], v[214:217], v[226:229], v[0:15]
	s_waitcnt lgkmcnt(3)
	v_mfma_f32_32x32x16_bf16 v[48:63], v[150:153], v[218:221], v[48:63]
	s_waitcnt lgkmcnt(2)
	v_mfma_f32_32x32x16_bf16 v[32:47], v[150:153], v[222:225], v[32:47]
	global_load_dwordx4 v[150:153], v[108:109], off offset:1920
	s_nop 0
	global_load_dwordx4 v[108:111], v[110:111], off offset:1920
	v_mfma_f32_32x32x16_bf16 v[16:31], v[154:157], v[218:221], v[16:31]
	ds_read_b128 v[158:161], v121 offset:64
	ds_read_b128 v[174:177], v121 offset:4672
	ds_read_b128 v[214:217], v122 offset:18496
	ds_read_b128 v[218:221], v122 offset:23104
	s_waitcnt vmcnt(17)
	ds_write_b128 v120, v[162:165] offset:46080
	s_waitcnt vmcnt(16)
	ds_write_b128 v120, v[178:181] offset:64512
	v_mfma_f32_32x32x16_bf16 v[0:15], v[154:157], v[222:225], v[0:15]
	global_load_dwordx4 v[154:157], v[104:105], off offset:1920
	s_nop 0
	global_load_dwordx4 v[104:107], v[106:107], off offset:1920
	s_waitcnt lgkmcnt(3)
	v_mfma_f32_32x32x16_bf16 v[48:63], v[158:161], v[214:217], v[48:63]
	s_waitcnt lgkmcnt(2)
	v_mfma_f32_32x32x16_bf16 v[32:47], v[158:161], v[218:221], v[32:47]
	v_mfma_f32_32x32x16_bf16 v[16:31], v[174:177], v[214:217], v[16:31]
	ds_read_b128 v[158:161], v121 offset:96
	ds_read_b128 v[162:165], v121 offset:4704
	ds_read_b128 v[178:181], v122 offset:18528
	ds_read_b128 v[214:217], v122 offset:23136
	s_waitcnt vmcnt(17)
	ds_write_b128 v120, v[166:169] offset:50688
	s_waitcnt vmcnt(16)
	ds_write_b128 v123, v[182:185] offset:13824
	v_mfma_f32_32x32x16_bf16 v[0:15], v[174:177], v[218:221], v[0:15]
	s_waitcnt lgkmcnt(3)
	v_mfma_f32_32x32x16_bf16 v[48:63], v[158:161], v[178:181], v[48:63]
	s_waitcnt lgkmcnt(0)
	s_barrier
; #define MFMA32(a, b, c) __builtin_amdgcn_mfma_f32_32x32x16_bf16((a), (b), (c), 0, 0, 0)
; DI float bf_lo(unsigned u) { return __uint_as_float(u << 16); }
; DI float bf_hi(unsigned u) { return __uint_as_float(u & 0xffff0000u); }
;     ...
;       for (int ks = 0; ks < KS; ++ks) {
;         if (!FDB) {
; #pragma unroll
;           for (int mi = 0; mi < MI; ++mi) af[ks & 1][mi] = *(const bf16x8*)(abase + mi * 32 * STR + ks * 16);
; #pragma unroll
;           for (int ni = 0; ni < NI; ++ni) bfr[ks & 1][ni] = *(const bf16x8*)(bbase + ni * 32 * STR + ks * 16);
;         }
; #pragma unroll
;         for (int c = ks; c < RCH; c += KS) *(u32x4*)(oth + (srow + RPP * c) * STR + skc) = rr[st ^ 1][c];
; #pragma unroll
;         for (int c = ks; c < CCH; c += KS) {
;           *(u32x4*)(oth + (RM + srow + RPP * c) * STR + skc) = cr[st ^ 1][c];
;           if (SUMSQ && cnt) {
; #pragma unroll
;             for (int e = 0; e < 4; ++e) { const float a_ = bf_lo(cr[st ^ 1][c][e]), b_ = bf_hi(cr[st ^ 1][c][e]); ss[c] += a_ * a_ + b_ * b_; }
;           }
;         }
; #pragma unroll
;         for (int c = ks; c < RCH; c += KS) rr[st ^ 1][c] = *(const u32x4*)(rp + (size_t)(RPP * c) * ldr + k0r);
; #pragma unroll
;         for (int c = ks; c < CCH; c += KS) cr[st ^ 1][c] = *(const u32x4*)(cp + (size_t)(RPP * c) * ldc + k0c);
;         __builtin_amdgcn_sched_barrier(0);
;         if (FDB && ks + 1 < KS) {
; #pragma unroll
;           for (int mi = 0; mi < MI; ++mi) af[(ks + 1) & 1][mi] = *(const bf16x8*)(abase + mi * 32 * STR + (ks + 1) * 16);
; #pragma unroll
;           for (int ni = 0; ni < NI; ++ni) bfr[(ks + 1) & 1][ni] = *(const bf16x8*)(bbase + ni * 32 * STR + (ks + 1) * 16);
;         }
; #pragma unroll
;         for (int mi = 0; mi < MI; ++mi)
; #pragma unroll
;           for (int ni = 0; ni < NI; ++ni) acc[mi][ni] = MFMA32(af[ks & 1][mi], bfr[ks & 1][ni], acc[mi][ni]);
;       }
;       __syncthreads();
	v_mfma_f32_32x32x16_bf16 v[32:47], v[158:161], v[214:217], v[32:47]
	v_mfma_f32_32x32x16_bf16 v[16:31], v[162:165], v[178:181], v[16:31]
	ds_read_b128 v[158:161], v121 offset:36864
	ds_read_b128 v[166:169], v121 offset:41472
	ds_read_b128 v[174:177], v122 offset:55296
	ds_read_b128 v[178:181], v122 offset:59904
	s_waitcnt vmcnt(15)
	ds_write_b128 v120, v[170:173]
	s_waitcnt vmcnt(14)
	ds_write_b128 v120, v[186:189] offset:18432
	v_mfma_f32_32x32x16_bf16 v[0:15], v[162:165], v[214:217], v[0:15]
	s_waitcnt lgkmcnt(3)
	v_mfma_f32_32x32x16_bf16 v[48:63], v[158:161], v[174:177], v[48:63]
	s_waitcnt lgkmcnt(2)
	v_mfma_f32_32x32x16_bf16 v[32:47], v[158:161], v[178:181], v[32:47]
	v_mfma_f32_32x32x16_bf16 v[16:31], v[166:169], v[174:177], v[16:31]
	ds_read_b128 v[158:161], v121 offset:36896
	ds_read_b128 v[162:165], v121 offset:41504
	ds_read_b128 v[170:173], v122 offset:55328
	ds_read_b128 v[174:177], v122 offset:59936
	s_waitcnt vmcnt(13)
	ds_write_b128 v120, v[190:193] offset:4608
	s_waitcnt vmcnt(12)
	ds_write_b128 v120, v[194:197] offset:23040
	v_mfma_f32_32x32x16_bf16 v[0:15], v[166:169], v[178:181], v[0:15]
	s_waitcnt lgkmcnt(3)
	v_mfma_f32_32x32x16_bf16 v[48:63], v[158:161], v[170:173], v[48:63]
	s_waitcnt lgkmcnt(2)
	v_mfma_f32_32x32x16_bf16 v[32:47], v[158:161], v[174:177], v[32:47]
	v_mfma_f32_32x32x16_bf16 v[16:31], v[162:165], v[170:173], v[16:31]
	ds_read_b128 v[158:161], v121 offset:36928
	ds_read_b128 v[166:169], v121 offset:41536
	ds_read_b128 v[170:173], v122 offset:55360
	ds_read_b128 v[178:181], v122 offset:59968
	s_waitcnt vmcnt(11)
	ds_write_b128 v120, v[206:209] offset:9216
	s_waitcnt vmcnt(10)
	ds_write_b128 v120, v[210:213] offset:27648
	v_mfma_f32_32x32x16_bf16 v[0:15], v[162:165], v[174:177], v[0:15]
	s_waitcnt lgkmcnt(3)
	v_mfma_f32_32x32x16_bf16 v[48:63], v[158:161], v[170:173], v[48:63]
	s_waitcnt lgkmcnt(2)
	v_mfma_f32_32x32x16_bf16 v[32:47], v[158:161], v[178:181], v[32:47]
	v_mfma_f32_32x32x16_bf16 v[16:31], v[166:169], v[170:173], v[16:31]
	ds_read_b128 v[158:161], v121 offset:36960
	ds_read_b128 v[162:165], v121 offset:41568
	ds_read_b128 v[170:173], v122 offset:55392
	ds_read_b128 v[174:177], v122 offset:60000
	s_waitcnt vmcnt(9)
	ds_write_b128 v120, v[198:201] offset:13824
	s_waitcnt vmcnt(8)
	ds_write_b128 v120, v[202:205] offset:32256
	v_mfma_f32_32x32x16_bf16 v[0:15], v[166:169], v[178:181], v[0:15]
	s_waitcnt lgkmcnt(3)
	v_mfma_f32_32x32x16_bf16 v[48:63], v[158:161], v[170:173], v[48:63]
	s_waitcnt lgkmcnt(0)
	s_barrier
	v_mfma_f32_32x32x16_bf16 v[32:47], v[158:161], v[174:177], v[32:47]
	v_mfma_f32_32x32x16_bf16 v[16:31], v[162:165], v[170:173], v[16:31]
	ds_read_b128 v[158:161], v121
	ds_read_b128 v[166:169], v121 offset:4608
	ds_read_b128 v[170:173], v122 offset:18432
	ds_read_b128 v[178:181], v122 offset:23040
	s_waitcnt vmcnt(7)
	ds_write_b128 v120, v[142:145] offset:36864
	s_waitcnt vmcnt(6)
	ds_write_b128 v120, v[116:119] offset:55296
	v_mfma_f32_32x32x16_bf16 v[0:15], v[162:165], v[174:177], v[0:15]
	s_waitcnt lgkmcnt(3)
	v_mfma_f32_32x32x16_bf16 v[48:63], v[158:161], v[170:173], v[48:63]
	s_waitcnt lgkmcnt(2)
	v_mfma_f32_32x32x16_bf16 v[32:47], v[158:161], v[178:181], v[32:47]
	ds_read_b128 v[116:119], v121 offset:32
	ds_read_b128 v[142:145], v121 offset:4640
	ds_read_b128 v[158:161], v122 offset:18464
	ds_read_b128 v[162:165], v122 offset:23072
	s_waitcnt vmcnt(5)
	ds_write_b128 v120, v[146:149] offset:41472
	s_waitcnt vmcnt(4)
	ds_write_b128 v120, v[112:115] offset:59904
	v_mfma_f32_32x32x16_bf16 v[16:31], v[166:169], v[170:173], v[16:31]
	v_mfma_f32_32x32x16_bf16 v[0:15], v[166:169], v[178:181], v[0:15]
	s_waitcnt lgkmcnt(3)
	v_mfma_f32_32x32x16_bf16 v[48:63], v[116:119], v[158:161], v[48:63]
	s_waitcnt lgkmcnt(2)
	v_mfma_f32_32x32x16_bf16 v[32:47], v[116:119], v[162:165], v[32:47]
	v_mfma_f32_32x32x16_bf16 v[16:31], v[142:145], v[158:161], v[16:31]
	ds_read_b128 v[112:115], v121 offset:64
	ds_read_b128 v[116:119], v121 offset:4672
	ds_read_b128 v[146:149], v122 offset:18496
	ds_read_b128 v[158:161], v122 offset:23104
	s_waitcnt vmcnt(3)
	ds_write_b128 v120, v[150:153] offset:46080
	s_waitcnt vmcnt(2)
	ds_write_b128 v120, v[108:111] offset:64512
	v_mfma_f32_32x32x16_bf16 v[0:15], v[142:145], v[162:165], v[0:15]
	s_waitcnt lgkmcnt(3)
	v_mfma_f32_32x32x16_bf16 v[48:63], v[112:115], v[146:149], v[48:63]
	s_waitcnt lgkmcnt(2)
	v_mfma_f32_32x32x16_bf16 v[32:47], v[112:115], v[158:161], v[32:47]
	v_mfma_f32_32x32x16_bf16 v[16:31], v[116:119], v[146:149], v[16:31]
	ds_read_b128 v[108:111], v121 offset:96
	ds_read_b128 v[112:115], v121 offset:4704
	ds_read_b128 v[142:145], v122 offset:18528
	ds_read_b128 v[146:149], v122 offset:23136
	s_waitcnt vmcnt(1)
	ds_write_b128 v120, v[154:157] offset:50688
	s_waitcnt vmcnt(0)
	ds_write_b128 v123, v[104:107] offset:13824
	v_mfma_f32_32x32x16_bf16 v[0:15], v[116:119], v[158:161], v[0:15]
	s_waitcnt lgkmcnt(3)
	v_mfma_f32_32x32x16_bf16 v[48:63], v[108:111], v[142:145], v[48:63]
	s_waitcnt lgkmcnt(0)
	s_barrier
; #define MFMA32(a, b, c) __builtin_amdgcn_mfma_f32_32x32x16_bf16((a), (b), (c), 0, 0, 0)
;     ...
;         for (int mi = 0; mi < MI; ++mi)
; #pragma unroll
;           for (int ni = 0; ni < NI; ++ni) acc[mi][ni] = MFMA32(af[ks & 1][mi], bfr[ks & 1][ni], acc[mi][ni]);
;       }
;       __syncthreads();
; DI void phase5(const Params& p, char* smem, const Sched sc) {
;     ...
;     const int b = m0 >> 13;
; #pragma unroll
;     for (int mi = 0; mi < 2; ++mi)
; #pragma unroll
;       for (int ni = 0; ni < 2; ++ni)
; #pragma unroll
;         for (int g = 0; g < 4; ++g) {
;           const f32x4 vv = {acc[mi][ni][4 * g], acc[mi][ni][4 * g + 1], acc[mi][ni][4 * g + 2], acc[mi][ni][4 * g + 3]};
;           *(f32x4*)(ct + (wc * 64 + ni * 32 + r) * CST + wr * 64 + mi * 32 + 8 * g + 4 * h) = vv;
;         }
;     __syncthreads();
;     const int c4 = (tid & 31) * 4, row0 = tid >> 5;
;     const f32x4 gt = *(const f32x4*)(p.ada + b * 3072 + 2048 + n0 + c4);
; #pragma unroll
;     for (int half = 0; half < 2; ++half) {
;       f32x4 xv[8];
; #pragma unroll
;       for (int j = 0; j < 8; ++j) xv[j] = *(const f32x4*)(p.x + (size_t)(m0 + row0 + 8 * (half * 8 + j)) * DM + n0 + c4);
; #pragma unroll
;       for (int j = 0; j < 8; ++j) {
;         const int row = row0 + 8 * (half * 8 + j);
;         const f32x4 cv = *(const f32x4*)(ct + row * CST + c4);
;         f32x4 o;
; #pragma unroll
;         for (int e = 0; e < 4; ++e) o[e] = xv[j][e] + gt[e] * cv[e];
;         *(f32x4*)(p.out + (size_t)(m0 + row) * DM + n0 + c4) = o;
	v_mfma_f32_32x32x16_bf16 v[32:47], v[108:111], v[146:149], v[32:47]
	v_mfma_f32_32x32x16_bf16 v[16:31], v[112:115], v[142:145], v[16:31]
	ds_read_b128 v[104:107], v121 offset:36864
	ds_read_b128 v[108:111], v121 offset:41472
	ds_read_b128 v[116:119], v122 offset:55296
	ds_read_b128 v[142:145], v122 offset:59904
	ds_write_b128 v120, v[84:87]
	ds_write_b128 v120, v[92:95] offset:18432
	v_mfma_f32_32x32x16_bf16 v[0:15], v[112:115], v[146:149], v[0:15]
	s_waitcnt lgkmcnt(3)
	v_mfma_f32_32x32x16_bf16 v[48:63], v[104:107], v[116:119], v[48:63]
	s_waitcnt lgkmcnt(2)
	v_mfma_f32_32x32x16_bf16 v[32:47], v[104:107], v[142:145], v[32:47]
	ds_read_b128 v[84:87], v121 offset:36896
	ds_read_b128 v[92:95], v121 offset:41504
	ds_read_b128 v[104:107], v122 offset:55328
	ds_read_b128 v[112:115], v122 offset:59936
	ds_write_b128 v120, v[80:83] offset:4608
	ds_write_b128 v120, v[88:91] offset:23040
	v_mfma_f32_32x32x16_bf16 v[16:31], v[108:111], v[116:119], v[16:31]
	v_mfma_f32_32x32x16_bf16 v[0:15], v[108:111], v[142:145], v[0:15]
	s_waitcnt lgkmcnt(3)
	v_mfma_f32_32x32x16_bf16 v[48:63], v[84:87], v[104:107], v[48:63]
	s_waitcnt lgkmcnt(2)
	v_mfma_f32_32x32x16_bf16 v[32:47], v[84:87], v[112:115], v[32:47]
	v_mfma_f32_32x32x16_bf16 v[16:31], v[92:95], v[104:107], v[16:31]
	ds_read_b128 v[80:83], v121 offset:36928
	ds_read_b128 v[84:87], v121 offset:41536
	ds_read_b128 v[88:91], v122 offset:55360
	ds_read_b128 v[104:107], v122 offset:59968
	ds_write_b128 v120, v[68:71] offset:9216
	ds_write_b128 v120, v[76:79] offset:27648
	v_mfma_f32_32x32x16_bf16 v[0:15], v[92:95], v[112:115], v[0:15]
	s_waitcnt lgkmcnt(3)
	v_mfma_f32_32x32x16_bf16 v[48:63], v[80:83], v[88:91], v[48:63]
	s_waitcnt lgkmcnt(2)
	v_mfma_f32_32x32x16_bf16 v[32:47], v[80:83], v[104:107], v[32:47]
	v_mfma_f32_32x32x16_bf16 v[16:31], v[84:87], v[88:91], v[16:31]
	ds_read_b128 v[68:71], v121 offset:36960
	ds_read_b128 v[76:79], v121 offset:41568
	ds_read_b128 v[80:83], v122 offset:55392
	ds_read_b128 v[88:91], v122 offset:60000
	ds_write_b128 v120, v[64:67] offset:13824
	ds_write_b128 v120, v[72:75] offset:32256
	v_mfma_f32_32x32x16_bf16 v[0:15], v[84:87], v[104:107], v[0:15]
	s_waitcnt lgkmcnt(3)
	v_mfma_f32_32x32x16_bf16 v[48:63], v[68:71], v[80:83], v[48:63]
	s_lshr_b32 s2, s27, 6
	s_mul_i32 s28, s2, 0xc00
	s_ashr_i32 s29, s28, 31
	s_lshl_b64 s[28:29], s[28:29], 2
	s_add_u32 s9, s6, s28
	s_addc_u32 s27, s7, s29
	s_lshl_b32 s2, s26, 2
	s_waitcnt lgkmcnt(2)
	v_mfma_f32_32x32x16_bf16 v[32:47], v[68:71], v[88:91], v[32:47]
	s_add_u32 s26, s9, s2
	s_waitcnt lgkmcnt(0)
	s_barrier
	s_barrier
	v_mfma_f32_32x32x16_bf16 v[0:15], v[76:79], v[88:91], v[0:15]
	ds_write_b128 v140, v[48:51]
	ds_write_b128 v140, v[52:55] offset:32
	ds_write_b128 v140, v[56:59] offset:64
	ds_write_b128 v140, v[60:63] offset:96
	s_nop 2
	ds_write_b128 v140, v[32:35] offset:16896
	s_addc_u32 s27, s27, 0
	s_add_i32 s25, s25, s33
	s_add_i32 s24, s24, s11
	s_cmpk_gt_i32 s25, 0x7f
	v_mfma_f32_32x32x16_bf16 v[16:31], v[76:79], v[80:83], v[16:31]
	ds_write_b128 v140, v[36:39] offset:16928
	ds_write_b128 v140, v[40:43] offset:16960
	ds_write_b128 v140, v[44:47] offset:16992
	s_nop 8
	ds_write_b128 v140, v[16:19] offset:128
	ds_write_b128 v140, v[20:23] offset:160
	ds_write_b128 v140, v[24:27] offset:192
	ds_write_b128 v140, v[28:31] offset:224
	ds_write_b128 v140, v[0:3] offset:17024
	ds_write_b128 v140, v[4:7] offset:17056
	ds_write_b128 v140, v[8:11] offset:17088
	ds_write_b128 v140, v[12:15] offset:17120
	v_or_b32_e32 v6, s8, v124
	v_lshl_add_u64 v[0:1], s[26:27], 0, v[96:97]
	v_ashrrev_i32_e32 v7, 31, v6
	v_add_co_u32_e32 v0, vcc, s15, v0
	v_lshl_add_u64 v[4:5], v[102:103], 0, s[2:3]
	v_lshlrev_b64 v[44:45], 12, v[6:7]
	v_addc_co_u32_e32 v1, vcc, 0, v1, vcc
	v_lshl_add_u64 v[48:49], v[4:5], 0, v[44:45]
	v_add_co_u32_e32 v12, vcc, s16, v48
	s_waitcnt lgkmcnt(0)
	s_barrier
	global_load_dwordx4 v[0:3], v[0:1], off
	v_addc_co_u32_e32 v13, vcc, 0, v49, vcc
	global_load_dwordx4 v[8:11], v[48:49], off
	v_add_co_u32_e32 v16, vcc, s12, v48
	global_load_dwordx4 v[12:15], v[12:13], off
	s_nop 0
	v_addc_co_u32_e32 v17, vcc, 0, v49, vcc
	global_load_dwordx4 v[16:19], v[16:17], off
	v_add_co_u32_e32 v20, vcc, s17, v48
	v_or_b32_e32 v24, 32, v6
	s_nop 0
	v_addc_co_u32_e32 v21, vcc, 0, v49, vcc
	global_load_dwordx4 v[20:23], v[20:21], off
	v_ashrrev_i32_e32 v25, 31, v24
	v_lshlrev_b64 v[24:25], 12, v[24:25]
	v_lshl_add_u64 v[24:25], v[4:5], 0, v[24:25]
	global_load_dwordx4 v[24:27], v[24:25], off
	v_add_co_u32_e32 v28, vcc, s18, v48
	ds_read_b128 v[40:43], v141
	s_nop 0
	v_addc_co_u32_e32 v29, vcc, 0, v49, vcc
	global_load_dwordx4 v[28:31], v[28:29], off
	v_add_co_u32_e32 v32, vcc, s14, v48
	v_lshl_add_u64 v[44:45], s[4:5], 0, v[44:45]
	s_nop 0
	v_addc_co_u32_e32 v33, vcc, 0, v49, vcc
	global_load_dwordx4 v[32:35], v[32:33], off
	v_add_co_u32_e32 v36, vcc, s19, v48
	v_lshl_add_u64 v[50:51], v[44:45], 0, s[2:3]
	s_nop 0
	v_addc_co_u32_e32 v37, vcc, 0, v49, vcc
	global_load_dwordx4 v[36:39], v[36:37], off
	ds_read_b128 v[44:47], v141 offset:4224
	s_waitcnt vmcnt(7) lgkmcnt(1)
	v_fmac_f32_e32 v10, v2, v42
	v_fmac_f32_e32 v11, v3, v43
	v_fmac_f32_e32 v8, v0, v40
	v_fmac_f32_e32 v9, v1, v41
	v_lshl_add_u64 v[40:41], v[50:51], 0, v[96:97]
	global_store_dwordx4 v[40:41], v[8:11], off
	s_waitcnt vmcnt(7) lgkmcnt(0)
	s_nop 0
	v_fma_f32 v8, v0, v44, v12
	v_fma_f32 v9, v1, v45, v13
	v_or_b32_e32 v12, s8, v125
	v_ashrrev_i32_e32 v13, 31, v12
	v_lshlrev_b64 v[12:13], 12, v[12:13]
	v_fma_f32 v10, v2, v46, v14
	v_fma_f32 v11, v3, v47, v15
	v_lshl_add_u64 v[40:41], s[4:5], 0, v[12:13]
	ds_read_b128 v[12:15], v141 offset:8448
	v_lshl_add_u64 v[40:41], v[40:41], 0, s[2:3]
	v_lshl_add_u64 v[40:41], v[40:41], 0, v[96:97]
	global_store_dwordx4 v[40:41], v[8:11], off
	ds_read_b128 v[8:11], v141 offset:12672
	s_waitcnt vmcnt(7) lgkmcnt(1)
; DI void phase5(const Params& p, char* smem, const Sched sc) {
;     ...
;     const int c4 = (tid & 31) * 4, row0 = tid >> 5;
;     const f32x4 gt = *(const f32x4*)(p.ada + b * 3072 + 2048 + n0 + c4);
; #pragma unroll
;     for (int half = 0; half < 2; ++half) {
;       f32x4 xv[8];
; #pragma unroll
;       for (int j = 0; j < 8; ++j) xv[j] = *(const f32x4*)(p.x + (size_t)(m0 + row0 + 8 * (half * 8 + j)) * DM + n0 + c4);
; #pragma unroll
;       for (int j = 0; j < 8; ++j) {
;         const int row = row0 + 8 * (half * 8 + j);
;         const f32x4 cv = *(const f32x4*)(ct + row * CST + c4);
;         f32x4 o;
; #pragma unroll
;         for (int e = 0; e < 4; ++e) o[e] = xv[j][e] + gt[e] * cv[e];
;         *(f32x4*)(p.out + (size_t)(m0 + row) * DM + n0 + c4) = o;
	v_fma_f32 v12, v0, v12, v16
	v_fma_f32 v13, v1, v13, v17
	v_or_b32_e32 v16, s8, v126
	v_ashrrev_i32_e32 v17, 31, v16
	v_lshlrev_b64 v[16:17], 12, v[16:17]
	v_lshl_add_u64 v[16:17], s[4:5], 0, v[16:17]
	v_lshl_add_u64 v[16:17], v[16:17], 0, s[2:3]
	v_fma_f32 v14, v2, v14, v18
	v_fma_f32 v15, v3, v15, v19
	v_lshl_add_u64 v[16:17], v[16:17], 0, v[96:97]
	global_store_dwordx4 v[16:17], v[12:15], off
	s_waitcnt vmcnt(7) lgkmcnt(0)
	v_fma_f32 v10, v2, v10, v22
	v_fma_f32 v11, v3, v11, v23
	v_fma_f32 v8, v0, v8, v20
	v_fma_f32 v9, v1, v9, v21
	v_or_b32_e32 v12, s8, v127
	v_ashrrev_i32_e32 v13, 31, v12
	v_lshlrev_b64 v[12:13], 12, v[12:13]
	v_lshl_add_u64 v[16:17], s[4:5], 0, v[12:13]
	v_lshl_add_u64 v[16:17], v[16:17], 0, s[2:3]
	v_lshl_add_u64 v[16:17], v[16:17], 0, v[96:97]
	ds_read_b128 v[12:15], v141 offset:16896
	global_store_dwordx4 v[16:17], v[8:11], off
	v_or_b32_e32 v16, s8, v128
	v_ashrrev_i32_e32 v17, 31, v16
	v_lshlrev_b64 v[16:17], 12, v[16:17]
	v_lshl_add_u64 v[16:17], s[4:5], 0, v[16:17]
	v_lshl_add_u64 v[16:17], v[16:17], 0, s[2:3]
	ds_read_b128 v[8:11], v141 offset:21120
	s_waitcnt vmcnt(7) lgkmcnt(1)
	v_fma_f32 v14, v2, v14, v26
	v_fma_f32 v15, v3, v15, v27
	v_fma_f32 v12, v0, v12, v24
	v_fma_f32 v13, v1, v13, v25
	v_lshl_add_u64 v[16:17], v[16:17], 0, v[96:97]
	global_store_dwordx4 v[16:17], v[12:15], off
	s_waitcnt vmcnt(7) lgkmcnt(0)
	v_fma_f32 v10, v2, v10, v30
	v_fma_f32 v11, v3, v11, v31
	v_fma_f32 v8, v0, v8, v28
	v_fma_f32 v9, v1, v9, v29
	v_or_b32_e32 v12, s8, v129
	v_ashrrev_i32_e32 v13, 31, v12
	v_lshlrev_b64 v[12:13], 12, v[12:13]
	v_lshl_add_u64 v[16:17], s[4:5], 0, v[12:13]
	v_lshl_add_u64 v[16:17], v[16:17], 0, s[2:3]
	v_lshl_add_u64 v[16:17], v[16:17], 0, v[96:97]
	ds_read_b128 v[12:15], v141 offset:25344
	global_store_dwordx4 v[16:17], v[8:11], off
	v_or_b32_e32 v16, s8, v130
	v_ashrrev_i32_e32 v17, 31, v16
	v_lshlrev_b64 v[16:17], 12, v[16:17]
	v_lshl_add_u64 v[16:17], s[4:5], 0, v[16:17]
	v_lshl_add_u64 v[16:17], v[16:17], 0, s[2:3]
	ds_read_b128 v[8:11], v141 offset:29568
	s_waitcnt vmcnt(7) lgkmcnt(1)
	v_fma_f32 v14, v2, v14, v34
	v_fma_f32 v15, v3, v15, v35
	v_fma_f32 v12, v0, v12, v32
	v_fma_f32 v13, v1, v13, v33
	v_lshl_add_u64 v[16:17], v[16:17], 0, v[96:97]
	global_store_dwordx4 v[16:17], v[12:15], off
	s_waitcnt vmcnt(7) lgkmcnt(0)
	v_fma_f32 v10, v2, v10, v38
	v_fma_f32 v11, v3, v11, v39
	v_fma_f32 v8, v0, v8, v36
	v_fma_f32 v9, v1, v9, v37
	v_or_b32_e32 v12, s8, v131
	v_ashrrev_i32_e32 v13, 31, v12
	v_lshlrev_b64 v[12:13], 12, v[12:13]
	v_lshl_add_u64 v[12:13], s[4:5], 0, v[12:13]
	v_lshl_add_u64 v[12:13], v[12:13], 0, s[2:3]
	v_lshl_add_u64 v[12:13], v[12:13], 0, v[96:97]
	global_store_dwordx4 v[12:13], v[8:11], off
	v_add_co_u32_e32 v12, vcc, s20, v48
	s_nop 0
	v_or_b32_e32 v8, 64, v6
	v_ashrrev_i32_e32 v9, 31, v8
	v_lshlrev_b64 v[8:9], 12, v[8:9]
	v_lshl_add_u64 v[8:9], v[4:5], 0, v[8:9]
	global_load_dwordx4 v[8:11], v[8:9], off
	v_addc_co_u32_e32 v13, vcc, 0, v49, vcc
	global_load_dwordx4 v[12:15], v[12:13], off
	v_add_co_u32_e32 v16, vcc, s21, v48
	v_or_b32_e32 v24, 0x60, v6
	s_nop 0
	v_addc_co_u32_e32 v17, vcc, 0, v49, vcc
	global_load_dwordx4 v[16:19], v[16:17], off
	v_add_co_u32_e32 v20, vcc, s22, v48
	v_ashrrev_i32_e32 v25, 31, v24
	s_nop 0
	v_addc_co_u32_e32 v21, vcc, 0, v49, vcc
	global_load_dwordx4 v[20:23], v[20:21], off
	v_lshlrev_b64 v[24:25], 12, v[24:25]
	v_lshl_add_u64 v[24:25], v[4:5], 0, v[24:25]
	global_load_dwordx4 v[24:27], v[24:25], off
	v_add_u32_e32 v28, 0x68, v6
	v_ashrrev_i32_e32 v29, 31, v28
	v_lshlrev_b64 v[28:29], 12, v[28:29]
	v_lshl_add_u64 v[28:29], v[4:5], 0, v[28:29]
	global_load_dwordx4 v[28:31], v[28:29], off
	v_add_u32_e32 v32, 0x70, v6
	v_add_u32_e32 v6, 0x78, v6
	v_ashrrev_i32_e32 v33, 31, v32
	v_ashrrev_i32_e32 v7, 31, v6
	v_lshlrev_b64 v[32:33], 12, v[32:33]
	v_lshlrev_b64 v[6:7], 12, v[6:7]
	v_lshl_add_u64 v[32:33], v[4:5], 0, v[32:33]
	v_lshl_add_u64 v[4:5], v[4:5], 0, v[6:7]
	global_load_dwordx4 v[32:35], v[32:33], off
	s_nop 0
	global_load_dwordx4 v[4:7], v[4:5], off
	ds_read_b128 v[36:39], v141 offset:33792
	ds_read_b128 v[40:43], v141 offset:38016
	s_waitcnt vmcnt(7) lgkmcnt(1)
; DI void phase5(const Params& p, char* smem, const Sched sc) {
;     ...
;     for (int half = 0; half < 2; ++half) {
;       f32x4 xv[8];
; #pragma unroll
;       for (int j = 0; j < 8; ++j) xv[j] = *(const f32x4*)(p.x + (size_t)(m0 + row0 + 8 * (half * 8 + j)) * DM + n0 + c4);
; #pragma unroll
;       for (int j = 0; j < 8; ++j) {
;         const int row = row0 + 8 * (half * 8 + j);
;         const f32x4 cv = *(const f32x4*)(ct + row * CST + c4);
;         f32x4 o;
; #pragma unroll
;         for (int e = 0; e < 4; ++e) o[e] = xv[j][e] + gt[e] * cv[e];
;         *(f32x4*)(p.out + (size_t)(m0 + row) * DM + n0 + c4) = o;
	v_fmac_f32_e32 v8, v0, v36
	v_fmac_f32_e32 v9, v1, v37
	v_or_b32_e32 v36, s8, v132
	v_ashrrev_i32_e32 v37, 31, v36
	v_lshlrev_b64 v[36:37], 12, v[36:37]
	v_lshl_add_u64 v[36:37], s[4:5], 0, v[36:37]
	v_lshl_add_u64 v[36:37], v[36:37], 0, s[2:3]
	v_fmac_f32_e32 v10, v2, v38
	v_fmac_f32_e32 v11, v3, v39
	v_lshl_add_u64 v[36:37], v[36:37], 0, v[96:97]
	global_store_dwordx4 v[36:37], v[8:11], off
	s_waitcnt vmcnt(7) lgkmcnt(0)
	s_nop 0
	v_fma_f32 v8, v0, v40, v12
	v_fma_f32 v9, v1, v41, v13
	v_or_b32_e32 v12, s8, v133
	v_ashrrev_i32_e32 v13, 31, v12
	v_lshlrev_b64 v[12:13], 12, v[12:13]
	v_fma_f32 v10, v2, v42, v14
	v_fma_f32 v11, v3, v43, v15
	v_lshl_add_u64 v[36:37], s[4:5], 0, v[12:13]
	ds_read_b128 v[12:15], v141 offset:42240
	v_lshl_add_u64 v[36:37], v[36:37], 0, s[2:3]
	v_lshl_add_u64 v[36:37], v[36:37], 0, v[96:97]
	global_store_dwordx4 v[36:37], v[8:11], off
	ds_read_b128 v[8:11], v141 offset:46464
	s_waitcnt vmcnt(7) lgkmcnt(1)
	v_fma_f32 v12, v0, v12, v16
	v_fma_f32 v13, v1, v13, v17
	v_or_b32_e32 v16, s8, v134
	v_ashrrev_i32_e32 v17, 31, v16
	v_lshlrev_b64 v[16:17], 12, v[16:17]
	v_lshl_add_u64 v[16:17], s[4:5], 0, v[16:17]
	v_lshl_add_u64 v[16:17], v[16:17], 0, s[2:3]
	v_fma_f32 v14, v2, v14, v18
	v_fma_f32 v15, v3, v15, v19
	v_lshl_add_u64 v[16:17], v[16:17], 0, v[96:97]
	global_store_dwordx4 v[16:17], v[12:15], off
	s_waitcnt vmcnt(7) lgkmcnt(0)
	v_fma_f32 v10, v2, v10, v22
	v_fma_f32 v11, v3, v11, v23
	v_fma_f32 v8, v0, v8, v20
	v_fma_f32 v9, v1, v9, v21
	v_or_b32_e32 v12, s8, v135
	v_ashrrev_i32_e32 v13, 31, v12
	v_lshlrev_b64 v[12:13], 12, v[12:13]
	v_lshl_add_u64 v[16:17], s[4:5], 0, v[12:13]
	v_lshl_add_u64 v[16:17], v[16:17], 0, s[2:3]
	v_lshl_add_u64 v[16:17], v[16:17], 0, v[96:97]
	ds_read_b128 v[12:15], v141 offset:50688
	global_store_dwordx4 v[16:17], v[8:11], off
	v_or_b32_e32 v16, s8, v136
	v_ashrrev_i32_e32 v17, 31, v16
	v_lshlrev_b64 v[16:17], 12, v[16:17]
	v_lshl_add_u64 v[16:17], s[4:5], 0, v[16:17]
	v_lshl_add_u64 v[16:17], v[16:17], 0, s[2:3]
	ds_read_b128 v[8:11], v141 offset:54912
	s_waitcnt vmcnt(7) lgkmcnt(1)
	v_fma_f32 v14, v2, v14, v26
	v_fma_f32 v15, v3, v15, v27
	v_fma_f32 v12, v0, v12, v24
	v_fma_f32 v13, v1, v13, v25
	v_lshl_add_u64 v[16:17], v[16:17], 0, v[96:97]
	global_store_dwordx4 v[16:17], v[12:15], off
	s_waitcnt vmcnt(7) lgkmcnt(0)
	v_fma_f32 v10, v2, v10, v30
	v_fma_f32 v11, v3, v11, v31
	v_fma_f32 v8, v0, v8, v28
	v_fma_f32 v9, v1, v9, v29
	v_add_u32_e32 v12, s8, v137
	v_ashrrev_i32_e32 v13, 31, v12
	v_lshlrev_b64 v[12:13], 12, v[12:13]
	v_lshl_add_u64 v[16:17], s[4:5], 0, v[12:13]
	v_lshl_add_u64 v[16:17], v[16:17], 0, s[2:3]
	v_lshl_add_u64 v[16:17], v[16:17], 0, v[96:97]
	ds_read_b128 v[12:15], v141 offset:59136
	global_store_dwordx4 v[16:17], v[8:11], off
	ds_read_b128 v[8:11], v141 offset:63360
	v_add_u32_e32 v16, s8, v138
	v_ashrrev_i32_e32 v17, 31, v16
	s_waitcnt vmcnt(7) lgkmcnt(1)
	v_fma_f32 v12, v0, v12, v32
	v_fma_f32 v13, v1, v13, v33
	v_lshlrev_b64 v[16:17], 12, v[16:17]
	s_waitcnt vmcnt(6) lgkmcnt(0)
	v_fma_f32 v0, v0, v8, v4
	v_fma_f32 v1, v1, v9, v5
	v_add_u32_e32 v4, s8, v139
	v_ashrrev_i32_e32 v5, 31, v4
	v_lshlrev_b64 v[4:5], 12, v[4:5]
	v_lshl_add_u64 v[16:17], s[4:5], 0, v[16:17]
	v_lshl_add_u64 v[4:5], s[4:5], 0, v[4:5]
	v_lshl_add_u64 v[16:17], v[16:17], 0, s[2:3]
	v_lshl_add_u64 v[4:5], v[4:5], 0, s[2:3]
	v_fma_f32 v14, v2, v14, v34
	v_fma_f32 v15, v3, v15, v35
	v_lshl_add_u64 v[16:17], v[16:17], 0, v[96:97]
	v_fma_f32 v2, v2, v10, v6
	v_fma_f32 v3, v3, v11, v7
	v_lshl_add_u64 v[4:5], v[4:5], 0, v[96:97]
	global_store_dwordx4 v[16:17], v[12:15], off
	global_store_dwordx4 v[4:5], v[0:3], off
	s_barrier
	s_cbranch_scc0 .LBB0_529
	s_branch .LBB0_526
